# cand18 + activation rotate/quantise phases visit prompt rows in descending order (most recently written rows first)
# speedup vs baseline: 1.0059x; 1.0059x over previous
.LBB0_998:
	s_or_b64 exec, exec, s[0:1]
	s_mov_b64 s[0:1], s[94:95]
	v_mov_b32_e32 v188, v0
	s_waitcnt lgkmcnt(0)
	s_barrier
	s_load_dwordx2 s[4:5], s[0:1], 0xc8
	v_readfirstlane_b32 s2, v188
	s_ashr_i32 s2, s2, 6
	v_and_b32_e32 v1, 63, v188
	s_add_i32 s6, s2, s81
	s_movk_i32 s10, 0x2000
	s_cmpk_lt_i32 s6, 0x2000
	v_cmp_gt_u32_e64 s[0:1], 48, v1
	v_lshlrev_b32_e32 v178, 4, v1
	v_lshlrev_b32_e32 v180, 5, v1
	s_cbranch_scc0 .LBB0_1021
	s_waitcnt lgkmcnt(0)
	s_add_u32 s2, s4, 0x4bd00000
	s_addc_u32 s3, s5, 0
	s_sub_i32 s98, 0x1fff, s6
	s_mul_i32 s8, s98, 0x5600
	s_mul_hi_i32 s7, s98, 0x5600
	s_add_u32 s24, s2, s8
	v_mov_b32_e32 v179, 0
	s_addc_u32 s25, s3, s7
	v_mov_b32_e32 v181, v179
	v_lshl_add_u64 v[74:75], s[24:25], 0, v[180:181]
	s_movk_i32 s7, 0x1000
	v_add_co_u32_e32 v20, vcc, s7, v74
	s_movk_i32 s36, 0x3000
	s_nop 0
	v_addc_co_u32_e32 v21, vcc, 0, v75, vcc
	v_add_co_u32_e32 v38, vcc, s10, v74
	s_mov_b64 s[8:9], 0x1000
	s_nop 0
	v_addc_co_u32_e32 v39, vcc, 0, v75, vcc
	v_add_co_u32_e32 v58, vcc, s36, v74
	s_mov_b64 s[10:11], 0x1800
	s_mov_b64 s[12:13], 0x2000
	s_mov_b64 s[14:15], 0x2800
	s_mov_b64 s[16:17], 0x3000
	v_addc_co_u32_e32 v59, vcc, 0, v75, vcc
	v_lshl_add_u64 v[18:19], v[74:75], 0, s[8:9]
	v_lshl_add_u64 v[26:27], v[74:75], 0, s[10:11]
	v_lshl_add_u64 v[30:31], v[74:75], 0, s[12:13]
	v_lshl_add_u64 v[42:43], v[74:75], 0, s[14:15]
	v_lshl_add_u64 v[44:45], v[74:75], 0, s[16:17]
	s_mov_b64 s[18:19], 0x3800
	s_mov_b64 s[20:21], 0x4000
	v_add_co_u32_e32 v66, vcc, 0x4000, v74
	global_load_dwordx4 v[2:5], v180, s[24:25] offset:16
	global_load_dwordx4 v[6:9], v180, s[24:25] offset:2048
	global_load_dwordx4 v[10:13], v180, s[24:25] offset:2064
	global_load_dwordx4 v[14:17], v[38:39], off offset:-4096
	global_load_dwordx4 v[22:25], v[18:19], off offset:16
	s_nop 0
	global_load_dwordx4 v[18:21], v[20:21], off offset:2048
	s_nop 0
	global_load_dwordx4 v[26:29], v[26:27], off offset:16
	s_nop 0
	global_load_dwordx4 v[34:37], v[30:31], off offset:16
	s_nop 0
	global_load_dwordx4 v[30:33], v[38:39], off
	s_nop 0
	global_load_dwordx4 v[38:41], v[38:39], off offset:2048
	s_nop 0
	global_load_dwordx4 v[46:49], v[42:43], off offset:16
	global_load_dwordx4 v[54:57], v[44:45], off offset:16
	v_lshl_add_u64 v[42:43], v[74:75], 0, s[18:19]
	v_lshl_add_u64 v[44:45], v[74:75], 0, s[20:21]
	v_addc_co_u32_e32 v67, vcc, 0, v75, vcc
	s_mov_b64 s[22:23], 0x4800
	global_load_dwordx4 v[50:53], v[58:59], off
	s_nop 0
	global_load_dwordx4 v[58:61], v[58:59], off offset:2048
	s_nop 0
	global_load_dwordx4 v[62:65], v[42:43], off offset:16
	global_load_dwordx4 v[154:157], v[44:45], off offset:16
	v_lshl_add_u64 v[68:69], v[74:75], 0, s[22:23]
	global_load_dwordx4 v[146:149], v[66:67], off
	global_load_dwordx4 v[102:105], v[66:67], off offset:2048
	global_load_dwordx4 v[42:45], v180, s[24:25]
	global_load_dwordx4 v[114:117], v[68:69], off offset:16
	v_mov_b32_e32 v70, v179
	v_mov_b32_e32 v71, v179
	v_mov_b32_e32 v72, v179
	v_mov_b32_e32 v73, v179
	v_mov_b32_e32 v66, v179
	v_mov_b32_e32 v67, v179
	v_mov_b32_e32 v68, v179
	v_mov_b32_e32 v69, v179
	s_and_saveexec_b64 s[24:25], s[0:1]
	s_cbranch_execz .LBB0_1001
	s_mov_b64 s[26:27], 0x5000
	v_add_co_u32_e32 v66, vcc, 0x5000, v74
	v_lshl_add_u64 v[70:71], v[74:75], 0, s[26:27]
	s_nop 0
	v_addc_co_u32_e32 v67, vcc, 0, v75, vcc
	global_load_dwordx4 v[66:69], v[66:67], off
	s_nop 0
	global_load_dwordx4 v[70:73], v[70:71], off offset:16
.LBB0_1001:
	s_or_b64 exec, exec, s[24:25]
	v_lshlrev_b32_e32 v74, 1, v178
	v_mov_b32_e32 v75, v179
	s_add_u32 s2, s2, 0xabfaa00
	s_addc_u32 s3, s3, 0
	v_lshl_add_u64 v[182:183], s[2:3], 0, v[74:75]
	v_lshl_add_u64 v[74:75], s[4:5], 0, v[178:179]
	s_mov_b64 s[2:3], 0x342fd500
	s_add_u32 s37, s4, 0x47407ffc
	v_lshl_add_u64 v[184:185], v[74:75], 0, s[2:3]
	v_lshlrev_b32_e32 v74, 30, v188
	s_addc_u32 s38, s5, 0
	v_lshlrev_b32_e32 v181, 31, v188
	v_and_b32_e32 v189, 0x80000000, v74
	v_cmp_eq_u32_e64 s[2:3], 0, v1
	s_movk_i32 s39, 0x2000
	s_mov_b64 s[24:25], 0x5000
	v_mbcnt_hi_u32_b32 v190, -1, v234
	s_mov_b32 s41, 0x42fe0000
	s_mov_b32 s44, 0xc0c0400
	s_mov_b32 s45, 0x4000c0c
	v_mov_b32_e32 v191, 0xffffaa00
	v_mov_b32_e32 v192, 0xffffd500
	s_mov_b32 s30, s6
	s_branch .LBB0_1004

.LBB0_1008:
	s_waitcnt vmcnt(19)
	v_lshlrev_b32_e32 v187, 16, v2
	s_waitcnt vmcnt(1)
	v_lshlrev_b32_e32 v186, 16, v42
	v_and_b32_e32 v195, 0xffff0000, v2
	v_and_b32_e32 v194, 0xffff0000, v42
	v_lshlrev_b32_e32 v197, 16, v3
	v_lshlrev_b32_e32 v196, 16, v43
	v_and_b32_e32 v3, 0xffff0000, v3
	v_and_b32_e32 v2, 0xffff0000, v43
	v_lshlrev_b32_e32 v43, 16, v4
	v_lshlrev_b32_e32 v42, 16, v44
	v_and_b32_e32 v199, 0xffff0000, v4
	v_and_b32_e32 v198, 0xffff0000, v44
	v_lshlrev_b32_e32 v201, 16, v5
	v_lshlrev_b32_e32 v200, 16, v45
	v_and_b32_e32 v5, 0xffff0000, v5
	v_and_b32_e32 v4, 0xffff0000, v45
	v_pk_add_f32 v[44:45], v[186:187], v[194:195]
	v_pk_add_f32 v[202:203], v[196:197], v[2:3]
	v_pk_add_f32 v[204:205], v[42:43], v[198:199]
	v_pk_add_f32 v[206:207], v[200:201], v[4:5]
	v_pk_add_f32 v[186:187], v[186:187], v[194:195] neg_lo:[0,1] neg_hi:[0,1]
	v_pk_add_f32 v[2:3], v[196:197], v[2:3] neg_lo:[0,1] neg_hi:[0,1]
	v_pk_add_f32 v[42:43], v[42:43], v[198:199] neg_lo:[0,1] neg_hi:[0,1]
	v_pk_add_f32 v[4:5], v[200:201], v[4:5] neg_lo:[0,1] neg_hi:[0,1]
	v_pk_add_f32 v[208:209], v[44:45], v[202:203] neg_lo:[0,1] neg_hi:[0,1]
	v_pk_add_f32 v[44:45], v[44:45], v[202:203]
	v_pk_add_f32 v[202:203], v[204:205], v[206:207]
	v_pk_add_f32 v[194:195], v[186:187], v[2:3] neg_lo:[0,1] neg_hi:[0,1]
	v_pk_add_f32 v[196:197], v[42:43], v[4:5] neg_lo:[0,1] neg_hi:[0,1]
	v_pk_add_f32 v[2:3], v[186:187], v[2:3]
	v_pk_add_f32 v[4:5], v[42:43], v[4:5]
	v_pk_add_f32 v[210:211], v[204:205], v[206:207] neg_lo:[0,1] neg_hi:[0,1]
	v_pk_add_f32 v[204:205], v[44:45], v[202:203]
	v_pk_add_f32 v[42:43], v[2:3], v[4:5]
	v_pk_add_f32 v[2:3], v[2:3], v[4:5] neg_lo:[0,1] neg_hi:[0,1]
	v_pk_add_f32 v[44:45], v[44:45], v[202:203] neg_lo:[0,1] neg_hi:[0,1]
	v_pk_add_f32 v[202:203], v[208:209], v[210:211]
	v_pk_add_f32 v[206:207], v[208:209], v[210:211] neg_lo:[0,1] neg_hi:[0,1]
	v_pk_add_f32 v[4:5], v[194:195], v[196:197]
	v_pk_add_f32 v[186:187], v[194:195], v[196:197] neg_lo:[0,1] neg_hi:[0,1]
	v_pk_add_f32 v[194:195], v[204:205], v[204:205] op_sel:[0,1] op_sel_hi:[1,0]
	v_pk_add_f32 v[210:211], v[2:3], v[2:3] op_sel:[0,1] op_sel_hi:[1,0]
	v_pk_add_f32 v[2:3], v[2:3], v[2:3] op_sel:[0,1] op_sel_hi:[1,0] neg_lo:[0,1] neg_hi:[0,1]
	v_pk_add_f32 v[196:197], v[204:205], v[204:205] op_sel:[0,1] op_sel_hi:[1,0] neg_lo:[0,1] neg_hi:[0,1]
	v_pk_add_f32 v[198:199], v[42:43], v[42:43] op_sel:[0,1] op_sel_hi:[1,0]
	v_pk_add_f32 v[204:205], v[4:5], v[4:5] op_sel:[0,1] op_sel_hi:[1,0]
	v_pk_add_f32 v[4:5], v[4:5], v[4:5] op_sel:[0,1] op_sel_hi:[1,0] neg_lo:[0,1] neg_hi:[0,1]
	v_pk_add_f32 v[214:215], v[186:187], v[186:187] op_sel:[0,1] op_sel_hi:[1,0]
	v_pk_add_f32 v[186:187], v[186:187], v[186:187] op_sel:[0,1] op_sel_hi:[1,0] neg_lo:[0,1] neg_hi:[0,1]
	v_xor_b32_e32 v3, v181, v194
	v_pk_add_f32 v[42:43], v[42:43], v[42:43] op_sel:[0,1] op_sel_hi:[1,0] neg_lo:[0,1] neg_hi:[0,1]
	v_pk_add_f32 v[200:201], v[202:203], v[202:203] op_sel:[0,1] op_sel_hi:[1,0]
	v_add_f32_dpp v3, v194, v3 quad_perm:[1,0,3,2] row_mask:0xf bank_mask:0xf bound_ctrl:1
	v_xor_b32_e32 v5, v181, v198
	v_xor_b32_e32 v199, v181, v186
	v_pk_add_f32 v[208:209], v[44:45], v[44:45] op_sel:[0,1] op_sel_hi:[1,0]
	v_pk_add_f32 v[44:45], v[44:45], v[44:45] op_sel:[0,1] op_sel_hi:[1,0] neg_lo:[0,1] neg_hi:[0,1]
	v_add_f32_dpp v5, v198, v5 quad_perm:[1,0,3,2] row_mask:0xf bank_mask:0xf bound_ctrl:1
	v_xor_b32_e32 v43, v181, v200
	v_add_f32_dpp v186, v186, v199 quad_perm:[1,0,3,2] row_mask:0xf bank_mask:0xf bound_ctrl:1
	v_xor_b32_e32 v199, v189, v3
	v_add_f32_dpp v43, v200, v43 quad_perm:[1,0,3,2] row_mask:0xf bank_mask:0xf bound_ctrl:1
	v_xor_b32_e32 v45, v181, v204
	v_add_f32_dpp v3, v3, v199 quad_perm:[2,3,0,1] row_mask:0xf bank_mask:0xf bound_ctrl:1
	v_xor_b32_e32 v199, v189, v5
	v_add_f32_dpp v45, v204, v45 quad_perm:[1,0,3,2] row_mask:0xf bank_mask:0xf bound_ctrl:1
	v_xor_b32_e32 v187, v181, v208
	v_add_f32_dpp v5, v5, v199 quad_perm:[2,3,0,1] row_mask:0xf bank_mask:0xf bound_ctrl:1
	v_xor_b32_e32 v199, v189, v43
	v_pk_add_f32 v[212:213], v[206:207], v[206:207] op_sel:[0,1] op_sel_hi:[1,0]
	v_add_f32_dpp v187, v208, v187 quad_perm:[1,0,3,2] row_mask:0xf bank_mask:0xf bound_ctrl:1
	v_xor_b32_e32 v193, v181, v210
	v_add_f32_dpp v43, v43, v199 quad_perm:[2,3,0,1] row_mask:0xf bank_mask:0xf bound_ctrl:1
	v_xor_b32_e32 v199, v189, v45
	v_add_f32_dpp v193, v210, v193 quad_perm:[1,0,3,2] row_mask:0xf bank_mask:0xf bound_ctrl:1
	v_xor_b32_e32 v194, v181, v212
	v_add_f32_dpp v45, v45, v199 quad_perm:[2,3,0,1] row_mask:0xf bank_mask:0xf bound_ctrl:1
	v_xor_b32_e32 v199, v189, v187
	v_add_f32_dpp v194, v212, v194 quad_perm:[1,0,3,2] row_mask:0xf bank_mask:0xf bound_ctrl:1
	v_xor_b32_e32 v195, v181, v214
	v_add_f32_dpp v187, v187, v199 quad_perm:[2,3,0,1] row_mask:0xf bank_mask:0xf bound_ctrl:1
	v_xor_b32_e32 v199, v189, v193
	v_add_f32_dpp v195, v214, v195 quad_perm:[1,0,3,2] row_mask:0xf bank_mask:0xf bound_ctrl:1
	v_xor_b32_e32 v197, v181, v196
	v_add_f32_dpp v193, v193, v199 quad_perm:[2,3,0,1] row_mask:0xf bank_mask:0xf bound_ctrl:1
	v_xor_b32_e32 v199, v189, v194
	v_pk_add_f32 v[202:203], v[202:203], v[202:203] op_sel:[0,1] op_sel_hi:[1,0] neg_lo:[0,1] neg_hi:[0,1]
	v_add_f32_dpp v196, v196, v197 quad_perm:[1,0,3,2] row_mask:0xf bank_mask:0xf bound_ctrl:1
	v_xor_b32_e32 v197, v181, v42
	v_add_f32_dpp v194, v194, v199 quad_perm:[2,3,0,1] row_mask:0xf bank_mask:0xf bound_ctrl:1
	v_xor_b32_e32 v199, v189, v195
	v_add_f32_dpp v42, v42, v197 quad_perm:[1,0,3,2] row_mask:0xf bank_mask:0xf bound_ctrl:1
	v_xor_b32_e32 v197, v181, v202
	v_add_f32_dpp v195, v195, v199 quad_perm:[2,3,0,1] row_mask:0xf bank_mask:0xf bound_ctrl:1
	v_xor_b32_e32 v199, v189, v196
	v_add_f32_dpp v197, v202, v197 quad_perm:[1,0,3,2] row_mask:0xf bank_mask:0xf bound_ctrl:1
	v_xor_b32_e32 v198, v181, v4
	v_add_f32_dpp v196, v196, v199 quad_perm:[2,3,0,1] row_mask:0xf bank_mask:0xf bound_ctrl:1
	v_xor_b32_e32 v199, v189, v42
	v_add_f32_dpp v4, v4, v198 quad_perm:[1,0,3,2] row_mask:0xf bank_mask:0xf bound_ctrl:1
	v_xor_b32_e32 v198, v181, v44
	v_add_f32_dpp v199, v42, v199 quad_perm:[2,3,0,1] row_mask:0xf bank_mask:0xf bound_ctrl:1
	v_xor_b32_e32 v42, v189, v197
	v_pk_add_f32 v[206:207], v[206:207], v[206:207] op_sel:[0,1] op_sel_hi:[1,0] neg_lo:[0,1] neg_hi:[0,1]
	v_add_f32_dpp v44, v44, v198 quad_perm:[1,0,3,2] row_mask:0xf bank_mask:0xf bound_ctrl:1
	v_xor_b32_e32 v198, v181, v2
	v_add_f32_dpp v197, v197, v42 quad_perm:[2,3,0,1] row_mask:0xf bank_mask:0xf bound_ctrl:1
	v_xor_b32_e32 v42, v189, v4
	v_add_f32_dpp v2, v2, v198 quad_perm:[1,0,3,2] row_mask:0xf bank_mask:0xf bound_ctrl:1
	v_xor_b32_e32 v198, v181, v206
	v_add_f32_dpp v4, v4, v42 quad_perm:[2,3,0,1] row_mask:0xf bank_mask:0xf bound_ctrl:1
	v_xor_b32_e32 v42, v189, v44
	v_add_f32_dpp v198, v206, v198 quad_perm:[1,0,3,2] row_mask:0xf bank_mask:0xf bound_ctrl:1
	s_ashr_i32 s31, s30, 31
	v_add_f32_dpp v200, v44, v42 quad_perm:[2,3,0,1] row_mask:0xf bank_mask:0xf bound_ctrl:1
	v_xor_b32_e32 v42, v189, v2
	v_max_f32_e64 v44, |v194|, |v195|
	s_nop 0
	v_add_f32_dpp v201, v2, v42 quad_perm:[2,3,0,1] row_mask:0xf bank_mask:0xf bound_ctrl:1
	v_xor_b32_e32 v2, v189, v198
	v_max_f32_e64 v42, |v43|, |v45|
	s_nop 0
	v_add_f32_dpp v198, v198, v2 quad_perm:[2,3,0,1] row_mask:0xf bank_mask:0xf bound_ctrl:1
	v_xor_b32_e32 v2, v189, v186
	s_nop 1
	v_add_f32_dpp v186, v186, v2 quad_perm:[2,3,0,1] row_mask:0xf bank_mask:0xf bound_ctrl:1
	v_max_f32_e64 v2, |v3|, |v5|
	v_max3_f32 v2, v2, 0, v42
	v_max_f32_e64 v42, |v187|, |v193|
	v_max3_f32 v2, v2, v42, v44
	v_max_f32_e64 v42, |v196|, |v199|
	v_max_f32_e64 v44, |v197|, |v4|
	v_max3_f32 v2, v2, v42, v44
	v_max_f32_e64 v42, |v200|, |v201|
	v_max_f32_e64 v44, |v198|, |v186|
	v_max3_f32 v216, v2, v42, v44
	v_cvt_pk_bf16_f32 v42, v3, v5
	v_cvt_pk_bf16_f32 v43, v43, v45
	v_cvt_pk_bf16_f32 v44, v187, v193
	v_cvt_pk_bf16_f32 v45, v194, v195
	v_cvt_pk_bf16_f32 v2, v196, v199
	v_cvt_pk_bf16_f32 v3, v197, v4
	v_cvt_pk_bf16_f32 v4, v200, v201
	v_cvt_pk_bf16_f32 v5, v198, v186
	v_and_b32_e32 v187, 0xffff0000, v13
	v_and_b32_e32 v186, 0xffff0000, v9
	v_lshlrev_b32_e32 v195, 16, v10
	v_lshlrev_b32_e32 v194, 16, v6
	v_and_b32_e32 v197, 0xffff0000, v10
	v_and_b32_e32 v196, 0xffff0000, v6
	v_lshlrev_b32_e32 v199, 16, v11
	v_lshlrev_b32_e32 v198, 16, v7
	v_and_b32_e32 v11, 0xffff0000, v11
	v_and_b32_e32 v10, 0xffff0000, v7
	v_lshlrev_b32_e32 v7, 16, v12
	v_lshlrev_b32_e32 v6, 16, v8
	v_and_b32_e32 v201, 0xffff0000, v12
	v_and_b32_e32 v200, 0xffff0000, v8
	v_lshlrev_b32_e32 v13, 16, v13
	v_lshlrev_b32_e32 v12, 16, v9
	v_pk_add_f32 v[8:9], v[194:195], v[196:197]
	v_pk_add_f32 v[202:203], v[198:199], v[10:11]
	v_pk_add_f32 v[204:205], v[6:7], v[200:201]
	v_pk_add_f32 v[206:207], v[12:13], v[186:187]
	v_pk_add_f32 v[194:195], v[194:195], v[196:197] neg_lo:[0,1] neg_hi:[0,1]
	v_pk_add_f32 v[10:11], v[198:199], v[10:11] neg_lo:[0,1] neg_hi:[0,1]
	v_pk_add_f32 v[6:7], v[6:7], v[200:201] neg_lo:[0,1] neg_hi:[0,1]
	v_pk_add_f32 v[12:13], v[12:13], v[186:187] neg_lo:[0,1] neg_hi:[0,1]
	v_pk_add_f32 v[208:209], v[8:9], v[202:203] neg_lo:[0,1] neg_hi:[0,1]
	v_pk_add_f32 v[8:9], v[8:9], v[202:203]
	v_pk_add_f32 v[202:203], v[204:205], v[206:207]
	v_pk_add_f32 v[186:187], v[194:195], v[10:11] neg_lo:[0,1] neg_hi:[0,1]
	v_pk_add_f32 v[196:197], v[6:7], v[12:13] neg_lo:[0,1] neg_hi:[0,1]
	v_pk_add_f32 v[10:11], v[194:195], v[10:11]
	v_pk_add_f32 v[6:7], v[6:7], v[12:13]
	v_pk_add_f32 v[210:211], v[204:205], v[206:207] neg_lo:[0,1] neg_hi:[0,1]
	v_pk_add_f32 v[204:205], v[8:9], v[202:203]
	v_pk_add_f32 v[12:13], v[10:11], v[6:7]
	v_pk_add_f32 v[6:7], v[10:11], v[6:7] neg_lo:[0,1] neg_hi:[0,1]
	v_pk_add_f32 v[8:9], v[8:9], v[202:203] neg_lo:[0,1] neg_hi:[0,1]
	v_pk_add_f32 v[202:203], v[208:209], v[210:211]
	v_pk_add_f32 v[206:207], v[208:209], v[210:211] neg_lo:[0,1] neg_hi:[0,1]
	v_pk_add_f32 v[10:11], v[186:187], v[196:197]
	v_pk_add_f32 v[186:187], v[186:187], v[196:197] neg_lo:[0,1] neg_hi:[0,1]
	v_pk_add_f32 v[194:195], v[204:205], v[204:205] op_sel:[0,1] op_sel_hi:[1,0]
	v_pk_add_f32 v[210:211], v[6:7], v[6:7] op_sel:[0,1] op_sel_hi:[1,0]
	v_pk_add_f32 v[6:7], v[6:7], v[6:7] op_sel:[0,1] op_sel_hi:[1,0] neg_lo:[0,1] neg_hi:[0,1]
	v_pk_add_f32 v[198:199], v[12:13], v[12:13] op_sel:[0,1] op_sel_hi:[1,0]
	v_pk_add_f32 v[208:209], v[8:9], v[8:9] op_sel:[0,1] op_sel_hi:[1,0]
	v_pk_add_f32 v[8:9], v[8:9], v[8:9] op_sel:[0,1] op_sel_hi:[1,0] neg_lo:[0,1] neg_hi:[0,1]
	v_pk_add_f32 v[214:215], v[186:187], v[186:187] op_sel:[0,1] op_sel_hi:[1,0]
	v_pk_add_f32 v[186:187], v[186:187], v[186:187] op_sel:[0,1] op_sel_hi:[1,0] neg_lo:[0,1] neg_hi:[0,1]
	v_xor_b32_e32 v7, v181, v194
	v_pk_add_f32 v[196:197], v[204:205], v[204:205] op_sel:[0,1] op_sel_hi:[1,0] neg_lo:[0,1] neg_hi:[0,1]
	v_pk_add_f32 v[200:201], v[202:203], v[202:203] op_sel:[0,1] op_sel_hi:[1,0]
	v_pk_add_f32 v[204:205], v[10:11], v[10:11] op_sel:[0,1] op_sel_hi:[1,0]
	v_pk_add_f32 v[10:11], v[10:11], v[10:11] op_sel:[0,1] op_sel_hi:[1,0] neg_lo:[0,1] neg_hi:[0,1]
	v_add_f32_dpp v7, v194, v7 quad_perm:[1,0,3,2] row_mask:0xf bank_mask:0xf bound_ctrl:1
	v_xor_b32_e32 v9, v181, v198
	v_xor_b32_e32 v199, v181, v186
	v_pk_add_f32 v[12:13], v[12:13], v[12:13] op_sel:[0,1] op_sel_hi:[1,0] neg_lo:[0,1] neg_hi:[0,1]
	v_add_f32_dpp v9, v198, v9 quad_perm:[1,0,3,2] row_mask:0xf bank_mask:0xf bound_ctrl:1
	v_xor_b32_e32 v11, v181, v200
	v_add_f32_dpp v186, v186, v199 quad_perm:[1,0,3,2] row_mask:0xf bank_mask:0xf bound_ctrl:1
	v_xor_b32_e32 v199, v189, v7
	v_add_f32_dpp v11, v200, v11 quad_perm:[1,0,3,2] row_mask:0xf bank_mask:0xf bound_ctrl:1
	v_xor_b32_e32 v13, v181, v204
	v_add_f32_dpp v7, v7, v199 quad_perm:[2,3,0,1] row_mask:0xf bank_mask:0xf bound_ctrl:1
	v_xor_b32_e32 v199, v189, v9
	v_add_f32_dpp v13, v204, v13 quad_perm:[1,0,3,2] row_mask:0xf bank_mask:0xf bound_ctrl:1
	v_xor_b32_e32 v187, v181, v208
	v_add_f32_dpp v9, v9, v199 quad_perm:[2,3,0,1] row_mask:0xf bank_mask:0xf bound_ctrl:1
	v_xor_b32_e32 v199, v189, v11
	v_pk_add_f32 v[212:213], v[206:207], v[206:207] op_sel:[0,1] op_sel_hi:[1,0]
	v_add_f32_dpp v187, v208, v187 quad_perm:[1,0,3,2] row_mask:0xf bank_mask:0xf bound_ctrl:1
	v_xor_b32_e32 v193, v181, v210
	v_add_f32_dpp v11, v11, v199 quad_perm:[2,3,0,1] row_mask:0xf bank_mask:0xf bound_ctrl:1
	v_xor_b32_e32 v199, v189, v13
	v_add_f32_dpp v193, v210, v193 quad_perm:[1,0,3,2] row_mask:0xf bank_mask:0xf bound_ctrl:1
	v_xor_b32_e32 v194, v181, v212
	v_add_f32_dpp v13, v13, v199 quad_perm:[2,3,0,1] row_mask:0xf bank_mask:0xf bound_ctrl:1
	v_xor_b32_e32 v199, v189, v187
	v_add_f32_dpp v194, v212, v194 quad_perm:[1,0,3,2] row_mask:0xf bank_mask:0xf bound_ctrl:1
	v_xor_b32_e32 v195, v181, v214
	v_add_f32_dpp v187, v187, v199 quad_perm:[2,3,0,1] row_mask:0xf bank_mask:0xf bound_ctrl:1
	v_xor_b32_e32 v199, v189, v193
	v_add_f32_dpp v195, v214, v195 quad_perm:[1,0,3,2] row_mask:0xf bank_mask:0xf bound_ctrl:1
	v_xor_b32_e32 v197, v181, v196
	v_add_f32_dpp v193, v193, v199 quad_perm:[2,3,0,1] row_mask:0xf bank_mask:0xf bound_ctrl:1
	v_xor_b32_e32 v199, v189, v194
	v_pk_add_f32 v[202:203], v[202:203], v[202:203] op_sel:[0,1] op_sel_hi:[1,0] neg_lo:[0,1] neg_hi:[0,1]
	v_add_f32_dpp v196, v196, v197 quad_perm:[1,0,3,2] row_mask:0xf bank_mask:0xf bound_ctrl:1
	v_xor_b32_e32 v197, v181, v12
	v_add_f32_dpp v194, v194, v199 quad_perm:[2,3,0,1] row_mask:0xf bank_mask:0xf bound_ctrl:1
	v_xor_b32_e32 v199, v189, v195
	v_add_f32_dpp v12, v12, v197 quad_perm:[1,0,3,2] row_mask:0xf bank_mask:0xf bound_ctrl:1
	v_xor_b32_e32 v197, v181, v202
	v_add_f32_dpp v195, v195, v199 quad_perm:[2,3,0,1] row_mask:0xf bank_mask:0xf bound_ctrl:1
	v_xor_b32_e32 v199, v189, v196
	v_add_f32_dpp v197, v202, v197 quad_perm:[1,0,3,2] row_mask:0xf bank_mask:0xf bound_ctrl:1
	v_xor_b32_e32 v198, v181, v10
	v_add_f32_dpp v196, v196, v199 quad_perm:[2,3,0,1] row_mask:0xf bank_mask:0xf bound_ctrl:1
	v_xor_b32_e32 v199, v189, v12
	v_add_f32_dpp v10, v10, v198 quad_perm:[1,0,3,2] row_mask:0xf bank_mask:0xf bound_ctrl:1
	v_xor_b32_e32 v198, v181, v8
	v_add_f32_dpp v12, v12, v199 quad_perm:[2,3,0,1] row_mask:0xf bank_mask:0xf bound_ctrl:1
	v_xor_b32_e32 v199, v189, v197
	v_pk_add_f32 v[206:207], v[206:207], v[206:207] op_sel:[0,1] op_sel_hi:[1,0] neg_lo:[0,1] neg_hi:[0,1]
	v_add_f32_dpp v8, v8, v198 quad_perm:[1,0,3,2] row_mask:0xf bank_mask:0xf bound_ctrl:1
	v_xor_b32_e32 v198, v181, v6
	v_add_f32_dpp v197, v197, v199 quad_perm:[2,3,0,1] row_mask:0xf bank_mask:0xf bound_ctrl:1
	v_xor_b32_e32 v199, v189, v10
	v_add_f32_dpp v6, v6, v198 quad_perm:[1,0,3,2] row_mask:0xf bank_mask:0xf bound_ctrl:1
	v_xor_b32_e32 v198, v181, v206
	v_add_f32_dpp v199, v10, v199 quad_perm:[2,3,0,1] row_mask:0xf bank_mask:0xf bound_ctrl:1
	v_xor_b32_e32 v10, v189, v8
	v_add_f32_dpp v198, v206, v198 quad_perm:[1,0,3,2] row_mask:0xf bank_mask:0xf bound_ctrl:1
	s_nop 0
	v_add_f32_dpp v200, v8, v10 quad_perm:[2,3,0,1] row_mask:0xf bank_mask:0xf bound_ctrl:1
	v_xor_b32_e32 v8, v189, v6
	v_max_f32_e64 v10, |v194|, |v195|
	s_nop 0
	v_add_f32_dpp v201, v6, v8 quad_perm:[2,3,0,1] row_mask:0xf bank_mask:0xf bound_ctrl:1
	v_xor_b32_e32 v6, v189, v198
	v_max_f32_e64 v8, |v11|, |v13|
	s_nop 0
	v_add_f32_dpp v198, v198, v6 quad_perm:[2,3,0,1] row_mask:0xf bank_mask:0xf bound_ctrl:1
	v_xor_b32_e32 v6, v189, v186
	s_nop 1
	v_add_f32_dpp v186, v186, v6 quad_perm:[2,3,0,1] row_mask:0xf bank_mask:0xf bound_ctrl:1
	v_max_f32_e64 v6, |v7|, |v9|
	v_max3_f32 v6, v216, v6, v8
	v_max_f32_e64 v8, |v187|, |v193|
	v_max3_f32 v6, v6, v8, v10
	v_max_f32_e64 v8, |v196|, |v12|
	v_max_f32_e64 v10, |v197|, |v199|
	v_max3_f32 v6, v6, v8, v10
	v_max_f32_e64 v8, |v200|, |v201|
	v_max_f32_e64 v10, |v198|, |v186|
	v_max3_f32 v216, v6, v8, v10
	v_cvt_pk_bf16_f32 v6, v7, v9
	v_cvt_pk_bf16_f32 v7, v11, v13
	v_cvt_pk_bf16_f32 v8, v187, v193
	v_cvt_pk_bf16_f32 v9, v194, v195
	v_cvt_pk_bf16_f32 v10, v196, v12
	v_cvt_pk_bf16_f32 v11, v197, v199
	v_cvt_pk_bf16_f32 v12, v200, v201
	v_cvt_pk_bf16_f32 v13, v198, v186
	v_and_b32_e32 v187, 0xffff0000, v25
	v_and_b32_e32 v186, 0xffff0000, v17
	v_lshlrev_b32_e32 v195, 16, v22
	v_lshlrev_b32_e32 v194, 16, v14
	v_and_b32_e32 v197, 0xffff0000, v22
	v_and_b32_e32 v196, 0xffff0000, v14
	v_lshlrev_b32_e32 v199, 16, v23
	v_lshlrev_b32_e32 v198, 16, v15
	v_and_b32_e32 v23, 0xffff0000, v23
	v_and_b32_e32 v22, 0xffff0000, v15
	v_lshlrev_b32_e32 v15, 16, v24
	v_lshlrev_b32_e32 v14, 16, v16
	v_and_b32_e32 v201, 0xffff0000, v24
	v_and_b32_e32 v200, 0xffff0000, v16
	v_lshlrev_b32_e32 v25, 16, v25
	v_lshlrev_b32_e32 v24, 16, v17
	v_pk_add_f32 v[16:17], v[194:195], v[196:197]
	v_pk_add_f32 v[202:203], v[198:199], v[22:23]
	v_pk_add_f32 v[204:205], v[14:15], v[200:201]
	v_pk_add_f32 v[206:207], v[24:25], v[186:187]
	v_pk_add_f32 v[194:195], v[194:195], v[196:197] neg_lo:[0,1] neg_hi:[0,1]
	v_pk_add_f32 v[22:23], v[198:199], v[22:23] neg_lo:[0,1] neg_hi:[0,1]
	v_pk_add_f32 v[14:15], v[14:15], v[200:201] neg_lo:[0,1] neg_hi:[0,1]
	v_pk_add_f32 v[24:25], v[24:25], v[186:187] neg_lo:[0,1] neg_hi:[0,1]
	v_pk_add_f32 v[208:209], v[16:17], v[202:203] neg_lo:[0,1] neg_hi:[0,1]
	v_pk_add_f32 v[16:17], v[16:17], v[202:203]
	v_pk_add_f32 v[202:203], v[204:205], v[206:207]
	v_pk_add_f32 v[186:187], v[194:195], v[22:23] neg_lo:[0,1] neg_hi:[0,1]
	v_pk_add_f32 v[196:197], v[14:15], v[24:25] neg_lo:[0,1] neg_hi:[0,1]
	v_pk_add_f32 v[22:23], v[194:195], v[22:23]
	v_pk_add_f32 v[14:15], v[14:15], v[24:25]
	v_pk_add_f32 v[210:211], v[204:205], v[206:207] neg_lo:[0,1] neg_hi:[0,1]
	v_pk_add_f32 v[204:205], v[16:17], v[202:203]
	v_pk_add_f32 v[24:25], v[22:23], v[14:15]
	v_pk_add_f32 v[14:15], v[22:23], v[14:15] neg_lo:[0,1] neg_hi:[0,1]
	v_pk_add_f32 v[16:17], v[16:17], v[202:203] neg_lo:[0,1] neg_hi:[0,1]
	v_pk_add_f32 v[202:203], v[208:209], v[210:211]
	v_pk_add_f32 v[206:207], v[208:209], v[210:211] neg_lo:[0,1] neg_hi:[0,1]
	v_pk_add_f32 v[22:23], v[186:187], v[196:197]
	v_pk_add_f32 v[186:187], v[186:187], v[196:197] neg_lo:[0,1] neg_hi:[0,1]
	v_pk_add_f32 v[194:195], v[204:205], v[204:205] op_sel:[0,1] op_sel_hi:[1,0]
	v_pk_add_f32 v[210:211], v[14:15], v[14:15] op_sel:[0,1] op_sel_hi:[1,0]
	v_pk_add_f32 v[14:15], v[14:15], v[14:15] op_sel:[0,1] op_sel_hi:[1,0] neg_lo:[0,1] neg_hi:[0,1]
	v_pk_add_f32 v[198:199], v[24:25], v[24:25] op_sel:[0,1] op_sel_hi:[1,0]
	v_pk_add_f32 v[208:209], v[16:17], v[16:17] op_sel:[0,1] op_sel_hi:[1,0]
	v_pk_add_f32 v[16:17], v[16:17], v[16:17] op_sel:[0,1] op_sel_hi:[1,0] neg_lo:[0,1] neg_hi:[0,1]
	v_pk_add_f32 v[214:215], v[186:187], v[186:187] op_sel:[0,1] op_sel_hi:[1,0]
	v_pk_add_f32 v[186:187], v[186:187], v[186:187] op_sel:[0,1] op_sel_hi:[1,0] neg_lo:[0,1] neg_hi:[0,1]
	v_xor_b32_e32 v15, v181, v194
	v_pk_add_f32 v[196:197], v[204:205], v[204:205] op_sel:[0,1] op_sel_hi:[1,0] neg_lo:[0,1] neg_hi:[0,1]
	v_pk_add_f32 v[200:201], v[202:203], v[202:203] op_sel:[0,1] op_sel_hi:[1,0]
	v_pk_add_f32 v[204:205], v[22:23], v[22:23] op_sel:[0,1] op_sel_hi:[1,0]
	v_pk_add_f32 v[22:23], v[22:23], v[22:23] op_sel:[0,1] op_sel_hi:[1,0] neg_lo:[0,1] neg_hi:[0,1]
	v_add_f32_dpp v15, v194, v15 quad_perm:[1,0,3,2] row_mask:0xf bank_mask:0xf bound_ctrl:1
	v_xor_b32_e32 v17, v181, v198
	v_xor_b32_e32 v199, v181, v186
	v_pk_add_f32 v[24:25], v[24:25], v[24:25] op_sel:[0,1] op_sel_hi:[1,0] neg_lo:[0,1] neg_hi:[0,1]
	v_add_f32_dpp v17, v198, v17 quad_perm:[1,0,3,2] row_mask:0xf bank_mask:0xf bound_ctrl:1
	v_xor_b32_e32 v23, v181, v200
	v_add_f32_dpp v186, v186, v199 quad_perm:[1,0,3,2] row_mask:0xf bank_mask:0xf bound_ctrl:1
	v_xor_b32_e32 v199, v189, v15
	v_add_f32_dpp v23, v200, v23 quad_perm:[1,0,3,2] row_mask:0xf bank_mask:0xf bound_ctrl:1
	v_xor_b32_e32 v25, v181, v204
	v_add_f32_dpp v15, v15, v199 quad_perm:[2,3,0,1] row_mask:0xf bank_mask:0xf bound_ctrl:1
	v_xor_b32_e32 v199, v189, v17
	v_add_f32_dpp v25, v204, v25 quad_perm:[1,0,3,2] row_mask:0xf bank_mask:0xf bound_ctrl:1
	v_xor_b32_e32 v187, v181, v208
	v_add_f32_dpp v17, v17, v199 quad_perm:[2,3,0,1] row_mask:0xf bank_mask:0xf bound_ctrl:1
	v_xor_b32_e32 v199, v189, v23
	v_pk_add_f32 v[212:213], v[206:207], v[206:207] op_sel:[0,1] op_sel_hi:[1,0]
	v_add_f32_dpp v187, v208, v187 quad_perm:[1,0,3,2] row_mask:0xf bank_mask:0xf bound_ctrl:1
	v_xor_b32_e32 v193, v181, v210
	v_add_f32_dpp v23, v23, v199 quad_perm:[2,3,0,1] row_mask:0xf bank_mask:0xf bound_ctrl:1
	v_xor_b32_e32 v199, v189, v25
	v_add_f32_dpp v193, v210, v193 quad_perm:[1,0,3,2] row_mask:0xf bank_mask:0xf bound_ctrl:1
	v_xor_b32_e32 v194, v181, v212
	v_add_f32_dpp v25, v25, v199 quad_perm:[2,3,0,1] row_mask:0xf bank_mask:0xf bound_ctrl:1
	v_xor_b32_e32 v199, v189, v187
	v_add_f32_dpp v194, v212, v194 quad_perm:[1,0,3,2] row_mask:0xf bank_mask:0xf bound_ctrl:1
	v_xor_b32_e32 v195, v181, v214
	v_add_f32_dpp v187, v187, v199 quad_perm:[2,3,0,1] row_mask:0xf bank_mask:0xf bound_ctrl:1
	v_xor_b32_e32 v199, v189, v193
	v_add_f32_dpp v195, v214, v195 quad_perm:[1,0,3,2] row_mask:0xf bank_mask:0xf bound_ctrl:1
	v_xor_b32_e32 v197, v181, v196
	v_add_f32_dpp v193, v193, v199 quad_perm:[2,3,0,1] row_mask:0xf bank_mask:0xf bound_ctrl:1
	v_xor_b32_e32 v199, v189, v194
	v_pk_add_f32 v[202:203], v[202:203], v[202:203] op_sel:[0,1] op_sel_hi:[1,0] neg_lo:[0,1] neg_hi:[0,1]
	v_add_f32_dpp v196, v196, v197 quad_perm:[1,0,3,2] row_mask:0xf bank_mask:0xf bound_ctrl:1
	v_xor_b32_e32 v197, v181, v24
	v_add_f32_dpp v194, v194, v199 quad_perm:[2,3,0,1] row_mask:0xf bank_mask:0xf bound_ctrl:1
	v_xor_b32_e32 v199, v189, v195
	v_add_f32_dpp v24, v24, v197 quad_perm:[1,0,3,2] row_mask:0xf bank_mask:0xf bound_ctrl:1
	v_xor_b32_e32 v197, v181, v202
	v_add_f32_dpp v195, v195, v199 quad_perm:[2,3,0,1] row_mask:0xf bank_mask:0xf bound_ctrl:1
	v_xor_b32_e32 v199, v189, v196
	v_add_f32_dpp v197, v202, v197 quad_perm:[1,0,3,2] row_mask:0xf bank_mask:0xf bound_ctrl:1
	v_xor_b32_e32 v198, v181, v22
	v_add_f32_dpp v196, v196, v199 quad_perm:[2,3,0,1] row_mask:0xf bank_mask:0xf bound_ctrl:1
	v_xor_b32_e32 v199, v189, v24
	v_add_f32_dpp v22, v22, v198 quad_perm:[1,0,3,2] row_mask:0xf bank_mask:0xf bound_ctrl:1
	v_xor_b32_e32 v198, v181, v16
	v_add_f32_dpp v24, v24, v199 quad_perm:[2,3,0,1] row_mask:0xf bank_mask:0xf bound_ctrl:1
	v_xor_b32_e32 v199, v189, v197
	v_pk_add_f32 v[206:207], v[206:207], v[206:207] op_sel:[0,1] op_sel_hi:[1,0] neg_lo:[0,1] neg_hi:[0,1]
	v_add_f32_dpp v16, v16, v198 quad_perm:[1,0,3,2] row_mask:0xf bank_mask:0xf bound_ctrl:1
	v_xor_b32_e32 v198, v181, v14
	v_add_f32_dpp v197, v197, v199 quad_perm:[2,3,0,1] row_mask:0xf bank_mask:0xf bound_ctrl:1
	v_xor_b32_e32 v199, v189, v22
	v_add_f32_dpp v14, v14, v198 quad_perm:[1,0,3,2] row_mask:0xf bank_mask:0xf bound_ctrl:1
	v_xor_b32_e32 v198, v181, v206
	v_add_f32_dpp v199, v22, v199 quad_perm:[2,3,0,1] row_mask:0xf bank_mask:0xf bound_ctrl:1
	v_xor_b32_e32 v22, v189, v16
	v_add_f32_dpp v198, v206, v198 quad_perm:[1,0,3,2] row_mask:0xf bank_mask:0xf bound_ctrl:1
	s_nop 0
	v_add_f32_dpp v200, v16, v22 quad_perm:[2,3,0,1] row_mask:0xf bank_mask:0xf bound_ctrl:1
	v_xor_b32_e32 v16, v189, v14
	v_max_f32_e64 v22, |v194|, |v195|
	s_nop 0
	v_add_f32_dpp v201, v14, v16 quad_perm:[2,3,0,1] row_mask:0xf bank_mask:0xf bound_ctrl:1
	v_xor_b32_e32 v14, v189, v198
	v_max_f32_e64 v16, |v23|, |v25|
	s_nop 0
	v_add_f32_dpp v198, v198, v14 quad_perm:[2,3,0,1] row_mask:0xf bank_mask:0xf bound_ctrl:1
	v_xor_b32_e32 v14, v189, v186
	s_nop 1
	v_add_f32_dpp v186, v186, v14 quad_perm:[2,3,0,1] row_mask:0xf bank_mask:0xf bound_ctrl:1
	v_max_f32_e64 v14, |v15|, |v17|
	v_max3_f32 v14, v216, v14, v16
	v_max_f32_e64 v16, |v187|, |v193|
	v_max3_f32 v14, v14, v16, v22
	v_max_f32_e64 v16, |v196|, |v24|
	v_max_f32_e64 v22, |v197|, |v199|
	v_max3_f32 v14, v14, v16, v22
	v_max_f32_e64 v16, |v200|, |v201|
	v_max_f32_e64 v22, |v198|, |v186|
	v_max3_f32 v216, v14, v16, v22
	v_cvt_pk_bf16_f32 v14, v15, v17
	v_cvt_pk_bf16_f32 v15, v23, v25
	v_cvt_pk_bf16_f32 v16, v187, v193
	v_cvt_pk_bf16_f32 v17, v194, v195
	v_cvt_pk_bf16_f32 v22, v196, v24
	v_cvt_pk_bf16_f32 v23, v197, v199
	v_cvt_pk_bf16_f32 v24, v200, v201
	v_cvt_pk_bf16_f32 v25, v198, v186
	v_and_b32_e32 v187, 0xffff0000, v29
	v_and_b32_e32 v186, 0xffff0000, v21
	v_lshlrev_b32_e32 v195, 16, v26
	v_lshlrev_b32_e32 v194, 16, v18
	v_and_b32_e32 v197, 0xffff0000, v26
	v_and_b32_e32 v196, 0xffff0000, v18
	v_lshlrev_b32_e32 v199, 16, v27
	v_lshlrev_b32_e32 v198, 16, v19
	v_and_b32_e32 v27, 0xffff0000, v27
	v_and_b32_e32 v26, 0xffff0000, v19
	v_lshlrev_b32_e32 v19, 16, v28
	v_lshlrev_b32_e32 v18, 16, v20
	v_and_b32_e32 v201, 0xffff0000, v28
	v_and_b32_e32 v200, 0xffff0000, v20
	v_lshlrev_b32_e32 v29, 16, v29
	v_lshlrev_b32_e32 v28, 16, v21
	v_pk_add_f32 v[20:21], v[194:195], v[196:197]
	v_pk_add_f32 v[202:203], v[198:199], v[26:27]
	v_pk_add_f32 v[204:205], v[18:19], v[200:201]
	v_pk_add_f32 v[206:207], v[28:29], v[186:187]
	v_pk_add_f32 v[194:195], v[194:195], v[196:197] neg_lo:[0,1] neg_hi:[0,1]
	v_pk_add_f32 v[26:27], v[198:199], v[26:27] neg_lo:[0,1] neg_hi:[0,1]
	v_pk_add_f32 v[18:19], v[18:19], v[200:201] neg_lo:[0,1] neg_hi:[0,1]
	v_pk_add_f32 v[28:29], v[28:29], v[186:187] neg_lo:[0,1] neg_hi:[0,1]
	v_pk_add_f32 v[208:209], v[20:21], v[202:203] neg_lo:[0,1] neg_hi:[0,1]
	v_pk_add_f32 v[20:21], v[20:21], v[202:203]
	v_pk_add_f32 v[202:203], v[204:205], v[206:207]
	v_pk_add_f32 v[186:187], v[194:195], v[26:27] neg_lo:[0,1] neg_hi:[0,1]
	v_pk_add_f32 v[196:197], v[18:19], v[28:29] neg_lo:[0,1] neg_hi:[0,1]
	v_pk_add_f32 v[26:27], v[194:195], v[26:27]
	v_pk_add_f32 v[18:19], v[18:19], v[28:29]
	v_pk_add_f32 v[210:211], v[204:205], v[206:207] neg_lo:[0,1] neg_hi:[0,1]
	v_pk_add_f32 v[204:205], v[20:21], v[202:203]
	v_pk_add_f32 v[28:29], v[26:27], v[18:19]
	v_pk_add_f32 v[18:19], v[26:27], v[18:19] neg_lo:[0,1] neg_hi:[0,1]
	v_pk_add_f32 v[20:21], v[20:21], v[202:203] neg_lo:[0,1] neg_hi:[0,1]
	v_pk_add_f32 v[202:203], v[208:209], v[210:211]
	v_pk_add_f32 v[206:207], v[208:209], v[210:211] neg_lo:[0,1] neg_hi:[0,1]
	v_pk_add_f32 v[26:27], v[186:187], v[196:197]
	v_pk_add_f32 v[186:187], v[186:187], v[196:197] neg_lo:[0,1] neg_hi:[0,1]
	v_pk_add_f32 v[194:195], v[204:205], v[204:205] op_sel:[0,1] op_sel_hi:[1,0]
	v_pk_add_f32 v[210:211], v[18:19], v[18:19] op_sel:[0,1] op_sel_hi:[1,0]
	v_pk_add_f32 v[18:19], v[18:19], v[18:19] op_sel:[0,1] op_sel_hi:[1,0] neg_lo:[0,1] neg_hi:[0,1]
	v_pk_add_f32 v[198:199], v[28:29], v[28:29] op_sel:[0,1] op_sel_hi:[1,0]
	v_pk_add_f32 v[208:209], v[20:21], v[20:21] op_sel:[0,1] op_sel_hi:[1,0]
	v_pk_add_f32 v[20:21], v[20:21], v[20:21] op_sel:[0,1] op_sel_hi:[1,0] neg_lo:[0,1] neg_hi:[0,1]
	v_pk_add_f32 v[214:215], v[186:187], v[186:187] op_sel:[0,1] op_sel_hi:[1,0]
	v_pk_add_f32 v[186:187], v[186:187], v[186:187] op_sel:[0,1] op_sel_hi:[1,0] neg_lo:[0,1] neg_hi:[0,1]
	v_xor_b32_e32 v19, v181, v194
	v_pk_add_f32 v[196:197], v[204:205], v[204:205] op_sel:[0,1] op_sel_hi:[1,0] neg_lo:[0,1] neg_hi:[0,1]
	v_pk_add_f32 v[200:201], v[202:203], v[202:203] op_sel:[0,1] op_sel_hi:[1,0]
	v_pk_add_f32 v[204:205], v[26:27], v[26:27] op_sel:[0,1] op_sel_hi:[1,0]
	v_pk_add_f32 v[26:27], v[26:27], v[26:27] op_sel:[0,1] op_sel_hi:[1,0] neg_lo:[0,1] neg_hi:[0,1]
	v_add_f32_dpp v19, v194, v19 quad_perm:[1,0,3,2] row_mask:0xf bank_mask:0xf bound_ctrl:1
	v_xor_b32_e32 v21, v181, v198
	v_xor_b32_e32 v199, v181, v186
	v_pk_add_f32 v[28:29], v[28:29], v[28:29] op_sel:[0,1] op_sel_hi:[1,0] neg_lo:[0,1] neg_hi:[0,1]
	v_add_f32_dpp v21, v198, v21 quad_perm:[1,0,3,2] row_mask:0xf bank_mask:0xf bound_ctrl:1
	v_xor_b32_e32 v27, v181, v200
	v_add_f32_dpp v186, v186, v199 quad_perm:[1,0,3,2] row_mask:0xf bank_mask:0xf bound_ctrl:1
	v_xor_b32_e32 v199, v189, v19
	v_add_f32_dpp v27, v200, v27 quad_perm:[1,0,3,2] row_mask:0xf bank_mask:0xf bound_ctrl:1
	v_xor_b32_e32 v29, v181, v204
	v_add_f32_dpp v19, v19, v199 quad_perm:[2,3,0,1] row_mask:0xf bank_mask:0xf bound_ctrl:1
	v_xor_b32_e32 v199, v189, v21
	v_add_f32_dpp v29, v204, v29 quad_perm:[1,0,3,2] row_mask:0xf bank_mask:0xf bound_ctrl:1
	v_xor_b32_e32 v187, v181, v208
	v_add_f32_dpp v21, v21, v199 quad_perm:[2,3,0,1] row_mask:0xf bank_mask:0xf bound_ctrl:1
	v_xor_b32_e32 v199, v189, v27
	v_pk_add_f32 v[212:213], v[206:207], v[206:207] op_sel:[0,1] op_sel_hi:[1,0]
	v_add_f32_dpp v187, v208, v187 quad_perm:[1,0,3,2] row_mask:0xf bank_mask:0xf bound_ctrl:1
	v_xor_b32_e32 v193, v181, v210
	v_add_f32_dpp v27, v27, v199 quad_perm:[2,3,0,1] row_mask:0xf bank_mask:0xf bound_ctrl:1
	v_xor_b32_e32 v199, v189, v29
	v_add_f32_dpp v193, v210, v193 quad_perm:[1,0,3,2] row_mask:0xf bank_mask:0xf bound_ctrl:1
	v_xor_b32_e32 v194, v181, v212
	v_add_f32_dpp v29, v29, v199 quad_perm:[2,3,0,1] row_mask:0xf bank_mask:0xf bound_ctrl:1
	v_xor_b32_e32 v199, v189, v187
	v_add_f32_dpp v194, v212, v194 quad_perm:[1,0,3,2] row_mask:0xf bank_mask:0xf bound_ctrl:1
	v_xor_b32_e32 v195, v181, v214
	v_add_f32_dpp v187, v187, v199 quad_perm:[2,3,0,1] row_mask:0xf bank_mask:0xf bound_ctrl:1
	v_xor_b32_e32 v199, v189, v193
	v_add_f32_dpp v195, v214, v195 quad_perm:[1,0,3,2] row_mask:0xf bank_mask:0xf bound_ctrl:1
	v_xor_b32_e32 v197, v181, v196
	v_add_f32_dpp v193, v193, v199 quad_perm:[2,3,0,1] row_mask:0xf bank_mask:0xf bound_ctrl:1
	v_xor_b32_e32 v199, v189, v194
	v_pk_add_f32 v[202:203], v[202:203], v[202:203] op_sel:[0,1] op_sel_hi:[1,0] neg_lo:[0,1] neg_hi:[0,1]
	v_add_f32_dpp v196, v196, v197 quad_perm:[1,0,3,2] row_mask:0xf bank_mask:0xf bound_ctrl:1
	v_xor_b32_e32 v197, v181, v28
	v_add_f32_dpp v194, v194, v199 quad_perm:[2,3,0,1] row_mask:0xf bank_mask:0xf bound_ctrl:1
	v_xor_b32_e32 v199, v189, v195
	v_add_f32_dpp v28, v28, v197 quad_perm:[1,0,3,2] row_mask:0xf bank_mask:0xf bound_ctrl:1
	v_xor_b32_e32 v197, v181, v202
	v_add_f32_dpp v195, v195, v199 quad_perm:[2,3,0,1] row_mask:0xf bank_mask:0xf bound_ctrl:1
	v_xor_b32_e32 v199, v189, v196
	v_add_f32_dpp v197, v202, v197 quad_perm:[1,0,3,2] row_mask:0xf bank_mask:0xf bound_ctrl:1
	v_xor_b32_e32 v198, v181, v26
	v_add_f32_dpp v196, v196, v199 quad_perm:[2,3,0,1] row_mask:0xf bank_mask:0xf bound_ctrl:1
	v_xor_b32_e32 v199, v189, v28
	v_add_f32_dpp v26, v26, v198 quad_perm:[1,0,3,2] row_mask:0xf bank_mask:0xf bound_ctrl:1
	v_xor_b32_e32 v198, v181, v20
	v_add_f32_dpp v28, v28, v199 quad_perm:[2,3,0,1] row_mask:0xf bank_mask:0xf bound_ctrl:1
	v_xor_b32_e32 v199, v189, v197
	v_pk_add_f32 v[206:207], v[206:207], v[206:207] op_sel:[0,1] op_sel_hi:[1,0] neg_lo:[0,1] neg_hi:[0,1]
	v_add_f32_dpp v20, v20, v198 quad_perm:[1,0,3,2] row_mask:0xf bank_mask:0xf bound_ctrl:1
	v_xor_b32_e32 v198, v181, v18
	v_add_f32_dpp v197, v197, v199 quad_perm:[2,3,0,1] row_mask:0xf bank_mask:0xf bound_ctrl:1
	v_xor_b32_e32 v199, v189, v26
	v_add_f32_dpp v18, v18, v198 quad_perm:[1,0,3,2] row_mask:0xf bank_mask:0xf bound_ctrl:1
	v_xor_b32_e32 v198, v181, v206
	v_add_f32_dpp v199, v26, v199 quad_perm:[2,3,0,1] row_mask:0xf bank_mask:0xf bound_ctrl:1
	v_xor_b32_e32 v26, v189, v20
	v_add_f32_dpp v198, v206, v198 quad_perm:[1,0,3,2] row_mask:0xf bank_mask:0xf bound_ctrl:1
	s_nop 0
	v_add_f32_dpp v200, v20, v26 quad_perm:[2,3,0,1] row_mask:0xf bank_mask:0xf bound_ctrl:1
	v_xor_b32_e32 v20, v189, v18
	v_max_f32_e64 v26, |v194|, |v195|
	s_nop 0
	v_add_f32_dpp v201, v18, v20 quad_perm:[2,3,0,1] row_mask:0xf bank_mask:0xf bound_ctrl:1
	v_xor_b32_e32 v18, v189, v198
	v_max_f32_e64 v20, |v27|, |v29|
	s_nop 0
	v_add_f32_dpp v198, v198, v18 quad_perm:[2,3,0,1] row_mask:0xf bank_mask:0xf bound_ctrl:1
	v_xor_b32_e32 v18, v189, v186
	s_nop 1
	v_add_f32_dpp v186, v186, v18 quad_perm:[2,3,0,1] row_mask:0xf bank_mask:0xf bound_ctrl:1
	v_max_f32_e64 v18, |v19|, |v21|
	v_max3_f32 v18, v216, v18, v20
	v_max_f32_e64 v20, |v187|, |v193|
	v_max3_f32 v18, v18, v20, v26
	v_max_f32_e64 v20, |v196|, |v28|
	v_max_f32_e64 v26, |v197|, |v199|
	v_max3_f32 v18, v18, v20, v26
	v_max_f32_e64 v20, |v200|, |v201|
	v_max_f32_e64 v26, |v198|, |v186|
	v_max3_f32 v216, v18, v20, v26
	v_cvt_pk_bf16_f32 v18, v19, v21
	v_cvt_pk_bf16_f32 v19, v27, v29
	v_cvt_pk_bf16_f32 v20, v187, v193
	v_cvt_pk_bf16_f32 v21, v194, v195
	v_cvt_pk_bf16_f32 v26, v196, v28
	v_cvt_pk_bf16_f32 v27, v197, v199
	v_cvt_pk_bf16_f32 v28, v200, v201
	v_cvt_pk_bf16_f32 v29, v198, v186
	v_and_b32_e32 v187, 0xffff0000, v37
	v_and_b32_e32 v186, 0xffff0000, v33
	v_lshlrev_b32_e32 v195, 16, v34
	v_lshlrev_b32_e32 v194, 16, v30
	v_and_b32_e32 v197, 0xffff0000, v34
	v_and_b32_e32 v196, 0xffff0000, v30
	v_lshlrev_b32_e32 v199, 16, v35
	v_lshlrev_b32_e32 v198, 16, v31
	v_and_b32_e32 v35, 0xffff0000, v35
	v_and_b32_e32 v34, 0xffff0000, v31
	v_lshlrev_b32_e32 v31, 16, v36
	v_lshlrev_b32_e32 v30, 16, v32
	v_and_b32_e32 v201, 0xffff0000, v36
	v_and_b32_e32 v200, 0xffff0000, v32
	v_lshlrev_b32_e32 v37, 16, v37
	v_lshlrev_b32_e32 v36, 16, v33
	v_pk_add_f32 v[32:33], v[194:195], v[196:197]
	v_pk_add_f32 v[202:203], v[198:199], v[34:35]
	v_pk_add_f32 v[204:205], v[30:31], v[200:201]
	v_pk_add_f32 v[206:207], v[36:37], v[186:187]
	v_pk_add_f32 v[194:195], v[194:195], v[196:197] neg_lo:[0,1] neg_hi:[0,1]
	v_pk_add_f32 v[34:35], v[198:199], v[34:35] neg_lo:[0,1] neg_hi:[0,1]
	v_pk_add_f32 v[30:31], v[30:31], v[200:201] neg_lo:[0,1] neg_hi:[0,1]
	v_pk_add_f32 v[36:37], v[36:37], v[186:187] neg_lo:[0,1] neg_hi:[0,1]
	v_pk_add_f32 v[208:209], v[32:33], v[202:203] neg_lo:[0,1] neg_hi:[0,1]
	v_pk_add_f32 v[32:33], v[32:33], v[202:203]
	v_pk_add_f32 v[202:203], v[204:205], v[206:207]
	v_pk_add_f32 v[186:187], v[194:195], v[34:35] neg_lo:[0,1] neg_hi:[0,1]
	v_pk_add_f32 v[196:197], v[30:31], v[36:37] neg_lo:[0,1] neg_hi:[0,1]
	v_pk_add_f32 v[34:35], v[194:195], v[34:35]
	v_pk_add_f32 v[30:31], v[30:31], v[36:37]
	v_pk_add_f32 v[210:211], v[204:205], v[206:207] neg_lo:[0,1] neg_hi:[0,1]
	v_pk_add_f32 v[204:205], v[32:33], v[202:203]
	v_pk_add_f32 v[36:37], v[34:35], v[30:31]
	v_pk_add_f32 v[30:31], v[34:35], v[30:31] neg_lo:[0,1] neg_hi:[0,1]
	v_pk_add_f32 v[32:33], v[32:33], v[202:203] neg_lo:[0,1] neg_hi:[0,1]
	v_pk_add_f32 v[202:203], v[208:209], v[210:211]
	v_pk_add_f32 v[206:207], v[208:209], v[210:211] neg_lo:[0,1] neg_hi:[0,1]
	v_pk_add_f32 v[34:35], v[186:187], v[196:197]
	v_pk_add_f32 v[186:187], v[186:187], v[196:197] neg_lo:[0,1] neg_hi:[0,1]
	v_pk_add_f32 v[194:195], v[204:205], v[204:205] op_sel:[0,1] op_sel_hi:[1,0]
	v_pk_add_f32 v[210:211], v[30:31], v[30:31] op_sel:[0,1] op_sel_hi:[1,0]
	v_pk_add_f32 v[30:31], v[30:31], v[30:31] op_sel:[0,1] op_sel_hi:[1,0] neg_lo:[0,1] neg_hi:[0,1]
	v_pk_add_f32 v[198:199], v[36:37], v[36:37] op_sel:[0,1] op_sel_hi:[1,0]
	v_pk_add_f32 v[208:209], v[32:33], v[32:33] op_sel:[0,1] op_sel_hi:[1,0]
	v_pk_add_f32 v[32:33], v[32:33], v[32:33] op_sel:[0,1] op_sel_hi:[1,0] neg_lo:[0,1] neg_hi:[0,1]
	v_pk_add_f32 v[214:215], v[186:187], v[186:187] op_sel:[0,1] op_sel_hi:[1,0]
	v_pk_add_f32 v[186:187], v[186:187], v[186:187] op_sel:[0,1] op_sel_hi:[1,0] neg_lo:[0,1] neg_hi:[0,1]
	v_xor_b32_e32 v31, v181, v194
	v_pk_add_f32 v[196:197], v[204:205], v[204:205] op_sel:[0,1] op_sel_hi:[1,0] neg_lo:[0,1] neg_hi:[0,1]
	v_pk_add_f32 v[200:201], v[202:203], v[202:203] op_sel:[0,1] op_sel_hi:[1,0]
	v_pk_add_f32 v[204:205], v[34:35], v[34:35] op_sel:[0,1] op_sel_hi:[1,0]
	v_pk_add_f32 v[34:35], v[34:35], v[34:35] op_sel:[0,1] op_sel_hi:[1,0] neg_lo:[0,1] neg_hi:[0,1]
	v_add_f32_dpp v31, v194, v31 quad_perm:[1,0,3,2] row_mask:0xf bank_mask:0xf bound_ctrl:1
	v_xor_b32_e32 v33, v181, v198
	v_xor_b32_e32 v199, v181, v186
	v_pk_add_f32 v[36:37], v[36:37], v[36:37] op_sel:[0,1] op_sel_hi:[1,0] neg_lo:[0,1] neg_hi:[0,1]
	v_add_f32_dpp v33, v198, v33 quad_perm:[1,0,3,2] row_mask:0xf bank_mask:0xf bound_ctrl:1
	v_xor_b32_e32 v35, v181, v200
	v_add_f32_dpp v186, v186, v199 quad_perm:[1,0,3,2] row_mask:0xf bank_mask:0xf bound_ctrl:1
	v_xor_b32_e32 v199, v189, v31
	v_add_f32_dpp v35, v200, v35 quad_perm:[1,0,3,2] row_mask:0xf bank_mask:0xf bound_ctrl:1
	v_xor_b32_e32 v37, v181, v204
	v_add_f32_dpp v31, v31, v199 quad_perm:[2,3,0,1] row_mask:0xf bank_mask:0xf bound_ctrl:1
	v_xor_b32_e32 v199, v189, v33
	v_add_f32_dpp v37, v204, v37 quad_perm:[1,0,3,2] row_mask:0xf bank_mask:0xf bound_ctrl:1
	v_xor_b32_e32 v187, v181, v208
	v_add_f32_dpp v33, v33, v199 quad_perm:[2,3,0,1] row_mask:0xf bank_mask:0xf bound_ctrl:1
	v_xor_b32_e32 v199, v189, v35
	v_pk_add_f32 v[212:213], v[206:207], v[206:207] op_sel:[0,1] op_sel_hi:[1,0]
	v_add_f32_dpp v187, v208, v187 quad_perm:[1,0,3,2] row_mask:0xf bank_mask:0xf bound_ctrl:1
	v_xor_b32_e32 v193, v181, v210
	v_add_f32_dpp v35, v35, v199 quad_perm:[2,3,0,1] row_mask:0xf bank_mask:0xf bound_ctrl:1
	v_xor_b32_e32 v199, v189, v37
	v_add_f32_dpp v193, v210, v193 quad_perm:[1,0,3,2] row_mask:0xf bank_mask:0xf bound_ctrl:1
	v_xor_b32_e32 v194, v181, v212
	v_add_f32_dpp v37, v37, v199 quad_perm:[2,3,0,1] row_mask:0xf bank_mask:0xf bound_ctrl:1
	v_xor_b32_e32 v199, v189, v187
	v_add_f32_dpp v194, v212, v194 quad_perm:[1,0,3,2] row_mask:0xf bank_mask:0xf bound_ctrl:1
	v_xor_b32_e32 v195, v181, v214
	v_add_f32_dpp v187, v187, v199 quad_perm:[2,3,0,1] row_mask:0xf bank_mask:0xf bound_ctrl:1
	v_xor_b32_e32 v199, v189, v193
	v_add_f32_dpp v195, v214, v195 quad_perm:[1,0,3,2] row_mask:0xf bank_mask:0xf bound_ctrl:1
	v_xor_b32_e32 v197, v181, v196
	v_add_f32_dpp v193, v193, v199 quad_perm:[2,3,0,1] row_mask:0xf bank_mask:0xf bound_ctrl:1
	v_xor_b32_e32 v199, v189, v194
	v_pk_add_f32 v[202:203], v[202:203], v[202:203] op_sel:[0,1] op_sel_hi:[1,0] neg_lo:[0,1] neg_hi:[0,1]
	v_add_f32_dpp v196, v196, v197 quad_perm:[1,0,3,2] row_mask:0xf bank_mask:0xf bound_ctrl:1
	v_xor_b32_e32 v197, v181, v36
	v_add_f32_dpp v194, v194, v199 quad_perm:[2,3,0,1] row_mask:0xf bank_mask:0xf bound_ctrl:1
	v_xor_b32_e32 v199, v189, v195
	v_add_f32_dpp v36, v36, v197 quad_perm:[1,0,3,2] row_mask:0xf bank_mask:0xf bound_ctrl:1
	v_xor_b32_e32 v197, v181, v202
	v_add_f32_dpp v195, v195, v199 quad_perm:[2,3,0,1] row_mask:0xf bank_mask:0xf bound_ctrl:1
	v_xor_b32_e32 v199, v189, v196
	v_add_f32_dpp v197, v202, v197 quad_perm:[1,0,3,2] row_mask:0xf bank_mask:0xf bound_ctrl:1
	v_xor_b32_e32 v198, v181, v34
	v_add_f32_dpp v196, v196, v199 quad_perm:[2,3,0,1] row_mask:0xf bank_mask:0xf bound_ctrl:1
	v_xor_b32_e32 v199, v189, v36
	v_add_f32_dpp v34, v34, v198 quad_perm:[1,0,3,2] row_mask:0xf bank_mask:0xf bound_ctrl:1
	v_xor_b32_e32 v198, v181, v32
	v_add_f32_dpp v36, v36, v199 quad_perm:[2,3,0,1] row_mask:0xf bank_mask:0xf bound_ctrl:1
	v_xor_b32_e32 v199, v189, v197
	v_pk_add_f32 v[206:207], v[206:207], v[206:207] op_sel:[0,1] op_sel_hi:[1,0] neg_lo:[0,1] neg_hi:[0,1]
	v_add_f32_dpp v32, v32, v198 quad_perm:[1,0,3,2] row_mask:0xf bank_mask:0xf bound_ctrl:1
	v_xor_b32_e32 v198, v181, v30
	v_add_f32_dpp v197, v197, v199 quad_perm:[2,3,0,1] row_mask:0xf bank_mask:0xf bound_ctrl:1
	v_xor_b32_e32 v199, v189, v34
	v_add_f32_dpp v30, v30, v198 quad_perm:[1,0,3,2] row_mask:0xf bank_mask:0xf bound_ctrl:1
	v_xor_b32_e32 v198, v181, v206
	v_add_f32_dpp v199, v34, v199 quad_perm:[2,3,0,1] row_mask:0xf bank_mask:0xf bound_ctrl:1
	v_xor_b32_e32 v34, v189, v32
	v_add_f32_dpp v198, v206, v198 quad_perm:[1,0,3,2] row_mask:0xf bank_mask:0xf bound_ctrl:1
	s_nop 0
	v_add_f32_dpp v200, v32, v34 quad_perm:[2,3,0,1] row_mask:0xf bank_mask:0xf bound_ctrl:1
	v_xor_b32_e32 v32, v189, v30
	v_max_f32_e64 v34, |v194|, |v195|
	s_nop 0
	v_add_f32_dpp v201, v30, v32 quad_perm:[2,3,0,1] row_mask:0xf bank_mask:0xf bound_ctrl:1
	v_xor_b32_e32 v30, v189, v198
	v_max_f32_e64 v32, |v35|, |v37|
	s_nop 0
	v_add_f32_dpp v198, v198, v30 quad_perm:[2,3,0,1] row_mask:0xf bank_mask:0xf bound_ctrl:1
	v_xor_b32_e32 v30, v189, v186
	s_nop 1
	v_add_f32_dpp v186, v186, v30 quad_perm:[2,3,0,1] row_mask:0xf bank_mask:0xf bound_ctrl:1
	v_max_f32_e64 v30, |v31|, |v33|
	v_max3_f32 v30, v216, v30, v32
	v_max_f32_e64 v32, |v187|, |v193|
	v_max3_f32 v30, v30, v32, v34
	v_max_f32_e64 v32, |v196|, |v36|
	v_max_f32_e64 v34, |v197|, |v199|
	v_max3_f32 v30, v30, v32, v34
	v_max_f32_e64 v32, |v200|, |v201|
	v_max_f32_e64 v34, |v198|, |v186|
	v_max3_f32 v216, v30, v32, v34
	v_cvt_pk_bf16_f32 v30, v31, v33
	v_cvt_pk_bf16_f32 v31, v35, v37
	v_cvt_pk_bf16_f32 v32, v187, v193
	v_cvt_pk_bf16_f32 v33, v194, v195
	v_cvt_pk_bf16_f32 v34, v196, v36
	v_cvt_pk_bf16_f32 v35, v197, v199
	v_cvt_pk_bf16_f32 v36, v200, v201
	v_cvt_pk_bf16_f32 v37, v198, v186
	v_and_b32_e32 v187, 0xffff0000, v49
	v_and_b32_e32 v186, 0xffff0000, v41
	v_lshlrev_b32_e32 v195, 16, v46
	v_lshlrev_b32_e32 v194, 16, v38
	v_and_b32_e32 v197, 0xffff0000, v46
	v_and_b32_e32 v196, 0xffff0000, v38
	v_lshlrev_b32_e32 v199, 16, v47
	v_lshlrev_b32_e32 v198, 16, v39
	v_and_b32_e32 v47, 0xffff0000, v47
	v_and_b32_e32 v46, 0xffff0000, v39
	v_lshlrev_b32_e32 v39, 16, v48
	v_lshlrev_b32_e32 v38, 16, v40
	v_and_b32_e32 v201, 0xffff0000, v48
	v_and_b32_e32 v200, 0xffff0000, v40
	v_lshlrev_b32_e32 v49, 16, v49
	v_lshlrev_b32_e32 v48, 16, v41
	v_pk_add_f32 v[40:41], v[194:195], v[196:197]
	v_pk_add_f32 v[202:203], v[198:199], v[46:47]
	v_pk_add_f32 v[204:205], v[38:39], v[200:201]
	v_pk_add_f32 v[206:207], v[48:49], v[186:187]
	v_pk_add_f32 v[194:195], v[194:195], v[196:197] neg_lo:[0,1] neg_hi:[0,1]
	v_pk_add_f32 v[46:47], v[198:199], v[46:47] neg_lo:[0,1] neg_hi:[0,1]
	v_pk_add_f32 v[38:39], v[38:39], v[200:201] neg_lo:[0,1] neg_hi:[0,1]
	v_pk_add_f32 v[48:49], v[48:49], v[186:187] neg_lo:[0,1] neg_hi:[0,1]
	v_pk_add_f32 v[208:209], v[40:41], v[202:203] neg_lo:[0,1] neg_hi:[0,1]
	v_pk_add_f32 v[40:41], v[40:41], v[202:203]
	v_pk_add_f32 v[202:203], v[204:205], v[206:207]
	v_pk_add_f32 v[186:187], v[194:195], v[46:47] neg_lo:[0,1] neg_hi:[0,1]
	v_pk_add_f32 v[196:197], v[38:39], v[48:49] neg_lo:[0,1] neg_hi:[0,1]
	v_pk_add_f32 v[46:47], v[194:195], v[46:47]
	v_pk_add_f32 v[38:39], v[38:39], v[48:49]
	v_pk_add_f32 v[210:211], v[204:205], v[206:207] neg_lo:[0,1] neg_hi:[0,1]
	v_pk_add_f32 v[204:205], v[40:41], v[202:203]
	v_pk_add_f32 v[48:49], v[46:47], v[38:39]
	v_pk_add_f32 v[38:39], v[46:47], v[38:39] neg_lo:[0,1] neg_hi:[0,1]
	v_pk_add_f32 v[40:41], v[40:41], v[202:203] neg_lo:[0,1] neg_hi:[0,1]
	v_pk_add_f32 v[202:203], v[208:209], v[210:211]
	v_pk_add_f32 v[206:207], v[208:209], v[210:211] neg_lo:[0,1] neg_hi:[0,1]
	v_pk_add_f32 v[46:47], v[186:187], v[196:197]
	v_pk_add_f32 v[186:187], v[186:187], v[196:197] neg_lo:[0,1] neg_hi:[0,1]
	v_pk_add_f32 v[194:195], v[204:205], v[204:205] op_sel:[0,1] op_sel_hi:[1,0]
	v_pk_add_f32 v[210:211], v[38:39], v[38:39] op_sel:[0,1] op_sel_hi:[1,0]
	v_pk_add_f32 v[38:39], v[38:39], v[38:39] op_sel:[0,1] op_sel_hi:[1,0] neg_lo:[0,1] neg_hi:[0,1]
	v_pk_add_f32 v[198:199], v[48:49], v[48:49] op_sel:[0,1] op_sel_hi:[1,0]
	v_pk_add_f32 v[208:209], v[40:41], v[40:41] op_sel:[0,1] op_sel_hi:[1,0]
	v_pk_add_f32 v[40:41], v[40:41], v[40:41] op_sel:[0,1] op_sel_hi:[1,0] neg_lo:[0,1] neg_hi:[0,1]
	v_pk_add_f32 v[214:215], v[186:187], v[186:187] op_sel:[0,1] op_sel_hi:[1,0]
	v_pk_add_f32 v[186:187], v[186:187], v[186:187] op_sel:[0,1] op_sel_hi:[1,0] neg_lo:[0,1] neg_hi:[0,1]
	v_xor_b32_e32 v39, v181, v194
	v_pk_add_f32 v[196:197], v[204:205], v[204:205] op_sel:[0,1] op_sel_hi:[1,0] neg_lo:[0,1] neg_hi:[0,1]
	v_pk_add_f32 v[200:201], v[202:203], v[202:203] op_sel:[0,1] op_sel_hi:[1,0]
	v_pk_add_f32 v[204:205], v[46:47], v[46:47] op_sel:[0,1] op_sel_hi:[1,0]
	v_pk_add_f32 v[46:47], v[46:47], v[46:47] op_sel:[0,1] op_sel_hi:[1,0] neg_lo:[0,1] neg_hi:[0,1]
	v_add_f32_dpp v39, v194, v39 quad_perm:[1,0,3,2] row_mask:0xf bank_mask:0xf bound_ctrl:1
	v_xor_b32_e32 v41, v181, v198
	v_xor_b32_e32 v199, v181, v186
	v_pk_add_f32 v[48:49], v[48:49], v[48:49] op_sel:[0,1] op_sel_hi:[1,0] neg_lo:[0,1] neg_hi:[0,1]
	v_add_f32_dpp v41, v198, v41 quad_perm:[1,0,3,2] row_mask:0xf bank_mask:0xf bound_ctrl:1
	v_xor_b32_e32 v47, v181, v200
	v_add_f32_dpp v186, v186, v199 quad_perm:[1,0,3,2] row_mask:0xf bank_mask:0xf bound_ctrl:1
	v_xor_b32_e32 v199, v189, v39
	v_add_f32_dpp v47, v200, v47 quad_perm:[1,0,3,2] row_mask:0xf bank_mask:0xf bound_ctrl:1
	v_xor_b32_e32 v49, v181, v204
	v_add_f32_dpp v39, v39, v199 quad_perm:[2,3,0,1] row_mask:0xf bank_mask:0xf bound_ctrl:1
	v_xor_b32_e32 v199, v189, v41
	v_add_f32_dpp v49, v204, v49 quad_perm:[1,0,3,2] row_mask:0xf bank_mask:0xf bound_ctrl:1
	v_xor_b32_e32 v187, v181, v208
	v_add_f32_dpp v41, v41, v199 quad_perm:[2,3,0,1] row_mask:0xf bank_mask:0xf bound_ctrl:1
	v_xor_b32_e32 v199, v189, v47
	v_pk_add_f32 v[212:213], v[206:207], v[206:207] op_sel:[0,1] op_sel_hi:[1,0]
	v_add_f32_dpp v187, v208, v187 quad_perm:[1,0,3,2] row_mask:0xf bank_mask:0xf bound_ctrl:1
	v_xor_b32_e32 v193, v181, v210
	v_add_f32_dpp v47, v47, v199 quad_perm:[2,3,0,1] row_mask:0xf bank_mask:0xf bound_ctrl:1
	v_xor_b32_e32 v199, v189, v49
	v_add_f32_dpp v193, v210, v193 quad_perm:[1,0,3,2] row_mask:0xf bank_mask:0xf bound_ctrl:1
	v_xor_b32_e32 v194, v181, v212
	v_add_f32_dpp v49, v49, v199 quad_perm:[2,3,0,1] row_mask:0xf bank_mask:0xf bound_ctrl:1
	v_xor_b32_e32 v199, v189, v187
	v_add_f32_dpp v194, v212, v194 quad_perm:[1,0,3,2] row_mask:0xf bank_mask:0xf bound_ctrl:1
	v_xor_b32_e32 v195, v181, v214
	v_add_f32_dpp v187, v187, v199 quad_perm:[2,3,0,1] row_mask:0xf bank_mask:0xf bound_ctrl:1
	v_xor_b32_e32 v199, v189, v193
	v_add_f32_dpp v195, v214, v195 quad_perm:[1,0,3,2] row_mask:0xf bank_mask:0xf bound_ctrl:1
	v_xor_b32_e32 v197, v181, v196
	v_add_f32_dpp v193, v193, v199 quad_perm:[2,3,0,1] row_mask:0xf bank_mask:0xf bound_ctrl:1
	v_xor_b32_e32 v199, v189, v194
	v_pk_add_f32 v[202:203], v[202:203], v[202:203] op_sel:[0,1] op_sel_hi:[1,0] neg_lo:[0,1] neg_hi:[0,1]
	v_add_f32_dpp v196, v196, v197 quad_perm:[1,0,3,2] row_mask:0xf bank_mask:0xf bound_ctrl:1
	v_xor_b32_e32 v197, v181, v48
	v_add_f32_dpp v194, v194, v199 quad_perm:[2,3,0,1] row_mask:0xf bank_mask:0xf bound_ctrl:1
	v_xor_b32_e32 v199, v189, v195
	v_add_f32_dpp v48, v48, v197 quad_perm:[1,0,3,2] row_mask:0xf bank_mask:0xf bound_ctrl:1
	v_xor_b32_e32 v197, v181, v202
	v_add_f32_dpp v195, v195, v199 quad_perm:[2,3,0,1] row_mask:0xf bank_mask:0xf bound_ctrl:1
	v_xor_b32_e32 v199, v189, v196
	v_add_f32_dpp v197, v202, v197 quad_perm:[1,0,3,2] row_mask:0xf bank_mask:0xf bound_ctrl:1
	v_xor_b32_e32 v198, v181, v46
	v_add_f32_dpp v196, v196, v199 quad_perm:[2,3,0,1] row_mask:0xf bank_mask:0xf bound_ctrl:1
	v_xor_b32_e32 v199, v189, v48
	v_add_f32_dpp v46, v46, v198 quad_perm:[1,0,3,2] row_mask:0xf bank_mask:0xf bound_ctrl:1
	v_xor_b32_e32 v198, v181, v40
	v_add_f32_dpp v48, v48, v199 quad_perm:[2,3,0,1] row_mask:0xf bank_mask:0xf bound_ctrl:1
	v_xor_b32_e32 v199, v189, v197
	v_pk_add_f32 v[206:207], v[206:207], v[206:207] op_sel:[0,1] op_sel_hi:[1,0] neg_lo:[0,1] neg_hi:[0,1]
	v_add_f32_dpp v40, v40, v198 quad_perm:[1,0,3,2] row_mask:0xf bank_mask:0xf bound_ctrl:1
	v_xor_b32_e32 v198, v181, v38
	v_add_f32_dpp v197, v197, v199 quad_perm:[2,3,0,1] row_mask:0xf bank_mask:0xf bound_ctrl:1
	v_xor_b32_e32 v199, v189, v46
	v_add_f32_dpp v38, v38, v198 quad_perm:[1,0,3,2] row_mask:0xf bank_mask:0xf bound_ctrl:1
	v_xor_b32_e32 v198, v181, v206
	v_add_f32_dpp v199, v46, v199 quad_perm:[2,3,0,1] row_mask:0xf bank_mask:0xf bound_ctrl:1
	v_xor_b32_e32 v46, v189, v40
	v_add_f32_dpp v198, v206, v198 quad_perm:[1,0,3,2] row_mask:0xf bank_mask:0xf bound_ctrl:1
	s_nop 0
	v_add_f32_dpp v200, v40, v46 quad_perm:[2,3,0,1] row_mask:0xf bank_mask:0xf bound_ctrl:1
	v_xor_b32_e32 v40, v189, v38
	v_max_f32_e64 v46, |v194|, |v195|
	s_nop 0
	v_add_f32_dpp v201, v38, v40 quad_perm:[2,3,0,1] row_mask:0xf bank_mask:0xf bound_ctrl:1
	v_xor_b32_e32 v38, v189, v198
	v_max_f32_e64 v40, |v47|, |v49|
	s_nop 0
	v_add_f32_dpp v198, v198, v38 quad_perm:[2,3,0,1] row_mask:0xf bank_mask:0xf bound_ctrl:1
	v_xor_b32_e32 v38, v189, v186
	s_nop 1
	v_add_f32_dpp v186, v186, v38 quad_perm:[2,3,0,1] row_mask:0xf bank_mask:0xf bound_ctrl:1
	v_max_f32_e64 v38, |v39|, |v41|
	v_max3_f32 v38, v216, v38, v40
	v_max_f32_e64 v40, |v187|, |v193|
	v_max3_f32 v38, v38, v40, v46
	v_max_f32_e64 v40, |v196|, |v48|
	v_max_f32_e64 v46, |v197|, |v199|
	v_max3_f32 v38, v38, v40, v46
	v_max_f32_e64 v40, |v200|, |v201|
	v_max_f32_e64 v46, |v198|, |v186|
	v_max3_f32 v216, v38, v40, v46
	v_cvt_pk_bf16_f32 v38, v39, v41
	v_cvt_pk_bf16_f32 v39, v47, v49
	v_cvt_pk_bf16_f32 v40, v187, v193
	v_cvt_pk_bf16_f32 v41, v194, v195
	v_cvt_pk_bf16_f32 v46, v196, v48
	v_cvt_pk_bf16_f32 v47, v197, v199
	v_cvt_pk_bf16_f32 v48, v200, v201
	v_cvt_pk_bf16_f32 v49, v198, v186
	v_and_b32_e32 v187, 0xffff0000, v57
	v_and_b32_e32 v186, 0xffff0000, v53
	v_lshlrev_b32_e32 v195, 16, v54
	v_lshlrev_b32_e32 v194, 16, v50
	v_and_b32_e32 v197, 0xffff0000, v54
	v_and_b32_e32 v196, 0xffff0000, v50
	v_lshlrev_b32_e32 v199, 16, v55
	v_lshlrev_b32_e32 v198, 16, v51
	v_and_b32_e32 v55, 0xffff0000, v55
	v_and_b32_e32 v54, 0xffff0000, v51
	v_lshlrev_b32_e32 v51, 16, v56
	v_lshlrev_b32_e32 v50, 16, v52
	v_and_b32_e32 v201, 0xffff0000, v56
	v_and_b32_e32 v200, 0xffff0000, v52
	v_lshlrev_b32_e32 v57, 16, v57
	v_lshlrev_b32_e32 v56, 16, v53
	v_pk_add_f32 v[52:53], v[194:195], v[196:197]
	v_pk_add_f32 v[202:203], v[198:199], v[54:55]
	v_pk_add_f32 v[204:205], v[50:51], v[200:201]
	v_pk_add_f32 v[206:207], v[56:57], v[186:187]
	v_pk_add_f32 v[194:195], v[194:195], v[196:197] neg_lo:[0,1] neg_hi:[0,1]
	v_pk_add_f32 v[54:55], v[198:199], v[54:55] neg_lo:[0,1] neg_hi:[0,1]
	v_pk_add_f32 v[50:51], v[50:51], v[200:201] neg_lo:[0,1] neg_hi:[0,1]
	v_pk_add_f32 v[56:57], v[56:57], v[186:187] neg_lo:[0,1] neg_hi:[0,1]
	v_pk_add_f32 v[208:209], v[52:53], v[202:203] neg_lo:[0,1] neg_hi:[0,1]
	v_pk_add_f32 v[52:53], v[52:53], v[202:203]
	v_pk_add_f32 v[202:203], v[204:205], v[206:207]
	v_pk_add_f32 v[186:187], v[194:195], v[54:55] neg_lo:[0,1] neg_hi:[0,1]
	v_pk_add_f32 v[196:197], v[50:51], v[56:57] neg_lo:[0,1] neg_hi:[0,1]
	v_pk_add_f32 v[54:55], v[194:195], v[54:55]
	v_pk_add_f32 v[50:51], v[50:51], v[56:57]
	v_pk_add_f32 v[210:211], v[204:205], v[206:207] neg_lo:[0,1] neg_hi:[0,1]
	v_pk_add_f32 v[204:205], v[52:53], v[202:203]
	v_pk_add_f32 v[56:57], v[54:55], v[50:51]
	v_pk_add_f32 v[50:51], v[54:55], v[50:51] neg_lo:[0,1] neg_hi:[0,1]
	v_pk_add_f32 v[52:53], v[52:53], v[202:203] neg_lo:[0,1] neg_hi:[0,1]
	v_pk_add_f32 v[202:203], v[208:209], v[210:211]
	v_pk_add_f32 v[206:207], v[208:209], v[210:211] neg_lo:[0,1] neg_hi:[0,1]
	v_pk_add_f32 v[54:55], v[186:187], v[196:197]
	v_pk_add_f32 v[186:187], v[186:187], v[196:197] neg_lo:[0,1] neg_hi:[0,1]
	v_pk_add_f32 v[194:195], v[204:205], v[204:205] op_sel:[0,1] op_sel_hi:[1,0]
	v_pk_add_f32 v[210:211], v[50:51], v[50:51] op_sel:[0,1] op_sel_hi:[1,0]
	v_pk_add_f32 v[50:51], v[50:51], v[50:51] op_sel:[0,1] op_sel_hi:[1,0] neg_lo:[0,1] neg_hi:[0,1]
	v_pk_add_f32 v[198:199], v[56:57], v[56:57] op_sel:[0,1] op_sel_hi:[1,0]
	v_pk_add_f32 v[208:209], v[52:53], v[52:53] op_sel:[0,1] op_sel_hi:[1,0]
	v_pk_add_f32 v[52:53], v[52:53], v[52:53] op_sel:[0,1] op_sel_hi:[1,0] neg_lo:[0,1] neg_hi:[0,1]
	v_pk_add_f32 v[214:215], v[186:187], v[186:187] op_sel:[0,1] op_sel_hi:[1,0]
	v_pk_add_f32 v[186:187], v[186:187], v[186:187] op_sel:[0,1] op_sel_hi:[1,0] neg_lo:[0,1] neg_hi:[0,1]
	v_xor_b32_e32 v51, v181, v194
	v_pk_add_f32 v[196:197], v[204:205], v[204:205] op_sel:[0,1] op_sel_hi:[1,0] neg_lo:[0,1] neg_hi:[0,1]
	v_pk_add_f32 v[200:201], v[202:203], v[202:203] op_sel:[0,1] op_sel_hi:[1,0]
	v_pk_add_f32 v[204:205], v[54:55], v[54:55] op_sel:[0,1] op_sel_hi:[1,0]
	v_pk_add_f32 v[54:55], v[54:55], v[54:55] op_sel:[0,1] op_sel_hi:[1,0] neg_lo:[0,1] neg_hi:[0,1]
	v_add_f32_dpp v51, v194, v51 quad_perm:[1,0,3,2] row_mask:0xf bank_mask:0xf bound_ctrl:1
	v_xor_b32_e32 v53, v181, v198
	v_xor_b32_e32 v199, v181, v186
	v_pk_add_f32 v[56:57], v[56:57], v[56:57] op_sel:[0,1] op_sel_hi:[1,0] neg_lo:[0,1] neg_hi:[0,1]
	v_add_f32_dpp v53, v198, v53 quad_perm:[1,0,3,2] row_mask:0xf bank_mask:0xf bound_ctrl:1
	v_xor_b32_e32 v55, v181, v200
	v_add_f32_dpp v186, v186, v199 quad_perm:[1,0,3,2] row_mask:0xf bank_mask:0xf bound_ctrl:1
	v_xor_b32_e32 v199, v189, v51
	v_add_f32_dpp v55, v200, v55 quad_perm:[1,0,3,2] row_mask:0xf bank_mask:0xf bound_ctrl:1
	v_xor_b32_e32 v57, v181, v204
	v_add_f32_dpp v51, v51, v199 quad_perm:[2,3,0,1] row_mask:0xf bank_mask:0xf bound_ctrl:1
	v_xor_b32_e32 v199, v189, v53
	v_add_f32_dpp v57, v204, v57 quad_perm:[1,0,3,2] row_mask:0xf bank_mask:0xf bound_ctrl:1
	v_xor_b32_e32 v187, v181, v208
	v_add_f32_dpp v53, v53, v199 quad_perm:[2,3,0,1] row_mask:0xf bank_mask:0xf bound_ctrl:1
	v_xor_b32_e32 v199, v189, v55
	v_pk_add_f32 v[212:213], v[206:207], v[206:207] op_sel:[0,1] op_sel_hi:[1,0]
	v_add_f32_dpp v187, v208, v187 quad_perm:[1,0,3,2] row_mask:0xf bank_mask:0xf bound_ctrl:1
	v_xor_b32_e32 v193, v181, v210
	v_add_f32_dpp v55, v55, v199 quad_perm:[2,3,0,1] row_mask:0xf bank_mask:0xf bound_ctrl:1
	v_xor_b32_e32 v199, v189, v57
	v_add_f32_dpp v193, v210, v193 quad_perm:[1,0,3,2] row_mask:0xf bank_mask:0xf bound_ctrl:1
	v_xor_b32_e32 v194, v181, v212
	v_add_f32_dpp v57, v57, v199 quad_perm:[2,3,0,1] row_mask:0xf bank_mask:0xf bound_ctrl:1
	v_xor_b32_e32 v199, v189, v187
	v_add_f32_dpp v194, v212, v194 quad_perm:[1,0,3,2] row_mask:0xf bank_mask:0xf bound_ctrl:1
	v_xor_b32_e32 v195, v181, v214
	v_add_f32_dpp v187, v187, v199 quad_perm:[2,3,0,1] row_mask:0xf bank_mask:0xf bound_ctrl:1
	v_xor_b32_e32 v199, v189, v193
	v_add_f32_dpp v195, v214, v195 quad_perm:[1,0,3,2] row_mask:0xf bank_mask:0xf bound_ctrl:1
	v_xor_b32_e32 v197, v181, v196
	v_add_f32_dpp v193, v193, v199 quad_perm:[2,3,0,1] row_mask:0xf bank_mask:0xf bound_ctrl:1
	v_xor_b32_e32 v199, v189, v194
	v_pk_add_f32 v[202:203], v[202:203], v[202:203] op_sel:[0,1] op_sel_hi:[1,0] neg_lo:[0,1] neg_hi:[0,1]
	v_add_f32_dpp v196, v196, v197 quad_perm:[1,0,3,2] row_mask:0xf bank_mask:0xf bound_ctrl:1
	v_xor_b32_e32 v197, v181, v56
	v_add_f32_dpp v194, v194, v199 quad_perm:[2,3,0,1] row_mask:0xf bank_mask:0xf bound_ctrl:1
	v_xor_b32_e32 v199, v189, v195
	v_add_f32_dpp v56, v56, v197 quad_perm:[1,0,3,2] row_mask:0xf bank_mask:0xf bound_ctrl:1
	v_xor_b32_e32 v197, v181, v202
	v_add_f32_dpp v195, v195, v199 quad_perm:[2,3,0,1] row_mask:0xf bank_mask:0xf bound_ctrl:1
	v_xor_b32_e32 v199, v189, v196
	v_add_f32_dpp v197, v202, v197 quad_perm:[1,0,3,2] row_mask:0xf bank_mask:0xf bound_ctrl:1
	v_xor_b32_e32 v198, v181, v54
	v_add_f32_dpp v196, v196, v199 quad_perm:[2,3,0,1] row_mask:0xf bank_mask:0xf bound_ctrl:1
	v_xor_b32_e32 v199, v189, v56
	v_add_f32_dpp v54, v54, v198 quad_perm:[1,0,3,2] row_mask:0xf bank_mask:0xf bound_ctrl:1
	v_xor_b32_e32 v198, v181, v52
	v_add_f32_dpp v56, v56, v199 quad_perm:[2,3,0,1] row_mask:0xf bank_mask:0xf bound_ctrl:1
	v_xor_b32_e32 v199, v189, v197
	v_pk_add_f32 v[206:207], v[206:207], v[206:207] op_sel:[0,1] op_sel_hi:[1,0] neg_lo:[0,1] neg_hi:[0,1]
	v_add_f32_dpp v52, v52, v198 quad_perm:[1,0,3,2] row_mask:0xf bank_mask:0xf bound_ctrl:1
	v_xor_b32_e32 v198, v181, v50
	v_add_f32_dpp v197, v197, v199 quad_perm:[2,3,0,1] row_mask:0xf bank_mask:0xf bound_ctrl:1
	v_xor_b32_e32 v199, v189, v54
	v_add_f32_dpp v50, v50, v198 quad_perm:[1,0,3,2] row_mask:0xf bank_mask:0xf bound_ctrl:1
	v_xor_b32_e32 v198, v181, v206
	v_add_f32_dpp v199, v54, v199 quad_perm:[2,3,0,1] row_mask:0xf bank_mask:0xf bound_ctrl:1
	v_xor_b32_e32 v54, v189, v52
	v_add_f32_dpp v198, v206, v198 quad_perm:[1,0,3,2] row_mask:0xf bank_mask:0xf bound_ctrl:1
	s_nop 0
	v_add_f32_dpp v200, v52, v54 quad_perm:[2,3,0,1] row_mask:0xf bank_mask:0xf bound_ctrl:1
	v_xor_b32_e32 v52, v189, v50
	v_max_f32_e64 v54, |v194|, |v195|
	s_nop 0
	v_add_f32_dpp v201, v50, v52 quad_perm:[2,3,0,1] row_mask:0xf bank_mask:0xf bound_ctrl:1
	v_xor_b32_e32 v50, v189, v198
	v_max_f32_e64 v52, |v55|, |v57|
	s_nop 0
	v_add_f32_dpp v198, v198, v50 quad_perm:[2,3,0,1] row_mask:0xf bank_mask:0xf bound_ctrl:1
	v_xor_b32_e32 v50, v189, v186
	s_nop 1
	v_add_f32_dpp v186, v186, v50 quad_perm:[2,3,0,1] row_mask:0xf bank_mask:0xf bound_ctrl:1
	v_max_f32_e64 v50, |v51|, |v53|
	v_max3_f32 v50, v216, v50, v52
	v_max_f32_e64 v52, |v187|, |v193|
	v_max3_f32 v50, v50, v52, v54
	v_max_f32_e64 v52, |v196|, |v56|
	v_max_f32_e64 v54, |v197|, |v199|
	v_max3_f32 v50, v50, v52, v54
	v_max_f32_e64 v52, |v200|, |v201|
	v_max_f32_e64 v54, |v198|, |v186|
	v_max3_f32 v216, v50, v52, v54
	v_cvt_pk_bf16_f32 v50, v51, v53
	v_cvt_pk_bf16_f32 v51, v55, v57
	v_cvt_pk_bf16_f32 v52, v187, v193
	v_cvt_pk_bf16_f32 v53, v194, v195
	v_cvt_pk_bf16_f32 v54, v196, v56
	v_cvt_pk_bf16_f32 v55, v197, v199
	v_cvt_pk_bf16_f32 v56, v200, v201
	v_cvt_pk_bf16_f32 v57, v198, v186
	v_and_b32_e32 v187, 0xffff0000, v65
	v_and_b32_e32 v186, 0xffff0000, v61
	v_lshlrev_b32_e32 v195, 16, v62
	v_lshlrev_b32_e32 v194, 16, v58
	v_and_b32_e32 v197, 0xffff0000, v62
	v_and_b32_e32 v196, 0xffff0000, v58
	v_lshlrev_b32_e32 v199, 16, v63
	v_lshlrev_b32_e32 v198, 16, v59
	v_and_b32_e32 v63, 0xffff0000, v63
	v_and_b32_e32 v62, 0xffff0000, v59
	v_lshlrev_b32_e32 v59, 16, v64
	v_lshlrev_b32_e32 v58, 16, v60
	v_and_b32_e32 v201, 0xffff0000, v64
	v_and_b32_e32 v200, 0xffff0000, v60
	v_lshlrev_b32_e32 v65, 16, v65
	v_lshlrev_b32_e32 v64, 16, v61
	v_pk_add_f32 v[60:61], v[194:195], v[196:197]
	v_pk_add_f32 v[202:203], v[198:199], v[62:63]
	v_pk_add_f32 v[204:205], v[58:59], v[200:201]
	v_pk_add_f32 v[206:207], v[64:65], v[186:187]
	v_pk_add_f32 v[194:195], v[194:195], v[196:197] neg_lo:[0,1] neg_hi:[0,1]
	v_pk_add_f32 v[62:63], v[198:199], v[62:63] neg_lo:[0,1] neg_hi:[0,1]
	v_pk_add_f32 v[58:59], v[58:59], v[200:201] neg_lo:[0,1] neg_hi:[0,1]
	v_pk_add_f32 v[64:65], v[64:65], v[186:187] neg_lo:[0,1] neg_hi:[0,1]
	v_pk_add_f32 v[208:209], v[60:61], v[202:203] neg_lo:[0,1] neg_hi:[0,1]
	v_pk_add_f32 v[60:61], v[60:61], v[202:203]
	v_pk_add_f32 v[202:203], v[204:205], v[206:207]
	v_pk_add_f32 v[186:187], v[194:195], v[62:63] neg_lo:[0,1] neg_hi:[0,1]
	v_pk_add_f32 v[196:197], v[58:59], v[64:65] neg_lo:[0,1] neg_hi:[0,1]
	v_pk_add_f32 v[62:63], v[194:195], v[62:63]
	v_pk_add_f32 v[58:59], v[58:59], v[64:65]
	v_pk_add_f32 v[210:211], v[204:205], v[206:207] neg_lo:[0,1] neg_hi:[0,1]
	v_pk_add_f32 v[204:205], v[60:61], v[202:203]
	v_pk_add_f32 v[64:65], v[62:63], v[58:59]
	v_pk_add_f32 v[58:59], v[62:63], v[58:59] neg_lo:[0,1] neg_hi:[0,1]
	v_pk_add_f32 v[60:61], v[60:61], v[202:203] neg_lo:[0,1] neg_hi:[0,1]
	v_pk_add_f32 v[202:203], v[208:209], v[210:211]
	v_pk_add_f32 v[206:207], v[208:209], v[210:211] neg_lo:[0,1] neg_hi:[0,1]
	v_pk_add_f32 v[62:63], v[186:187], v[196:197]
	v_pk_add_f32 v[186:187], v[186:187], v[196:197] neg_lo:[0,1] neg_hi:[0,1]
	v_pk_add_f32 v[194:195], v[204:205], v[204:205] op_sel:[0,1] op_sel_hi:[1,0]
	v_pk_add_f32 v[210:211], v[58:59], v[58:59] op_sel:[0,1] op_sel_hi:[1,0]
	v_pk_add_f32 v[58:59], v[58:59], v[58:59] op_sel:[0,1] op_sel_hi:[1,0] neg_lo:[0,1] neg_hi:[0,1]
	v_pk_add_f32 v[198:199], v[64:65], v[64:65] op_sel:[0,1] op_sel_hi:[1,0]
	v_pk_add_f32 v[208:209], v[60:61], v[60:61] op_sel:[0,1] op_sel_hi:[1,0]
	v_pk_add_f32 v[60:61], v[60:61], v[60:61] op_sel:[0,1] op_sel_hi:[1,0] neg_lo:[0,1] neg_hi:[0,1]
	v_pk_add_f32 v[214:215], v[186:187], v[186:187] op_sel:[0,1] op_sel_hi:[1,0]
	v_pk_add_f32 v[186:187], v[186:187], v[186:187] op_sel:[0,1] op_sel_hi:[1,0] neg_lo:[0,1] neg_hi:[0,1]
	v_xor_b32_e32 v59, v181, v194
	v_pk_add_f32 v[196:197], v[204:205], v[204:205] op_sel:[0,1] op_sel_hi:[1,0] neg_lo:[0,1] neg_hi:[0,1]
	v_pk_add_f32 v[200:201], v[202:203], v[202:203] op_sel:[0,1] op_sel_hi:[1,0]
	v_pk_add_f32 v[204:205], v[62:63], v[62:63] op_sel:[0,1] op_sel_hi:[1,0]
	v_pk_add_f32 v[62:63], v[62:63], v[62:63] op_sel:[0,1] op_sel_hi:[1,0] neg_lo:[0,1] neg_hi:[0,1]
	v_add_f32_dpp v59, v194, v59 quad_perm:[1,0,3,2] row_mask:0xf bank_mask:0xf bound_ctrl:1
	v_xor_b32_e32 v61, v181, v198
	v_xor_b32_e32 v199, v181, v186
	v_pk_add_f32 v[64:65], v[64:65], v[64:65] op_sel:[0,1] op_sel_hi:[1,0] neg_lo:[0,1] neg_hi:[0,1]
	v_add_f32_dpp v61, v198, v61 quad_perm:[1,0,3,2] row_mask:0xf bank_mask:0xf bound_ctrl:1
	v_xor_b32_e32 v63, v181, v200
	v_add_f32_dpp v186, v186, v199 quad_perm:[1,0,3,2] row_mask:0xf bank_mask:0xf bound_ctrl:1
	v_xor_b32_e32 v199, v189, v59
	v_add_f32_dpp v63, v200, v63 quad_perm:[1,0,3,2] row_mask:0xf bank_mask:0xf bound_ctrl:1
	v_xor_b32_e32 v65, v181, v204
	v_add_f32_dpp v59, v59, v199 quad_perm:[2,3,0,1] row_mask:0xf bank_mask:0xf bound_ctrl:1
	v_xor_b32_e32 v199, v189, v61
	v_add_f32_dpp v65, v204, v65 quad_perm:[1,0,3,2] row_mask:0xf bank_mask:0xf bound_ctrl:1
	v_xor_b32_e32 v187, v181, v208
	v_add_f32_dpp v61, v61, v199 quad_perm:[2,3,0,1] row_mask:0xf bank_mask:0xf bound_ctrl:1
	v_xor_b32_e32 v199, v189, v63
	v_pk_add_f32 v[212:213], v[206:207], v[206:207] op_sel:[0,1] op_sel_hi:[1,0]
	v_add_f32_dpp v187, v208, v187 quad_perm:[1,0,3,2] row_mask:0xf bank_mask:0xf bound_ctrl:1
	v_xor_b32_e32 v193, v181, v210
	v_add_f32_dpp v63, v63, v199 quad_perm:[2,3,0,1] row_mask:0xf bank_mask:0xf bound_ctrl:1
	v_xor_b32_e32 v199, v189, v65
	v_add_f32_dpp v193, v210, v193 quad_perm:[1,0,3,2] row_mask:0xf bank_mask:0xf bound_ctrl:1
	v_xor_b32_e32 v194, v181, v212
	v_add_f32_dpp v65, v65, v199 quad_perm:[2,3,0,1] row_mask:0xf bank_mask:0xf bound_ctrl:1
	v_xor_b32_e32 v199, v189, v187
	v_add_f32_dpp v194, v212, v194 quad_perm:[1,0,3,2] row_mask:0xf bank_mask:0xf bound_ctrl:1
	v_xor_b32_e32 v195, v181, v214
	v_add_f32_dpp v187, v187, v199 quad_perm:[2,3,0,1] row_mask:0xf bank_mask:0xf bound_ctrl:1
	v_xor_b32_e32 v199, v189, v193
	v_add_f32_dpp v195, v214, v195 quad_perm:[1,0,3,2] row_mask:0xf bank_mask:0xf bound_ctrl:1
	v_xor_b32_e32 v197, v181, v196
	v_add_f32_dpp v193, v193, v199 quad_perm:[2,3,0,1] row_mask:0xf bank_mask:0xf bound_ctrl:1
	v_xor_b32_e32 v199, v189, v194
	v_pk_add_f32 v[202:203], v[202:203], v[202:203] op_sel:[0,1] op_sel_hi:[1,0] neg_lo:[0,1] neg_hi:[0,1]
	v_add_f32_dpp v196, v196, v197 quad_perm:[1,0,3,2] row_mask:0xf bank_mask:0xf bound_ctrl:1
	v_xor_b32_e32 v197, v181, v64
	v_add_f32_dpp v194, v194, v199 quad_perm:[2,3,0,1] row_mask:0xf bank_mask:0xf bound_ctrl:1
	v_xor_b32_e32 v199, v189, v195
	v_add_f32_dpp v64, v64, v197 quad_perm:[1,0,3,2] row_mask:0xf bank_mask:0xf bound_ctrl:1
	v_xor_b32_e32 v197, v181, v202
	v_add_f32_dpp v195, v195, v199 quad_perm:[2,3,0,1] row_mask:0xf bank_mask:0xf bound_ctrl:1
	v_xor_b32_e32 v199, v189, v196
	v_add_f32_dpp v197, v202, v197 quad_perm:[1,0,3,2] row_mask:0xf bank_mask:0xf bound_ctrl:1
	v_xor_b32_e32 v198, v181, v62
	v_add_f32_dpp v196, v196, v199 quad_perm:[2,3,0,1] row_mask:0xf bank_mask:0xf bound_ctrl:1
	v_xor_b32_e32 v199, v189, v64
	v_add_f32_dpp v62, v62, v198 quad_perm:[1,0,3,2] row_mask:0xf bank_mask:0xf bound_ctrl:1
	v_xor_b32_e32 v198, v181, v60
	v_add_f32_dpp v64, v64, v199 quad_perm:[2,3,0,1] row_mask:0xf bank_mask:0xf bound_ctrl:1
	v_xor_b32_e32 v199, v189, v197
	v_pk_add_f32 v[206:207], v[206:207], v[206:207] op_sel:[0,1] op_sel_hi:[1,0] neg_lo:[0,1] neg_hi:[0,1]
	v_add_f32_dpp v60, v60, v198 quad_perm:[1,0,3,2] row_mask:0xf bank_mask:0xf bound_ctrl:1
	v_xor_b32_e32 v198, v181, v58
	v_add_f32_dpp v197, v197, v199 quad_perm:[2,3,0,1] row_mask:0xf bank_mask:0xf bound_ctrl:1
	v_xor_b32_e32 v199, v189, v62
	v_add_f32_dpp v58, v58, v198 quad_perm:[1,0,3,2] row_mask:0xf bank_mask:0xf bound_ctrl:1
	v_xor_b32_e32 v198, v181, v206
	v_add_f32_dpp v199, v62, v199 quad_perm:[2,3,0,1] row_mask:0xf bank_mask:0xf bound_ctrl:1
	v_xor_b32_e32 v62, v189, v60
	v_add_f32_dpp v198, v206, v198 quad_perm:[1,0,3,2] row_mask:0xf bank_mask:0xf bound_ctrl:1
	s_nop 0
	v_add_f32_dpp v200, v60, v62 quad_perm:[2,3,0,1] row_mask:0xf bank_mask:0xf bound_ctrl:1
	v_xor_b32_e32 v60, v189, v58
	v_max_f32_e64 v62, |v194|, |v195|
	s_nop 0
	v_add_f32_dpp v201, v58, v60 quad_perm:[2,3,0,1] row_mask:0xf bank_mask:0xf bound_ctrl:1
	v_xor_b32_e32 v58, v189, v198
	v_max_f32_e64 v60, |v63|, |v65|
	s_nop 0
	v_add_f32_dpp v198, v198, v58 quad_perm:[2,3,0,1] row_mask:0xf bank_mask:0xf bound_ctrl:1
	v_xor_b32_e32 v58, v189, v186
	s_nop 1
	v_add_f32_dpp v186, v186, v58 quad_perm:[2,3,0,1] row_mask:0xf bank_mask:0xf bound_ctrl:1
	v_max_f32_e64 v58, |v59|, |v61|
	v_max3_f32 v58, v216, v58, v60
	v_max_f32_e64 v60, |v187|, |v193|
	v_max3_f32 v58, v58, v60, v62
	v_max_f32_e64 v60, |v196|, |v64|
	v_max_f32_e64 v62, |v197|, |v199|
	v_max3_f32 v58, v58, v60, v62
	v_max_f32_e64 v60, |v200|, |v201|
	v_max_f32_e64 v62, |v198|, |v186|
	v_max3_f32 v216, v58, v60, v62
	v_cvt_pk_bf16_f32 v58, v59, v61
	v_cvt_pk_bf16_f32 v59, v63, v65
	v_cvt_pk_bf16_f32 v60, v187, v193
	v_cvt_pk_bf16_f32 v61, v194, v195
	v_cvt_pk_bf16_f32 v62, v196, v64
	v_cvt_pk_bf16_f32 v63, v197, v199
	v_cvt_pk_bf16_f32 v64, v200, v201
	v_cvt_pk_bf16_f32 v65, v198, v186
	v_and_b32_e32 v187, 0xffff0000, v157
	v_and_b32_e32 v186, 0xffff0000, v149
	v_lshlrev_b32_e32 v195, 16, v154
	v_lshlrev_b32_e32 v194, 16, v146
	v_and_b32_e32 v197, 0xffff0000, v154
	v_and_b32_e32 v196, 0xffff0000, v146
	v_lshlrev_b32_e32 v199, 16, v155
	v_lshlrev_b32_e32 v198, 16, v147
	v_and_b32_e32 v155, 0xffff0000, v155
	v_and_b32_e32 v154, 0xffff0000, v147
	v_lshlrev_b32_e32 v147, 16, v156
	v_lshlrev_b32_e32 v146, 16, v148
	v_and_b32_e32 v201, 0xffff0000, v156
	v_and_b32_e32 v200, 0xffff0000, v148
	v_lshlrev_b32_e32 v157, 16, v157
	v_lshlrev_b32_e32 v156, 16, v149
	v_pk_add_f32 v[148:149], v[194:195], v[196:197]
	v_pk_add_f32 v[202:203], v[198:199], v[154:155]
	v_pk_add_f32 v[204:205], v[146:147], v[200:201]
	v_pk_add_f32 v[206:207], v[156:157], v[186:187]
	v_pk_add_f32 v[194:195], v[194:195], v[196:197] neg_lo:[0,1] neg_hi:[0,1]
	v_pk_add_f32 v[154:155], v[198:199], v[154:155] neg_lo:[0,1] neg_hi:[0,1]
	v_pk_add_f32 v[146:147], v[146:147], v[200:201] neg_lo:[0,1] neg_hi:[0,1]
	v_pk_add_f32 v[156:157], v[156:157], v[186:187] neg_lo:[0,1] neg_hi:[0,1]
	v_pk_add_f32 v[208:209], v[148:149], v[202:203] neg_lo:[0,1] neg_hi:[0,1]
	v_pk_add_f32 v[148:149], v[148:149], v[202:203]
	v_pk_add_f32 v[202:203], v[204:205], v[206:207]
	v_pk_add_f32 v[186:187], v[194:195], v[154:155] neg_lo:[0,1] neg_hi:[0,1]
	v_pk_add_f32 v[196:197], v[146:147], v[156:157] neg_lo:[0,1] neg_hi:[0,1]
	v_pk_add_f32 v[154:155], v[194:195], v[154:155]
	v_pk_add_f32 v[146:147], v[146:147], v[156:157]
	v_pk_add_f32 v[210:211], v[204:205], v[206:207] neg_lo:[0,1] neg_hi:[0,1]
	v_pk_add_f32 v[204:205], v[148:149], v[202:203]
	v_pk_add_f32 v[156:157], v[154:155], v[146:147]
	v_pk_add_f32 v[146:147], v[154:155], v[146:147] neg_lo:[0,1] neg_hi:[0,1]
	v_pk_add_f32 v[148:149], v[148:149], v[202:203] neg_lo:[0,1] neg_hi:[0,1]
	v_pk_add_f32 v[202:203], v[208:209], v[210:211]
	v_pk_add_f32 v[206:207], v[208:209], v[210:211] neg_lo:[0,1] neg_hi:[0,1]
	v_pk_add_f32 v[154:155], v[186:187], v[196:197]
	v_pk_add_f32 v[186:187], v[186:187], v[196:197] neg_lo:[0,1] neg_hi:[0,1]
	v_pk_add_f32 v[194:195], v[204:205], v[204:205] op_sel:[0,1] op_sel_hi:[1,0]
	v_pk_add_f32 v[210:211], v[146:147], v[146:147] op_sel:[0,1] op_sel_hi:[1,0]
	v_pk_add_f32 v[146:147], v[146:147], v[146:147] op_sel:[0,1] op_sel_hi:[1,0] neg_lo:[0,1] neg_hi:[0,1]
	v_pk_add_f32 v[198:199], v[156:157], v[156:157] op_sel:[0,1] op_sel_hi:[1,0]
	v_pk_add_f32 v[208:209], v[148:149], v[148:149] op_sel:[0,1] op_sel_hi:[1,0]
	v_pk_add_f32 v[148:149], v[148:149], v[148:149] op_sel:[0,1] op_sel_hi:[1,0] neg_lo:[0,1] neg_hi:[0,1]
	v_pk_add_f32 v[214:215], v[186:187], v[186:187] op_sel:[0,1] op_sel_hi:[1,0]
	v_pk_add_f32 v[186:187], v[186:187], v[186:187] op_sel:[0,1] op_sel_hi:[1,0] neg_lo:[0,1] neg_hi:[0,1]
	v_xor_b32_e32 v147, v181, v194
	v_pk_add_f32 v[196:197], v[204:205], v[204:205] op_sel:[0,1] op_sel_hi:[1,0] neg_lo:[0,1] neg_hi:[0,1]
	v_pk_add_f32 v[200:201], v[202:203], v[202:203] op_sel:[0,1] op_sel_hi:[1,0]
	v_pk_add_f32 v[204:205], v[154:155], v[154:155] op_sel:[0,1] op_sel_hi:[1,0]
	v_pk_add_f32 v[154:155], v[154:155], v[154:155] op_sel:[0,1] op_sel_hi:[1,0] neg_lo:[0,1] neg_hi:[0,1]
	v_add_f32_dpp v147, v194, v147 quad_perm:[1,0,3,2] row_mask:0xf bank_mask:0xf bound_ctrl:1
	v_xor_b32_e32 v149, v181, v198
	v_xor_b32_e32 v199, v181, v186
	v_pk_add_f32 v[156:157], v[156:157], v[156:157] op_sel:[0,1] op_sel_hi:[1,0] neg_lo:[0,1] neg_hi:[0,1]
	v_add_f32_dpp v149, v198, v149 quad_perm:[1,0,3,2] row_mask:0xf bank_mask:0xf bound_ctrl:1
	v_xor_b32_e32 v155, v181, v200
	v_xor_b32_e32 v187, v181, v208
	v_add_f32_dpp v186, v186, v199 quad_perm:[1,0,3,2] row_mask:0xf bank_mask:0xf bound_ctrl:1
	v_xor_b32_e32 v199, v189, v147
	v_add_f32_dpp v155, v200, v155 quad_perm:[1,0,3,2] row_mask:0xf bank_mask:0xf bound_ctrl:1
	v_xor_b32_e32 v157, v181, v204
	v_add_f32_dpp v187, v208, v187 quad_perm:[1,0,3,2] row_mask:0xf bank_mask:0xf bound_ctrl:1
	v_add_f32_dpp v208, v147, v199 quad_perm:[2,3,0,1] row_mask:0xf bank_mask:0xf bound_ctrl:1
	v_xor_b32_e32 v147, v189, v149
	v_add_f32_dpp v157, v204, v157 quad_perm:[1,0,3,2] row_mask:0xf bank_mask:0xf bound_ctrl:1
	v_xor_b32_e32 v193, v181, v210
	v_add_f32_dpp v209, v149, v147 quad_perm:[2,3,0,1] row_mask:0xf bank_mask:0xf bound_ctrl:1
	v_xor_b32_e32 v147, v189, v155
	v_pk_add_f32 v[212:213], v[206:207], v[206:207] op_sel:[0,1] op_sel_hi:[1,0]
	v_add_f32_dpp v193, v210, v193 quad_perm:[1,0,3,2] row_mask:0xf bank_mask:0xf bound_ctrl:1
	v_add_f32_dpp v210, v155, v147 quad_perm:[2,3,0,1] row_mask:0xf bank_mask:0xf bound_ctrl:1
	v_xor_b32_e32 v147, v189, v157
	v_xor_b32_e32 v194, v181, v212
	v_xor_b32_e32 v195, v181, v214
	v_add_f32_dpp v211, v157, v147 quad_perm:[2,3,0,1] row_mask:0xf bank_mask:0xf bound_ctrl:1
	v_xor_b32_e32 v147, v189, v187
	v_add_f32_dpp v194, v212, v194 quad_perm:[1,0,3,2] row_mask:0xf bank_mask:0xf bound_ctrl:1
	v_add_f32_dpp v195, v214, v195 quad_perm:[1,0,3,2] row_mask:0xf bank_mask:0xf bound_ctrl:1
	v_add_f32_dpp v212, v187, v147 quad_perm:[2,3,0,1] row_mask:0xf bank_mask:0xf bound_ctrl:1
	v_xor_b32_e32 v147, v189, v193
	v_xor_b32_e32 v197, v181, v196
	v_pk_add_f32 v[202:203], v[202:203], v[202:203] op_sel:[0,1] op_sel_hi:[1,0] neg_lo:[0,1] neg_hi:[0,1]
	v_add_f32_dpp v213, v193, v147 quad_perm:[2,3,0,1] row_mask:0xf bank_mask:0xf bound_ctrl:1
	v_xor_b32_e32 v147, v189, v194
	v_add_f32_dpp v196, v196, v197 quad_perm:[1,0,3,2] row_mask:0xf bank_mask:0xf bound_ctrl:1
	v_xor_b32_e32 v197, v181, v156
	v_add_f32_dpp v214, v194, v147 quad_perm:[2,3,0,1] row_mask:0xf bank_mask:0xf bound_ctrl:1
	v_xor_b32_e32 v147, v189, v195
	v_add_f32_dpp v156, v156, v197 quad_perm:[1,0,3,2] row_mask:0xf bank_mask:0xf bound_ctrl:1
	v_xor_b32_e32 v197, v181, v202
	v_add_f32_dpp v215, v195, v147 quad_perm:[2,3,0,1] row_mask:0xf bank_mask:0xf bound_ctrl:1
	v_xor_b32_e32 v147, v189, v196
	v_add_f32_dpp v197, v202, v197 quad_perm:[1,0,3,2] row_mask:0xf bank_mask:0xf bound_ctrl:1
	v_xor_b32_e32 v198, v181, v154
	v_add_f32_dpp v217, v196, v147 quad_perm:[2,3,0,1] row_mask:0xf bank_mask:0xf bound_ctrl:1
	v_xor_b32_e32 v147, v189, v156
	v_add_f32_dpp v154, v154, v198 quad_perm:[1,0,3,2] row_mask:0xf bank_mask:0xf bound_ctrl:1
	v_xor_b32_e32 v198, v181, v148
	v_add_f32_dpp v218, v156, v147 quad_perm:[2,3,0,1] row_mask:0xf bank_mask:0xf bound_ctrl:1
	v_xor_b32_e32 v147, v189, v197
	v_pk_add_f32 v[206:207], v[206:207], v[206:207] op_sel:[0,1] op_sel_hi:[1,0] neg_lo:[0,1] neg_hi:[0,1]
	v_add_f32_dpp v148, v148, v198 quad_perm:[1,0,3,2] row_mask:0xf bank_mask:0xf bound_ctrl:1
	v_xor_b32_e32 v198, v181, v146
	v_add_f32_dpp v219, v197, v147 quad_perm:[2,3,0,1] row_mask:0xf bank_mask:0xf bound_ctrl:1
	v_xor_b32_e32 v147, v189, v154
	v_add_f32_dpp v146, v146, v198 quad_perm:[1,0,3,2] row_mask:0xf bank_mask:0xf bound_ctrl:1
	v_xor_b32_e32 v198, v181, v206
	v_add_f32_dpp v220, v154, v147 quad_perm:[2,3,0,1] row_mask:0xf bank_mask:0xf bound_ctrl:1
	v_xor_b32_e32 v147, v189, v148
	v_add_f32_dpp v198, v206, v198 quad_perm:[1,0,3,2] row_mask:0xf bank_mask:0xf bound_ctrl:1
	s_waitcnt vmcnt(0)
	v_lshlrev_b32_e32 v149, 16, v114
	v_add_f32_dpp v221, v148, v147 quad_perm:[2,3,0,1] row_mask:0xf bank_mask:0xf bound_ctrl:1
	v_xor_b32_e32 v147, v189, v146
	v_max_f32_e64 v148, |v214|, |v215|
	v_and_b32_e32 v155, 0xffff0000, v114
	v_add_f32_dpp v222, v146, v147 quad_perm:[2,3,0,1] row_mask:0xf bank_mask:0xf bound_ctrl:1
	v_xor_b32_e32 v146, v189, v198
	v_max_f32_e64 v147, |v210|, |v211|
	v_and_b32_e32 v154, 0xffff0000, v102
	v_add_f32_dpp v223, v198, v146 quad_perm:[2,3,0,1] row_mask:0xf bank_mask:0xf bound_ctrl:1
	v_xor_b32_e32 v146, v189, v186
	v_lshlrev_b32_e32 v157, 16, v115
	v_lshlrev_b32_e32 v156, 16, v103
	v_add_f32_dpp v224, v186, v146 quad_perm:[2,3,0,1] row_mask:0xf bank_mask:0xf bound_ctrl:1
	v_max_f32_e64 v146, |v208|, |v209|
	v_max3_f32 v146, v216, v146, v147
	v_max_f32_e64 v147, |v212|, |v213|
	v_max3_f32 v146, v146, v147, v148
	v_max_f32_e64 v147, |v217|, |v218|
	v_max_f32_e64 v148, |v219|, |v220|
	v_max3_f32 v146, v146, v147, v148
	v_max_f32_e64 v147, |v221|, |v222|
	v_max_f32_e64 v148, |v223|, |v224|
	v_max3_f32 v193, v146, v147, v148
	v_and_b32_e32 v147, 0xffff0000, v117
	v_and_b32_e32 v146, 0xffff0000, v105
	v_lshlrev_b32_e32 v148, 16, v102
	v_and_b32_e32 v115, 0xffff0000, v115
	v_and_b32_e32 v114, 0xffff0000, v103
	v_lshlrev_b32_e32 v103, 16, v116
	v_lshlrev_b32_e32 v102, 16, v104
	v_and_b32_e32 v187, 0xffff0000, v116
	v_and_b32_e32 v186, 0xffff0000, v104
	v_lshlrev_b32_e32 v117, 16, v117
	v_lshlrev_b32_e32 v116, 16, v105
	v_pk_add_f32 v[104:105], v[148:149], v[154:155]
	v_pk_add_f32 v[194:195], v[156:157], v[114:115]
	v_pk_add_f32 v[196:197], v[102:103], v[186:187]
	v_pk_add_f32 v[198:199], v[116:117], v[146:147]
	v_pk_add_f32 v[148:149], v[148:149], v[154:155] neg_lo:[0,1] neg_hi:[0,1]
	v_pk_add_f32 v[114:115], v[156:157], v[114:115] neg_lo:[0,1] neg_hi:[0,1]
	v_pk_add_f32 v[102:103], v[102:103], v[186:187] neg_lo:[0,1] neg_hi:[0,1]
	v_pk_add_f32 v[116:117], v[116:117], v[146:147] neg_lo:[0,1] neg_hi:[0,1]
	v_pk_add_f32 v[200:201], v[104:105], v[194:195] neg_lo:[0,1] neg_hi:[0,1]
	v_pk_add_f32 v[202:203], v[196:197], v[198:199] neg_lo:[0,1] neg_hi:[0,1]
	v_pk_add_f32 v[104:105], v[104:105], v[194:195]
	v_pk_add_f32 v[194:195], v[196:197], v[198:199]
	v_pk_add_f32 v[146:147], v[148:149], v[114:115] neg_lo:[0,1] neg_hi:[0,1]
	v_pk_add_f32 v[154:155], v[102:103], v[116:117] neg_lo:[0,1] neg_hi:[0,1]
	v_pk_add_f32 v[114:115], v[148:149], v[114:115]
	v_pk_add_f32 v[102:103], v[102:103], v[116:117]
	v_pk_add_f32 v[196:197], v[104:105], v[194:195]
	v_pk_add_f32 v[104:105], v[104:105], v[194:195] neg_lo:[0,1] neg_hi:[0,1]
	v_pk_add_f32 v[194:195], v[200:201], v[202:203]
	v_pk_add_f32 v[116:117], v[114:115], v[102:103]
	v_pk_add_f32 v[102:103], v[114:115], v[102:103] neg_lo:[0,1] neg_hi:[0,1]
	v_pk_add_f32 v[114:115], v[146:147], v[154:155]
	v_pk_add_f32 v[198:199], v[200:201], v[202:203] neg_lo:[0,1] neg_hi:[0,1]
	v_pk_add_f32 v[146:147], v[146:147], v[154:155] neg_lo:[0,1] neg_hi:[0,1]
	v_pk_add_f32 v[148:149], v[196:197], v[196:197] op_sel:[0,1] op_sel_hi:[1,0]
	v_pk_add_f32 v[154:155], v[196:197], v[196:197] op_sel:[0,1] op_sel_hi:[1,0] neg_lo:[0,1] neg_hi:[0,1]
	v_pk_add_f32 v[186:187], v[194:195], v[194:195] op_sel:[0,1] op_sel_hi:[1,0]
	v_pk_add_f32 v[196:197], v[114:115], v[114:115] op_sel:[0,1] op_sel_hi:[1,0]
	v_pk_add_f32 v[114:115], v[114:115], v[114:115] op_sel:[0,1] op_sel_hi:[1,0] neg_lo:[0,1] neg_hi:[0,1]
	v_pk_add_f32 v[202:203], v[102:103], v[102:103] op_sel:[0,1] op_sel_hi:[1,0]
	v_pk_add_f32 v[102:103], v[102:103], v[102:103] op_sel:[0,1] op_sel_hi:[1,0] neg_lo:[0,1] neg_hi:[0,1]
	v_pk_add_f32 v[156:157], v[116:117], v[116:117] op_sel:[0,1] op_sel_hi:[1,0]
	v_pk_add_f32 v[200:201], v[104:105], v[104:105] op_sel:[0,1] op_sel_hi:[1,0]
	v_pk_add_f32 v[104:105], v[104:105], v[104:105] op_sel:[0,1] op_sel_hi:[1,0] neg_lo:[0,1] neg_hi:[0,1]
	v_pk_add_f32 v[206:207], v[146:147], v[146:147] op_sel:[0,1] op_sel_hi:[1,0]
	v_pk_add_f32 v[146:147], v[146:147], v[146:147] op_sel:[0,1] op_sel_hi:[1,0] neg_lo:[0,1] neg_hi:[0,1]
	v_xor_b32_e32 v103, v181, v148
	v_xor_b32_e32 v115, v181, v186
	v_xor_b32_e32 v105, v181, v156
	v_add_f32_dpp v103, v148, v103 quad_perm:[1,0,3,2] row_mask:0xf bank_mask:0xf bound_ctrl:1
	v_add_f32_dpp v115, v186, v115 quad_perm:[1,0,3,2] row_mask:0xf bank_mask:0xf bound_ctrl:1
	v_xor_b32_e32 v186, v181, v146
	v_pk_add_f32 v[116:117], v[116:117], v[116:117] op_sel:[0,1] op_sel_hi:[1,0] neg_lo:[0,1] neg_hi:[0,1]
	v_add_f32_dpp v105, v156, v105 quad_perm:[1,0,3,2] row_mask:0xf bank_mask:0xf bound_ctrl:1
	v_xor_b32_e32 v147, v181, v200
	v_add_f32_dpp v146, v146, v186 quad_perm:[1,0,3,2] row_mask:0xf bank_mask:0xf bound_ctrl:1
	v_xor_b32_e32 v186, v189, v103
	v_xor_b32_e32 v117, v181, v196
	v_add_f32_dpp v147, v200, v147 quad_perm:[1,0,3,2] row_mask:0xf bank_mask:0xf bound_ctrl:1
	v_add_f32_dpp v200, v103, v186 quad_perm:[2,3,0,1] row_mask:0xf bank_mask:0xf bound_ctrl:1
	v_xor_b32_e32 v103, v189, v105
	v_add_f32_dpp v117, v196, v117 quad_perm:[1,0,3,2] row_mask:0xf bank_mask:0xf bound_ctrl:1
	v_xor_b32_e32 v148, v181, v202
	v_add_f32_dpp v201, v105, v103 quad_perm:[2,3,0,1] row_mask:0xf bank_mask:0xf bound_ctrl:1
	v_xor_b32_e32 v103, v189, v115
	v_pk_add_f32 v[204:205], v[198:199], v[198:199] op_sel:[0,1] op_sel_hi:[1,0]
	v_add_f32_dpp v148, v202, v148 quad_perm:[1,0,3,2] row_mask:0xf bank_mask:0xf bound_ctrl:1
	v_add_f32_dpp v202, v115, v103 quad_perm:[2,3,0,1] row_mask:0xf bank_mask:0xf bound_ctrl:1
	v_xor_b32_e32 v103, v189, v117
	v_xor_b32_e32 v149, v181, v204
	v_xor_b32_e32 v155, v181, v206
	v_add_f32_dpp v203, v117, v103 quad_perm:[2,3,0,1] row_mask:0xf bank_mask:0xf bound_ctrl:1
	v_xor_b32_e32 v103, v189, v147
	v_add_f32_dpp v149, v204, v149 quad_perm:[1,0,3,2] row_mask:0xf bank_mask:0xf bound_ctrl:1
	v_add_f32_dpp v155, v206, v155 quad_perm:[1,0,3,2] row_mask:0xf bank_mask:0xf bound_ctrl:1
	v_add_f32_dpp v204, v147, v103 quad_perm:[2,3,0,1] row_mask:0xf bank_mask:0xf bound_ctrl:1
	v_xor_b32_e32 v103, v189, v148
	v_xor_b32_e32 v156, v181, v154
	v_pk_add_f32 v[194:195], v[194:195], v[194:195] op_sel:[0,1] op_sel_hi:[1,0] neg_lo:[0,1] neg_hi:[0,1]
	v_add_f32_dpp v205, v148, v103 quad_perm:[2,3,0,1] row_mask:0xf bank_mask:0xf bound_ctrl:1
	v_xor_b32_e32 v103, v189, v149
	v_add_f32_dpp v154, v154, v156 quad_perm:[1,0,3,2] row_mask:0xf bank_mask:0xf bound_ctrl:1
	v_xor_b32_e32 v156, v181, v116
	v_add_f32_dpp v206, v149, v103 quad_perm:[2,3,0,1] row_mask:0xf bank_mask:0xf bound_ctrl:1
	v_xor_b32_e32 v103, v189, v155
	v_add_f32_dpp v116, v116, v156 quad_perm:[1,0,3,2] row_mask:0xf bank_mask:0xf bound_ctrl:1
	v_xor_b32_e32 v156, v181, v194
	v_add_f32_dpp v207, v155, v103 quad_perm:[2,3,0,1] row_mask:0xf bank_mask:0xf bound_ctrl:1
	v_xor_b32_e32 v103, v189, v154
	v_add_f32_dpp v156, v194, v156 quad_perm:[1,0,3,2] row_mask:0xf bank_mask:0xf bound_ctrl:1
	v_xor_b32_e32 v157, v181, v114
	v_add_f32_dpp v216, v154, v103 quad_perm:[2,3,0,1] row_mask:0xf bank_mask:0xf bound_ctrl:1
	v_xor_b32_e32 v103, v189, v116
	v_add_f32_dpp v114, v114, v157 quad_perm:[1,0,3,2] row_mask:0xf bank_mask:0xf bound_ctrl:1
	v_xor_b32_e32 v157, v181, v104
	v_add_f32_dpp v225, v116, v103 quad_perm:[2,3,0,1] row_mask:0xf bank_mask:0xf bound_ctrl:1
	v_xor_b32_e32 v103, v189, v156
	v_pk_add_f32 v[198:199], v[198:199], v[198:199] op_sel:[0,1] op_sel_hi:[1,0] neg_lo:[0,1] neg_hi:[0,1]
	v_add_f32_dpp v104, v104, v157 quad_perm:[1,0,3,2] row_mask:0xf bank_mask:0xf bound_ctrl:1
	v_xor_b32_e32 v157, v181, v102
	v_add_f32_dpp v226, v156, v103 quad_perm:[2,3,0,1] row_mask:0xf bank_mask:0xf bound_ctrl:1
	v_xor_b32_e32 v103, v189, v114
	v_add_f32_dpp v102, v102, v157 quad_perm:[1,0,3,2] row_mask:0xf bank_mask:0xf bound_ctrl:1
	v_xor_b32_e32 v157, v181, v198
	v_add_f32_dpp v227, v114, v103 quad_perm:[2,3,0,1] row_mask:0xf bank_mask:0xf bound_ctrl:1
	v_xor_b32_e32 v103, v189, v104
	v_add_f32_dpp v157, v198, v157 quad_perm:[1,0,3,2] row_mask:0xf bank_mask:0xf bound_ctrl:1
	v_lshlrev_b32_e32 v105, 16, v70
	v_add_f32_dpp v228, v104, v103 quad_perm:[2,3,0,1] row_mask:0xf bank_mask:0xf bound_ctrl:1
	v_xor_b32_e32 v103, v189, v102
	v_max_f32_e64 v104, |v206|, |v207|
	v_and_b32_e32 v115, 0xffff0000, v70
	v_add_f32_dpp v229, v102, v103 quad_perm:[2,3,0,1] row_mask:0xf bank_mask:0xf bound_ctrl:1
	v_xor_b32_e32 v102, v189, v157
	v_max_f32_e64 v103, |v202|, |v203|
	v_and_b32_e32 v114, 0xffff0000, v66
	v_add_f32_dpp v230, v157, v102 quad_perm:[2,3,0,1] row_mask:0xf bank_mask:0xf bound_ctrl:1
	v_xor_b32_e32 v102, v189, v146
	v_lshlrev_b32_e32 v116, 16, v67
	v_lshlrev_b32_e32 v117, 16, v71
	v_add_f32_dpp v231, v146, v102 quad_perm:[2,3,0,1] row_mask:0xf bank_mask:0xf bound_ctrl:1
	v_max_f32_e64 v102, |v200|, |v201|
	v_max3_f32 v102, v193, v102, v103
	v_max_f32_e64 v103, |v204|, |v205|
	v_max3_f32 v102, v102, v103, v104
	v_max_f32_e64 v103, |v216|, |v225|
	v_max_f32_e64 v104, |v226|, |v227|
	v_max3_f32 v102, v102, v103, v104
	v_max_f32_e64 v103, |v228|, |v229|
	v_max_f32_e64 v104, |v230|, |v231|
	v_max3_f32 v193, v102, v103, v104
	v_and_b32_e32 v103, 0xffff0000, v73
	v_and_b32_e32 v102, 0xffff0000, v69
	v_lshlrev_b32_e32 v104, 16, v66
	v_and_b32_e32 v71, 0xffff0000, v71
	v_and_b32_e32 v70, 0xffff0000, v67
	v_lshlrev_b32_e32 v67, 16, v72
	v_lshlrev_b32_e32 v66, 16, v68
	v_and_b32_e32 v147, 0xffff0000, v72
	v_and_b32_e32 v146, 0xffff0000, v68
	v_lshlrev_b32_e32 v68, 16, v69
	v_lshlrev_b32_e32 v69, 16, v73
	v_pk_add_f32 v[72:73], v[104:105], v[114:115]
	v_pk_add_f32 v[148:149], v[116:117], v[70:71]
	v_pk_add_f32 v[154:155], v[66:67], v[146:147]
	v_pk_add_f32 v[156:157], v[68:69], v[102:103]
	v_pk_add_f32 v[104:105], v[104:105], v[114:115] neg_lo:[0,1] neg_hi:[0,1]
	v_pk_add_f32 v[70:71], v[116:117], v[70:71] neg_lo:[0,1] neg_hi:[0,1]
	v_pk_add_f32 v[66:67], v[66:67], v[146:147] neg_lo:[0,1] neg_hi:[0,1]
	v_pk_add_f32 v[68:69], v[68:69], v[102:103] neg_lo:[0,1] neg_hi:[0,1]
	v_pk_add_f32 v[186:187], v[72:73], v[148:149] neg_lo:[0,1] neg_hi:[0,1]
	v_pk_add_f32 v[194:195], v[154:155], v[156:157] neg_lo:[0,1] neg_hi:[0,1]
	v_pk_add_f32 v[72:73], v[72:73], v[148:149]
	v_pk_add_f32 v[148:149], v[154:155], v[156:157]
	v_pk_add_f32 v[102:103], v[104:105], v[70:71] neg_lo:[0,1] neg_hi:[0,1]
	v_pk_add_f32 v[114:115], v[66:67], v[68:69] neg_lo:[0,1] neg_hi:[0,1]
	v_pk_add_f32 v[70:71], v[104:105], v[70:71]
	v_pk_add_f32 v[66:67], v[66:67], v[68:69]
	v_pk_add_f32 v[154:155], v[72:73], v[148:149]
	v_pk_add_f32 v[72:73], v[72:73], v[148:149] neg_lo:[0,1] neg_hi:[0,1]
	v_pk_add_f32 v[148:149], v[186:187], v[194:195]
	v_pk_add_f32 v[68:69], v[70:71], v[66:67]
	v_pk_add_f32 v[66:67], v[70:71], v[66:67] neg_lo:[0,1] neg_hi:[0,1]
	v_pk_add_f32 v[70:71], v[102:103], v[114:115]
	v_pk_add_f32 v[156:157], v[186:187], v[194:195] neg_lo:[0,1] neg_hi:[0,1]
	v_pk_add_f32 v[102:103], v[102:103], v[114:115] neg_lo:[0,1] neg_hi:[0,1]
	v_pk_add_f32 v[104:105], v[154:155], v[154:155] op_sel:[0,1] op_sel_hi:[1,0]
	v_pk_add_f32 v[114:115], v[154:155], v[154:155] op_sel:[0,1] op_sel_hi:[1,0] neg_lo:[0,1] neg_hi:[0,1]
	v_pk_add_f32 v[146:147], v[148:149], v[148:149] op_sel:[0,1] op_sel_hi:[1,0]
	v_pk_add_f32 v[154:155], v[70:71], v[70:71] op_sel:[0,1] op_sel_hi:[1,0]
	v_pk_add_f32 v[70:71], v[70:71], v[70:71] op_sel:[0,1] op_sel_hi:[1,0] neg_lo:[0,1] neg_hi:[0,1]
	v_pk_add_f32 v[194:195], v[66:67], v[66:67] op_sel:[0,1] op_sel_hi:[1,0]
	v_pk_add_f32 v[66:67], v[66:67], v[66:67] op_sel:[0,1] op_sel_hi:[1,0] neg_lo:[0,1] neg_hi:[0,1]
	v_pk_add_f32 v[116:117], v[68:69], v[68:69] op_sel:[0,1] op_sel_hi:[1,0]
	v_pk_add_f32 v[68:69], v[68:69], v[68:69] op_sel:[0,1] op_sel_hi:[1,0] neg_lo:[0,1] neg_hi:[0,1]
	v_pk_add_f32 v[198:199], v[102:103], v[102:103] op_sel:[0,1] op_sel_hi:[1,0]
	v_pk_add_f32 v[102:103], v[102:103], v[102:103] op_sel:[0,1] op_sel_hi:[1,0] neg_lo:[0,1] neg_hi:[0,1]
	v_xor_b32_e32 v67, v181, v104
	v_xor_b32_e32 v71, v181, v146
	v_xor_b32_e32 v69, v181, v116
	v_add_f32_dpp v67, v104, v67 quad_perm:[1,0,3,2] row_mask:0xf bank_mask:0xf bound_ctrl:1
	v_add_f32_dpp v71, v146, v71 quad_perm:[1,0,3,2] row_mask:0xf bank_mask:0xf bound_ctrl:1
	v_xor_b32_e32 v146, v181, v102
	v_pk_add_f32 v[186:187], v[72:73], v[72:73] op_sel:[0,1] op_sel_hi:[1,0]
	v_pk_add_f32 v[72:73], v[72:73], v[72:73] op_sel:[0,1] op_sel_hi:[1,0] neg_lo:[0,1] neg_hi:[0,1]
	v_add_f32_dpp v69, v116, v69 quad_perm:[1,0,3,2] row_mask:0xf bank_mask:0xf bound_ctrl:1
	v_add_f32_dpp v102, v102, v146 quad_perm:[1,0,3,2] row_mask:0xf bank_mask:0xf bound_ctrl:1
	v_xor_b32_e32 v146, v189, v67
	v_xor_b32_e32 v73, v181, v154
	v_xor_b32_e32 v103, v181, v186
	v_add_f32_dpp v67, v67, v146 quad_perm:[2,3,0,1] row_mask:0xf bank_mask:0xf bound_ctrl:1
	v_xor_b32_e32 v146, v189, v69
	v_add_f32_dpp v73, v154, v73 quad_perm:[1,0,3,2] row_mask:0xf bank_mask:0xf bound_ctrl:1
	v_pk_add_f32 v[196:197], v[156:157], v[156:157] op_sel:[0,1] op_sel_hi:[1,0]
	v_add_f32_dpp v69, v69, v146 quad_perm:[2,3,0,1] row_mask:0xf bank_mask:0xf bound_ctrl:1
	v_xor_b32_e32 v146, v189, v71
	v_add_f32_dpp v103, v186, v103 quad_perm:[1,0,3,2] row_mask:0xf bank_mask:0xf bound_ctrl:1
	v_xor_b32_e32 v104, v181, v194
	v_add_f32_dpp v71, v71, v146 quad_perm:[2,3,0,1] row_mask:0xf bank_mask:0xf bound_ctrl:1
	v_xor_b32_e32 v146, v189, v73
	v_add_f32_dpp v104, v194, v104 quad_perm:[1,0,3,2] row_mask:0xf bank_mask:0xf bound_ctrl:1
	v_xor_b32_e32 v105, v181, v196
	v_add_f32_dpp v73, v73, v146 quad_perm:[2,3,0,1] row_mask:0xf bank_mask:0xf bound_ctrl:1
	v_xor_b32_e32 v146, v189, v103
	v_add_f32_dpp v105, v196, v105 quad_perm:[1,0,3,2] row_mask:0xf bank_mask:0xf bound_ctrl:1
	v_xor_b32_e32 v115, v181, v198
	v_add_f32_dpp v186, v103, v146 quad_perm:[2,3,0,1] row_mask:0xf bank_mask:0xf bound_ctrl:1
	v_xor_b32_e32 v103, v189, v104
	v_add_f32_dpp v115, v198, v115 quad_perm:[1,0,3,2] row_mask:0xf bank_mask:0xf bound_ctrl:1
	v_xor_b32_e32 v116, v181, v114
	v_add_f32_dpp v187, v104, v103 quad_perm:[2,3,0,1] row_mask:0xf bank_mask:0xf bound_ctrl:1
	v_xor_b32_e32 v103, v189, v105
	v_pk_add_f32 v[148:149], v[148:149], v[148:149] op_sel:[0,1] op_sel_hi:[1,0] neg_lo:[0,1] neg_hi:[0,1]
	v_add_f32_dpp v114, v114, v116 quad_perm:[1,0,3,2] row_mask:0xf bank_mask:0xf bound_ctrl:1
	v_xor_b32_e32 v116, v181, v68
	v_add_f32_dpp v198, v105, v103 quad_perm:[2,3,0,1] row_mask:0xf bank_mask:0xf bound_ctrl:1
	v_xor_b32_e32 v103, v189, v115
	v_add_f32_dpp v68, v68, v116 quad_perm:[1,0,3,2] row_mask:0xf bank_mask:0xf bound_ctrl:1
	v_xor_b32_e32 v116, v181, v148
	v_add_f32_dpp v199, v115, v103 quad_perm:[2,3,0,1] row_mask:0xf bank_mask:0xf bound_ctrl:1
	v_xor_b32_e32 v103, v189, v114
	v_add_f32_dpp v116, v148, v116 quad_perm:[1,0,3,2] row_mask:0xf bank_mask:0xf bound_ctrl:1
	v_xor_b32_e32 v117, v181, v70
	v_add_f32_dpp v232, v114, v103 quad_perm:[2,3,0,1] row_mask:0xf bank_mask:0xf bound_ctrl:1
	v_xor_b32_e32 v103, v189, v68
	v_add_f32_dpp v70, v70, v117 quad_perm:[1,0,3,2] row_mask:0xf bank_mask:0xf bound_ctrl:1
	v_xor_b32_e32 v117, v181, v72
	v_add_f32_dpp v233, v68, v103 quad_perm:[2,3,0,1] row_mask:0xf bank_mask:0xf bound_ctrl:1
	v_xor_b32_e32 v68, v189, v116
	v_pk_add_f32 v[156:157], v[156:157], v[156:157] op_sel:[0,1] op_sel_hi:[1,0] neg_lo:[0,1] neg_hi:[0,1]
	v_add_f32_dpp v72, v72, v117 quad_perm:[1,0,3,2] row_mask:0xf bank_mask:0xf bound_ctrl:1
	v_xor_b32_e32 v117, v181, v66
	v_add_f32_dpp v235, v116, v68 quad_perm:[2,3,0,1] row_mask:0xf bank_mask:0xf bound_ctrl:1
	v_xor_b32_e32 v68, v189, v70
	v_add_f32_dpp v66, v66, v117 quad_perm:[1,0,3,2] row_mask:0xf bank_mask:0xf bound_ctrl:1
	v_xor_b32_e32 v117, v181, v156
	v_add_f32_dpp v236, v70, v68 quad_perm:[2,3,0,1] row_mask:0xf bank_mask:0xf bound_ctrl:1
	v_xor_b32_e32 v68, v189, v72
	v_add_f32_dpp v117, v156, v117 quad_perm:[1,0,3,2] row_mask:0xf bank_mask:0xf bound_ctrl:1
	v_max_f32_e64 v70, |v198|, |v199|
	v_add_f32_dpp v72, v72, v68 quad_perm:[2,3,0,1] row_mask:0xf bank_mask:0xf bound_ctrl:1
	v_xor_b32_e32 v68, v189, v66
	v_cvt_pk_bf16_f32 v146, v208, v209
	v_cvt_pk_bf16_f32 v147, v210, v211
	v_cvt_pk_bf16_f32 v148, v212, v213
	v_cvt_pk_bf16_f32 v149, v214, v215
	v_cvt_pk_bf16_f32 v154, v217, v218
	s_nop 1
	v_add_f32_dpp v237, v66, v68 quad_perm:[2,3,0,1] row_mask:0xf bank_mask:0xf bound_ctrl:1
	v_xor_b32_e32 v66, v189, v117
	v_max_f32_e64 v68, |v71|, |v73|
	v_cvt_pk_bf16_f32 v155, v219, v220
	v_cvt_pk_bf16_f32 v156, v221, v222
	v_cvt_pk_bf16_f32 v157, v223, v224
	s_nop 0
	v_add_f32_dpp v238, v117, v66 quad_perm:[2,3,0,1] row_mask:0xf bank_mask:0xf bound_ctrl:1
	v_xor_b32_e32 v66, v189, v102
	s_nop 1
	v_add_f32_dpp v239, v102, v66 quad_perm:[2,3,0,1] row_mask:0xf bank_mask:0xf bound_ctrl:1
	v_max_f32_e64 v66, |v67|, |v69|
	v_max3_f32 v66, v193, v66, v68
	v_max_f32_e64 v68, |v186|, |v187|
	v_max3_f32 v66, v66, v68, v70
	v_max_f32_e64 v68, |v232|, |v233|
	v_max_f32_e64 v70, |v235|, |v236|
	v_max3_f32 v66, v66, v68, v70
	v_max_f32_e64 v68, |v72|, |v237|
	v_max_f32_e64 v70, |v238|, |v239|
	v_max3_f32 v66, v66, v68, v70
	v_and_b32_e32 v68, 64, v190
	v_add_u32_e32 v70, 64, v68
	v_xor_b32_e32 v68, 1, v190
	v_cmp_lt_i32_e32 vcc, v68, v70
	v_cvt_pk_bf16_f32 v102, v200, v201
	v_cvt_pk_bf16_f32 v103, v202, v203
	v_cvt_pk_bf16_f32 v104, v204, v205
	v_cvt_pk_bf16_f32 v105, v206, v207
	v_cvt_pk_bf16_f32 v114, v216, v225
	s_nop 1
	v_cndmask_b32_e32 v68, v190, v68, vcc
	v_lshlrev_b32_e32 v193, 2, v68
	ds_bpermute_b32 v68, v193, v66
	v_cvt_pk_bf16_f32 v115, v226, v227
	v_cvt_pk_bf16_f32 v116, v228, v229
	v_cvt_pk_bf16_f32 v117, v230, v231
	s_waitcnt lgkmcnt(0)
	v_max_f32_e32 v68, v68, v68
	v_max_f32_e32 v66, v66, v68
	v_xor_b32_e32 v68, 2, v190
	v_cmp_lt_i32_e32 vcc, v68, v70
	s_nop 1
	v_cndmask_b32_e32 v68, v190, v68, vcc
	v_lshlrev_b32_e32 v194, 2, v68
	ds_bpermute_b32 v68, v194, v66
	s_waitcnt lgkmcnt(0)
	v_max_f32_e32 v68, v68, v68
	v_max_f32_e32 v66, v66, v68
	v_xor_b32_e32 v68, 4, v190
	v_cmp_lt_i32_e32 vcc, v68, v70
	s_nop 1
	v_cndmask_b32_e32 v68, v190, v68, vcc
	v_lshlrev_b32_e32 v195, 2, v68
	ds_bpermute_b32 v68, v195, v66
	s_waitcnt lgkmcnt(0)
	v_max_f32_e32 v68, v68, v68
	v_max_f32_e32 v66, v66, v68
	v_xor_b32_e32 v68, 8, v190
	v_cmp_lt_i32_e32 vcc, v68, v70
	s_nop 1
	v_cndmask_b32_e32 v68, v190, v68, vcc
	v_lshlrev_b32_e32 v196, 2, v68
	ds_bpermute_b32 v68, v196, v66
	s_waitcnt lgkmcnt(0)
	v_max_f32_e32 v68, v68, v68
	v_max_f32_e32 v200, v66, v68
	v_xor_b32_e32 v66, 16, v190
	v_cmp_lt_i32_e32 vcc, v66, v70
	s_nop 1
	v_cndmask_b32_e32 v66, v190, v66, vcc
	v_lshlrev_b32_e32 v197, 2, v66
	ds_bpermute_b32 v201, v197, v200
	v_cvt_pk_bf16_f32 v66, v67, v69
	v_cvt_pk_bf16_f32 v67, v71, v73
	v_cvt_pk_bf16_f32 v68, v186, v187
	v_cvt_pk_bf16_f32 v69, v198, v199
	s_waitcnt lgkmcnt(0)
	v_max_f32_e32 v71, v201, v201
	v_max_f32_e32 v186, v200, v71
	v_xor_b32_e32 v71, 32, v190
	v_cmp_lt_i32_e32 vcc, v71, v70
	s_nop 1
	v_cndmask_b32_e32 v70, v190, v71, vcc
	v_lshlrev_b32_e32 v198, 2, v70
	ds_bpermute_b32 v187, v198, v186
	v_cvt_pk_bf16_f32 v70, v232, v233
	v_cvt_pk_bf16_f32 v71, v235, v236
	v_cvt_pk_bf16_f32 v72, v72, v237
	v_cvt_pk_bf16_f32 v73, v238, v239
	s_waitcnt lgkmcnt(0)
	v_max_f32_e32 v187, v187, v187
	v_max_f32_e32 v186, v186, v187
	s_and_saveexec_b64 s[34:35], s[2:3]
	s_cbranch_execz .LBB0_1010
	s_lshl_b64 s[46:47], s[30:31], 2
	s_sub_u32 s46, s37, s46
	s_subb_u32 s47, s38, s47
	v_mul_f32_e32 v187, 0x3a810204, v186
	global_store_dword v179, v187, s[46:47]

.LBB0_1017:
	v_lshlrev_b32_e32 v187, 16, v78
	v_lshlrev_b32_e32 v186, 16, v74
	v_and_b32_e32 v201, 0xffff0000, v78
	v_and_b32_e32 v200, 0xffff0000, v74
	v_lshlrev_b32_e32 v202, 16, v75
	v_lshlrev_b32_e32 v203, 16, v79
	v_and_b32_e32 v79, 0xffff0000, v79
	v_and_b32_e32 v78, 0xffff0000, v75
	v_lshlrev_b32_e32 v75, 16, v80
	v_lshlrev_b32_e32 v74, 16, v76
	v_and_b32_e32 v205, 0xffff0000, v80
	v_and_b32_e32 v204, 0xffff0000, v76
	v_lshlrev_b32_e32 v206, 16, v77
	v_lshlrev_b32_e32 v207, 16, v81
	v_and_b32_e32 v81, 0xffff0000, v81
	v_and_b32_e32 v80, 0xffff0000, v77
	v_pk_add_f32 v[76:77], v[186:187], v[200:201]
	v_pk_add_f32 v[208:209], v[202:203], v[78:79]
	v_pk_add_f32 v[210:211], v[74:75], v[204:205]
	v_pk_add_f32 v[212:213], v[206:207], v[80:81]
	v_pk_add_f32 v[186:187], v[186:187], v[200:201] neg_lo:[0,1] neg_hi:[0,1]
	v_pk_add_f32 v[78:79], v[202:203], v[78:79] neg_lo:[0,1] neg_hi:[0,1]
	v_pk_add_f32 v[74:75], v[74:75], v[204:205] neg_lo:[0,1] neg_hi:[0,1]
	v_pk_add_f32 v[80:81], v[206:207], v[80:81] neg_lo:[0,1] neg_hi:[0,1]
	v_pk_add_f32 v[214:215], v[76:77], v[208:209] neg_lo:[0,1] neg_hi:[0,1]
	v_pk_add_f32 v[76:77], v[76:77], v[208:209]
	v_pk_add_f32 v[208:209], v[210:211], v[212:213]
	v_pk_add_f32 v[200:201], v[186:187], v[78:79] neg_lo:[0,1] neg_hi:[0,1]
	v_pk_add_f32 v[202:203], v[74:75], v[80:81] neg_lo:[0,1] neg_hi:[0,1]
	v_pk_add_f32 v[78:79], v[186:187], v[78:79]
	v_pk_add_f32 v[74:75], v[74:75], v[80:81]
	v_pk_add_f32 v[216:217], v[210:211], v[212:213] neg_lo:[0,1] neg_hi:[0,1]
	v_pk_add_f32 v[210:211], v[76:77], v[208:209]
	v_pk_add_f32 v[80:81], v[78:79], v[74:75]
	v_pk_add_f32 v[74:75], v[78:79], v[74:75] neg_lo:[0,1] neg_hi:[0,1]
	v_pk_add_f32 v[76:77], v[76:77], v[208:209] neg_lo:[0,1] neg_hi:[0,1]
	v_pk_add_f32 v[208:209], v[214:215], v[216:217]
	v_pk_add_f32 v[212:213], v[214:215], v[216:217] neg_lo:[0,1] neg_hi:[0,1]
	v_pk_add_f32 v[78:79], v[200:201], v[202:203]
	v_pk_add_f32 v[186:187], v[200:201], v[202:203] neg_lo:[0,1] neg_hi:[0,1]
	v_pk_add_f32 v[200:201], v[210:211], v[210:211] op_sel:[1,0] op_sel_hi:[0,1]
	v_pk_add_f32 v[216:217], v[74:75], v[74:75] op_sel:[1,0] op_sel_hi:[0,1]
	v_pk_add_f32 v[74:75], v[74:75], v[74:75] op_sel:[0,1] op_sel_hi:[1,0] neg_lo:[0,1] neg_hi:[0,1]
	v_pk_add_f32 v[204:205], v[80:81], v[80:81] op_sel:[1,0] op_sel_hi:[0,1]
	v_pk_add_f32 v[214:215], v[76:77], v[76:77] op_sel:[1,0] op_sel_hi:[0,1]
	v_pk_add_f32 v[76:77], v[76:77], v[76:77] op_sel:[0,1] op_sel_hi:[1,0] neg_lo:[0,1] neg_hi:[0,1]
	v_pk_add_f32 v[220:221], v[186:187], v[186:187] op_sel:[1,0] op_sel_hi:[0,1]
	v_pk_add_f32 v[186:187], v[186:187], v[186:187] op_sel:[0,1] op_sel_hi:[1,0] neg_lo:[0,1] neg_hi:[0,1]
	v_xor_b32_e32 v75, v181, v200
	v_pk_add_f32 v[202:203], v[210:211], v[210:211] op_sel:[0,1] op_sel_hi:[1,0] neg_lo:[0,1] neg_hi:[0,1]
	v_pk_add_f32 v[206:207], v[208:209], v[208:209] op_sel:[1,0] op_sel_hi:[0,1]
	v_pk_add_f32 v[210:211], v[78:79], v[78:79] op_sel:[1,0] op_sel_hi:[0,1]
	v_pk_add_f32 v[78:79], v[78:79], v[78:79] op_sel:[0,1] op_sel_hi:[1,0] neg_lo:[0,1] neg_hi:[0,1]
	v_add_f32_dpp v75, v200, v75 quad_perm:[1,0,3,2] row_mask:0xf bank_mask:0xf bound_ctrl:1
	v_xor_b32_e32 v77, v181, v204
	v_xor_b32_e32 v205, v181, v186
	v_pk_add_f32 v[80:81], v[80:81], v[80:81] op_sel:[0,1] op_sel_hi:[1,0] neg_lo:[0,1] neg_hi:[0,1]
	v_add_f32_dpp v77, v204, v77 quad_perm:[1,0,3,2] row_mask:0xf bank_mask:0xf bound_ctrl:1
	v_xor_b32_e32 v79, v181, v206
	v_add_f32_dpp v186, v186, v205 quad_perm:[1,0,3,2] row_mask:0xf bank_mask:0xf bound_ctrl:1
	v_xor_b32_e32 v205, v189, v75
	v_add_f32_dpp v79, v206, v79 quad_perm:[1,0,3,2] row_mask:0xf bank_mask:0xf bound_ctrl:1
	v_xor_b32_e32 v81, v181, v210
	v_add_f32_dpp v75, v75, v205 quad_perm:[2,3,0,1] row_mask:0xf bank_mask:0xf bound_ctrl:1
	v_xor_b32_e32 v205, v189, v77
	v_add_f32_dpp v81, v210, v81 quad_perm:[1,0,3,2] row_mask:0xf bank_mask:0xf bound_ctrl:1
	v_xor_b32_e32 v187, v181, v214
	v_add_f32_dpp v77, v77, v205 quad_perm:[2,3,0,1] row_mask:0xf bank_mask:0xf bound_ctrl:1
	v_xor_b32_e32 v205, v189, v79
	v_pk_add_f32 v[218:219], v[212:213], v[212:213] op_sel:[1,0] op_sel_hi:[0,1]
	v_add_f32_dpp v187, v214, v187 quad_perm:[1,0,3,2] row_mask:0xf bank_mask:0xf bound_ctrl:1
	v_xor_b32_e32 v199, v181, v216
	v_add_f32_dpp v79, v79, v205 quad_perm:[2,3,0,1] row_mask:0xf bank_mask:0xf bound_ctrl:1
	v_xor_b32_e32 v205, v189, v81
	v_add_f32_dpp v199, v216, v199 quad_perm:[1,0,3,2] row_mask:0xf bank_mask:0xf bound_ctrl:1
	v_xor_b32_e32 v200, v181, v218
	v_add_f32_dpp v81, v81, v205 quad_perm:[2,3,0,1] row_mask:0xf bank_mask:0xf bound_ctrl:1
	v_xor_b32_e32 v205, v189, v187
	v_add_f32_dpp v200, v218, v200 quad_perm:[1,0,3,2] row_mask:0xf bank_mask:0xf bound_ctrl:1
	v_xor_b32_e32 v201, v181, v220
	v_add_f32_dpp v187, v187, v205 quad_perm:[2,3,0,1] row_mask:0xf bank_mask:0xf bound_ctrl:1
	v_xor_b32_e32 v205, v189, v199
	v_add_f32_dpp v201, v220, v201 quad_perm:[1,0,3,2] row_mask:0xf bank_mask:0xf bound_ctrl:1
	v_xor_b32_e32 v203, v181, v202
	v_add_f32_dpp v199, v199, v205 quad_perm:[2,3,0,1] row_mask:0xf bank_mask:0xf bound_ctrl:1
	v_xor_b32_e32 v205, v189, v200
	v_pk_add_f32 v[208:209], v[208:209], v[208:209] op_sel:[0,1] op_sel_hi:[1,0] neg_lo:[0,1] neg_hi:[0,1]
	v_add_f32_dpp v202, v202, v203 quad_perm:[1,0,3,2] row_mask:0xf bank_mask:0xf bound_ctrl:1
	v_xor_b32_e32 v203, v181, v80
	v_add_f32_dpp v200, v200, v205 quad_perm:[2,3,0,1] row_mask:0xf bank_mask:0xf bound_ctrl:1
	v_xor_b32_e32 v205, v189, v201
	v_add_f32_dpp v80, v80, v203 quad_perm:[1,0,3,2] row_mask:0xf bank_mask:0xf bound_ctrl:1
	v_xor_b32_e32 v203, v181, v208
	v_add_f32_dpp v201, v201, v205 quad_perm:[2,3,0,1] row_mask:0xf bank_mask:0xf bound_ctrl:1
	v_xor_b32_e32 v205, v189, v202
	v_add_f32_dpp v203, v208, v203 quad_perm:[1,0,3,2] row_mask:0xf bank_mask:0xf bound_ctrl:1
	v_xor_b32_e32 v204, v181, v78
	v_add_f32_dpp v202, v202, v205 quad_perm:[2,3,0,1] row_mask:0xf bank_mask:0xf bound_ctrl:1
	v_xor_b32_e32 v205, v189, v80
	v_add_f32_dpp v78, v78, v204 quad_perm:[1,0,3,2] row_mask:0xf bank_mask:0xf bound_ctrl:1
	v_xor_b32_e32 v204, v181, v76
	v_add_f32_dpp v80, v80, v205 quad_perm:[2,3,0,1] row_mask:0xf bank_mask:0xf bound_ctrl:1
	v_xor_b32_e32 v205, v189, v203
	v_pk_add_f32 v[212:213], v[212:213], v[212:213] op_sel:[0,1] op_sel_hi:[1,0] neg_lo:[0,1] neg_hi:[0,1]
	v_add_f32_dpp v76, v76, v204 quad_perm:[1,0,3,2] row_mask:0xf bank_mask:0xf bound_ctrl:1
	v_xor_b32_e32 v204, v181, v74
	v_add_f32_dpp v203, v203, v205 quad_perm:[2,3,0,1] row_mask:0xf bank_mask:0xf bound_ctrl:1
	v_xor_b32_e32 v205, v189, v78
	v_add_f32_dpp v74, v74, v204 quad_perm:[1,0,3,2] row_mask:0xf bank_mask:0xf bound_ctrl:1
	v_xor_b32_e32 v204, v181, v212
	v_add_f32_dpp v205, v78, v205 quad_perm:[2,3,0,1] row_mask:0xf bank_mask:0xf bound_ctrl:1
	v_xor_b32_e32 v78, v189, v76
	v_add_f32_dpp v204, v212, v204 quad_perm:[1,0,3,2] row_mask:0xf bank_mask:0xf bound_ctrl:1
	s_ashr_i32 s27, s26, 31
	v_add_f32_dpp v206, v76, v78 quad_perm:[2,3,0,1] row_mask:0xf bank_mask:0xf bound_ctrl:1
	v_xor_b32_e32 v76, v189, v74
	v_max_f32_e64 v78, |v200|, |v201|
	s_nop 0
	v_add_f32_dpp v207, v74, v76 quad_perm:[2,3,0,1] row_mask:0xf bank_mask:0xf bound_ctrl:1
	v_xor_b32_e32 v74, v189, v204
	v_max_f32_e64 v76, |v79|, |v81|
	s_nop 0
	v_add_f32_dpp v204, v204, v74 quad_perm:[2,3,0,1] row_mask:0xf bank_mask:0xf bound_ctrl:1
	v_xor_b32_e32 v74, v189, v186
	s_nop 1
	v_add_f32_dpp v186, v186, v74 quad_perm:[2,3,0,1] row_mask:0xf bank_mask:0xf bound_ctrl:1
	v_max_f32_e64 v74, |v75|, |v77|
	v_max3_f32 v74, v74, 0, v76
	v_max_f32_e64 v76, |v187|, |v199|
	v_max3_f32 v74, v74, v76, v78
	v_max_f32_e64 v76, |v202|, |v80|
	v_max_f32_e64 v78, |v203|, |v205|
	v_max3_f32 v74, v74, v76, v78
	v_max_f32_e64 v76, |v206|, |v207|
	v_max_f32_e64 v78, |v204|, |v186|
	v_max3_f32 v222, v74, v76, v78
	v_cvt_pk_bf16_f32 v74, v75, v77
	v_cvt_pk_bf16_f32 v75, v79, v81
	v_cvt_pk_bf16_f32 v76, v187, v199
	v_cvt_pk_bf16_f32 v77, v200, v201
	v_cvt_pk_bf16_f32 v78, v202, v80
	v_cvt_pk_bf16_f32 v79, v203, v205
	v_cvt_pk_bf16_f32 v80, v206, v207
	v_cvt_pk_bf16_f32 v81, v204, v186
	v_and_b32_e32 v187, 0xffff0000, v89
	v_and_b32_e32 v186, 0xffff0000, v85
	v_lshlrev_b32_e32 v201, 16, v86
	v_lshlrev_b32_e32 v200, 16, v82
	v_and_b32_e32 v203, 0xffff0000, v86
	v_and_b32_e32 v202, 0xffff0000, v82
	v_lshlrev_b32_e32 v204, 16, v83
	v_lshlrev_b32_e32 v205, 16, v87
	v_and_b32_e32 v87, 0xffff0000, v87
	v_and_b32_e32 v86, 0xffff0000, v83
	v_lshlrev_b32_e32 v83, 16, v88
	v_lshlrev_b32_e32 v82, 16, v84
	v_and_b32_e32 v207, 0xffff0000, v88
	v_and_b32_e32 v206, 0xffff0000, v84
	v_lshlrev_b32_e32 v84, 16, v85
	v_lshlrev_b32_e32 v85, 16, v89
	v_pk_add_f32 v[88:89], v[200:201], v[202:203]
	v_pk_add_f32 v[208:209], v[204:205], v[86:87]
	v_pk_add_f32 v[210:211], v[82:83], v[206:207]
	v_pk_add_f32 v[212:213], v[84:85], v[186:187]
	v_pk_add_f32 v[200:201], v[200:201], v[202:203] neg_lo:[0,1] neg_hi:[0,1]
	v_pk_add_f32 v[86:87], v[204:205], v[86:87] neg_lo:[0,1] neg_hi:[0,1]
	v_pk_add_f32 v[82:83], v[82:83], v[206:207] neg_lo:[0,1] neg_hi:[0,1]
	v_pk_add_f32 v[84:85], v[84:85], v[186:187] neg_lo:[0,1] neg_hi:[0,1]
	v_pk_add_f32 v[214:215], v[88:89], v[208:209] neg_lo:[0,1] neg_hi:[0,1]
	v_pk_add_f32 v[88:89], v[88:89], v[208:209]
	v_pk_add_f32 v[208:209], v[210:211], v[212:213]
	v_pk_add_f32 v[186:187], v[200:201], v[86:87] neg_lo:[0,1] neg_hi:[0,1]
	v_pk_add_f32 v[202:203], v[82:83], v[84:85] neg_lo:[0,1] neg_hi:[0,1]
	v_pk_add_f32 v[86:87], v[200:201], v[86:87]
	v_pk_add_f32 v[82:83], v[82:83], v[84:85]
	v_pk_add_f32 v[216:217], v[210:211], v[212:213] neg_lo:[0,1] neg_hi:[0,1]
	v_pk_add_f32 v[210:211], v[88:89], v[208:209]
	v_pk_add_f32 v[84:85], v[86:87], v[82:83]
	v_pk_add_f32 v[82:83], v[86:87], v[82:83] neg_lo:[0,1] neg_hi:[0,1]
	v_pk_add_f32 v[88:89], v[88:89], v[208:209] neg_lo:[0,1] neg_hi:[0,1]
	v_pk_add_f32 v[208:209], v[214:215], v[216:217]
	v_pk_add_f32 v[212:213], v[214:215], v[216:217] neg_lo:[0,1] neg_hi:[0,1]
	v_pk_add_f32 v[86:87], v[186:187], v[202:203]
	v_pk_add_f32 v[186:187], v[186:187], v[202:203] neg_lo:[0,1] neg_hi:[0,1]
	v_pk_add_f32 v[200:201], v[210:211], v[210:211] op_sel:[1,0] op_sel_hi:[0,1]
	v_pk_add_f32 v[216:217], v[82:83], v[82:83] op_sel:[1,0] op_sel_hi:[0,1]
	v_pk_add_f32 v[82:83], v[82:83], v[82:83] op_sel:[0,1] op_sel_hi:[1,0] neg_lo:[0,1] neg_hi:[0,1]
	v_pk_add_f32 v[204:205], v[84:85], v[84:85] op_sel:[1,0] op_sel_hi:[0,1]
	v_pk_add_f32 v[84:85], v[84:85], v[84:85] op_sel:[0,1] op_sel_hi:[1,0] neg_lo:[0,1] neg_hi:[0,1]
	v_pk_add_f32 v[220:221], v[186:187], v[186:187] op_sel:[1,0] op_sel_hi:[0,1]
	v_pk_add_f32 v[186:187], v[186:187], v[186:187] op_sel:[0,1] op_sel_hi:[1,0] neg_lo:[0,1] neg_hi:[0,1]
	v_xor_b32_e32 v83, v181, v200
	v_pk_add_f32 v[202:203], v[210:211], v[210:211] op_sel:[0,1] op_sel_hi:[1,0] neg_lo:[0,1] neg_hi:[0,1]
	v_pk_add_f32 v[206:207], v[208:209], v[208:209] op_sel:[1,0] op_sel_hi:[0,1]
	v_pk_add_f32 v[210:211], v[86:87], v[86:87] op_sel:[1,0] op_sel_hi:[0,1]
	v_pk_add_f32 v[86:87], v[86:87], v[86:87] op_sel:[0,1] op_sel_hi:[1,0] neg_lo:[0,1] neg_hi:[0,1]
	v_add_f32_dpp v83, v200, v83 quad_perm:[1,0,3,2] row_mask:0xf bank_mask:0xf bound_ctrl:1
	v_xor_b32_e32 v85, v181, v204
	v_xor_b32_e32 v205, v181, v186
	v_pk_add_f32 v[214:215], v[88:89], v[88:89] op_sel:[1,0] op_sel_hi:[0,1]
	v_pk_add_f32 v[88:89], v[88:89], v[88:89] op_sel:[0,1] op_sel_hi:[1,0] neg_lo:[0,1] neg_hi:[0,1]
	v_add_f32_dpp v85, v204, v85 quad_perm:[1,0,3,2] row_mask:0xf bank_mask:0xf bound_ctrl:1
	v_xor_b32_e32 v87, v181, v206
	v_add_f32_dpp v186, v186, v205 quad_perm:[1,0,3,2] row_mask:0xf bank_mask:0xf bound_ctrl:1
	v_xor_b32_e32 v205, v189, v83
	v_add_f32_dpp v87, v206, v87 quad_perm:[1,0,3,2] row_mask:0xf bank_mask:0xf bound_ctrl:1
	v_xor_b32_e32 v89, v181, v210
	v_add_f32_dpp v83, v83, v205 quad_perm:[2,3,0,1] row_mask:0xf bank_mask:0xf bound_ctrl:1
	v_xor_b32_e32 v205, v189, v85
	v_add_f32_dpp v89, v210, v89 quad_perm:[1,0,3,2] row_mask:0xf bank_mask:0xf bound_ctrl:1
	v_xor_b32_e32 v187, v181, v214
	v_add_f32_dpp v85, v85, v205 quad_perm:[2,3,0,1] row_mask:0xf bank_mask:0xf bound_ctrl:1
	v_xor_b32_e32 v205, v189, v87
	v_pk_add_f32 v[218:219], v[212:213], v[212:213] op_sel:[1,0] op_sel_hi:[0,1]
	v_add_f32_dpp v187, v214, v187 quad_perm:[1,0,3,2] row_mask:0xf bank_mask:0xf bound_ctrl:1
	v_xor_b32_e32 v199, v181, v216
	v_add_f32_dpp v87, v87, v205 quad_perm:[2,3,0,1] row_mask:0xf bank_mask:0xf bound_ctrl:1
	v_xor_b32_e32 v205, v189, v89
	v_add_f32_dpp v199, v216, v199 quad_perm:[1,0,3,2] row_mask:0xf bank_mask:0xf bound_ctrl:1
	v_xor_b32_e32 v200, v181, v218
	v_add_f32_dpp v89, v89, v205 quad_perm:[2,3,0,1] row_mask:0xf bank_mask:0xf bound_ctrl:1
	v_xor_b32_e32 v205, v189, v187
	v_add_f32_dpp v200, v218, v200 quad_perm:[1,0,3,2] row_mask:0xf bank_mask:0xf bound_ctrl:1
	v_xor_b32_e32 v201, v181, v220
	v_add_f32_dpp v187, v187, v205 quad_perm:[2,3,0,1] row_mask:0xf bank_mask:0xf bound_ctrl:1
	v_xor_b32_e32 v205, v189, v199
	v_add_f32_dpp v201, v220, v201 quad_perm:[1,0,3,2] row_mask:0xf bank_mask:0xf bound_ctrl:1
	v_xor_b32_e32 v203, v181, v202
	v_add_f32_dpp v199, v199, v205 quad_perm:[2,3,0,1] row_mask:0xf bank_mask:0xf bound_ctrl:1
	v_xor_b32_e32 v205, v189, v200
	v_pk_add_f32 v[208:209], v[208:209], v[208:209] op_sel:[0,1] op_sel_hi:[1,0] neg_lo:[0,1] neg_hi:[0,1]
	v_add_f32_dpp v202, v202, v203 quad_perm:[1,0,3,2] row_mask:0xf bank_mask:0xf bound_ctrl:1
	v_xor_b32_e32 v203, v181, v84
	v_add_f32_dpp v200, v200, v205 quad_perm:[2,3,0,1] row_mask:0xf bank_mask:0xf bound_ctrl:1
	v_xor_b32_e32 v205, v189, v201
	v_add_f32_dpp v84, v84, v203 quad_perm:[1,0,3,2] row_mask:0xf bank_mask:0xf bound_ctrl:1
	v_xor_b32_e32 v203, v181, v208
	v_add_f32_dpp v201, v201, v205 quad_perm:[2,3,0,1] row_mask:0xf bank_mask:0xf bound_ctrl:1
	v_xor_b32_e32 v205, v189, v202
	v_add_f32_dpp v203, v208, v203 quad_perm:[1,0,3,2] row_mask:0xf bank_mask:0xf bound_ctrl:1
	v_xor_b32_e32 v204, v181, v86
	v_add_f32_dpp v202, v202, v205 quad_perm:[2,3,0,1] row_mask:0xf bank_mask:0xf bound_ctrl:1
	v_xor_b32_e32 v205, v189, v84
	v_add_f32_dpp v86, v86, v204 quad_perm:[1,0,3,2] row_mask:0xf bank_mask:0xf bound_ctrl:1
	v_xor_b32_e32 v204, v181, v88
	v_add_f32_dpp v205, v84, v205 quad_perm:[2,3,0,1] row_mask:0xf bank_mask:0xf bound_ctrl:1
	v_xor_b32_e32 v84, v189, v203
	v_pk_add_f32 v[212:213], v[212:213], v[212:213] op_sel:[0,1] op_sel_hi:[1,0] neg_lo:[0,1] neg_hi:[0,1]
	v_add_f32_dpp v88, v88, v204 quad_perm:[1,0,3,2] row_mask:0xf bank_mask:0xf bound_ctrl:1
	v_xor_b32_e32 v204, v181, v82
	v_add_f32_dpp v203, v203, v84 quad_perm:[2,3,0,1] row_mask:0xf bank_mask:0xf bound_ctrl:1
	v_xor_b32_e32 v84, v189, v86
	v_add_f32_dpp v82, v82, v204 quad_perm:[1,0,3,2] row_mask:0xf bank_mask:0xf bound_ctrl:1
	v_xor_b32_e32 v204, v181, v212
	v_add_f32_dpp v206, v86, v84 quad_perm:[2,3,0,1] row_mask:0xf bank_mask:0xf bound_ctrl:1
	v_xor_b32_e32 v84, v189, v88
	v_add_f32_dpp v204, v212, v204 quad_perm:[1,0,3,2] row_mask:0xf bank_mask:0xf bound_ctrl:1
	v_max_f32_e64 v86, |v200|, |v201|
	v_add_f32_dpp v88, v88, v84 quad_perm:[2,3,0,1] row_mask:0xf bank_mask:0xf bound_ctrl:1
	v_xor_b32_e32 v84, v189, v82
	s_nop 1
	v_add_f32_dpp v207, v82, v84 quad_perm:[2,3,0,1] row_mask:0xf bank_mask:0xf bound_ctrl:1
	v_xor_b32_e32 v82, v189, v204
	v_max_f32_e64 v84, |v87|, |v89|
	s_nop 0
	v_add_f32_dpp v204, v204, v82 quad_perm:[2,3,0,1] row_mask:0xf bank_mask:0xf bound_ctrl:1
	v_xor_b32_e32 v82, v189, v186
	s_nop 1
	v_add_f32_dpp v186, v186, v82 quad_perm:[2,3,0,1] row_mask:0xf bank_mask:0xf bound_ctrl:1
	v_max_f32_e64 v82, |v83|, |v85|
	v_max3_f32 v82, v222, v82, v84
	v_max_f32_e64 v84, |v187|, |v199|
	v_max3_f32 v82, v82, v84, v86
	v_max_f32_e64 v84, |v202|, |v205|
	v_max_f32_e64 v86, |v203|, |v206|
	v_max3_f32 v82, v82, v84, v86
	v_max_f32_e64 v84, |v88|, |v207|
	v_max_f32_e64 v86, |v204|, |v186|
	v_max3_f32 v222, v82, v84, v86
	v_cvt_pk_bf16_f32 v82, v83, v85
	v_cvt_pk_bf16_f32 v83, v87, v89
	v_cvt_pk_bf16_f32 v84, v187, v199
	v_cvt_pk_bf16_f32 v85, v200, v201
	v_cvt_pk_bf16_f32 v86, v202, v205
	v_cvt_pk_bf16_f32 v87, v203, v206
	v_cvt_pk_bf16_f32 v88, v88, v207
	v_cvt_pk_bf16_f32 v89, v204, v186
	v_and_b32_e32 v187, 0xffff0000, v97
	v_and_b32_e32 v186, 0xffff0000, v93
	v_lshlrev_b32_e32 v201, 16, v94
	v_lshlrev_b32_e32 v200, 16, v90
	v_and_b32_e32 v203, 0xffff0000, v94
	v_and_b32_e32 v202, 0xffff0000, v90
	v_lshlrev_b32_e32 v204, 16, v91
	v_lshlrev_b32_e32 v205, 16, v95
	v_and_b32_e32 v95, 0xffff0000, v95
	v_and_b32_e32 v94, 0xffff0000, v91
	v_lshlrev_b32_e32 v91, 16, v96
	v_lshlrev_b32_e32 v90, 16, v92
	v_and_b32_e32 v207, 0xffff0000, v96
	v_and_b32_e32 v206, 0xffff0000, v92
	v_lshlrev_b32_e32 v92, 16, v93
	v_lshlrev_b32_e32 v93, 16, v97
	v_pk_add_f32 v[96:97], v[200:201], v[202:203]
	v_pk_add_f32 v[208:209], v[204:205], v[94:95]
	v_pk_add_f32 v[210:211], v[90:91], v[206:207]
	v_pk_add_f32 v[212:213], v[92:93], v[186:187]
	v_pk_add_f32 v[200:201], v[200:201], v[202:203] neg_lo:[0,1] neg_hi:[0,1]
	v_pk_add_f32 v[94:95], v[204:205], v[94:95] neg_lo:[0,1] neg_hi:[0,1]
	v_pk_add_f32 v[90:91], v[90:91], v[206:207] neg_lo:[0,1] neg_hi:[0,1]
	v_pk_add_f32 v[92:93], v[92:93], v[186:187] neg_lo:[0,1] neg_hi:[0,1]
	v_pk_add_f32 v[214:215], v[96:97], v[208:209] neg_lo:[0,1] neg_hi:[0,1]
	v_pk_add_f32 v[96:97], v[96:97], v[208:209]
	v_pk_add_f32 v[208:209], v[210:211], v[212:213]
	v_pk_add_f32 v[186:187], v[200:201], v[94:95] neg_lo:[0,1] neg_hi:[0,1]
	v_pk_add_f32 v[202:203], v[90:91], v[92:93] neg_lo:[0,1] neg_hi:[0,1]
	v_pk_add_f32 v[94:95], v[200:201], v[94:95]
	v_pk_add_f32 v[90:91], v[90:91], v[92:93]
	v_pk_add_f32 v[216:217], v[210:211], v[212:213] neg_lo:[0,1] neg_hi:[0,1]
	v_pk_add_f32 v[210:211], v[96:97], v[208:209]
	v_pk_add_f32 v[92:93], v[94:95], v[90:91]
	v_pk_add_f32 v[90:91], v[94:95], v[90:91] neg_lo:[0,1] neg_hi:[0,1]
	v_pk_add_f32 v[96:97], v[96:97], v[208:209] neg_lo:[0,1] neg_hi:[0,1]
	v_pk_add_f32 v[208:209], v[214:215], v[216:217]
	v_pk_add_f32 v[212:213], v[214:215], v[216:217] neg_lo:[0,1] neg_hi:[0,1]
	v_pk_add_f32 v[94:95], v[186:187], v[202:203]
	v_pk_add_f32 v[186:187], v[186:187], v[202:203] neg_lo:[0,1] neg_hi:[0,1]
	v_pk_add_f32 v[200:201], v[210:211], v[210:211] op_sel:[1,0] op_sel_hi:[0,1]
	v_pk_add_f32 v[216:217], v[90:91], v[90:91] op_sel:[1,0] op_sel_hi:[0,1]
	v_pk_add_f32 v[90:91], v[90:91], v[90:91] op_sel:[0,1] op_sel_hi:[1,0] neg_lo:[0,1] neg_hi:[0,1]
	v_pk_add_f32 v[204:205], v[92:93], v[92:93] op_sel:[1,0] op_sel_hi:[0,1]
	v_pk_add_f32 v[92:93], v[92:93], v[92:93] op_sel:[0,1] op_sel_hi:[1,0] neg_lo:[0,1] neg_hi:[0,1]
	v_pk_add_f32 v[220:221], v[186:187], v[186:187] op_sel:[1,0] op_sel_hi:[0,1]
	v_pk_add_f32 v[186:187], v[186:187], v[186:187] op_sel:[0,1] op_sel_hi:[1,0] neg_lo:[0,1] neg_hi:[0,1]
	v_xor_b32_e32 v91, v181, v200
	v_pk_add_f32 v[202:203], v[210:211], v[210:211] op_sel:[0,1] op_sel_hi:[1,0] neg_lo:[0,1] neg_hi:[0,1]
	v_pk_add_f32 v[206:207], v[208:209], v[208:209] op_sel:[1,0] op_sel_hi:[0,1]
	v_pk_add_f32 v[210:211], v[94:95], v[94:95] op_sel:[1,0] op_sel_hi:[0,1]
	v_pk_add_f32 v[94:95], v[94:95], v[94:95] op_sel:[0,1] op_sel_hi:[1,0] neg_lo:[0,1] neg_hi:[0,1]
	v_add_f32_dpp v91, v200, v91 quad_perm:[1,0,3,2] row_mask:0xf bank_mask:0xf bound_ctrl:1
	v_xor_b32_e32 v93, v181, v204
	v_xor_b32_e32 v205, v181, v186
	v_pk_add_f32 v[214:215], v[96:97], v[96:97] op_sel:[1,0] op_sel_hi:[0,1]
	v_pk_add_f32 v[96:97], v[96:97], v[96:97] op_sel:[0,1] op_sel_hi:[1,0] neg_lo:[0,1] neg_hi:[0,1]
	v_add_f32_dpp v93, v204, v93 quad_perm:[1,0,3,2] row_mask:0xf bank_mask:0xf bound_ctrl:1
	v_xor_b32_e32 v95, v181, v206
	v_add_f32_dpp v186, v186, v205 quad_perm:[1,0,3,2] row_mask:0xf bank_mask:0xf bound_ctrl:1
	v_xor_b32_e32 v205, v189, v91
	v_add_f32_dpp v95, v206, v95 quad_perm:[1,0,3,2] row_mask:0xf bank_mask:0xf bound_ctrl:1
	v_xor_b32_e32 v97, v181, v210
	v_add_f32_dpp v91, v91, v205 quad_perm:[2,3,0,1] row_mask:0xf bank_mask:0xf bound_ctrl:1
	v_xor_b32_e32 v205, v189, v93
	v_add_f32_dpp v97, v210, v97 quad_perm:[1,0,3,2] row_mask:0xf bank_mask:0xf bound_ctrl:1
	v_xor_b32_e32 v187, v181, v214
	v_add_f32_dpp v93, v93, v205 quad_perm:[2,3,0,1] row_mask:0xf bank_mask:0xf bound_ctrl:1
	v_xor_b32_e32 v205, v189, v95
	v_pk_add_f32 v[218:219], v[212:213], v[212:213] op_sel:[1,0] op_sel_hi:[0,1]
	v_add_f32_dpp v187, v214, v187 quad_perm:[1,0,3,2] row_mask:0xf bank_mask:0xf bound_ctrl:1
	v_xor_b32_e32 v199, v181, v216
	v_add_f32_dpp v95, v95, v205 quad_perm:[2,3,0,1] row_mask:0xf bank_mask:0xf bound_ctrl:1
	v_xor_b32_e32 v205, v189, v97
	v_add_f32_dpp v199, v216, v199 quad_perm:[1,0,3,2] row_mask:0xf bank_mask:0xf bound_ctrl:1
	v_xor_b32_e32 v200, v181, v218
	v_add_f32_dpp v97, v97, v205 quad_perm:[2,3,0,1] row_mask:0xf bank_mask:0xf bound_ctrl:1
	v_xor_b32_e32 v205, v189, v187
	v_add_f32_dpp v200, v218, v200 quad_perm:[1,0,3,2] row_mask:0xf bank_mask:0xf bound_ctrl:1
	v_xor_b32_e32 v201, v181, v220
	v_add_f32_dpp v187, v187, v205 quad_perm:[2,3,0,1] row_mask:0xf bank_mask:0xf bound_ctrl:1
	v_xor_b32_e32 v205, v189, v199
	v_add_f32_dpp v201, v220, v201 quad_perm:[1,0,3,2] row_mask:0xf bank_mask:0xf bound_ctrl:1
	v_xor_b32_e32 v203, v181, v202
	v_add_f32_dpp v199, v199, v205 quad_perm:[2,3,0,1] row_mask:0xf bank_mask:0xf bound_ctrl:1
	v_xor_b32_e32 v205, v189, v200
	v_pk_add_f32 v[208:209], v[208:209], v[208:209] op_sel:[0,1] op_sel_hi:[1,0] neg_lo:[0,1] neg_hi:[0,1]
	v_add_f32_dpp v202, v202, v203 quad_perm:[1,0,3,2] row_mask:0xf bank_mask:0xf bound_ctrl:1
	v_xor_b32_e32 v203, v181, v92
	v_add_f32_dpp v200, v200, v205 quad_perm:[2,3,0,1] row_mask:0xf bank_mask:0xf bound_ctrl:1
	v_xor_b32_e32 v205, v189, v201
	v_add_f32_dpp v92, v92, v203 quad_perm:[1,0,3,2] row_mask:0xf bank_mask:0xf bound_ctrl:1
	v_xor_b32_e32 v203, v181, v208
	v_add_f32_dpp v201, v201, v205 quad_perm:[2,3,0,1] row_mask:0xf bank_mask:0xf bound_ctrl:1
	v_xor_b32_e32 v205, v189, v202
	v_add_f32_dpp v203, v208, v203 quad_perm:[1,0,3,2] row_mask:0xf bank_mask:0xf bound_ctrl:1
	v_xor_b32_e32 v204, v181, v94
	v_add_f32_dpp v202, v202, v205 quad_perm:[2,3,0,1] row_mask:0xf bank_mask:0xf bound_ctrl:1
	v_xor_b32_e32 v205, v189, v92
	v_add_f32_dpp v94, v94, v204 quad_perm:[1,0,3,2] row_mask:0xf bank_mask:0xf bound_ctrl:1
	v_xor_b32_e32 v204, v181, v96
	v_add_f32_dpp v205, v92, v205 quad_perm:[2,3,0,1] row_mask:0xf bank_mask:0xf bound_ctrl:1
	v_xor_b32_e32 v92, v189, v203
	v_pk_add_f32 v[212:213], v[212:213], v[212:213] op_sel:[0,1] op_sel_hi:[1,0] neg_lo:[0,1] neg_hi:[0,1]
	v_add_f32_dpp v96, v96, v204 quad_perm:[1,0,3,2] row_mask:0xf bank_mask:0xf bound_ctrl:1
	v_xor_b32_e32 v204, v181, v90
	v_add_f32_dpp v203, v203, v92 quad_perm:[2,3,0,1] row_mask:0xf bank_mask:0xf bound_ctrl:1
	v_xor_b32_e32 v92, v189, v94
	v_add_f32_dpp v90, v90, v204 quad_perm:[1,0,3,2] row_mask:0xf bank_mask:0xf bound_ctrl:1
	v_xor_b32_e32 v204, v181, v212
	v_add_f32_dpp v206, v94, v92 quad_perm:[2,3,0,1] row_mask:0xf bank_mask:0xf bound_ctrl:1
	v_xor_b32_e32 v92, v189, v96
	v_add_f32_dpp v204, v212, v204 quad_perm:[1,0,3,2] row_mask:0xf bank_mask:0xf bound_ctrl:1
	v_max_f32_e64 v94, |v200|, |v201|
	v_add_f32_dpp v96, v96, v92 quad_perm:[2,3,0,1] row_mask:0xf bank_mask:0xf bound_ctrl:1
	v_xor_b32_e32 v92, v189, v90
	s_nop 1
	v_add_f32_dpp v207, v90, v92 quad_perm:[2,3,0,1] row_mask:0xf bank_mask:0xf bound_ctrl:1
	v_xor_b32_e32 v90, v189, v204
	v_max_f32_e64 v92, |v95|, |v97|
	s_nop 0
	v_add_f32_dpp v204, v204, v90 quad_perm:[2,3,0,1] row_mask:0xf bank_mask:0xf bound_ctrl:1
	v_xor_b32_e32 v90, v189, v186
	s_nop 1
	v_add_f32_dpp v186, v186, v90 quad_perm:[2,3,0,1] row_mask:0xf bank_mask:0xf bound_ctrl:1
	v_max_f32_e64 v90, |v91|, |v93|
	v_max3_f32 v90, v222, v90, v92
	v_max_f32_e64 v92, |v187|, |v199|
	v_max3_f32 v90, v90, v92, v94
	v_max_f32_e64 v92, |v202|, |v205|
	v_max_f32_e64 v94, |v203|, |v206|
	v_max3_f32 v90, v90, v92, v94
	v_max_f32_e64 v92, |v96|, |v207|
	v_max_f32_e64 v94, |v204|, |v186|
	v_max3_f32 v222, v90, v92, v94
	v_cvt_pk_bf16_f32 v90, v91, v93
	v_cvt_pk_bf16_f32 v91, v95, v97
	v_cvt_pk_bf16_f32 v92, v187, v199
	v_cvt_pk_bf16_f32 v93, v200, v201
	v_cvt_pk_bf16_f32 v94, v202, v205
	v_cvt_pk_bf16_f32 v95, v203, v206
	v_cvt_pk_bf16_f32 v96, v96, v207
	v_cvt_pk_bf16_f32 v97, v204, v186
	v_and_b32_e32 v187, 0xffff0000, v109
	v_and_b32_e32 v186, 0xffff0000, v101
	v_lshlrev_b32_e32 v201, 16, v106
	v_lshlrev_b32_e32 v200, 16, v98
	v_and_b32_e32 v203, 0xffff0000, v106
	v_and_b32_e32 v202, 0xffff0000, v98
	v_lshlrev_b32_e32 v204, 16, v99
	v_lshlrev_b32_e32 v205, 16, v107
	v_and_b32_e32 v107, 0xffff0000, v107
	v_and_b32_e32 v106, 0xffff0000, v99
	v_lshlrev_b32_e32 v99, 16, v108
	v_lshlrev_b32_e32 v98, 16, v100
	v_and_b32_e32 v207, 0xffff0000, v108
	v_and_b32_e32 v206, 0xffff0000, v100
	v_lshlrev_b32_e32 v100, 16, v101
	v_lshlrev_b32_e32 v101, 16, v109
	v_pk_add_f32 v[108:109], v[200:201], v[202:203]
	v_pk_add_f32 v[208:209], v[204:205], v[106:107]
	v_pk_add_f32 v[210:211], v[98:99], v[206:207]
	v_pk_add_f32 v[212:213], v[100:101], v[186:187]
	v_pk_add_f32 v[200:201], v[200:201], v[202:203] neg_lo:[0,1] neg_hi:[0,1]
	v_pk_add_f32 v[106:107], v[204:205], v[106:107] neg_lo:[0,1] neg_hi:[0,1]
	v_pk_add_f32 v[98:99], v[98:99], v[206:207] neg_lo:[0,1] neg_hi:[0,1]
	v_pk_add_f32 v[100:101], v[100:101], v[186:187] neg_lo:[0,1] neg_hi:[0,1]
	v_pk_add_f32 v[214:215], v[108:109], v[208:209] neg_lo:[0,1] neg_hi:[0,1]
	v_pk_add_f32 v[108:109], v[108:109], v[208:209]
	v_pk_add_f32 v[208:209], v[210:211], v[212:213]
	v_pk_add_f32 v[186:187], v[200:201], v[106:107] neg_lo:[0,1] neg_hi:[0,1]
	v_pk_add_f32 v[202:203], v[98:99], v[100:101] neg_lo:[0,1] neg_hi:[0,1]
	v_pk_add_f32 v[106:107], v[200:201], v[106:107]
	v_pk_add_f32 v[98:99], v[98:99], v[100:101]
	v_pk_add_f32 v[216:217], v[210:211], v[212:213] neg_lo:[0,1] neg_hi:[0,1]
	v_pk_add_f32 v[210:211], v[108:109], v[208:209]
	v_pk_add_f32 v[100:101], v[106:107], v[98:99]
	v_pk_add_f32 v[98:99], v[106:107], v[98:99] neg_lo:[0,1] neg_hi:[0,1]
	v_pk_add_f32 v[108:109], v[108:109], v[208:209] neg_lo:[0,1] neg_hi:[0,1]
	v_pk_add_f32 v[208:209], v[214:215], v[216:217]
	v_pk_add_f32 v[212:213], v[214:215], v[216:217] neg_lo:[0,1] neg_hi:[0,1]
	v_pk_add_f32 v[106:107], v[186:187], v[202:203]
	v_pk_add_f32 v[186:187], v[186:187], v[202:203] neg_lo:[0,1] neg_hi:[0,1]
	v_pk_add_f32 v[200:201], v[210:211], v[210:211] op_sel:[1,0] op_sel_hi:[0,1]
	v_pk_add_f32 v[216:217], v[98:99], v[98:99] op_sel:[1,0] op_sel_hi:[0,1]
	v_pk_add_f32 v[98:99], v[98:99], v[98:99] op_sel:[0,1] op_sel_hi:[1,0] neg_lo:[0,1] neg_hi:[0,1]
	v_pk_add_f32 v[204:205], v[100:101], v[100:101] op_sel:[1,0] op_sel_hi:[0,1]
	v_pk_add_f32 v[100:101], v[100:101], v[100:101] op_sel:[0,1] op_sel_hi:[1,0] neg_lo:[0,1] neg_hi:[0,1]
	v_pk_add_f32 v[220:221], v[186:187], v[186:187] op_sel:[1,0] op_sel_hi:[0,1]
	v_pk_add_f32 v[186:187], v[186:187], v[186:187] op_sel:[0,1] op_sel_hi:[1,0] neg_lo:[0,1] neg_hi:[0,1]
	v_xor_b32_e32 v99, v181, v200
	v_pk_add_f32 v[202:203], v[210:211], v[210:211] op_sel:[0,1] op_sel_hi:[1,0] neg_lo:[0,1] neg_hi:[0,1]
	v_pk_add_f32 v[206:207], v[208:209], v[208:209] op_sel:[1,0] op_sel_hi:[0,1]
	v_pk_add_f32 v[210:211], v[106:107], v[106:107] op_sel:[1,0] op_sel_hi:[0,1]
	v_pk_add_f32 v[106:107], v[106:107], v[106:107] op_sel:[0,1] op_sel_hi:[1,0] neg_lo:[0,1] neg_hi:[0,1]
	v_add_f32_dpp v99, v200, v99 quad_perm:[1,0,3,2] row_mask:0xf bank_mask:0xf bound_ctrl:1
	v_xor_b32_e32 v101, v181, v204
	v_xor_b32_e32 v205, v181, v186
	v_pk_add_f32 v[214:215], v[108:109], v[108:109] op_sel:[1,0] op_sel_hi:[0,1]
	v_pk_add_f32 v[108:109], v[108:109], v[108:109] op_sel:[0,1] op_sel_hi:[1,0] neg_lo:[0,1] neg_hi:[0,1]
	v_add_f32_dpp v101, v204, v101 quad_perm:[1,0,3,2] row_mask:0xf bank_mask:0xf bound_ctrl:1
	v_xor_b32_e32 v107, v181, v206
	v_add_f32_dpp v186, v186, v205 quad_perm:[1,0,3,2] row_mask:0xf bank_mask:0xf bound_ctrl:1
	v_xor_b32_e32 v205, v189, v99
	v_add_f32_dpp v107, v206, v107 quad_perm:[1,0,3,2] row_mask:0xf bank_mask:0xf bound_ctrl:1
	v_xor_b32_e32 v109, v181, v210
	v_add_f32_dpp v99, v99, v205 quad_perm:[2,3,0,1] row_mask:0xf bank_mask:0xf bound_ctrl:1
	v_xor_b32_e32 v205, v189, v101
	v_add_f32_dpp v109, v210, v109 quad_perm:[1,0,3,2] row_mask:0xf bank_mask:0xf bound_ctrl:1
	v_xor_b32_e32 v187, v181, v214
	v_add_f32_dpp v101, v101, v205 quad_perm:[2,3,0,1] row_mask:0xf bank_mask:0xf bound_ctrl:1
	v_xor_b32_e32 v205, v189, v107
	v_pk_add_f32 v[218:219], v[212:213], v[212:213] op_sel:[1,0] op_sel_hi:[0,1]
	v_add_f32_dpp v187, v214, v187 quad_perm:[1,0,3,2] row_mask:0xf bank_mask:0xf bound_ctrl:1
	v_xor_b32_e32 v199, v181, v216
	v_add_f32_dpp v107, v107, v205 quad_perm:[2,3,0,1] row_mask:0xf bank_mask:0xf bound_ctrl:1
	v_xor_b32_e32 v205, v189, v109
	v_add_f32_dpp v199, v216, v199 quad_perm:[1,0,3,2] row_mask:0xf bank_mask:0xf bound_ctrl:1
	v_xor_b32_e32 v200, v181, v218
	v_add_f32_dpp v109, v109, v205 quad_perm:[2,3,0,1] row_mask:0xf bank_mask:0xf bound_ctrl:1
	v_xor_b32_e32 v205, v189, v187
	v_add_f32_dpp v200, v218, v200 quad_perm:[1,0,3,2] row_mask:0xf bank_mask:0xf bound_ctrl:1
	v_xor_b32_e32 v201, v181, v220
	v_add_f32_dpp v187, v187, v205 quad_perm:[2,3,0,1] row_mask:0xf bank_mask:0xf bound_ctrl:1
	v_xor_b32_e32 v205, v189, v199
	v_add_f32_dpp v201, v220, v201 quad_perm:[1,0,3,2] row_mask:0xf bank_mask:0xf bound_ctrl:1
	v_xor_b32_e32 v203, v181, v202
	v_add_f32_dpp v199, v199, v205 quad_perm:[2,3,0,1] row_mask:0xf bank_mask:0xf bound_ctrl:1
	v_xor_b32_e32 v205, v189, v200
	v_pk_add_f32 v[208:209], v[208:209], v[208:209] op_sel:[0,1] op_sel_hi:[1,0] neg_lo:[0,1] neg_hi:[0,1]
	v_add_f32_dpp v202, v202, v203 quad_perm:[1,0,3,2] row_mask:0xf bank_mask:0xf bound_ctrl:1
	v_xor_b32_e32 v203, v181, v100
	v_add_f32_dpp v200, v200, v205 quad_perm:[2,3,0,1] row_mask:0xf bank_mask:0xf bound_ctrl:1
	v_xor_b32_e32 v205, v189, v201
	v_add_f32_dpp v100, v100, v203 quad_perm:[1,0,3,2] row_mask:0xf bank_mask:0xf bound_ctrl:1
	v_xor_b32_e32 v203, v181, v208
	v_add_f32_dpp v201, v201, v205 quad_perm:[2,3,0,1] row_mask:0xf bank_mask:0xf bound_ctrl:1
	v_xor_b32_e32 v205, v189, v202
	v_add_f32_dpp v203, v208, v203 quad_perm:[1,0,3,2] row_mask:0xf bank_mask:0xf bound_ctrl:1
	v_xor_b32_e32 v204, v181, v106
	v_add_f32_dpp v202, v202, v205 quad_perm:[2,3,0,1] row_mask:0xf bank_mask:0xf bound_ctrl:1
	v_xor_b32_e32 v205, v189, v100
	v_add_f32_dpp v106, v106, v204 quad_perm:[1,0,3,2] row_mask:0xf bank_mask:0xf bound_ctrl:1
	v_xor_b32_e32 v204, v181, v108
	v_add_f32_dpp v205, v100, v205 quad_perm:[2,3,0,1] row_mask:0xf bank_mask:0xf bound_ctrl:1
	v_xor_b32_e32 v100, v189, v203
	v_pk_add_f32 v[212:213], v[212:213], v[212:213] op_sel:[0,1] op_sel_hi:[1,0] neg_lo:[0,1] neg_hi:[0,1]
	v_add_f32_dpp v108, v108, v204 quad_perm:[1,0,3,2] row_mask:0xf bank_mask:0xf bound_ctrl:1
	v_xor_b32_e32 v204, v181, v98
	v_add_f32_dpp v203, v203, v100 quad_perm:[2,3,0,1] row_mask:0xf bank_mask:0xf bound_ctrl:1
	v_xor_b32_e32 v100, v189, v106
	v_add_f32_dpp v98, v98, v204 quad_perm:[1,0,3,2] row_mask:0xf bank_mask:0xf bound_ctrl:1
	v_xor_b32_e32 v204, v181, v212
	v_add_f32_dpp v206, v106, v100 quad_perm:[2,3,0,1] row_mask:0xf bank_mask:0xf bound_ctrl:1
	v_xor_b32_e32 v100, v189, v108
	v_add_f32_dpp v204, v212, v204 quad_perm:[1,0,3,2] row_mask:0xf bank_mask:0xf bound_ctrl:1
	v_max_f32_e64 v106, |v200|, |v201|
	v_add_f32_dpp v108, v108, v100 quad_perm:[2,3,0,1] row_mask:0xf bank_mask:0xf bound_ctrl:1
	v_xor_b32_e32 v100, v189, v98
	s_nop 1
	v_add_f32_dpp v207, v98, v100 quad_perm:[2,3,0,1] row_mask:0xf bank_mask:0xf bound_ctrl:1
	v_xor_b32_e32 v98, v189, v204
	v_max_f32_e64 v100, |v107|, |v109|
	s_nop 0
	v_add_f32_dpp v204, v204, v98 quad_perm:[2,3,0,1] row_mask:0xf bank_mask:0xf bound_ctrl:1
	v_xor_b32_e32 v98, v189, v186
	s_nop 1
	v_add_f32_dpp v186, v186, v98 quad_perm:[2,3,0,1] row_mask:0xf bank_mask:0xf bound_ctrl:1
	v_max_f32_e64 v98, |v99|, |v101|
	v_max3_f32 v98, v222, v98, v100
	v_max_f32_e64 v100, |v187|, |v199|
	v_max3_f32 v98, v98, v100, v106
	v_max_f32_e64 v100, |v202|, |v205|
	v_max_f32_e64 v106, |v203|, |v206|
	v_max3_f32 v98, v98, v100, v106
	v_max_f32_e64 v100, |v108|, |v207|
	v_max_f32_e64 v106, |v204|, |v186|
	v_max3_f32 v222, v98, v100, v106
	v_cvt_pk_bf16_f32 v98, v99, v101
	v_cvt_pk_bf16_f32 v99, v107, v109
	v_cvt_pk_bf16_f32 v100, v187, v199
	v_cvt_pk_bf16_f32 v101, v200, v201
	v_cvt_pk_bf16_f32 v106, v202, v205
	v_cvt_pk_bf16_f32 v107, v203, v206
	v_cvt_pk_bf16_f32 v108, v108, v207
	v_cvt_pk_bf16_f32 v109, v204, v186
	v_and_b32_e32 v187, 0xffff0000, v121
	v_and_b32_e32 v186, 0xffff0000, v113
	v_lshlrev_b32_e32 v201, 16, v118
	v_lshlrev_b32_e32 v200, 16, v110
	v_and_b32_e32 v203, 0xffff0000, v118
	v_and_b32_e32 v202, 0xffff0000, v110
	v_lshlrev_b32_e32 v204, 16, v111
	v_lshlrev_b32_e32 v205, 16, v119
	v_and_b32_e32 v119, 0xffff0000, v119
	v_and_b32_e32 v118, 0xffff0000, v111
	v_lshlrev_b32_e32 v111, 16, v120
	v_lshlrev_b32_e32 v110, 16, v112
	v_and_b32_e32 v207, 0xffff0000, v120
	v_and_b32_e32 v206, 0xffff0000, v112
	v_lshlrev_b32_e32 v112, 16, v113
	v_lshlrev_b32_e32 v113, 16, v121
	v_pk_add_f32 v[120:121], v[200:201], v[202:203]
	v_pk_add_f32 v[208:209], v[204:205], v[118:119]
	v_pk_add_f32 v[210:211], v[110:111], v[206:207]
	v_pk_add_f32 v[212:213], v[112:113], v[186:187]
	v_pk_add_f32 v[200:201], v[200:201], v[202:203] neg_lo:[0,1] neg_hi:[0,1]
	v_pk_add_f32 v[118:119], v[204:205], v[118:119] neg_lo:[0,1] neg_hi:[0,1]
	v_pk_add_f32 v[110:111], v[110:111], v[206:207] neg_lo:[0,1] neg_hi:[0,1]
	v_pk_add_f32 v[112:113], v[112:113], v[186:187] neg_lo:[0,1] neg_hi:[0,1]
	v_pk_add_f32 v[214:215], v[120:121], v[208:209] neg_lo:[0,1] neg_hi:[0,1]
	v_pk_add_f32 v[120:121], v[120:121], v[208:209]
	v_pk_add_f32 v[208:209], v[210:211], v[212:213]
	v_pk_add_f32 v[186:187], v[200:201], v[118:119] neg_lo:[0,1] neg_hi:[0,1]
	v_pk_add_f32 v[202:203], v[110:111], v[112:113] neg_lo:[0,1] neg_hi:[0,1]
	v_pk_add_f32 v[118:119], v[200:201], v[118:119]
	v_pk_add_f32 v[110:111], v[110:111], v[112:113]
	v_pk_add_f32 v[216:217], v[210:211], v[212:213] neg_lo:[0,1] neg_hi:[0,1]
	v_pk_add_f32 v[210:211], v[120:121], v[208:209]
	v_pk_add_f32 v[112:113], v[118:119], v[110:111]
	v_pk_add_f32 v[110:111], v[118:119], v[110:111] neg_lo:[0,1] neg_hi:[0,1]
	v_pk_add_f32 v[120:121], v[120:121], v[208:209] neg_lo:[0,1] neg_hi:[0,1]
	v_pk_add_f32 v[208:209], v[214:215], v[216:217]
	v_pk_add_f32 v[212:213], v[214:215], v[216:217] neg_lo:[0,1] neg_hi:[0,1]
	v_pk_add_f32 v[118:119], v[186:187], v[202:203]
	v_pk_add_f32 v[186:187], v[186:187], v[202:203] neg_lo:[0,1] neg_hi:[0,1]
	v_pk_add_f32 v[200:201], v[210:211], v[210:211] op_sel:[1,0] op_sel_hi:[0,1]
	v_pk_add_f32 v[216:217], v[110:111], v[110:111] op_sel:[1,0] op_sel_hi:[0,1]
	v_pk_add_f32 v[110:111], v[110:111], v[110:111] op_sel:[0,1] op_sel_hi:[1,0] neg_lo:[0,1] neg_hi:[0,1]
	v_pk_add_f32 v[204:205], v[112:113], v[112:113] op_sel:[1,0] op_sel_hi:[0,1]
	v_pk_add_f32 v[112:113], v[112:113], v[112:113] op_sel:[0,1] op_sel_hi:[1,0] neg_lo:[0,1] neg_hi:[0,1]
	v_pk_add_f32 v[220:221], v[186:187], v[186:187] op_sel:[1,0] op_sel_hi:[0,1]
	v_pk_add_f32 v[186:187], v[186:187], v[186:187] op_sel:[0,1] op_sel_hi:[1,0] neg_lo:[0,1] neg_hi:[0,1]
	v_xor_b32_e32 v111, v181, v200
	v_pk_add_f32 v[202:203], v[210:211], v[210:211] op_sel:[0,1] op_sel_hi:[1,0] neg_lo:[0,1] neg_hi:[0,1]
	v_pk_add_f32 v[206:207], v[208:209], v[208:209] op_sel:[1,0] op_sel_hi:[0,1]
	v_pk_add_f32 v[210:211], v[118:119], v[118:119] op_sel:[1,0] op_sel_hi:[0,1]
	v_pk_add_f32 v[118:119], v[118:119], v[118:119] op_sel:[0,1] op_sel_hi:[1,0] neg_lo:[0,1] neg_hi:[0,1]
	v_add_f32_dpp v111, v200, v111 quad_perm:[1,0,3,2] row_mask:0xf bank_mask:0xf bound_ctrl:1
	v_xor_b32_e32 v113, v181, v204
	v_xor_b32_e32 v205, v181, v186
	v_pk_add_f32 v[214:215], v[120:121], v[120:121] op_sel:[1,0] op_sel_hi:[0,1]
	v_pk_add_f32 v[120:121], v[120:121], v[120:121] op_sel:[0,1] op_sel_hi:[1,0] neg_lo:[0,1] neg_hi:[0,1]
	v_add_f32_dpp v113, v204, v113 quad_perm:[1,0,3,2] row_mask:0xf bank_mask:0xf bound_ctrl:1
	v_xor_b32_e32 v119, v181, v206
	v_add_f32_dpp v186, v186, v205 quad_perm:[1,0,3,2] row_mask:0xf bank_mask:0xf bound_ctrl:1
	v_xor_b32_e32 v205, v189, v111
	v_add_f32_dpp v119, v206, v119 quad_perm:[1,0,3,2] row_mask:0xf bank_mask:0xf bound_ctrl:1
	v_xor_b32_e32 v121, v181, v210
	v_add_f32_dpp v111, v111, v205 quad_perm:[2,3,0,1] row_mask:0xf bank_mask:0xf bound_ctrl:1
	v_xor_b32_e32 v205, v189, v113
	v_add_f32_dpp v121, v210, v121 quad_perm:[1,0,3,2] row_mask:0xf bank_mask:0xf bound_ctrl:1
	v_xor_b32_e32 v187, v181, v214
	v_add_f32_dpp v113, v113, v205 quad_perm:[2,3,0,1] row_mask:0xf bank_mask:0xf bound_ctrl:1
	v_xor_b32_e32 v205, v189, v119
	v_pk_add_f32 v[218:219], v[212:213], v[212:213] op_sel:[1,0] op_sel_hi:[0,1]
	v_add_f32_dpp v187, v214, v187 quad_perm:[1,0,3,2] row_mask:0xf bank_mask:0xf bound_ctrl:1
	v_xor_b32_e32 v199, v181, v216
	v_add_f32_dpp v119, v119, v205 quad_perm:[2,3,0,1] row_mask:0xf bank_mask:0xf bound_ctrl:1
	v_xor_b32_e32 v205, v189, v121
	v_add_f32_dpp v199, v216, v199 quad_perm:[1,0,3,2] row_mask:0xf bank_mask:0xf bound_ctrl:1
	v_xor_b32_e32 v200, v181, v218
	v_add_f32_dpp v121, v121, v205 quad_perm:[2,3,0,1] row_mask:0xf bank_mask:0xf bound_ctrl:1
	v_xor_b32_e32 v205, v189, v187
	v_add_f32_dpp v200, v218, v200 quad_perm:[1,0,3,2] row_mask:0xf bank_mask:0xf bound_ctrl:1
	v_xor_b32_e32 v201, v181, v220
	v_add_f32_dpp v187, v187, v205 quad_perm:[2,3,0,1] row_mask:0xf bank_mask:0xf bound_ctrl:1
	v_xor_b32_e32 v205, v189, v199
	v_add_f32_dpp v201, v220, v201 quad_perm:[1,0,3,2] row_mask:0xf bank_mask:0xf bound_ctrl:1
	v_xor_b32_e32 v203, v181, v202
	v_add_f32_dpp v199, v199, v205 quad_perm:[2,3,0,1] row_mask:0xf bank_mask:0xf bound_ctrl:1
	v_xor_b32_e32 v205, v189, v200
	v_pk_add_f32 v[208:209], v[208:209], v[208:209] op_sel:[0,1] op_sel_hi:[1,0] neg_lo:[0,1] neg_hi:[0,1]
	v_add_f32_dpp v202, v202, v203 quad_perm:[1,0,3,2] row_mask:0xf bank_mask:0xf bound_ctrl:1
	v_xor_b32_e32 v203, v181, v112
	v_add_f32_dpp v200, v200, v205 quad_perm:[2,3,0,1] row_mask:0xf bank_mask:0xf bound_ctrl:1
	v_xor_b32_e32 v205, v189, v201
	v_add_f32_dpp v112, v112, v203 quad_perm:[1,0,3,2] row_mask:0xf bank_mask:0xf bound_ctrl:1
	v_xor_b32_e32 v203, v181, v208
	v_add_f32_dpp v201, v201, v205 quad_perm:[2,3,0,1] row_mask:0xf bank_mask:0xf bound_ctrl:1
	v_xor_b32_e32 v205, v189, v202
	v_add_f32_dpp v203, v208, v203 quad_perm:[1,0,3,2] row_mask:0xf bank_mask:0xf bound_ctrl:1
	v_xor_b32_e32 v204, v181, v118
	v_add_f32_dpp v202, v202, v205 quad_perm:[2,3,0,1] row_mask:0xf bank_mask:0xf bound_ctrl:1
	v_xor_b32_e32 v205, v189, v112
	v_add_f32_dpp v118, v118, v204 quad_perm:[1,0,3,2] row_mask:0xf bank_mask:0xf bound_ctrl:1
	v_xor_b32_e32 v204, v181, v120
	v_add_f32_dpp v205, v112, v205 quad_perm:[2,3,0,1] row_mask:0xf bank_mask:0xf bound_ctrl:1
	v_xor_b32_e32 v112, v189, v203
	v_pk_add_f32 v[212:213], v[212:213], v[212:213] op_sel:[0,1] op_sel_hi:[1,0] neg_lo:[0,1] neg_hi:[0,1]
	v_add_f32_dpp v120, v120, v204 quad_perm:[1,0,3,2] row_mask:0xf bank_mask:0xf bound_ctrl:1
	v_xor_b32_e32 v204, v181, v110
	v_add_f32_dpp v203, v203, v112 quad_perm:[2,3,0,1] row_mask:0xf bank_mask:0xf bound_ctrl:1
	v_xor_b32_e32 v112, v189, v118
	v_add_f32_dpp v110, v110, v204 quad_perm:[1,0,3,2] row_mask:0xf bank_mask:0xf bound_ctrl:1
	v_xor_b32_e32 v204, v181, v212
	v_add_f32_dpp v206, v118, v112 quad_perm:[2,3,0,1] row_mask:0xf bank_mask:0xf bound_ctrl:1
	v_xor_b32_e32 v112, v189, v120
	v_add_f32_dpp v204, v212, v204 quad_perm:[1,0,3,2] row_mask:0xf bank_mask:0xf bound_ctrl:1
	v_max_f32_e64 v118, |v200|, |v201|
	v_add_f32_dpp v120, v120, v112 quad_perm:[2,3,0,1] row_mask:0xf bank_mask:0xf bound_ctrl:1
	v_xor_b32_e32 v112, v189, v110
	s_nop 1
	v_add_f32_dpp v207, v110, v112 quad_perm:[2,3,0,1] row_mask:0xf bank_mask:0xf bound_ctrl:1
	v_xor_b32_e32 v110, v189, v204
	v_max_f32_e64 v112, |v119|, |v121|
	s_nop 0
	v_add_f32_dpp v204, v204, v110 quad_perm:[2,3,0,1] row_mask:0xf bank_mask:0xf bound_ctrl:1
	v_xor_b32_e32 v110, v189, v186
	s_nop 1
	v_add_f32_dpp v186, v186, v110 quad_perm:[2,3,0,1] row_mask:0xf bank_mask:0xf bound_ctrl:1
	v_max_f32_e64 v110, |v111|, |v113|
	v_max3_f32 v110, v222, v110, v112
	v_max_f32_e64 v112, |v187|, |v199|
	v_max3_f32 v110, v110, v112, v118
	v_max_f32_e64 v112, |v202|, |v205|
	v_max_f32_e64 v118, |v203|, |v206|
	v_max3_f32 v110, v110, v112, v118
	v_max_f32_e64 v112, |v120|, |v207|
	v_max_f32_e64 v118, |v204|, |v186|
	v_max3_f32 v222, v110, v112, v118
	v_cvt_pk_bf16_f32 v110, v111, v113
	v_cvt_pk_bf16_f32 v111, v119, v121
	v_cvt_pk_bf16_f32 v112, v187, v199
	v_cvt_pk_bf16_f32 v113, v200, v201
	v_cvt_pk_bf16_f32 v118, v202, v205
	v_cvt_pk_bf16_f32 v119, v203, v206
	v_cvt_pk_bf16_f32 v120, v120, v207
	v_cvt_pk_bf16_f32 v121, v204, v186
	v_and_b32_e32 v187, 0xffff0000, v129
	v_and_b32_e32 v186, 0xffff0000, v125
	v_lshlrev_b32_e32 v201, 16, v126
	v_lshlrev_b32_e32 v200, 16, v122
	v_and_b32_e32 v203, 0xffff0000, v126
	v_and_b32_e32 v202, 0xffff0000, v122
	v_lshlrev_b32_e32 v204, 16, v123
	v_lshlrev_b32_e32 v205, 16, v127
	v_and_b32_e32 v127, 0xffff0000, v127
	v_and_b32_e32 v126, 0xffff0000, v123
	v_lshlrev_b32_e32 v123, 16, v128
	v_lshlrev_b32_e32 v122, 16, v124
	v_and_b32_e32 v207, 0xffff0000, v128
	v_and_b32_e32 v206, 0xffff0000, v124
	v_lshlrev_b32_e32 v124, 16, v125
	v_lshlrev_b32_e32 v125, 16, v129
	v_pk_add_f32 v[128:129], v[200:201], v[202:203]
	v_pk_add_f32 v[208:209], v[204:205], v[126:127]
	v_pk_add_f32 v[210:211], v[122:123], v[206:207]
	v_pk_add_f32 v[212:213], v[124:125], v[186:187]
	v_pk_add_f32 v[200:201], v[200:201], v[202:203] neg_lo:[0,1] neg_hi:[0,1]
	v_pk_add_f32 v[126:127], v[204:205], v[126:127] neg_lo:[0,1] neg_hi:[0,1]
	v_pk_add_f32 v[122:123], v[122:123], v[206:207] neg_lo:[0,1] neg_hi:[0,1]
	v_pk_add_f32 v[124:125], v[124:125], v[186:187] neg_lo:[0,1] neg_hi:[0,1]
	v_pk_add_f32 v[214:215], v[128:129], v[208:209] neg_lo:[0,1] neg_hi:[0,1]
	v_pk_add_f32 v[128:129], v[128:129], v[208:209]
	v_pk_add_f32 v[208:209], v[210:211], v[212:213]
	v_pk_add_f32 v[186:187], v[200:201], v[126:127] neg_lo:[0,1] neg_hi:[0,1]
	v_pk_add_f32 v[202:203], v[122:123], v[124:125] neg_lo:[0,1] neg_hi:[0,1]
	v_pk_add_f32 v[126:127], v[200:201], v[126:127]
	v_pk_add_f32 v[122:123], v[122:123], v[124:125]
	v_pk_add_f32 v[216:217], v[210:211], v[212:213] neg_lo:[0,1] neg_hi:[0,1]
	v_pk_add_f32 v[210:211], v[128:129], v[208:209]
	v_pk_add_f32 v[124:125], v[126:127], v[122:123]
	v_pk_add_f32 v[122:123], v[126:127], v[122:123] neg_lo:[0,1] neg_hi:[0,1]
	v_pk_add_f32 v[128:129], v[128:129], v[208:209] neg_lo:[0,1] neg_hi:[0,1]
	v_pk_add_f32 v[208:209], v[214:215], v[216:217]
	v_pk_add_f32 v[212:213], v[214:215], v[216:217] neg_lo:[0,1] neg_hi:[0,1]
	v_pk_add_f32 v[126:127], v[186:187], v[202:203]
	v_pk_add_f32 v[186:187], v[186:187], v[202:203] neg_lo:[0,1] neg_hi:[0,1]
	v_pk_add_f32 v[200:201], v[210:211], v[210:211] op_sel:[1,0] op_sel_hi:[0,1]
	v_pk_add_f32 v[216:217], v[122:123], v[122:123] op_sel:[1,0] op_sel_hi:[0,1]
	v_pk_add_f32 v[122:123], v[122:123], v[122:123] op_sel:[0,1] op_sel_hi:[1,0] neg_lo:[0,1] neg_hi:[0,1]
	v_pk_add_f32 v[204:205], v[124:125], v[124:125] op_sel:[1,0] op_sel_hi:[0,1]
	v_pk_add_f32 v[124:125], v[124:125], v[124:125] op_sel:[0,1] op_sel_hi:[1,0] neg_lo:[0,1] neg_hi:[0,1]
	v_pk_add_f32 v[220:221], v[186:187], v[186:187] op_sel:[1,0] op_sel_hi:[0,1]
	v_pk_add_f32 v[186:187], v[186:187], v[186:187] op_sel:[0,1] op_sel_hi:[1,0] neg_lo:[0,1] neg_hi:[0,1]
	v_xor_b32_e32 v123, v181, v200
	v_pk_add_f32 v[202:203], v[210:211], v[210:211] op_sel:[0,1] op_sel_hi:[1,0] neg_lo:[0,1] neg_hi:[0,1]
	v_pk_add_f32 v[206:207], v[208:209], v[208:209] op_sel:[1,0] op_sel_hi:[0,1]
	v_pk_add_f32 v[210:211], v[126:127], v[126:127] op_sel:[1,0] op_sel_hi:[0,1]
	v_pk_add_f32 v[126:127], v[126:127], v[126:127] op_sel:[0,1] op_sel_hi:[1,0] neg_lo:[0,1] neg_hi:[0,1]
	v_add_f32_dpp v123, v200, v123 quad_perm:[1,0,3,2] row_mask:0xf bank_mask:0xf bound_ctrl:1
	v_xor_b32_e32 v125, v181, v204
	v_xor_b32_e32 v205, v181, v186
	v_pk_add_f32 v[214:215], v[128:129], v[128:129] op_sel:[1,0] op_sel_hi:[0,1]
	v_pk_add_f32 v[128:129], v[128:129], v[128:129] op_sel:[0,1] op_sel_hi:[1,0] neg_lo:[0,1] neg_hi:[0,1]
	v_add_f32_dpp v125, v204, v125 quad_perm:[1,0,3,2] row_mask:0xf bank_mask:0xf bound_ctrl:1
	v_xor_b32_e32 v127, v181, v206
	v_add_f32_dpp v186, v186, v205 quad_perm:[1,0,3,2] row_mask:0xf bank_mask:0xf bound_ctrl:1
	v_xor_b32_e32 v205, v189, v123
	v_add_f32_dpp v127, v206, v127 quad_perm:[1,0,3,2] row_mask:0xf bank_mask:0xf bound_ctrl:1
	v_xor_b32_e32 v129, v181, v210
	v_add_f32_dpp v123, v123, v205 quad_perm:[2,3,0,1] row_mask:0xf bank_mask:0xf bound_ctrl:1
	v_xor_b32_e32 v205, v189, v125
	v_add_f32_dpp v129, v210, v129 quad_perm:[1,0,3,2] row_mask:0xf bank_mask:0xf bound_ctrl:1
	v_xor_b32_e32 v187, v181, v214
	v_add_f32_dpp v125, v125, v205 quad_perm:[2,3,0,1] row_mask:0xf bank_mask:0xf bound_ctrl:1
	v_xor_b32_e32 v205, v189, v127
	v_pk_add_f32 v[218:219], v[212:213], v[212:213] op_sel:[1,0] op_sel_hi:[0,1]
	v_add_f32_dpp v187, v214, v187 quad_perm:[1,0,3,2] row_mask:0xf bank_mask:0xf bound_ctrl:1
	v_xor_b32_e32 v199, v181, v216
	v_add_f32_dpp v127, v127, v205 quad_perm:[2,3,0,1] row_mask:0xf bank_mask:0xf bound_ctrl:1
	v_xor_b32_e32 v205, v189, v129
	v_add_f32_dpp v199, v216, v199 quad_perm:[1,0,3,2] row_mask:0xf bank_mask:0xf bound_ctrl:1
	v_xor_b32_e32 v200, v181, v218
	v_add_f32_dpp v129, v129, v205 quad_perm:[2,3,0,1] row_mask:0xf bank_mask:0xf bound_ctrl:1
	v_xor_b32_e32 v205, v189, v187
	v_add_f32_dpp v200, v218, v200 quad_perm:[1,0,3,2] row_mask:0xf bank_mask:0xf bound_ctrl:1
	v_xor_b32_e32 v201, v181, v220
	v_add_f32_dpp v187, v187, v205 quad_perm:[2,3,0,1] row_mask:0xf bank_mask:0xf bound_ctrl:1
	v_xor_b32_e32 v205, v189, v199
	v_add_f32_dpp v201, v220, v201 quad_perm:[1,0,3,2] row_mask:0xf bank_mask:0xf bound_ctrl:1
	v_xor_b32_e32 v203, v181, v202
	v_add_f32_dpp v199, v199, v205 quad_perm:[2,3,0,1] row_mask:0xf bank_mask:0xf bound_ctrl:1
	v_xor_b32_e32 v205, v189, v200
	v_pk_add_f32 v[208:209], v[208:209], v[208:209] op_sel:[0,1] op_sel_hi:[1,0] neg_lo:[0,1] neg_hi:[0,1]
	v_add_f32_dpp v202, v202, v203 quad_perm:[1,0,3,2] row_mask:0xf bank_mask:0xf bound_ctrl:1
	v_xor_b32_e32 v203, v181, v124
	v_add_f32_dpp v200, v200, v205 quad_perm:[2,3,0,1] row_mask:0xf bank_mask:0xf bound_ctrl:1
	v_xor_b32_e32 v205, v189, v201
	v_add_f32_dpp v124, v124, v203 quad_perm:[1,0,3,2] row_mask:0xf bank_mask:0xf bound_ctrl:1
	v_xor_b32_e32 v203, v181, v208
	v_add_f32_dpp v201, v201, v205 quad_perm:[2,3,0,1] row_mask:0xf bank_mask:0xf bound_ctrl:1
	v_xor_b32_e32 v205, v189, v202
	v_add_f32_dpp v203, v208, v203 quad_perm:[1,0,3,2] row_mask:0xf bank_mask:0xf bound_ctrl:1
	v_xor_b32_e32 v204, v181, v126
	v_add_f32_dpp v202, v202, v205 quad_perm:[2,3,0,1] row_mask:0xf bank_mask:0xf bound_ctrl:1
	v_xor_b32_e32 v205, v189, v124
	v_add_f32_dpp v126, v126, v204 quad_perm:[1,0,3,2] row_mask:0xf bank_mask:0xf bound_ctrl:1
	v_xor_b32_e32 v204, v181, v128
	v_add_f32_dpp v205, v124, v205 quad_perm:[2,3,0,1] row_mask:0xf bank_mask:0xf bound_ctrl:1
	v_xor_b32_e32 v124, v189, v203
	v_pk_add_f32 v[212:213], v[212:213], v[212:213] op_sel:[0,1] op_sel_hi:[1,0] neg_lo:[0,1] neg_hi:[0,1]
	v_add_f32_dpp v128, v128, v204 quad_perm:[1,0,3,2] row_mask:0xf bank_mask:0xf bound_ctrl:1
	v_xor_b32_e32 v204, v181, v122
	v_add_f32_dpp v203, v203, v124 quad_perm:[2,3,0,1] row_mask:0xf bank_mask:0xf bound_ctrl:1
	v_xor_b32_e32 v124, v189, v126
	v_add_f32_dpp v122, v122, v204 quad_perm:[1,0,3,2] row_mask:0xf bank_mask:0xf bound_ctrl:1
	v_xor_b32_e32 v204, v181, v212
	v_add_f32_dpp v206, v126, v124 quad_perm:[2,3,0,1] row_mask:0xf bank_mask:0xf bound_ctrl:1
	v_xor_b32_e32 v124, v189, v128
	v_add_f32_dpp v204, v212, v204 quad_perm:[1,0,3,2] row_mask:0xf bank_mask:0xf bound_ctrl:1
	v_max_f32_e64 v126, |v200|, |v201|
	v_add_f32_dpp v128, v128, v124 quad_perm:[2,3,0,1] row_mask:0xf bank_mask:0xf bound_ctrl:1
	v_xor_b32_e32 v124, v189, v122
	s_nop 1
	v_add_f32_dpp v207, v122, v124 quad_perm:[2,3,0,1] row_mask:0xf bank_mask:0xf bound_ctrl:1
	v_xor_b32_e32 v122, v189, v204
	v_max_f32_e64 v124, |v127|, |v129|
	s_nop 0
	v_add_f32_dpp v204, v204, v122 quad_perm:[2,3,0,1] row_mask:0xf bank_mask:0xf bound_ctrl:1
	v_xor_b32_e32 v122, v189, v186
	s_nop 1
	v_add_f32_dpp v186, v186, v122 quad_perm:[2,3,0,1] row_mask:0xf bank_mask:0xf bound_ctrl:1
	v_max_f32_e64 v122, |v123|, |v125|
	v_max3_f32 v122, v222, v122, v124
	v_max_f32_e64 v124, |v187|, |v199|
	v_max3_f32 v122, v122, v124, v126
	v_max_f32_e64 v124, |v202|, |v205|
	v_max_f32_e64 v126, |v203|, |v206|
	v_max3_f32 v122, v122, v124, v126
	v_max_f32_e64 v124, |v128|, |v207|
	v_max_f32_e64 v126, |v204|, |v186|
	v_max3_f32 v222, v122, v124, v126
	v_cvt_pk_bf16_f32 v122, v123, v125
	v_cvt_pk_bf16_f32 v123, v127, v129
	v_cvt_pk_bf16_f32 v124, v187, v199
	v_cvt_pk_bf16_f32 v125, v200, v201
	v_cvt_pk_bf16_f32 v126, v202, v205
	v_cvt_pk_bf16_f32 v127, v203, v206
	v_cvt_pk_bf16_f32 v128, v128, v207
	v_cvt_pk_bf16_f32 v129, v204, v186
	v_and_b32_e32 v187, 0xffff0000, v137
	v_and_b32_e32 v186, 0xffff0000, v133
	v_lshlrev_b32_e32 v201, 16, v134
	v_lshlrev_b32_e32 v200, 16, v130
	v_and_b32_e32 v203, 0xffff0000, v134
	v_and_b32_e32 v202, 0xffff0000, v130
	v_lshlrev_b32_e32 v204, 16, v131
	v_lshlrev_b32_e32 v205, 16, v135
	v_and_b32_e32 v135, 0xffff0000, v135
	v_and_b32_e32 v134, 0xffff0000, v131
	v_lshlrev_b32_e32 v131, 16, v136
	v_lshlrev_b32_e32 v130, 16, v132
	v_and_b32_e32 v207, 0xffff0000, v136
	v_and_b32_e32 v206, 0xffff0000, v132
	v_lshlrev_b32_e32 v132, 16, v133
	v_lshlrev_b32_e32 v133, 16, v137
	v_pk_add_f32 v[136:137], v[200:201], v[202:203]
	v_pk_add_f32 v[208:209], v[204:205], v[134:135]
	v_pk_add_f32 v[210:211], v[130:131], v[206:207]
	v_pk_add_f32 v[212:213], v[132:133], v[186:187]
	v_pk_add_f32 v[200:201], v[200:201], v[202:203] neg_lo:[0,1] neg_hi:[0,1]
	v_pk_add_f32 v[134:135], v[204:205], v[134:135] neg_lo:[0,1] neg_hi:[0,1]
	v_pk_add_f32 v[130:131], v[130:131], v[206:207] neg_lo:[0,1] neg_hi:[0,1]
	v_pk_add_f32 v[132:133], v[132:133], v[186:187] neg_lo:[0,1] neg_hi:[0,1]
	v_pk_add_f32 v[214:215], v[136:137], v[208:209] neg_lo:[0,1] neg_hi:[0,1]
	v_pk_add_f32 v[136:137], v[136:137], v[208:209]
	v_pk_add_f32 v[208:209], v[210:211], v[212:213]
	v_pk_add_f32 v[186:187], v[200:201], v[134:135] neg_lo:[0,1] neg_hi:[0,1]
	v_pk_add_f32 v[202:203], v[130:131], v[132:133] neg_lo:[0,1] neg_hi:[0,1]
	v_pk_add_f32 v[134:135], v[200:201], v[134:135]
	v_pk_add_f32 v[130:131], v[130:131], v[132:133]
	v_pk_add_f32 v[216:217], v[210:211], v[212:213] neg_lo:[0,1] neg_hi:[0,1]
	v_pk_add_f32 v[210:211], v[136:137], v[208:209]
	v_pk_add_f32 v[132:133], v[134:135], v[130:131]
	v_pk_add_f32 v[130:131], v[134:135], v[130:131] neg_lo:[0,1] neg_hi:[0,1]
	v_pk_add_f32 v[136:137], v[136:137], v[208:209] neg_lo:[0,1] neg_hi:[0,1]
	v_pk_add_f32 v[208:209], v[214:215], v[216:217]
	v_pk_add_f32 v[212:213], v[214:215], v[216:217] neg_lo:[0,1] neg_hi:[0,1]
	v_pk_add_f32 v[134:135], v[186:187], v[202:203]
	v_pk_add_f32 v[186:187], v[186:187], v[202:203] neg_lo:[0,1] neg_hi:[0,1]
	v_pk_add_f32 v[200:201], v[210:211], v[210:211] op_sel:[1,0] op_sel_hi:[0,1]
	v_pk_add_f32 v[216:217], v[130:131], v[130:131] op_sel:[1,0] op_sel_hi:[0,1]
	v_pk_add_f32 v[130:131], v[130:131], v[130:131] op_sel:[0,1] op_sel_hi:[1,0] neg_lo:[0,1] neg_hi:[0,1]
	v_pk_add_f32 v[204:205], v[132:133], v[132:133] op_sel:[1,0] op_sel_hi:[0,1]
	v_pk_add_f32 v[132:133], v[132:133], v[132:133] op_sel:[0,1] op_sel_hi:[1,0] neg_lo:[0,1] neg_hi:[0,1]
	v_pk_add_f32 v[220:221], v[186:187], v[186:187] op_sel:[1,0] op_sel_hi:[0,1]
	v_pk_add_f32 v[186:187], v[186:187], v[186:187] op_sel:[0,1] op_sel_hi:[1,0] neg_lo:[0,1] neg_hi:[0,1]
	v_xor_b32_e32 v131, v181, v200
	v_pk_add_f32 v[202:203], v[210:211], v[210:211] op_sel:[0,1] op_sel_hi:[1,0] neg_lo:[0,1] neg_hi:[0,1]
	v_pk_add_f32 v[206:207], v[208:209], v[208:209] op_sel:[1,0] op_sel_hi:[0,1]
	v_pk_add_f32 v[210:211], v[134:135], v[134:135] op_sel:[1,0] op_sel_hi:[0,1]
	v_pk_add_f32 v[134:135], v[134:135], v[134:135] op_sel:[0,1] op_sel_hi:[1,0] neg_lo:[0,1] neg_hi:[0,1]
	v_add_f32_dpp v131, v200, v131 quad_perm:[1,0,3,2] row_mask:0xf bank_mask:0xf bound_ctrl:1
	v_xor_b32_e32 v133, v181, v204
	v_xor_b32_e32 v205, v181, v186
	v_pk_add_f32 v[214:215], v[136:137], v[136:137] op_sel:[1,0] op_sel_hi:[0,1]
	v_pk_add_f32 v[136:137], v[136:137], v[136:137] op_sel:[0,1] op_sel_hi:[1,0] neg_lo:[0,1] neg_hi:[0,1]
	v_add_f32_dpp v133, v204, v133 quad_perm:[1,0,3,2] row_mask:0xf bank_mask:0xf bound_ctrl:1
	v_xor_b32_e32 v135, v181, v206
	v_add_f32_dpp v186, v186, v205 quad_perm:[1,0,3,2] row_mask:0xf bank_mask:0xf bound_ctrl:1
	v_xor_b32_e32 v205, v189, v131
	v_add_f32_dpp v135, v206, v135 quad_perm:[1,0,3,2] row_mask:0xf bank_mask:0xf bound_ctrl:1
	v_xor_b32_e32 v137, v181, v210
	v_add_f32_dpp v131, v131, v205 quad_perm:[2,3,0,1] row_mask:0xf bank_mask:0xf bound_ctrl:1
	v_xor_b32_e32 v205, v189, v133
	v_add_f32_dpp v137, v210, v137 quad_perm:[1,0,3,2] row_mask:0xf bank_mask:0xf bound_ctrl:1
	v_xor_b32_e32 v187, v181, v214
	v_add_f32_dpp v133, v133, v205 quad_perm:[2,3,0,1] row_mask:0xf bank_mask:0xf bound_ctrl:1
	v_xor_b32_e32 v205, v189, v135
	v_pk_add_f32 v[218:219], v[212:213], v[212:213] op_sel:[1,0] op_sel_hi:[0,1]
	v_add_f32_dpp v187, v214, v187 quad_perm:[1,0,3,2] row_mask:0xf bank_mask:0xf bound_ctrl:1
	v_xor_b32_e32 v199, v181, v216
	v_add_f32_dpp v135, v135, v205 quad_perm:[2,3,0,1] row_mask:0xf bank_mask:0xf bound_ctrl:1
	v_xor_b32_e32 v205, v189, v137
	v_add_f32_dpp v199, v216, v199 quad_perm:[1,0,3,2] row_mask:0xf bank_mask:0xf bound_ctrl:1
	v_xor_b32_e32 v200, v181, v218
	v_add_f32_dpp v137, v137, v205 quad_perm:[2,3,0,1] row_mask:0xf bank_mask:0xf bound_ctrl:1
	v_xor_b32_e32 v205, v189, v187
	v_add_f32_dpp v200, v218, v200 quad_perm:[1,0,3,2] row_mask:0xf bank_mask:0xf bound_ctrl:1
	v_xor_b32_e32 v201, v181, v220
	v_add_f32_dpp v187, v187, v205 quad_perm:[2,3,0,1] row_mask:0xf bank_mask:0xf bound_ctrl:1
	v_xor_b32_e32 v205, v189, v199
	v_add_f32_dpp v201, v220, v201 quad_perm:[1,0,3,2] row_mask:0xf bank_mask:0xf bound_ctrl:1
	v_xor_b32_e32 v203, v181, v202
	v_add_f32_dpp v199, v199, v205 quad_perm:[2,3,0,1] row_mask:0xf bank_mask:0xf bound_ctrl:1
	v_xor_b32_e32 v205, v189, v200
	v_pk_add_f32 v[208:209], v[208:209], v[208:209] op_sel:[0,1] op_sel_hi:[1,0] neg_lo:[0,1] neg_hi:[0,1]
	v_add_f32_dpp v202, v202, v203 quad_perm:[1,0,3,2] row_mask:0xf bank_mask:0xf bound_ctrl:1
	v_xor_b32_e32 v203, v181, v132
	v_add_f32_dpp v200, v200, v205 quad_perm:[2,3,0,1] row_mask:0xf bank_mask:0xf bound_ctrl:1
	v_xor_b32_e32 v205, v189, v201
	v_add_f32_dpp v132, v132, v203 quad_perm:[1,0,3,2] row_mask:0xf bank_mask:0xf bound_ctrl:1
	v_xor_b32_e32 v203, v181, v208
	v_add_f32_dpp v201, v201, v205 quad_perm:[2,3,0,1] row_mask:0xf bank_mask:0xf bound_ctrl:1
	v_xor_b32_e32 v205, v189, v202
	v_add_f32_dpp v203, v208, v203 quad_perm:[1,0,3,2] row_mask:0xf bank_mask:0xf bound_ctrl:1
	v_xor_b32_e32 v204, v181, v134
	v_add_f32_dpp v202, v202, v205 quad_perm:[2,3,0,1] row_mask:0xf bank_mask:0xf bound_ctrl:1
	v_xor_b32_e32 v205, v189, v132
	v_add_f32_dpp v134, v134, v204 quad_perm:[1,0,3,2] row_mask:0xf bank_mask:0xf bound_ctrl:1
	v_xor_b32_e32 v204, v181, v136
	v_add_f32_dpp v205, v132, v205 quad_perm:[2,3,0,1] row_mask:0xf bank_mask:0xf bound_ctrl:1
	v_xor_b32_e32 v132, v189, v203
	v_pk_add_f32 v[212:213], v[212:213], v[212:213] op_sel:[0,1] op_sel_hi:[1,0] neg_lo:[0,1] neg_hi:[0,1]
	v_add_f32_dpp v136, v136, v204 quad_perm:[1,0,3,2] row_mask:0xf bank_mask:0xf bound_ctrl:1
	v_xor_b32_e32 v204, v181, v130
	v_add_f32_dpp v203, v203, v132 quad_perm:[2,3,0,1] row_mask:0xf bank_mask:0xf bound_ctrl:1
	v_xor_b32_e32 v132, v189, v134
	v_add_f32_dpp v130, v130, v204 quad_perm:[1,0,3,2] row_mask:0xf bank_mask:0xf bound_ctrl:1
	v_xor_b32_e32 v204, v181, v212
	v_add_f32_dpp v206, v134, v132 quad_perm:[2,3,0,1] row_mask:0xf bank_mask:0xf bound_ctrl:1
	v_xor_b32_e32 v132, v189, v136
	v_add_f32_dpp v204, v212, v204 quad_perm:[1,0,3,2] row_mask:0xf bank_mask:0xf bound_ctrl:1
	v_max_f32_e64 v134, |v200|, |v201|
	v_add_f32_dpp v136, v136, v132 quad_perm:[2,3,0,1] row_mask:0xf bank_mask:0xf bound_ctrl:1
	v_xor_b32_e32 v132, v189, v130
	s_nop 1
	v_add_f32_dpp v207, v130, v132 quad_perm:[2,3,0,1] row_mask:0xf bank_mask:0xf bound_ctrl:1
	v_xor_b32_e32 v130, v189, v204
	v_max_f32_e64 v132, |v135|, |v137|
	s_nop 0
	v_add_f32_dpp v204, v204, v130 quad_perm:[2,3,0,1] row_mask:0xf bank_mask:0xf bound_ctrl:1
	v_xor_b32_e32 v130, v189, v186
	s_nop 1
	v_add_f32_dpp v186, v186, v130 quad_perm:[2,3,0,1] row_mask:0xf bank_mask:0xf bound_ctrl:1
	v_max_f32_e64 v130, |v131|, |v133|
	v_max3_f32 v130, v222, v130, v132
	v_max_f32_e64 v132, |v187|, |v199|
	v_max3_f32 v130, v130, v132, v134
	v_max_f32_e64 v132, |v202|, |v205|
	v_max_f32_e64 v134, |v203|, |v206|
	v_max3_f32 v130, v130, v132, v134
	v_max_f32_e64 v132, |v136|, |v207|
	v_max_f32_e64 v134, |v204|, |v186|
	v_max3_f32 v222, v130, v132, v134
	v_cvt_pk_bf16_f32 v130, v131, v133
	v_cvt_pk_bf16_f32 v131, v135, v137
	v_cvt_pk_bf16_f32 v132, v187, v199
	v_cvt_pk_bf16_f32 v133, v200, v201
	v_cvt_pk_bf16_f32 v134, v202, v205
	v_cvt_pk_bf16_f32 v135, v203, v206
	v_cvt_pk_bf16_f32 v136, v136, v207
	v_cvt_pk_bf16_f32 v137, v204, v186
	v_and_b32_e32 v187, 0xffff0000, v145
	v_and_b32_e32 v186, 0xffff0000, v141
	v_lshlrev_b32_e32 v201, 16, v142
	v_lshlrev_b32_e32 v200, 16, v138
	v_and_b32_e32 v203, 0xffff0000, v142
	v_and_b32_e32 v202, 0xffff0000, v138
	v_lshlrev_b32_e32 v204, 16, v139
	v_lshlrev_b32_e32 v205, 16, v143
	v_and_b32_e32 v143, 0xffff0000, v143
	v_and_b32_e32 v142, 0xffff0000, v139
	v_lshlrev_b32_e32 v139, 16, v144
	v_lshlrev_b32_e32 v138, 16, v140
	v_and_b32_e32 v207, 0xffff0000, v144
	v_and_b32_e32 v206, 0xffff0000, v140
	v_lshlrev_b32_e32 v140, 16, v141
	v_lshlrev_b32_e32 v141, 16, v145
	v_pk_add_f32 v[144:145], v[200:201], v[202:203]
	v_pk_add_f32 v[208:209], v[204:205], v[142:143]
	v_pk_add_f32 v[210:211], v[138:139], v[206:207]
	v_pk_add_f32 v[212:213], v[140:141], v[186:187]
	v_pk_add_f32 v[200:201], v[200:201], v[202:203] neg_lo:[0,1] neg_hi:[0,1]
	v_pk_add_f32 v[142:143], v[204:205], v[142:143] neg_lo:[0,1] neg_hi:[0,1]
	v_pk_add_f32 v[138:139], v[138:139], v[206:207] neg_lo:[0,1] neg_hi:[0,1]
	v_pk_add_f32 v[140:141], v[140:141], v[186:187] neg_lo:[0,1] neg_hi:[0,1]
	v_pk_add_f32 v[214:215], v[144:145], v[208:209] neg_lo:[0,1] neg_hi:[0,1]
	v_pk_add_f32 v[144:145], v[144:145], v[208:209]
	v_pk_add_f32 v[208:209], v[210:211], v[212:213]
	v_pk_add_f32 v[186:187], v[200:201], v[142:143] neg_lo:[0,1] neg_hi:[0,1]
	v_pk_add_f32 v[202:203], v[138:139], v[140:141] neg_lo:[0,1] neg_hi:[0,1]
	v_pk_add_f32 v[142:143], v[200:201], v[142:143]
	v_pk_add_f32 v[138:139], v[138:139], v[140:141]
	v_pk_add_f32 v[216:217], v[210:211], v[212:213] neg_lo:[0,1] neg_hi:[0,1]
	v_pk_add_f32 v[210:211], v[144:145], v[208:209]
	v_pk_add_f32 v[140:141], v[142:143], v[138:139]
	v_pk_add_f32 v[138:139], v[142:143], v[138:139] neg_lo:[0,1] neg_hi:[0,1]
	v_pk_add_f32 v[144:145], v[144:145], v[208:209] neg_lo:[0,1] neg_hi:[0,1]
	v_pk_add_f32 v[208:209], v[214:215], v[216:217]
	v_pk_add_f32 v[212:213], v[214:215], v[216:217] neg_lo:[0,1] neg_hi:[0,1]
	v_pk_add_f32 v[142:143], v[186:187], v[202:203]
	v_pk_add_f32 v[186:187], v[186:187], v[202:203] neg_lo:[0,1] neg_hi:[0,1]
	v_pk_add_f32 v[200:201], v[210:211], v[210:211] op_sel:[1,0] op_sel_hi:[0,1]
	v_pk_add_f32 v[216:217], v[138:139], v[138:139] op_sel:[1,0] op_sel_hi:[0,1]
	v_pk_add_f32 v[138:139], v[138:139], v[138:139] op_sel:[0,1] op_sel_hi:[1,0] neg_lo:[0,1] neg_hi:[0,1]
	v_pk_add_f32 v[204:205], v[140:141], v[140:141] op_sel:[1,0] op_sel_hi:[0,1]
	v_pk_add_f32 v[140:141], v[140:141], v[140:141] op_sel:[0,1] op_sel_hi:[1,0] neg_lo:[0,1] neg_hi:[0,1]
	v_pk_add_f32 v[220:221], v[186:187], v[186:187] op_sel:[1,0] op_sel_hi:[0,1]
	v_pk_add_f32 v[186:187], v[186:187], v[186:187] op_sel:[0,1] op_sel_hi:[1,0] neg_lo:[0,1] neg_hi:[0,1]
	v_xor_b32_e32 v139, v181, v200
	v_pk_add_f32 v[202:203], v[210:211], v[210:211] op_sel:[0,1] op_sel_hi:[1,0] neg_lo:[0,1] neg_hi:[0,1]
	v_pk_add_f32 v[206:207], v[208:209], v[208:209] op_sel:[1,0] op_sel_hi:[0,1]
	v_pk_add_f32 v[210:211], v[142:143], v[142:143] op_sel:[1,0] op_sel_hi:[0,1]
	v_pk_add_f32 v[142:143], v[142:143], v[142:143] op_sel:[0,1] op_sel_hi:[1,0] neg_lo:[0,1] neg_hi:[0,1]
	v_add_f32_dpp v139, v200, v139 quad_perm:[1,0,3,2] row_mask:0xf bank_mask:0xf bound_ctrl:1
	v_xor_b32_e32 v141, v181, v204
	v_xor_b32_e32 v205, v181, v186
	v_pk_add_f32 v[214:215], v[144:145], v[144:145] op_sel:[1,0] op_sel_hi:[0,1]
	v_pk_add_f32 v[144:145], v[144:145], v[144:145] op_sel:[0,1] op_sel_hi:[1,0] neg_lo:[0,1] neg_hi:[0,1]
	v_add_f32_dpp v141, v204, v141 quad_perm:[1,0,3,2] row_mask:0xf bank_mask:0xf bound_ctrl:1
	v_xor_b32_e32 v143, v181, v206
	v_add_f32_dpp v186, v186, v205 quad_perm:[1,0,3,2] row_mask:0xf bank_mask:0xf bound_ctrl:1
	v_xor_b32_e32 v205, v189, v139
	v_add_f32_dpp v143, v206, v143 quad_perm:[1,0,3,2] row_mask:0xf bank_mask:0xf bound_ctrl:1
	v_xor_b32_e32 v145, v181, v210
	v_add_f32_dpp v139, v139, v205 quad_perm:[2,3,0,1] row_mask:0xf bank_mask:0xf bound_ctrl:1
	v_xor_b32_e32 v205, v189, v141
	v_add_f32_dpp v145, v210, v145 quad_perm:[1,0,3,2] row_mask:0xf bank_mask:0xf bound_ctrl:1
	v_xor_b32_e32 v187, v181, v214
	v_add_f32_dpp v141, v141, v205 quad_perm:[2,3,0,1] row_mask:0xf bank_mask:0xf bound_ctrl:1
	v_xor_b32_e32 v205, v189, v143
	v_pk_add_f32 v[218:219], v[212:213], v[212:213] op_sel:[1,0] op_sel_hi:[0,1]
	v_add_f32_dpp v187, v214, v187 quad_perm:[1,0,3,2] row_mask:0xf bank_mask:0xf bound_ctrl:1
	v_xor_b32_e32 v199, v181, v216
	v_add_f32_dpp v143, v143, v205 quad_perm:[2,3,0,1] row_mask:0xf bank_mask:0xf bound_ctrl:1
	v_xor_b32_e32 v205, v189, v145
	v_add_f32_dpp v199, v216, v199 quad_perm:[1,0,3,2] row_mask:0xf bank_mask:0xf bound_ctrl:1
	v_xor_b32_e32 v200, v181, v218
	v_add_f32_dpp v145, v145, v205 quad_perm:[2,3,0,1] row_mask:0xf bank_mask:0xf bound_ctrl:1
	v_xor_b32_e32 v205, v189, v187
	v_add_f32_dpp v200, v218, v200 quad_perm:[1,0,3,2] row_mask:0xf bank_mask:0xf bound_ctrl:1
	v_xor_b32_e32 v201, v181, v220
	v_add_f32_dpp v187, v187, v205 quad_perm:[2,3,0,1] row_mask:0xf bank_mask:0xf bound_ctrl:1
	v_xor_b32_e32 v205, v189, v199
	v_add_f32_dpp v201, v220, v201 quad_perm:[1,0,3,2] row_mask:0xf bank_mask:0xf bound_ctrl:1
	v_xor_b32_e32 v203, v181, v202
	v_add_f32_dpp v199, v199, v205 quad_perm:[2,3,0,1] row_mask:0xf bank_mask:0xf bound_ctrl:1
	v_xor_b32_e32 v205, v189, v200
	v_pk_add_f32 v[208:209], v[208:209], v[208:209] op_sel:[0,1] op_sel_hi:[1,0] neg_lo:[0,1] neg_hi:[0,1]
	v_add_f32_dpp v202, v202, v203 quad_perm:[1,0,3,2] row_mask:0xf bank_mask:0xf bound_ctrl:1
	v_xor_b32_e32 v203, v181, v140
	v_add_f32_dpp v200, v200, v205 quad_perm:[2,3,0,1] row_mask:0xf bank_mask:0xf bound_ctrl:1
	v_xor_b32_e32 v205, v189, v201
	v_add_f32_dpp v140, v140, v203 quad_perm:[1,0,3,2] row_mask:0xf bank_mask:0xf bound_ctrl:1
	v_xor_b32_e32 v203, v181, v208
	v_add_f32_dpp v201, v201, v205 quad_perm:[2,3,0,1] row_mask:0xf bank_mask:0xf bound_ctrl:1
	v_xor_b32_e32 v205, v189, v202
	v_add_f32_dpp v203, v208, v203 quad_perm:[1,0,3,2] row_mask:0xf bank_mask:0xf bound_ctrl:1
	v_xor_b32_e32 v204, v181, v142
	v_add_f32_dpp v202, v202, v205 quad_perm:[2,3,0,1] row_mask:0xf bank_mask:0xf bound_ctrl:1
	v_xor_b32_e32 v205, v189, v140
	v_add_f32_dpp v142, v142, v204 quad_perm:[1,0,3,2] row_mask:0xf bank_mask:0xf bound_ctrl:1
	v_xor_b32_e32 v204, v181, v144
	v_add_f32_dpp v205, v140, v205 quad_perm:[2,3,0,1] row_mask:0xf bank_mask:0xf bound_ctrl:1
	v_xor_b32_e32 v140, v189, v203
	v_pk_add_f32 v[212:213], v[212:213], v[212:213] op_sel:[0,1] op_sel_hi:[1,0] neg_lo:[0,1] neg_hi:[0,1]
	v_add_f32_dpp v144, v144, v204 quad_perm:[1,0,3,2] row_mask:0xf bank_mask:0xf bound_ctrl:1
	v_xor_b32_e32 v204, v181, v138
	v_add_f32_dpp v203, v203, v140 quad_perm:[2,3,0,1] row_mask:0xf bank_mask:0xf bound_ctrl:1
	v_xor_b32_e32 v140, v189, v142
	v_add_f32_dpp v138, v138, v204 quad_perm:[1,0,3,2] row_mask:0xf bank_mask:0xf bound_ctrl:1
	v_xor_b32_e32 v204, v181, v212
	v_add_f32_dpp v206, v142, v140 quad_perm:[2,3,0,1] row_mask:0xf bank_mask:0xf bound_ctrl:1
	v_xor_b32_e32 v140, v189, v144
	v_add_f32_dpp v204, v212, v204 quad_perm:[1,0,3,2] row_mask:0xf bank_mask:0xf bound_ctrl:1
	v_max_f32_e64 v142, |v200|, |v201|
	v_add_f32_dpp v144, v144, v140 quad_perm:[2,3,0,1] row_mask:0xf bank_mask:0xf bound_ctrl:1
	v_xor_b32_e32 v140, v189, v138
	s_nop 1
	v_add_f32_dpp v207, v138, v140 quad_perm:[2,3,0,1] row_mask:0xf bank_mask:0xf bound_ctrl:1
	v_xor_b32_e32 v138, v189, v204
	v_max_f32_e64 v140, |v143|, |v145|
	s_nop 0
	v_add_f32_dpp v204, v204, v138 quad_perm:[2,3,0,1] row_mask:0xf bank_mask:0xf bound_ctrl:1
	v_xor_b32_e32 v138, v189, v186
	s_nop 1
	v_add_f32_dpp v186, v186, v138 quad_perm:[2,3,0,1] row_mask:0xf bank_mask:0xf bound_ctrl:1
	v_max_f32_e64 v138, |v139|, |v141|
	v_max3_f32 v138, v222, v138, v140
	v_max_f32_e64 v140, |v187|, |v199|
	v_max3_f32 v138, v138, v140, v142
	v_max_f32_e64 v140, |v202|, |v205|
	v_max_f32_e64 v142, |v203|, |v206|
	v_max3_f32 v138, v138, v140, v142
	v_max_f32_e64 v140, |v144|, |v207|
	v_max_f32_e64 v142, |v204|, |v186|
	v_max3_f32 v222, v138, v140, v142
	v_cvt_pk_bf16_f32 v138, v139, v141
	v_cvt_pk_bf16_f32 v139, v143, v145
	v_cvt_pk_bf16_f32 v140, v187, v199
	v_cvt_pk_bf16_f32 v141, v200, v201
	v_cvt_pk_bf16_f32 v142, v202, v205
	v_cvt_pk_bf16_f32 v143, v203, v206
	v_cvt_pk_bf16_f32 v144, v144, v207
	v_cvt_pk_bf16_f32 v145, v204, v186
	v_and_b32_e32 v187, 0xffff0000, v177
	v_and_b32_e32 v186, 0xffff0000, v173
	v_lshlrev_b32_e32 v201, 16, v174
	v_lshlrev_b32_e32 v200, 16, v170
	v_and_b32_e32 v203, 0xffff0000, v174
	v_and_b32_e32 v202, 0xffff0000, v170
	v_lshlrev_b32_e32 v204, 16, v171
	v_lshlrev_b32_e32 v205, 16, v175
	v_and_b32_e32 v175, 0xffff0000, v175
	v_and_b32_e32 v174, 0xffff0000, v171
	v_lshlrev_b32_e32 v171, 16, v176
	v_lshlrev_b32_e32 v170, 16, v172
	v_and_b32_e32 v207, 0xffff0000, v176
	v_and_b32_e32 v206, 0xffff0000, v172
	v_lshlrev_b32_e32 v172, 16, v173
	v_lshlrev_b32_e32 v173, 16, v177
	v_pk_add_f32 v[176:177], v[200:201], v[202:203]
	v_pk_add_f32 v[208:209], v[204:205], v[174:175]
	v_pk_add_f32 v[210:211], v[170:171], v[206:207]
	v_pk_add_f32 v[212:213], v[172:173], v[186:187]
	v_pk_add_f32 v[200:201], v[200:201], v[202:203] neg_lo:[0,1] neg_hi:[0,1]
	v_pk_add_f32 v[174:175], v[204:205], v[174:175] neg_lo:[0,1] neg_hi:[0,1]
	v_pk_add_f32 v[170:171], v[170:171], v[206:207] neg_lo:[0,1] neg_hi:[0,1]
	v_pk_add_f32 v[172:173], v[172:173], v[186:187] neg_lo:[0,1] neg_hi:[0,1]
	v_pk_add_f32 v[214:215], v[176:177], v[208:209] neg_lo:[0,1] neg_hi:[0,1]
	v_pk_add_f32 v[176:177], v[176:177], v[208:209]
	v_pk_add_f32 v[208:209], v[210:211], v[212:213]
	v_pk_add_f32 v[186:187], v[200:201], v[174:175] neg_lo:[0,1] neg_hi:[0,1]
	v_pk_add_f32 v[202:203], v[170:171], v[172:173] neg_lo:[0,1] neg_hi:[0,1]
	v_pk_add_f32 v[174:175], v[200:201], v[174:175]
	v_pk_add_f32 v[170:171], v[170:171], v[172:173]
	v_pk_add_f32 v[216:217], v[210:211], v[212:213] neg_lo:[0,1] neg_hi:[0,1]
	v_pk_add_f32 v[210:211], v[176:177], v[208:209]
	v_pk_add_f32 v[172:173], v[174:175], v[170:171]
	v_pk_add_f32 v[170:171], v[174:175], v[170:171] neg_lo:[0,1] neg_hi:[0,1]
	v_pk_add_f32 v[176:177], v[176:177], v[208:209] neg_lo:[0,1] neg_hi:[0,1]
	v_pk_add_f32 v[208:209], v[214:215], v[216:217]
	v_pk_add_f32 v[212:213], v[214:215], v[216:217] neg_lo:[0,1] neg_hi:[0,1]
	v_pk_add_f32 v[174:175], v[186:187], v[202:203]
	v_pk_add_f32 v[186:187], v[186:187], v[202:203] neg_lo:[0,1] neg_hi:[0,1]
	v_pk_add_f32 v[200:201], v[210:211], v[210:211] op_sel:[1,0] op_sel_hi:[0,1]
	v_pk_add_f32 v[216:217], v[170:171], v[170:171] op_sel:[1,0] op_sel_hi:[0,1]
	v_pk_add_f32 v[170:171], v[170:171], v[170:171] op_sel:[0,1] op_sel_hi:[1,0] neg_lo:[0,1] neg_hi:[0,1]
	v_pk_add_f32 v[204:205], v[172:173], v[172:173] op_sel:[1,0] op_sel_hi:[0,1]
	v_pk_add_f32 v[172:173], v[172:173], v[172:173] op_sel:[0,1] op_sel_hi:[1,0] neg_lo:[0,1] neg_hi:[0,1]
	v_pk_add_f32 v[220:221], v[186:187], v[186:187] op_sel:[1,0] op_sel_hi:[0,1]
	v_pk_add_f32 v[186:187], v[186:187], v[186:187] op_sel:[0,1] op_sel_hi:[1,0] neg_lo:[0,1] neg_hi:[0,1]
	v_xor_b32_e32 v171, v181, v200
	v_pk_add_f32 v[202:203], v[210:211], v[210:211] op_sel:[0,1] op_sel_hi:[1,0] neg_lo:[0,1] neg_hi:[0,1]
	v_pk_add_f32 v[206:207], v[208:209], v[208:209] op_sel:[1,0] op_sel_hi:[0,1]
	v_pk_add_f32 v[210:211], v[174:175], v[174:175] op_sel:[1,0] op_sel_hi:[0,1]
	v_pk_add_f32 v[174:175], v[174:175], v[174:175] op_sel:[0,1] op_sel_hi:[1,0] neg_lo:[0,1] neg_hi:[0,1]
	v_pk_add_f32 v[214:215], v[176:177], v[176:177] op_sel:[1,0] op_sel_hi:[0,1]
	v_add_f32_dpp v171, v200, v171 quad_perm:[1,0,3,2] row_mask:0xf bank_mask:0xf bound_ctrl:1
	v_xor_b32_e32 v173, v181, v204
	v_xor_b32_e32 v205, v181, v186
	v_pk_add_f32 v[176:177], v[176:177], v[176:177] op_sel:[0,1] op_sel_hi:[1,0] neg_lo:[0,1] neg_hi:[0,1]
	v_add_f32_dpp v173, v204, v173 quad_perm:[1,0,3,2] row_mask:0xf bank_mask:0xf bound_ctrl:1
	v_xor_b32_e32 v175, v181, v206
	v_xor_b32_e32 v187, v181, v214
	v_add_f32_dpp v186, v186, v205 quad_perm:[1,0,3,2] row_mask:0xf bank_mask:0xf bound_ctrl:1
	v_xor_b32_e32 v205, v189, v171
	v_add_f32_dpp v175, v206, v175 quad_perm:[1,0,3,2] row_mask:0xf bank_mask:0xf bound_ctrl:1
	v_xor_b32_e32 v177, v181, v210
	v_add_f32_dpp v187, v214, v187 quad_perm:[1,0,3,2] row_mask:0xf bank_mask:0xf bound_ctrl:1
	v_add_f32_dpp v214, v171, v205 quad_perm:[2,3,0,1] row_mask:0xf bank_mask:0xf bound_ctrl:1
	v_xor_b32_e32 v171, v189, v173
	v_add_f32_dpp v177, v210, v177 quad_perm:[1,0,3,2] row_mask:0xf bank_mask:0xf bound_ctrl:1
	v_xor_b32_e32 v199, v181, v216
	v_add_f32_dpp v215, v173, v171 quad_perm:[2,3,0,1] row_mask:0xf bank_mask:0xf bound_ctrl:1
	v_xor_b32_e32 v171, v189, v175
	v_pk_add_f32 v[218:219], v[212:213], v[212:213] op_sel:[1,0] op_sel_hi:[0,1]
	v_add_f32_dpp v199, v216, v199 quad_perm:[1,0,3,2] row_mask:0xf bank_mask:0xf bound_ctrl:1
	v_add_f32_dpp v216, v175, v171 quad_perm:[2,3,0,1] row_mask:0xf bank_mask:0xf bound_ctrl:1
	v_xor_b32_e32 v171, v189, v177
	v_xor_b32_e32 v200, v181, v218
	v_xor_b32_e32 v201, v181, v220
	v_add_f32_dpp v217, v177, v171 quad_perm:[2,3,0,1] row_mask:0xf bank_mask:0xf bound_ctrl:1
	v_xor_b32_e32 v171, v189, v187
	v_add_f32_dpp v200, v218, v200 quad_perm:[1,0,3,2] row_mask:0xf bank_mask:0xf bound_ctrl:1
	v_add_f32_dpp v201, v220, v201 quad_perm:[1,0,3,2] row_mask:0xf bank_mask:0xf bound_ctrl:1
	v_add_f32_dpp v218, v187, v171 quad_perm:[2,3,0,1] row_mask:0xf bank_mask:0xf bound_ctrl:1
	v_xor_b32_e32 v171, v189, v199
	v_xor_b32_e32 v203, v181, v202
	v_pk_add_f32 v[208:209], v[208:209], v[208:209] op_sel:[0,1] op_sel_hi:[1,0] neg_lo:[0,1] neg_hi:[0,1]
	v_add_f32_dpp v199, v199, v171 quad_perm:[2,3,0,1] row_mask:0xf bank_mask:0xf bound_ctrl:1
	v_xor_b32_e32 v171, v189, v200
	v_add_f32_dpp v202, v202, v203 quad_perm:[1,0,3,2] row_mask:0xf bank_mask:0xf bound_ctrl:1
	v_xor_b32_e32 v203, v181, v172
	v_add_f32_dpp v219, v200, v171 quad_perm:[2,3,0,1] row_mask:0xf bank_mask:0xf bound_ctrl:1
	v_xor_b32_e32 v171, v189, v201
	v_add_f32_dpp v172, v172, v203 quad_perm:[1,0,3,2] row_mask:0xf bank_mask:0xf bound_ctrl:1
	v_xor_b32_e32 v203, v181, v208
	v_add_f32_dpp v220, v201, v171 quad_perm:[2,3,0,1] row_mask:0xf bank_mask:0xf bound_ctrl:1
	v_xor_b32_e32 v171, v189, v202
	v_add_f32_dpp v203, v208, v203 quad_perm:[1,0,3,2] row_mask:0xf bank_mask:0xf bound_ctrl:1
	v_xor_b32_e32 v204, v181, v174
	v_add_f32_dpp v221, v202, v171 quad_perm:[2,3,0,1] row_mask:0xf bank_mask:0xf bound_ctrl:1
	v_xor_b32_e32 v171, v189, v172
	v_add_f32_dpp v174, v174, v204 quad_perm:[1,0,3,2] row_mask:0xf bank_mask:0xf bound_ctrl:1
	v_xor_b32_e32 v204, v181, v176
	v_add_f32_dpp v223, v172, v171 quad_perm:[2,3,0,1] row_mask:0xf bank_mask:0xf bound_ctrl:1
	v_xor_b32_e32 v171, v189, v203
	v_pk_add_f32 v[212:213], v[212:213], v[212:213] op_sel:[0,1] op_sel_hi:[1,0] neg_lo:[0,1] neg_hi:[0,1]
	v_add_f32_dpp v176, v176, v204 quad_perm:[1,0,3,2] row_mask:0xf bank_mask:0xf bound_ctrl:1
	v_xor_b32_e32 v204, v181, v170
	v_add_f32_dpp v224, v203, v171 quad_perm:[2,3,0,1] row_mask:0xf bank_mask:0xf bound_ctrl:1
	v_xor_b32_e32 v171, v189, v174
	v_add_f32_dpp v170, v170, v204 quad_perm:[1,0,3,2] row_mask:0xf bank_mask:0xf bound_ctrl:1
	v_xor_b32_e32 v204, v181, v212
	v_add_f32_dpp v225, v174, v171 quad_perm:[2,3,0,1] row_mask:0xf bank_mask:0xf bound_ctrl:1
	v_xor_b32_e32 v171, v189, v176
	v_add_f32_dpp v204, v212, v204 quad_perm:[1,0,3,2] row_mask:0xf bank_mask:0xf bound_ctrl:1
	v_max_f32_e64 v172, |v219|, |v220|
	v_add_f32_dpp v226, v176, v171 quad_perm:[2,3,0,1] row_mask:0xf bank_mask:0xf bound_ctrl:1
	v_xor_b32_e32 v171, v189, v170
	v_lshlrev_b32_e32 v173, 16, v166
	v_and_b32_e32 v175, 0xffff0000, v166
	v_add_f32_dpp v227, v170, v171 quad_perm:[2,3,0,1] row_mask:0xf bank_mask:0xf bound_ctrl:1
	v_xor_b32_e32 v170, v189, v204
	v_max_f32_e64 v171, |v216|, |v217|
	v_and_b32_e32 v174, 0xffff0000, v162
	v_add_f32_dpp v228, v204, v170 quad_perm:[2,3,0,1] row_mask:0xf bank_mask:0xf bound_ctrl:1
	v_xor_b32_e32 v170, v189, v186
	v_lshlrev_b32_e32 v176, 16, v163
	v_lshlrev_b32_e32 v177, 16, v167
	v_add_f32_dpp v229, v186, v170 quad_perm:[2,3,0,1] row_mask:0xf bank_mask:0xf bound_ctrl:1
	v_max_f32_e64 v170, |v214|, |v215|
	v_max3_f32 v170, v222, v170, v171
	v_max_f32_e64 v171, |v218|, |v199|
	v_max3_f32 v170, v170, v171, v172
	v_max_f32_e64 v171, |v221|, |v223|
	v_max_f32_e64 v172, |v224|, |v225|
	v_max3_f32 v170, v170, v171, v172
	v_max_f32_e64 v171, |v226|, |v227|
	v_max_f32_e64 v172, |v228|, |v229|
	v_max3_f32 v222, v170, v171, v172
	v_and_b32_e32 v171, 0xffff0000, v169
	v_and_b32_e32 v170, 0xffff0000, v165
	v_lshlrev_b32_e32 v172, 16, v162
	v_and_b32_e32 v167, 0xffff0000, v167
	v_and_b32_e32 v166, 0xffff0000, v163
	v_lshlrev_b32_e32 v163, 16, v168
	v_lshlrev_b32_e32 v162, 16, v164
	v_and_b32_e32 v187, 0xffff0000, v168
	v_and_b32_e32 v186, 0xffff0000, v164
	v_lshlrev_b32_e32 v164, 16, v165
	v_lshlrev_b32_e32 v165, 16, v169
	v_pk_add_f32 v[168:169], v[172:173], v[174:175]
	v_pk_add_f32 v[200:201], v[176:177], v[166:167]
	v_pk_add_f32 v[202:203], v[162:163], v[186:187]
	v_pk_add_f32 v[204:205], v[164:165], v[170:171]
	v_pk_add_f32 v[172:173], v[172:173], v[174:175] neg_lo:[0,1] neg_hi:[0,1]
	v_pk_add_f32 v[166:167], v[176:177], v[166:167] neg_lo:[0,1] neg_hi:[0,1]
	v_pk_add_f32 v[162:163], v[162:163], v[186:187] neg_lo:[0,1] neg_hi:[0,1]
	v_pk_add_f32 v[164:165], v[164:165], v[170:171] neg_lo:[0,1] neg_hi:[0,1]
	v_pk_add_f32 v[206:207], v[168:169], v[200:201] neg_lo:[0,1] neg_hi:[0,1]
	v_pk_add_f32 v[208:209], v[202:203], v[204:205] neg_lo:[0,1] neg_hi:[0,1]
	v_pk_add_f32 v[168:169], v[168:169], v[200:201]
	v_pk_add_f32 v[200:201], v[202:203], v[204:205]
	v_pk_add_f32 v[170:171], v[172:173], v[166:167] neg_lo:[0,1] neg_hi:[0,1]
	v_pk_add_f32 v[174:175], v[162:163], v[164:165] neg_lo:[0,1] neg_hi:[0,1]
	v_pk_add_f32 v[166:167], v[172:173], v[166:167]
	v_pk_add_f32 v[162:163], v[162:163], v[164:165]
	v_pk_add_f32 v[202:203], v[168:169], v[200:201]
	v_pk_add_f32 v[168:169], v[168:169], v[200:201] neg_lo:[0,1] neg_hi:[0,1]
	v_pk_add_f32 v[200:201], v[206:207], v[208:209]
	v_pk_add_f32 v[164:165], v[166:167], v[162:163]
	v_pk_add_f32 v[162:163], v[166:167], v[162:163] neg_lo:[0,1] neg_hi:[0,1]
	v_pk_add_f32 v[166:167], v[170:171], v[174:175]
	v_pk_add_f32 v[204:205], v[206:207], v[208:209] neg_lo:[0,1] neg_hi:[0,1]
	v_pk_add_f32 v[170:171], v[170:171], v[174:175] neg_lo:[0,1] neg_hi:[0,1]
	v_pk_add_f32 v[172:173], v[202:203], v[202:203] op_sel:[1,0] op_sel_hi:[0,1]
	v_pk_add_f32 v[174:175], v[202:203], v[202:203] op_sel:[0,1] op_sel_hi:[1,0] neg_lo:[0,1] neg_hi:[0,1]
	v_pk_add_f32 v[186:187], v[200:201], v[200:201] op_sel:[1,0] op_sel_hi:[0,1]
	v_pk_add_f32 v[202:203], v[166:167], v[166:167] op_sel:[1,0] op_sel_hi:[0,1]
	v_pk_add_f32 v[166:167], v[166:167], v[166:167] op_sel:[0,1] op_sel_hi:[1,0] neg_lo:[0,1] neg_hi:[0,1]
	v_pk_add_f32 v[208:209], v[162:163], v[162:163] op_sel:[1,0] op_sel_hi:[0,1]
	v_pk_add_f32 v[162:163], v[162:163], v[162:163] op_sel:[0,1] op_sel_hi:[1,0] neg_lo:[0,1] neg_hi:[0,1]
	v_pk_add_f32 v[176:177], v[164:165], v[164:165] op_sel:[1,0] op_sel_hi:[0,1]
	v_pk_add_f32 v[164:165], v[164:165], v[164:165] op_sel:[0,1] op_sel_hi:[1,0] neg_lo:[0,1] neg_hi:[0,1]
	v_pk_add_f32 v[212:213], v[170:171], v[170:171] op_sel:[1,0] op_sel_hi:[0,1]
	v_pk_add_f32 v[170:171], v[170:171], v[170:171] op_sel:[0,1] op_sel_hi:[1,0] neg_lo:[0,1] neg_hi:[0,1]
	v_xor_b32_e32 v163, v181, v172
	v_xor_b32_e32 v167, v181, v186
	v_pk_add_f32 v[206:207], v[168:169], v[168:169] op_sel:[1,0] op_sel_hi:[0,1]
	v_add_f32_dpp v163, v172, v163 quad_perm:[1,0,3,2] row_mask:0xf bank_mask:0xf bound_ctrl:1
	v_xor_b32_e32 v165, v181, v176
	v_add_f32_dpp v167, v186, v167 quad_perm:[1,0,3,2] row_mask:0xf bank_mask:0xf bound_ctrl:1
	v_xor_b32_e32 v186, v181, v170
	v_pk_add_f32 v[168:169], v[168:169], v[168:169] op_sel:[0,1] op_sel_hi:[1,0] neg_lo:[0,1] neg_hi:[0,1]
	v_add_f32_dpp v165, v176, v165 quad_perm:[1,0,3,2] row_mask:0xf bank_mask:0xf bound_ctrl:1
	v_xor_b32_e32 v171, v181, v206
	v_add_f32_dpp v170, v170, v186 quad_perm:[1,0,3,2] row_mask:0xf bank_mask:0xf bound_ctrl:1
	v_xor_b32_e32 v186, v189, v163
	v_xor_b32_e32 v169, v181, v202
	v_add_f32_dpp v171, v206, v171 quad_perm:[1,0,3,2] row_mask:0xf bank_mask:0xf bound_ctrl:1
	v_add_f32_dpp v206, v163, v186 quad_perm:[2,3,0,1] row_mask:0xf bank_mask:0xf bound_ctrl:1
	v_xor_b32_e32 v163, v189, v165
	v_add_f32_dpp v169, v202, v169 quad_perm:[1,0,3,2] row_mask:0xf bank_mask:0xf bound_ctrl:1
	v_xor_b32_e32 v172, v181, v208
	v_add_f32_dpp v207, v165, v163 quad_perm:[2,3,0,1] row_mask:0xf bank_mask:0xf bound_ctrl:1
	v_xor_b32_e32 v163, v189, v167
	v_pk_add_f32 v[210:211], v[204:205], v[204:205] op_sel:[1,0] op_sel_hi:[0,1]
	v_add_f32_dpp v172, v208, v172 quad_perm:[1,0,3,2] row_mask:0xf bank_mask:0xf bound_ctrl:1
	v_add_f32_dpp v208, v167, v163 quad_perm:[2,3,0,1] row_mask:0xf bank_mask:0xf bound_ctrl:1
	v_xor_b32_e32 v163, v189, v169
	v_xor_b32_e32 v173, v181, v210
	v_xor_b32_e32 v175, v181, v212
	v_add_f32_dpp v209, v169, v163 quad_perm:[2,3,0,1] row_mask:0xf bank_mask:0xf bound_ctrl:1
	v_xor_b32_e32 v163, v189, v171
	v_add_f32_dpp v173, v210, v173 quad_perm:[1,0,3,2] row_mask:0xf bank_mask:0xf bound_ctrl:1
	v_add_f32_dpp v175, v212, v175 quad_perm:[1,0,3,2] row_mask:0xf bank_mask:0xf bound_ctrl:1
	v_add_f32_dpp v210, v171, v163 quad_perm:[2,3,0,1] row_mask:0xf bank_mask:0xf bound_ctrl:1
	v_xor_b32_e32 v163, v189, v172
	v_xor_b32_e32 v176, v181, v174
	v_pk_add_f32 v[200:201], v[200:201], v[200:201] op_sel:[0,1] op_sel_hi:[1,0] neg_lo:[0,1] neg_hi:[0,1]
	v_add_f32_dpp v211, v172, v163 quad_perm:[2,3,0,1] row_mask:0xf bank_mask:0xf bound_ctrl:1
	v_xor_b32_e32 v163, v189, v173
	v_add_f32_dpp v174, v174, v176 quad_perm:[1,0,3,2] row_mask:0xf bank_mask:0xf bound_ctrl:1
	v_xor_b32_e32 v176, v181, v164
	v_add_f32_dpp v212, v173, v163 quad_perm:[2,3,0,1] row_mask:0xf bank_mask:0xf bound_ctrl:1
	v_xor_b32_e32 v163, v189, v175
	v_add_f32_dpp v164, v164, v176 quad_perm:[1,0,3,2] row_mask:0xf bank_mask:0xf bound_ctrl:1
	v_xor_b32_e32 v176, v181, v200
	v_add_f32_dpp v213, v175, v163 quad_perm:[2,3,0,1] row_mask:0xf bank_mask:0xf bound_ctrl:1
	v_xor_b32_e32 v163, v189, v174
	v_add_f32_dpp v176, v200, v176 quad_perm:[1,0,3,2] row_mask:0xf bank_mask:0xf bound_ctrl:1
	v_xor_b32_e32 v177, v181, v166
	v_add_f32_dpp v230, v174, v163 quad_perm:[2,3,0,1] row_mask:0xf bank_mask:0xf bound_ctrl:1
	v_xor_b32_e32 v163, v189, v164
	v_add_f32_dpp v166, v166, v177 quad_perm:[1,0,3,2] row_mask:0xf bank_mask:0xf bound_ctrl:1
	v_xor_b32_e32 v177, v181, v168
	v_add_f32_dpp v231, v164, v163 quad_perm:[2,3,0,1] row_mask:0xf bank_mask:0xf bound_ctrl:1
	v_xor_b32_e32 v163, v189, v176
	v_pk_add_f32 v[204:205], v[204:205], v[204:205] op_sel:[0,1] op_sel_hi:[1,0] neg_lo:[0,1] neg_hi:[0,1]
	v_add_f32_dpp v168, v168, v177 quad_perm:[1,0,3,2] row_mask:0xf bank_mask:0xf bound_ctrl:1
	v_xor_b32_e32 v177, v181, v162
	v_add_f32_dpp v232, v176, v163 quad_perm:[2,3,0,1] row_mask:0xf bank_mask:0xf bound_ctrl:1
	v_xor_b32_e32 v163, v189, v166
	v_add_f32_dpp v162, v162, v177 quad_perm:[1,0,3,2] row_mask:0xf bank_mask:0xf bound_ctrl:1
	v_xor_b32_e32 v177, v181, v204
	v_add_f32_dpp v233, v166, v163 quad_perm:[2,3,0,1] row_mask:0xf bank_mask:0xf bound_ctrl:1
	v_xor_b32_e32 v163, v189, v168
	v_add_f32_dpp v177, v204, v177 quad_perm:[1,0,3,2] row_mask:0xf bank_mask:0xf bound_ctrl:1
	v_max_f32_e64 v164, |v212|, |v213|
	v_add_f32_dpp v235, v168, v163 quad_perm:[2,3,0,1] row_mask:0xf bank_mask:0xf bound_ctrl:1
	v_xor_b32_e32 v163, v189, v162
	v_lshlrev_b32_e32 v165, 16, v158
	v_and_b32_e32 v167, 0xffff0000, v158
	v_add_f32_dpp v236, v162, v163 quad_perm:[2,3,0,1] row_mask:0xf bank_mask:0xf bound_ctrl:1
	v_xor_b32_e32 v162, v189, v177
	v_max_f32_e64 v163, |v208|, |v209|
	v_and_b32_e32 v166, 0xffff0000, v150
	v_add_f32_dpp v237, v177, v162 quad_perm:[2,3,0,1] row_mask:0xf bank_mask:0xf bound_ctrl:1
	v_xor_b32_e32 v162, v189, v170
	v_lshlrev_b32_e32 v168, 16, v151
	v_lshlrev_b32_e32 v169, 16, v159
	v_add_f32_dpp v238, v170, v162 quad_perm:[2,3,0,1] row_mask:0xf bank_mask:0xf bound_ctrl:1
	v_max_f32_e64 v162, |v206|, |v207|
	v_max3_f32 v162, v222, v162, v163
	v_max_f32_e64 v163, |v210|, |v211|
	v_max3_f32 v162, v162, v163, v164
	v_max_f32_e64 v163, |v230|, |v231|
	v_max_f32_e64 v164, |v232|, |v233|
	v_max3_f32 v162, v162, v163, v164
	v_max_f32_e64 v163, |v235|, |v236|
	v_max_f32_e64 v164, |v237|, |v238|
	v_max3_f32 v222, v162, v163, v164
	v_and_b32_e32 v163, 0xffff0000, v161
	v_and_b32_e32 v162, 0xffff0000, v153
	v_lshlrev_b32_e32 v164, 16, v150
	v_and_b32_e32 v159, 0xffff0000, v159
	v_and_b32_e32 v158, 0xffff0000, v151
	v_lshlrev_b32_e32 v151, 16, v160
	v_lshlrev_b32_e32 v150, 16, v152
	v_and_b32_e32 v171, 0xffff0000, v160
	v_and_b32_e32 v170, 0xffff0000, v152
	v_lshlrev_b32_e32 v152, 16, v153
	v_lshlrev_b32_e32 v153, 16, v161
	v_pk_add_f32 v[160:161], v[164:165], v[166:167]
	v_pk_add_f32 v[172:173], v[168:169], v[158:159]
	v_pk_add_f32 v[174:175], v[150:151], v[170:171]
	v_pk_add_f32 v[176:177], v[152:153], v[162:163]
	v_pk_add_f32 v[164:165], v[164:165], v[166:167] neg_lo:[0,1] neg_hi:[0,1]
	v_pk_add_f32 v[158:159], v[168:169], v[158:159] neg_lo:[0,1] neg_hi:[0,1]
	v_pk_add_f32 v[150:151], v[150:151], v[170:171] neg_lo:[0,1] neg_hi:[0,1]
	v_pk_add_f32 v[152:153], v[152:153], v[162:163] neg_lo:[0,1] neg_hi:[0,1]
	v_pk_add_f32 v[186:187], v[160:161], v[172:173] neg_lo:[0,1] neg_hi:[0,1]
	v_pk_add_f32 v[200:201], v[174:175], v[176:177] neg_lo:[0,1] neg_hi:[0,1]
	v_pk_add_f32 v[160:161], v[160:161], v[172:173]
	v_pk_add_f32 v[172:173], v[174:175], v[176:177]
	v_pk_add_f32 v[162:163], v[164:165], v[158:159] neg_lo:[0,1] neg_hi:[0,1]
	v_pk_add_f32 v[166:167], v[150:151], v[152:153] neg_lo:[0,1] neg_hi:[0,1]
	v_pk_add_f32 v[158:159], v[164:165], v[158:159]
	v_pk_add_f32 v[150:151], v[150:151], v[152:153]
	v_pk_add_f32 v[174:175], v[160:161], v[172:173]
	v_pk_add_f32 v[160:161], v[160:161], v[172:173] neg_lo:[0,1] neg_hi:[0,1]
	v_pk_add_f32 v[172:173], v[186:187], v[200:201]
	v_pk_add_f32 v[152:153], v[158:159], v[150:151]
	v_pk_add_f32 v[150:151], v[158:159], v[150:151] neg_lo:[0,1] neg_hi:[0,1]
	v_pk_add_f32 v[158:159], v[162:163], v[166:167]
	v_pk_add_f32 v[176:177], v[186:187], v[200:201] neg_lo:[0,1] neg_hi:[0,1]
	v_pk_add_f32 v[162:163], v[162:163], v[166:167] neg_lo:[0,1] neg_hi:[0,1]
	v_pk_add_f32 v[164:165], v[174:175], v[174:175] op_sel:[1,0] op_sel_hi:[0,1]
	v_pk_add_f32 v[166:167], v[174:175], v[174:175] op_sel:[0,1] op_sel_hi:[1,0] neg_lo:[0,1] neg_hi:[0,1]
	v_pk_add_f32 v[170:171], v[172:173], v[172:173] op_sel:[1,0] op_sel_hi:[0,1]
	v_pk_add_f32 v[174:175], v[158:159], v[158:159] op_sel:[1,0] op_sel_hi:[0,1]
	v_pk_add_f32 v[158:159], v[158:159], v[158:159] op_sel:[0,1] op_sel_hi:[1,0] neg_lo:[0,1] neg_hi:[0,1]
	v_pk_add_f32 v[200:201], v[150:151], v[150:151] op_sel:[1,0] op_sel_hi:[0,1]
	v_pk_add_f32 v[150:151], v[150:151], v[150:151] op_sel:[0,1] op_sel_hi:[1,0] neg_lo:[0,1] neg_hi:[0,1]
	v_pk_add_f32 v[168:169], v[152:153], v[152:153] op_sel:[1,0] op_sel_hi:[0,1]
	v_pk_add_f32 v[152:153], v[152:153], v[152:153] op_sel:[0,1] op_sel_hi:[1,0] neg_lo:[0,1] neg_hi:[0,1]
	v_pk_add_f32 v[204:205], v[162:163], v[162:163] op_sel:[1,0] op_sel_hi:[0,1]
	v_pk_add_f32 v[162:163], v[162:163], v[162:163] op_sel:[0,1] op_sel_hi:[1,0] neg_lo:[0,1] neg_hi:[0,1]
	v_xor_b32_e32 v151, v181, v164
	v_xor_b32_e32 v159, v181, v170
	v_xor_b32_e32 v153, v181, v168
	v_add_f32_dpp v151, v164, v151 quad_perm:[1,0,3,2] row_mask:0xf bank_mask:0xf bound_ctrl:1
	v_add_f32_dpp v159, v170, v159 quad_perm:[1,0,3,2] row_mask:0xf bank_mask:0xf bound_ctrl:1
	v_xor_b32_e32 v170, v181, v162
	v_pk_add_f32 v[186:187], v[160:161], v[160:161] op_sel:[1,0] op_sel_hi:[0,1]
	v_pk_add_f32 v[160:161], v[160:161], v[160:161] op_sel:[0,1] op_sel_hi:[1,0] neg_lo:[0,1] neg_hi:[0,1]
	v_add_f32_dpp v153, v168, v153 quad_perm:[1,0,3,2] row_mask:0xf bank_mask:0xf bound_ctrl:1
	v_add_f32_dpp v162, v162, v170 quad_perm:[1,0,3,2] row_mask:0xf bank_mask:0xf bound_ctrl:1
	v_xor_b32_e32 v170, v189, v151
	v_xor_b32_e32 v161, v181, v174
	v_xor_b32_e32 v163, v181, v186
	v_add_f32_dpp v151, v151, v170 quad_perm:[2,3,0,1] row_mask:0xf bank_mask:0xf bound_ctrl:1
	v_xor_b32_e32 v170, v189, v153
	v_add_f32_dpp v161, v174, v161 quad_perm:[1,0,3,2] row_mask:0xf bank_mask:0xf bound_ctrl:1
	v_pk_add_f32 v[202:203], v[176:177], v[176:177] op_sel:[1,0] op_sel_hi:[0,1]
	v_add_f32_dpp v153, v153, v170 quad_perm:[2,3,0,1] row_mask:0xf bank_mask:0xf bound_ctrl:1
	v_xor_b32_e32 v170, v189, v159
	v_add_f32_dpp v163, v186, v163 quad_perm:[1,0,3,2] row_mask:0xf bank_mask:0xf bound_ctrl:1
	v_xor_b32_e32 v164, v181, v200
	v_add_f32_dpp v159, v159, v170 quad_perm:[2,3,0,1] row_mask:0xf bank_mask:0xf bound_ctrl:1
	v_xor_b32_e32 v170, v189, v161
	v_add_f32_dpp v164, v200, v164 quad_perm:[1,0,3,2] row_mask:0xf bank_mask:0xf bound_ctrl:1
	v_xor_b32_e32 v165, v181, v202
	v_add_f32_dpp v161, v161, v170 quad_perm:[2,3,0,1] row_mask:0xf bank_mask:0xf bound_ctrl:1
	v_xor_b32_e32 v170, v189, v163
	v_add_f32_dpp v165, v202, v165 quad_perm:[1,0,3,2] row_mask:0xf bank_mask:0xf bound_ctrl:1
	v_xor_b32_e32 v167, v181, v204
	v_add_f32_dpp v186, v163, v170 quad_perm:[2,3,0,1] row_mask:0xf bank_mask:0xf bound_ctrl:1
	v_xor_b32_e32 v163, v189, v164
	v_add_f32_dpp v167, v204, v167 quad_perm:[1,0,3,2] row_mask:0xf bank_mask:0xf bound_ctrl:1
	v_xor_b32_e32 v168, v181, v166
	v_add_f32_dpp v187, v164, v163 quad_perm:[2,3,0,1] row_mask:0xf bank_mask:0xf bound_ctrl:1
	v_xor_b32_e32 v163, v189, v165
	v_pk_add_f32 v[172:173], v[172:173], v[172:173] op_sel:[0,1] op_sel_hi:[1,0] neg_lo:[0,1] neg_hi:[0,1]
	v_add_f32_dpp v166, v166, v168 quad_perm:[1,0,3,2] row_mask:0xf bank_mask:0xf bound_ctrl:1
	v_xor_b32_e32 v168, v181, v152
	v_add_f32_dpp v200, v165, v163 quad_perm:[2,3,0,1] row_mask:0xf bank_mask:0xf bound_ctrl:1
	v_xor_b32_e32 v163, v189, v167
	v_add_f32_dpp v152, v152, v168 quad_perm:[1,0,3,2] row_mask:0xf bank_mask:0xf bound_ctrl:1
	v_xor_b32_e32 v168, v181, v172
	v_add_f32_dpp v201, v167, v163 quad_perm:[2,3,0,1] row_mask:0xf bank_mask:0xf bound_ctrl:1
	v_xor_b32_e32 v163, v189, v166
	v_add_f32_dpp v168, v172, v168 quad_perm:[1,0,3,2] row_mask:0xf bank_mask:0xf bound_ctrl:1
	v_xor_b32_e32 v169, v181, v158
	v_add_f32_dpp v202, v166, v163 quad_perm:[2,3,0,1] row_mask:0xf bank_mask:0xf bound_ctrl:1
	v_xor_b32_e32 v163, v189, v152
	v_add_f32_dpp v158, v158, v169 quad_perm:[1,0,3,2] row_mask:0xf bank_mask:0xf bound_ctrl:1
	v_xor_b32_e32 v169, v181, v160
	v_add_f32_dpp v203, v152, v163 quad_perm:[2,3,0,1] row_mask:0xf bank_mask:0xf bound_ctrl:1
	v_xor_b32_e32 v152, v189, v168
	v_pk_add_f32 v[176:177], v[176:177], v[176:177] op_sel:[0,1] op_sel_hi:[1,0] neg_lo:[0,1] neg_hi:[0,1]
	v_add_f32_dpp v160, v160, v169 quad_perm:[1,0,3,2] row_mask:0xf bank_mask:0xf bound_ctrl:1
	v_xor_b32_e32 v169, v181, v150
	v_add_f32_dpp v204, v168, v152 quad_perm:[2,3,0,1] row_mask:0xf bank_mask:0xf bound_ctrl:1
	v_xor_b32_e32 v152, v189, v158
	v_add_f32_dpp v150, v150, v169 quad_perm:[1,0,3,2] row_mask:0xf bank_mask:0xf bound_ctrl:1
	v_xor_b32_e32 v169, v181, v176
	v_add_f32_dpp v205, v158, v152 quad_perm:[2,3,0,1] row_mask:0xf bank_mask:0xf bound_ctrl:1
	v_xor_b32_e32 v152, v189, v160
	v_add_f32_dpp v169, v176, v169 quad_perm:[1,0,3,2] row_mask:0xf bank_mask:0xf bound_ctrl:1
	v_max_f32_e64 v158, |v200|, |v201|
	v_add_f32_dpp v160, v160, v152 quad_perm:[2,3,0,1] row_mask:0xf bank_mask:0xf bound_ctrl:1
	v_xor_b32_e32 v152, v189, v150
	v_cvt_pk_bf16_f32 v170, v214, v215
	v_cvt_pk_bf16_f32 v171, v216, v217
	v_cvt_pk_bf16_f32 v172, v218, v199
	v_cvt_pk_bf16_f32 v173, v219, v220
	v_cvt_pk_bf16_f32 v174, v221, v223
	s_nop 1
	v_add_f32_dpp v239, v150, v152 quad_perm:[2,3,0,1] row_mask:0xf bank_mask:0xf bound_ctrl:1
	v_xor_b32_e32 v150, v189, v169
	v_max_f32_e64 v152, |v159|, |v161|
	v_cvt_pk_bf16_f32 v175, v224, v225
	v_cvt_pk_bf16_f32 v176, v226, v227
	v_cvt_pk_bf16_f32 v177, v228, v229
	s_nop 0
	v_add_f32_dpp v240, v169, v150 quad_perm:[2,3,0,1] row_mask:0xf bank_mask:0xf bound_ctrl:1
	v_xor_b32_e32 v150, v189, v162
	s_nop 1
	v_add_f32_dpp v241, v162, v150 quad_perm:[2,3,0,1] row_mask:0xf bank_mask:0xf bound_ctrl:1
	v_max_f32_e64 v150, |v151|, |v153|
	v_max3_f32 v150, v222, v150, v152
	v_max_f32_e64 v152, |v186|, |v187|
	v_max3_f32 v150, v150, v152, v158
	v_max_f32_e64 v152, |v202|, |v203|
	v_max_f32_e64 v158, |v204|, |v205|
	v_max3_f32 v150, v150, v152, v158
	v_max_f32_e64 v152, |v160|, |v239|
	v_max_f32_e64 v158, |v240|, |v241|
	v_max3_f32 v150, v150, v152, v158
	ds_bpermute_b32 v152, v193, v150
	v_cvt_pk_bf16_f32 v162, v206, v207
	v_cvt_pk_bf16_f32 v163, v208, v209
	v_cvt_pk_bf16_f32 v164, v210, v211
	v_cvt_pk_bf16_f32 v165, v212, v213
	s_waitcnt lgkmcnt(0)
	v_max_f32_e32 v152, v152, v152
	v_max_f32_e32 v150, v150, v152
	ds_bpermute_b32 v152, v194, v150
	v_cvt_pk_bf16_f32 v166, v230, v231
	v_cvt_pk_bf16_f32 v167, v232, v233
	v_cvt_pk_bf16_f32 v168, v235, v236
	v_cvt_pk_bf16_f32 v169, v237, v238
	s_waitcnt lgkmcnt(0)
	v_max_f32_e32 v152, v152, v152
	v_max_f32_e32 v150, v150, v152
	ds_bpermute_b32 v152, v195, v150
	s_waitcnt lgkmcnt(0)
	v_max_f32_e32 v152, v152, v152
	v_max_f32_e32 v150, v150, v152
	ds_bpermute_b32 v152, v196, v150
	s_waitcnt lgkmcnt(0)
	v_max_f32_e32 v152, v152, v152
	v_max_f32_e32 v158, v150, v152
	ds_bpermute_b32 v193, v197, v158
	v_cvt_pk_bf16_f32 v150, v151, v153
	v_cvt_pk_bf16_f32 v151, v159, v161
	v_cvt_pk_bf16_f32 v152, v186, v187
	v_cvt_pk_bf16_f32 v153, v200, v201
	s_waitcnt lgkmcnt(0)
	v_max_f32_e32 v159, v193, v193
	v_max_f32_e32 v186, v158, v159
	ds_bpermute_b32 v187, v198, v186
	v_cvt_pk_bf16_f32 v158, v202, v203
	v_cvt_pk_bf16_f32 v159, v204, v205
	v_cvt_pk_bf16_f32 v160, v160, v239
	v_cvt_pk_bf16_f32 v161, v240, v241
	s_waitcnt lgkmcnt(0)
	v_max_f32_e32 v187, v187, v187
	v_max_f32_e32 v186, v186, v187
	s_and_saveexec_b64 s[28:29], s[2:3]
	s_cbranch_execz .LBB0_1019
	s_lshl_b64 s[30:31], s[26:27], 2
	s_sub_u32 s30, s37, s30
	s_subb_u32 s31, s38, s31
	v_mul_f32_e32 v187, 0x3a810204, v186
	global_store_dword v179, v187, s[30:31]

.LBB0_1850:
	s_or_b64 exec, exec, s[0:1]
	s_mov_b64 s[0:1], s[94:95]
	v_mov_b32_e32 v188, v0
	s_waitcnt lgkmcnt(0)
	s_barrier
	s_load_dwordx2 s[4:5], s[0:1], 0xc8
	v_readfirstlane_b32 s2, v188
	s_ashr_i32 s2, s2, 6
	v_and_b32_e32 v1, 63, v188
	s_add_i32 s6, s2, s80
	s_movk_i32 s10, 0x2000
	s_cmpk_lt_i32 s6, 0x2000
	v_cmp_gt_u32_e64 s[0:1], 48, v1
	v_lshlrev_b32_e32 v178, 4, v1
	v_lshlrev_b32_e32 v180, 5, v1
	s_cbranch_scc0 .LBB0_1873
	s_waitcnt lgkmcnt(0)
	s_add_u32 s2, s4, 0x4bd00000
	s_addc_u32 s3, s5, 0
	s_sub_i32 s98, 0x1fff, s6
	s_mul_i32 s8, s98, 0x5600
	s_mul_hi_i32 s7, s98, 0x5600
	s_add_u32 s24, s2, s8
	v_mov_b32_e32 v179, 0
	s_addc_u32 s25, s3, s7
	v_mov_b32_e32 v181, v179
	v_lshl_add_u64 v[74:75], s[24:25], 0, v[180:181]
	s_movk_i32 s7, 0x1000
	v_add_co_u32_e32 v28, vcc, s7, v74
	s_movk_i32 s36, 0x3000
	s_nop 0
	v_addc_co_u32_e32 v29, vcc, 0, v75, vcc
	v_add_co_u32_e32 v42, vcc, s10, v74
	s_mov_b64 s[8:9], 0x1000
	s_nop 0
	v_addc_co_u32_e32 v43, vcc, 0, v75, vcc
	s_mov_b64 s[10:11], 0x1800
	s_mov_b64 s[12:13], 0x2000
	v_add_co_u32_e32 v62, vcc, s36, v74
	v_lshl_add_u64 v[26:27], v[74:75], 0, s[8:9]
	v_lshl_add_u64 v[30:31], v[74:75], 0, s[10:11]
	v_lshl_add_u64 v[32:33], v[74:75], 0, s[12:13]
	s_mov_b64 s[14:15], 0x2800
	s_mov_b64 s[16:17], 0x3000
	v_addc_co_u32_e32 v63, vcc, 0, v75, vcc
	global_load_dwordx4 v[2:5], v180, s[24:25] offset:16
	global_load_dwordx4 v[6:9], v180, s[24:25] offset:2048
	global_load_dwordx4 v[10:13], v180, s[24:25] offset:2064
	global_load_dwordx4 v[14:17], v[42:43], off offset:-4096
	global_load_dwordx4 v[22:25], v[26:27], off offset:16
	global_load_dwordx4 v[18:21], v[28:29], off offset:2048
	s_nop 0
	global_load_dwordx4 v[26:29], v[30:31], off offset:16
	global_load_dwordx4 v[34:37], v[32:33], off offset:16
	v_lshl_add_u64 v[44:45], v[74:75], 0, s[14:15]
	global_load_dwordx4 v[30:33], v[42:43], off
	global_load_dwordx4 v[38:41], v[42:43], off offset:2048
	v_lshl_add_u64 v[42:43], v[74:75], 0, s[16:17]
	s_mov_b64 s[18:19], 0x3800
	s_mov_b64 s[20:21], 0x4000
	v_add_co_u32_e32 v66, vcc, 0x4000, v74
	global_load_dwordx4 v[46:49], v[44:45], off offset:16
	global_load_dwordx4 v[54:57], v[42:43], off offset:16
	v_lshl_add_u64 v[42:43], v[74:75], 0, s[18:19]
	v_lshl_add_u64 v[44:45], v[74:75], 0, s[20:21]
	v_addc_co_u32_e32 v67, vcc, 0, v75, vcc
	s_mov_b64 s[22:23], 0x4800
	global_load_dwordx4 v[50:53], v[62:63], off
	global_load_dwordx4 v[58:61], v[62:63], off offset:2048
	s_nop 0
	global_load_dwordx4 v[62:65], v[42:43], off offset:16
	global_load_dwordx4 v[154:157], v[44:45], off offset:16
	v_lshl_add_u64 v[68:69], v[74:75], 0, s[22:23]
	global_load_dwordx4 v[146:149], v[66:67], off
	global_load_dwordx4 v[98:101], v[66:67], off offset:2048
	global_load_dwordx4 v[42:45], v180, s[24:25]
	global_load_dwordx4 v[110:113], v[68:69], off offset:16
	v_mov_b32_e32 v70, v179
	v_mov_b32_e32 v71, v179
	v_mov_b32_e32 v72, v179
	v_mov_b32_e32 v73, v179
	v_mov_b32_e32 v66, v179
	v_mov_b32_e32 v67, v179
	v_mov_b32_e32 v68, v179
	v_mov_b32_e32 v69, v179
	s_and_saveexec_b64 s[24:25], s[0:1]
	s_cbranch_execz .LBB0_1853
	s_mov_b64 s[26:27], 0x5000
	v_lshl_add_u64 v[76:77], v[74:75], 0, s[26:27]
	v_add_co_u32_e32 v74, vcc, 0x5000, v74
	s_nop 1
	v_addc_co_u32_e32 v75, vcc, 0, v75, vcc
	global_load_dwordx4 v[66:69], v[74:75], off
	global_load_dwordx4 v[70:73], v[76:77], off offset:16
.LBB0_1853:
	s_or_b64 exec, exec, s[24:25]
	v_lshlrev_b32_e32 v74, 1, v178
	v_mov_b32_e32 v75, v179
	s_add_u32 s2, s2, 0xabfaa00
	s_addc_u32 s3, s3, 0
	v_lshl_add_u64 v[182:183], s[2:3], 0, v[74:75]
	v_lshl_add_u64 v[74:75], s[4:5], 0, v[178:179]
	s_mov_b64 s[2:3], 0x342fd500
	s_add_u32 s37, s4, 0x47407ffc
	v_lshl_add_u64 v[184:185], v[74:75], 0, s[2:3]
	v_lshlrev_b32_e32 v74, 30, v188
	s_addc_u32 s38, s5, 0
	v_lshlrev_b32_e32 v181, 31, v188
	v_and_b32_e32 v189, 0x80000000, v74
	v_cmp_eq_u32_e64 s[2:3], 0, v1
	s_movk_i32 s39, 0x2000
	s_mov_b64 s[24:25], 0x5000
	v_mbcnt_hi_u32_b32 v190, -1, v234
	s_mov_b32 s41, 0x42fe0000
	s_mov_b32 s43, 0xc0c0400
	s_mov_b32 s44, 0x4000c0c
	v_mov_b32_e32 v191, 0xffffaa00
	v_mov_b32_e32 v192, 0xffffd500
	s_mov_b32 s30, s6
	s_branch .LBB0_1856

.LBB0_1860:
	s_waitcnt vmcnt(19)
	v_lshlrev_b32_e32 v187, 16, v2
	s_waitcnt vmcnt(1)
	v_lshlrev_b32_e32 v186, 16, v42
	v_and_b32_e32 v195, 0xffff0000, v2
	v_and_b32_e32 v194, 0xffff0000, v42
	v_lshlrev_b32_e32 v197, 16, v3
	v_lshlrev_b32_e32 v196, 16, v43
	v_and_b32_e32 v3, 0xffff0000, v3
	v_and_b32_e32 v2, 0xffff0000, v43
	v_lshlrev_b32_e32 v43, 16, v4
	v_lshlrev_b32_e32 v42, 16, v44
	v_and_b32_e32 v199, 0xffff0000, v4
	v_and_b32_e32 v198, 0xffff0000, v44
	v_lshlrev_b32_e32 v201, 16, v5
	v_lshlrev_b32_e32 v200, 16, v45
	v_and_b32_e32 v5, 0xffff0000, v5
	v_and_b32_e32 v4, 0xffff0000, v45
	v_pk_add_f32 v[44:45], v[186:187], v[194:195]
	v_pk_add_f32 v[202:203], v[196:197], v[2:3]
	v_pk_add_f32 v[204:205], v[42:43], v[198:199]
	v_pk_add_f32 v[206:207], v[200:201], v[4:5]
	v_pk_add_f32 v[186:187], v[186:187], v[194:195] neg_lo:[0,1] neg_hi:[0,1]
	v_pk_add_f32 v[2:3], v[196:197], v[2:3] neg_lo:[0,1] neg_hi:[0,1]
	v_pk_add_f32 v[42:43], v[42:43], v[198:199] neg_lo:[0,1] neg_hi:[0,1]
	v_pk_add_f32 v[4:5], v[200:201], v[4:5] neg_lo:[0,1] neg_hi:[0,1]
	v_pk_add_f32 v[208:209], v[44:45], v[202:203] neg_lo:[0,1] neg_hi:[0,1]
	v_pk_add_f32 v[44:45], v[44:45], v[202:203]
	v_pk_add_f32 v[202:203], v[204:205], v[206:207]
	v_pk_add_f32 v[194:195], v[186:187], v[2:3] neg_lo:[0,1] neg_hi:[0,1]
	v_pk_add_f32 v[196:197], v[42:43], v[4:5] neg_lo:[0,1] neg_hi:[0,1]
	v_pk_add_f32 v[2:3], v[186:187], v[2:3]
	v_pk_add_f32 v[4:5], v[42:43], v[4:5]
	v_pk_add_f32 v[210:211], v[204:205], v[206:207] neg_lo:[0,1] neg_hi:[0,1]
	v_pk_add_f32 v[204:205], v[44:45], v[202:203]
	v_pk_add_f32 v[42:43], v[2:3], v[4:5]
	v_pk_add_f32 v[2:3], v[2:3], v[4:5] neg_lo:[0,1] neg_hi:[0,1]
	v_pk_add_f32 v[44:45], v[44:45], v[202:203] neg_lo:[0,1] neg_hi:[0,1]
	v_pk_add_f32 v[202:203], v[208:209], v[210:211]
	v_pk_add_f32 v[206:207], v[208:209], v[210:211] neg_lo:[0,1] neg_hi:[0,1]
	v_pk_add_f32 v[4:5], v[194:195], v[196:197]
	v_pk_add_f32 v[186:187], v[194:195], v[196:197] neg_lo:[0,1] neg_hi:[0,1]
	v_pk_add_f32 v[194:195], v[204:205], v[204:205] op_sel:[0,1] op_sel_hi:[1,0]
	v_pk_add_f32 v[210:211], v[2:3], v[2:3] op_sel:[0,1] op_sel_hi:[1,0]
	v_pk_add_f32 v[2:3], v[2:3], v[2:3] op_sel:[0,1] op_sel_hi:[1,0] neg_lo:[0,1] neg_hi:[0,1]
	v_pk_add_f32 v[196:197], v[204:205], v[204:205] op_sel:[0,1] op_sel_hi:[1,0] neg_lo:[0,1] neg_hi:[0,1]
	v_pk_add_f32 v[198:199], v[42:43], v[42:43] op_sel:[0,1] op_sel_hi:[1,0]
	v_pk_add_f32 v[204:205], v[4:5], v[4:5] op_sel:[0,1] op_sel_hi:[1,0]
	v_pk_add_f32 v[4:5], v[4:5], v[4:5] op_sel:[0,1] op_sel_hi:[1,0] neg_lo:[0,1] neg_hi:[0,1]
	v_pk_add_f32 v[214:215], v[186:187], v[186:187] op_sel:[0,1] op_sel_hi:[1,0]
	v_pk_add_f32 v[186:187], v[186:187], v[186:187] op_sel:[0,1] op_sel_hi:[1,0] neg_lo:[0,1] neg_hi:[0,1]
	v_xor_b32_e32 v3, v181, v194
	v_pk_add_f32 v[42:43], v[42:43], v[42:43] op_sel:[0,1] op_sel_hi:[1,0] neg_lo:[0,1] neg_hi:[0,1]
	v_pk_add_f32 v[200:201], v[202:203], v[202:203] op_sel:[0,1] op_sel_hi:[1,0]
	v_add_f32_dpp v3, v194, v3 quad_perm:[1,0,3,2] row_mask:0xf bank_mask:0xf bound_ctrl:1
	v_xor_b32_e32 v5, v181, v198
	v_xor_b32_e32 v199, v181, v186
	v_pk_add_f32 v[208:209], v[44:45], v[44:45] op_sel:[0,1] op_sel_hi:[1,0]
	v_pk_add_f32 v[44:45], v[44:45], v[44:45] op_sel:[0,1] op_sel_hi:[1,0] neg_lo:[0,1] neg_hi:[0,1]
	v_add_f32_dpp v5, v198, v5 quad_perm:[1,0,3,2] row_mask:0xf bank_mask:0xf bound_ctrl:1
	v_xor_b32_e32 v43, v181, v200
	v_add_f32_dpp v186, v186, v199 quad_perm:[1,0,3,2] row_mask:0xf bank_mask:0xf bound_ctrl:1
	v_xor_b32_e32 v199, v189, v3
	v_add_f32_dpp v43, v200, v43 quad_perm:[1,0,3,2] row_mask:0xf bank_mask:0xf bound_ctrl:1
	v_xor_b32_e32 v45, v181, v204
	v_add_f32_dpp v3, v3, v199 quad_perm:[2,3,0,1] row_mask:0xf bank_mask:0xf bound_ctrl:1
	v_xor_b32_e32 v199, v189, v5
	v_add_f32_dpp v45, v204, v45 quad_perm:[1,0,3,2] row_mask:0xf bank_mask:0xf bound_ctrl:1
	v_xor_b32_e32 v187, v181, v208
	v_add_f32_dpp v5, v5, v199 quad_perm:[2,3,0,1] row_mask:0xf bank_mask:0xf bound_ctrl:1
	v_xor_b32_e32 v199, v189, v43
	v_pk_add_f32 v[212:213], v[206:207], v[206:207] op_sel:[0,1] op_sel_hi:[1,0]
	v_add_f32_dpp v187, v208, v187 quad_perm:[1,0,3,2] row_mask:0xf bank_mask:0xf bound_ctrl:1
	v_xor_b32_e32 v193, v181, v210
	v_add_f32_dpp v43, v43, v199 quad_perm:[2,3,0,1] row_mask:0xf bank_mask:0xf bound_ctrl:1
	v_xor_b32_e32 v199, v189, v45
	v_add_f32_dpp v193, v210, v193 quad_perm:[1,0,3,2] row_mask:0xf bank_mask:0xf bound_ctrl:1
	v_xor_b32_e32 v194, v181, v212
	v_add_f32_dpp v45, v45, v199 quad_perm:[2,3,0,1] row_mask:0xf bank_mask:0xf bound_ctrl:1
	v_xor_b32_e32 v199, v189, v187
	v_add_f32_dpp v194, v212, v194 quad_perm:[1,0,3,2] row_mask:0xf bank_mask:0xf bound_ctrl:1
	v_xor_b32_e32 v195, v181, v214
	v_add_f32_dpp v187, v187, v199 quad_perm:[2,3,0,1] row_mask:0xf bank_mask:0xf bound_ctrl:1
	v_xor_b32_e32 v199, v189, v193
	v_add_f32_dpp v195, v214, v195 quad_perm:[1,0,3,2] row_mask:0xf bank_mask:0xf bound_ctrl:1
	v_xor_b32_e32 v197, v181, v196
	v_add_f32_dpp v193, v193, v199 quad_perm:[2,3,0,1] row_mask:0xf bank_mask:0xf bound_ctrl:1
	v_xor_b32_e32 v199, v189, v194
	v_pk_add_f32 v[202:203], v[202:203], v[202:203] op_sel:[0,1] op_sel_hi:[1,0] neg_lo:[0,1] neg_hi:[0,1]
	v_add_f32_dpp v196, v196, v197 quad_perm:[1,0,3,2] row_mask:0xf bank_mask:0xf bound_ctrl:1
	v_xor_b32_e32 v197, v181, v42
	v_add_f32_dpp v194, v194, v199 quad_perm:[2,3,0,1] row_mask:0xf bank_mask:0xf bound_ctrl:1
	v_xor_b32_e32 v199, v189, v195
	v_add_f32_dpp v42, v42, v197 quad_perm:[1,0,3,2] row_mask:0xf bank_mask:0xf bound_ctrl:1
	v_xor_b32_e32 v197, v181, v202
	v_add_f32_dpp v195, v195, v199 quad_perm:[2,3,0,1] row_mask:0xf bank_mask:0xf bound_ctrl:1
	v_xor_b32_e32 v199, v189, v196
	v_add_f32_dpp v197, v202, v197 quad_perm:[1,0,3,2] row_mask:0xf bank_mask:0xf bound_ctrl:1
	v_xor_b32_e32 v198, v181, v4
	v_add_f32_dpp v196, v196, v199 quad_perm:[2,3,0,1] row_mask:0xf bank_mask:0xf bound_ctrl:1
	v_xor_b32_e32 v199, v189, v42
	v_add_f32_dpp v4, v4, v198 quad_perm:[1,0,3,2] row_mask:0xf bank_mask:0xf bound_ctrl:1
	v_xor_b32_e32 v198, v181, v44
	v_add_f32_dpp v199, v42, v199 quad_perm:[2,3,0,1] row_mask:0xf bank_mask:0xf bound_ctrl:1
	v_xor_b32_e32 v42, v189, v197
	v_pk_add_f32 v[206:207], v[206:207], v[206:207] op_sel:[0,1] op_sel_hi:[1,0] neg_lo:[0,1] neg_hi:[0,1]
	v_add_f32_dpp v44, v44, v198 quad_perm:[1,0,3,2] row_mask:0xf bank_mask:0xf bound_ctrl:1
	v_xor_b32_e32 v198, v181, v2
	v_add_f32_dpp v197, v197, v42 quad_perm:[2,3,0,1] row_mask:0xf bank_mask:0xf bound_ctrl:1
	v_xor_b32_e32 v42, v189, v4
	v_add_f32_dpp v2, v2, v198 quad_perm:[1,0,3,2] row_mask:0xf bank_mask:0xf bound_ctrl:1
	v_xor_b32_e32 v198, v181, v206
	v_add_f32_dpp v4, v4, v42 quad_perm:[2,3,0,1] row_mask:0xf bank_mask:0xf bound_ctrl:1
	v_xor_b32_e32 v42, v189, v44
	v_add_f32_dpp v198, v206, v198 quad_perm:[1,0,3,2] row_mask:0xf bank_mask:0xf bound_ctrl:1
	s_ashr_i32 s31, s30, 31
	v_add_f32_dpp v200, v44, v42 quad_perm:[2,3,0,1] row_mask:0xf bank_mask:0xf bound_ctrl:1
	v_xor_b32_e32 v42, v189, v2
	v_max_f32_e64 v44, |v194|, |v195|
	s_nop 0
	v_add_f32_dpp v201, v2, v42 quad_perm:[2,3,0,1] row_mask:0xf bank_mask:0xf bound_ctrl:1
	v_xor_b32_e32 v2, v189, v198
	v_max_f32_e64 v42, |v43|, |v45|
	s_nop 0
	v_add_f32_dpp v198, v198, v2 quad_perm:[2,3,0,1] row_mask:0xf bank_mask:0xf bound_ctrl:1
	v_xor_b32_e32 v2, v189, v186
	s_nop 1
	v_add_f32_dpp v186, v186, v2 quad_perm:[2,3,0,1] row_mask:0xf bank_mask:0xf bound_ctrl:1
	v_max_f32_e64 v2, |v3|, |v5|
	v_max3_f32 v2, v2, 0, v42
	v_max_f32_e64 v42, |v187|, |v193|
	v_max3_f32 v2, v2, v42, v44
	v_max_f32_e64 v42, |v196|, |v199|
	v_max_f32_e64 v44, |v197|, |v4|
	v_max3_f32 v2, v2, v42, v44
	v_max_f32_e64 v42, |v200|, |v201|
	v_max_f32_e64 v44, |v198|, |v186|
	v_max3_f32 v216, v2, v42, v44
	v_cvt_pk_bf16_f32 v42, v3, v5
	v_cvt_pk_bf16_f32 v43, v43, v45
	v_cvt_pk_bf16_f32 v44, v187, v193
	v_cvt_pk_bf16_f32 v45, v194, v195
	v_cvt_pk_bf16_f32 v2, v196, v199
	v_cvt_pk_bf16_f32 v3, v197, v4
	v_cvt_pk_bf16_f32 v4, v200, v201
	v_cvt_pk_bf16_f32 v5, v198, v186
	v_and_b32_e32 v187, 0xffff0000, v13
	v_and_b32_e32 v186, 0xffff0000, v9
	v_lshlrev_b32_e32 v195, 16, v10
	v_lshlrev_b32_e32 v194, 16, v6
	v_and_b32_e32 v197, 0xffff0000, v10
	v_and_b32_e32 v196, 0xffff0000, v6
	v_lshlrev_b32_e32 v199, 16, v11
	v_lshlrev_b32_e32 v198, 16, v7
	v_and_b32_e32 v11, 0xffff0000, v11
	v_and_b32_e32 v10, 0xffff0000, v7
	v_lshlrev_b32_e32 v7, 16, v12
	v_lshlrev_b32_e32 v6, 16, v8
	v_and_b32_e32 v201, 0xffff0000, v12
	v_and_b32_e32 v200, 0xffff0000, v8
	v_lshlrev_b32_e32 v13, 16, v13
	v_lshlrev_b32_e32 v12, 16, v9
	v_pk_add_f32 v[8:9], v[194:195], v[196:197]
	v_pk_add_f32 v[202:203], v[198:199], v[10:11]
	v_pk_add_f32 v[204:205], v[6:7], v[200:201]
	v_pk_add_f32 v[206:207], v[12:13], v[186:187]
	v_pk_add_f32 v[194:195], v[194:195], v[196:197] neg_lo:[0,1] neg_hi:[0,1]
	v_pk_add_f32 v[10:11], v[198:199], v[10:11] neg_lo:[0,1] neg_hi:[0,1]
	v_pk_add_f32 v[6:7], v[6:7], v[200:201] neg_lo:[0,1] neg_hi:[0,1]
	v_pk_add_f32 v[12:13], v[12:13], v[186:187] neg_lo:[0,1] neg_hi:[0,1]
	v_pk_add_f32 v[208:209], v[8:9], v[202:203] neg_lo:[0,1] neg_hi:[0,1]
	v_pk_add_f32 v[8:9], v[8:9], v[202:203]
	v_pk_add_f32 v[202:203], v[204:205], v[206:207]
	v_pk_add_f32 v[186:187], v[194:195], v[10:11] neg_lo:[0,1] neg_hi:[0,1]
	v_pk_add_f32 v[196:197], v[6:7], v[12:13] neg_lo:[0,1] neg_hi:[0,1]
	v_pk_add_f32 v[10:11], v[194:195], v[10:11]
	v_pk_add_f32 v[6:7], v[6:7], v[12:13]
	v_pk_add_f32 v[210:211], v[204:205], v[206:207] neg_lo:[0,1] neg_hi:[0,1]
	v_pk_add_f32 v[204:205], v[8:9], v[202:203]
	v_pk_add_f32 v[12:13], v[10:11], v[6:7]
	v_pk_add_f32 v[6:7], v[10:11], v[6:7] neg_lo:[0,1] neg_hi:[0,1]
	v_pk_add_f32 v[8:9], v[8:9], v[202:203] neg_lo:[0,1] neg_hi:[0,1]
	v_pk_add_f32 v[202:203], v[208:209], v[210:211]
	v_pk_add_f32 v[206:207], v[208:209], v[210:211] neg_lo:[0,1] neg_hi:[0,1]
	v_pk_add_f32 v[10:11], v[186:187], v[196:197]
	v_pk_add_f32 v[186:187], v[186:187], v[196:197] neg_lo:[0,1] neg_hi:[0,1]
	v_pk_add_f32 v[194:195], v[204:205], v[204:205] op_sel:[0,1] op_sel_hi:[1,0]
	v_pk_add_f32 v[210:211], v[6:7], v[6:7] op_sel:[0,1] op_sel_hi:[1,0]
	v_pk_add_f32 v[6:7], v[6:7], v[6:7] op_sel:[0,1] op_sel_hi:[1,0] neg_lo:[0,1] neg_hi:[0,1]
	v_pk_add_f32 v[198:199], v[12:13], v[12:13] op_sel:[0,1] op_sel_hi:[1,0]
	v_pk_add_f32 v[208:209], v[8:9], v[8:9] op_sel:[0,1] op_sel_hi:[1,0]
	v_pk_add_f32 v[8:9], v[8:9], v[8:9] op_sel:[0,1] op_sel_hi:[1,0] neg_lo:[0,1] neg_hi:[0,1]
	v_pk_add_f32 v[214:215], v[186:187], v[186:187] op_sel:[0,1] op_sel_hi:[1,0]
	v_pk_add_f32 v[186:187], v[186:187], v[186:187] op_sel:[0,1] op_sel_hi:[1,0] neg_lo:[0,1] neg_hi:[0,1]
	v_xor_b32_e32 v7, v181, v194
	v_pk_add_f32 v[196:197], v[204:205], v[204:205] op_sel:[0,1] op_sel_hi:[1,0] neg_lo:[0,1] neg_hi:[0,1]
	v_pk_add_f32 v[200:201], v[202:203], v[202:203] op_sel:[0,1] op_sel_hi:[1,0]
	v_pk_add_f32 v[204:205], v[10:11], v[10:11] op_sel:[0,1] op_sel_hi:[1,0]
	v_pk_add_f32 v[10:11], v[10:11], v[10:11] op_sel:[0,1] op_sel_hi:[1,0] neg_lo:[0,1] neg_hi:[0,1]
	v_add_f32_dpp v7, v194, v7 quad_perm:[1,0,3,2] row_mask:0xf bank_mask:0xf bound_ctrl:1
	v_xor_b32_e32 v9, v181, v198
	v_xor_b32_e32 v199, v181, v186
	v_pk_add_f32 v[12:13], v[12:13], v[12:13] op_sel:[0,1] op_sel_hi:[1,0] neg_lo:[0,1] neg_hi:[0,1]
	v_add_f32_dpp v9, v198, v9 quad_perm:[1,0,3,2] row_mask:0xf bank_mask:0xf bound_ctrl:1
	v_xor_b32_e32 v11, v181, v200
	v_add_f32_dpp v186, v186, v199 quad_perm:[1,0,3,2] row_mask:0xf bank_mask:0xf bound_ctrl:1
	v_xor_b32_e32 v199, v189, v7
	v_add_f32_dpp v11, v200, v11 quad_perm:[1,0,3,2] row_mask:0xf bank_mask:0xf bound_ctrl:1
	v_xor_b32_e32 v13, v181, v204
	v_add_f32_dpp v7, v7, v199 quad_perm:[2,3,0,1] row_mask:0xf bank_mask:0xf bound_ctrl:1
	v_xor_b32_e32 v199, v189, v9
	v_add_f32_dpp v13, v204, v13 quad_perm:[1,0,3,2] row_mask:0xf bank_mask:0xf bound_ctrl:1
	v_xor_b32_e32 v187, v181, v208
	v_add_f32_dpp v9, v9, v199 quad_perm:[2,3,0,1] row_mask:0xf bank_mask:0xf bound_ctrl:1
	v_xor_b32_e32 v199, v189, v11
	v_pk_add_f32 v[212:213], v[206:207], v[206:207] op_sel:[0,1] op_sel_hi:[1,0]
	v_add_f32_dpp v187, v208, v187 quad_perm:[1,0,3,2] row_mask:0xf bank_mask:0xf bound_ctrl:1
	v_xor_b32_e32 v193, v181, v210
	v_add_f32_dpp v11, v11, v199 quad_perm:[2,3,0,1] row_mask:0xf bank_mask:0xf bound_ctrl:1
	v_xor_b32_e32 v199, v189, v13
	v_add_f32_dpp v193, v210, v193 quad_perm:[1,0,3,2] row_mask:0xf bank_mask:0xf bound_ctrl:1
	v_xor_b32_e32 v194, v181, v212
	v_add_f32_dpp v13, v13, v199 quad_perm:[2,3,0,1] row_mask:0xf bank_mask:0xf bound_ctrl:1
	v_xor_b32_e32 v199, v189, v187
	v_add_f32_dpp v194, v212, v194 quad_perm:[1,0,3,2] row_mask:0xf bank_mask:0xf bound_ctrl:1
	v_xor_b32_e32 v195, v181, v214
	v_add_f32_dpp v187, v187, v199 quad_perm:[2,3,0,1] row_mask:0xf bank_mask:0xf bound_ctrl:1
	v_xor_b32_e32 v199, v189, v193
	v_add_f32_dpp v195, v214, v195 quad_perm:[1,0,3,2] row_mask:0xf bank_mask:0xf bound_ctrl:1
	v_xor_b32_e32 v197, v181, v196
	v_add_f32_dpp v193, v193, v199 quad_perm:[2,3,0,1] row_mask:0xf bank_mask:0xf bound_ctrl:1
	v_xor_b32_e32 v199, v189, v194
	v_pk_add_f32 v[202:203], v[202:203], v[202:203] op_sel:[0,1] op_sel_hi:[1,0] neg_lo:[0,1] neg_hi:[0,1]
	v_add_f32_dpp v196, v196, v197 quad_perm:[1,0,3,2] row_mask:0xf bank_mask:0xf bound_ctrl:1
	v_xor_b32_e32 v197, v181, v12
	v_add_f32_dpp v194, v194, v199 quad_perm:[2,3,0,1] row_mask:0xf bank_mask:0xf bound_ctrl:1
	v_xor_b32_e32 v199, v189, v195
	v_add_f32_dpp v12, v12, v197 quad_perm:[1,0,3,2] row_mask:0xf bank_mask:0xf bound_ctrl:1
	v_xor_b32_e32 v197, v181, v202
	v_add_f32_dpp v195, v195, v199 quad_perm:[2,3,0,1] row_mask:0xf bank_mask:0xf bound_ctrl:1
	v_xor_b32_e32 v199, v189, v196
	v_add_f32_dpp v197, v202, v197 quad_perm:[1,0,3,2] row_mask:0xf bank_mask:0xf bound_ctrl:1
	v_xor_b32_e32 v198, v181, v10
	v_add_f32_dpp v196, v196, v199 quad_perm:[2,3,0,1] row_mask:0xf bank_mask:0xf bound_ctrl:1
	v_xor_b32_e32 v199, v189, v12
	v_add_f32_dpp v10, v10, v198 quad_perm:[1,0,3,2] row_mask:0xf bank_mask:0xf bound_ctrl:1
	v_xor_b32_e32 v198, v181, v8
	v_add_f32_dpp v12, v12, v199 quad_perm:[2,3,0,1] row_mask:0xf bank_mask:0xf bound_ctrl:1
	v_xor_b32_e32 v199, v189, v197
	v_pk_add_f32 v[206:207], v[206:207], v[206:207] op_sel:[0,1] op_sel_hi:[1,0] neg_lo:[0,1] neg_hi:[0,1]
	v_add_f32_dpp v8, v8, v198 quad_perm:[1,0,3,2] row_mask:0xf bank_mask:0xf bound_ctrl:1
	v_xor_b32_e32 v198, v181, v6
	v_add_f32_dpp v197, v197, v199 quad_perm:[2,3,0,1] row_mask:0xf bank_mask:0xf bound_ctrl:1
	v_xor_b32_e32 v199, v189, v10
	v_add_f32_dpp v6, v6, v198 quad_perm:[1,0,3,2] row_mask:0xf bank_mask:0xf bound_ctrl:1
	v_xor_b32_e32 v198, v181, v206
	v_add_f32_dpp v199, v10, v199 quad_perm:[2,3,0,1] row_mask:0xf bank_mask:0xf bound_ctrl:1
	v_xor_b32_e32 v10, v189, v8
	v_add_f32_dpp v198, v206, v198 quad_perm:[1,0,3,2] row_mask:0xf bank_mask:0xf bound_ctrl:1
	s_nop 0
	v_add_f32_dpp v200, v8, v10 quad_perm:[2,3,0,1] row_mask:0xf bank_mask:0xf bound_ctrl:1
	v_xor_b32_e32 v8, v189, v6
	v_max_f32_e64 v10, |v194|, |v195|
	s_nop 0
	v_add_f32_dpp v201, v6, v8 quad_perm:[2,3,0,1] row_mask:0xf bank_mask:0xf bound_ctrl:1
	v_xor_b32_e32 v6, v189, v198
	v_max_f32_e64 v8, |v11|, |v13|
	s_nop 0
	v_add_f32_dpp v198, v198, v6 quad_perm:[2,3,0,1] row_mask:0xf bank_mask:0xf bound_ctrl:1
	v_xor_b32_e32 v6, v189, v186
	s_nop 1
	v_add_f32_dpp v186, v186, v6 quad_perm:[2,3,0,1] row_mask:0xf bank_mask:0xf bound_ctrl:1
	v_max_f32_e64 v6, |v7|, |v9|
	v_max3_f32 v6, v216, v6, v8
	v_max_f32_e64 v8, |v187|, |v193|
	v_max3_f32 v6, v6, v8, v10
	v_max_f32_e64 v8, |v196|, |v12|
	v_max_f32_e64 v10, |v197|, |v199|
	v_max3_f32 v6, v6, v8, v10
	v_max_f32_e64 v8, |v200|, |v201|
	v_max_f32_e64 v10, |v198|, |v186|
	v_max3_f32 v216, v6, v8, v10
	v_cvt_pk_bf16_f32 v6, v7, v9
	v_cvt_pk_bf16_f32 v7, v11, v13
	v_cvt_pk_bf16_f32 v8, v187, v193
	v_cvt_pk_bf16_f32 v9, v194, v195
	v_cvt_pk_bf16_f32 v10, v196, v12
	v_cvt_pk_bf16_f32 v11, v197, v199
	v_cvt_pk_bf16_f32 v12, v200, v201
	v_cvt_pk_bf16_f32 v13, v198, v186
	v_and_b32_e32 v187, 0xffff0000, v25
	v_and_b32_e32 v186, 0xffff0000, v17
	v_lshlrev_b32_e32 v195, 16, v22
	v_lshlrev_b32_e32 v194, 16, v14
	v_and_b32_e32 v197, 0xffff0000, v22
	v_and_b32_e32 v196, 0xffff0000, v14
	v_lshlrev_b32_e32 v199, 16, v23
	v_lshlrev_b32_e32 v198, 16, v15
	v_and_b32_e32 v23, 0xffff0000, v23
	v_and_b32_e32 v22, 0xffff0000, v15
	v_lshlrev_b32_e32 v15, 16, v24
	v_lshlrev_b32_e32 v14, 16, v16
	v_and_b32_e32 v201, 0xffff0000, v24
	v_and_b32_e32 v200, 0xffff0000, v16
	v_lshlrev_b32_e32 v25, 16, v25
	v_lshlrev_b32_e32 v24, 16, v17
	v_pk_add_f32 v[16:17], v[194:195], v[196:197]
	v_pk_add_f32 v[202:203], v[198:199], v[22:23]
	v_pk_add_f32 v[204:205], v[14:15], v[200:201]
	v_pk_add_f32 v[206:207], v[24:25], v[186:187]
	v_pk_add_f32 v[194:195], v[194:195], v[196:197] neg_lo:[0,1] neg_hi:[0,1]
	v_pk_add_f32 v[22:23], v[198:199], v[22:23] neg_lo:[0,1] neg_hi:[0,1]
	v_pk_add_f32 v[14:15], v[14:15], v[200:201] neg_lo:[0,1] neg_hi:[0,1]
	v_pk_add_f32 v[24:25], v[24:25], v[186:187] neg_lo:[0,1] neg_hi:[0,1]
	v_pk_add_f32 v[208:209], v[16:17], v[202:203] neg_lo:[0,1] neg_hi:[0,1]
	v_pk_add_f32 v[16:17], v[16:17], v[202:203]
	v_pk_add_f32 v[202:203], v[204:205], v[206:207]
	v_pk_add_f32 v[186:187], v[194:195], v[22:23] neg_lo:[0,1] neg_hi:[0,1]
	v_pk_add_f32 v[196:197], v[14:15], v[24:25] neg_lo:[0,1] neg_hi:[0,1]
	v_pk_add_f32 v[22:23], v[194:195], v[22:23]
	v_pk_add_f32 v[14:15], v[14:15], v[24:25]
	v_pk_add_f32 v[210:211], v[204:205], v[206:207] neg_lo:[0,1] neg_hi:[0,1]
	v_pk_add_f32 v[204:205], v[16:17], v[202:203]
	v_pk_add_f32 v[24:25], v[22:23], v[14:15]
	v_pk_add_f32 v[14:15], v[22:23], v[14:15] neg_lo:[0,1] neg_hi:[0,1]
	v_pk_add_f32 v[16:17], v[16:17], v[202:203] neg_lo:[0,1] neg_hi:[0,1]
	v_pk_add_f32 v[202:203], v[208:209], v[210:211]
	v_pk_add_f32 v[206:207], v[208:209], v[210:211] neg_lo:[0,1] neg_hi:[0,1]
	v_pk_add_f32 v[22:23], v[186:187], v[196:197]
	v_pk_add_f32 v[186:187], v[186:187], v[196:197] neg_lo:[0,1] neg_hi:[0,1]
	v_pk_add_f32 v[194:195], v[204:205], v[204:205] op_sel:[0,1] op_sel_hi:[1,0]
	v_pk_add_f32 v[210:211], v[14:15], v[14:15] op_sel:[0,1] op_sel_hi:[1,0]
	v_pk_add_f32 v[14:15], v[14:15], v[14:15] op_sel:[0,1] op_sel_hi:[1,0] neg_lo:[0,1] neg_hi:[0,1]
	v_pk_add_f32 v[198:199], v[24:25], v[24:25] op_sel:[0,1] op_sel_hi:[1,0]
	v_pk_add_f32 v[208:209], v[16:17], v[16:17] op_sel:[0,1] op_sel_hi:[1,0]
	v_pk_add_f32 v[16:17], v[16:17], v[16:17] op_sel:[0,1] op_sel_hi:[1,0] neg_lo:[0,1] neg_hi:[0,1]
	v_pk_add_f32 v[214:215], v[186:187], v[186:187] op_sel:[0,1] op_sel_hi:[1,0]
	v_pk_add_f32 v[186:187], v[186:187], v[186:187] op_sel:[0,1] op_sel_hi:[1,0] neg_lo:[0,1] neg_hi:[0,1]
	v_xor_b32_e32 v15, v181, v194
	v_pk_add_f32 v[196:197], v[204:205], v[204:205] op_sel:[0,1] op_sel_hi:[1,0] neg_lo:[0,1] neg_hi:[0,1]
	v_pk_add_f32 v[200:201], v[202:203], v[202:203] op_sel:[0,1] op_sel_hi:[1,0]
	v_pk_add_f32 v[204:205], v[22:23], v[22:23] op_sel:[0,1] op_sel_hi:[1,0]
	v_pk_add_f32 v[22:23], v[22:23], v[22:23] op_sel:[0,1] op_sel_hi:[1,0] neg_lo:[0,1] neg_hi:[0,1]
	v_add_f32_dpp v15, v194, v15 quad_perm:[1,0,3,2] row_mask:0xf bank_mask:0xf bound_ctrl:1
	v_xor_b32_e32 v17, v181, v198
	v_xor_b32_e32 v199, v181, v186
	v_pk_add_f32 v[24:25], v[24:25], v[24:25] op_sel:[0,1] op_sel_hi:[1,0] neg_lo:[0,1] neg_hi:[0,1]
	v_add_f32_dpp v17, v198, v17 quad_perm:[1,0,3,2] row_mask:0xf bank_mask:0xf bound_ctrl:1
	v_xor_b32_e32 v23, v181, v200
	v_add_f32_dpp v186, v186, v199 quad_perm:[1,0,3,2] row_mask:0xf bank_mask:0xf bound_ctrl:1
	v_xor_b32_e32 v199, v189, v15
	v_add_f32_dpp v23, v200, v23 quad_perm:[1,0,3,2] row_mask:0xf bank_mask:0xf bound_ctrl:1
	v_xor_b32_e32 v25, v181, v204
	v_add_f32_dpp v15, v15, v199 quad_perm:[2,3,0,1] row_mask:0xf bank_mask:0xf bound_ctrl:1
	v_xor_b32_e32 v199, v189, v17
	v_add_f32_dpp v25, v204, v25 quad_perm:[1,0,3,2] row_mask:0xf bank_mask:0xf bound_ctrl:1
	v_xor_b32_e32 v187, v181, v208
	v_add_f32_dpp v17, v17, v199 quad_perm:[2,3,0,1] row_mask:0xf bank_mask:0xf bound_ctrl:1
	v_xor_b32_e32 v199, v189, v23
	v_pk_add_f32 v[212:213], v[206:207], v[206:207] op_sel:[0,1] op_sel_hi:[1,0]
	v_add_f32_dpp v187, v208, v187 quad_perm:[1,0,3,2] row_mask:0xf bank_mask:0xf bound_ctrl:1
	v_xor_b32_e32 v193, v181, v210
	v_add_f32_dpp v23, v23, v199 quad_perm:[2,3,0,1] row_mask:0xf bank_mask:0xf bound_ctrl:1
	v_xor_b32_e32 v199, v189, v25
	v_add_f32_dpp v193, v210, v193 quad_perm:[1,0,3,2] row_mask:0xf bank_mask:0xf bound_ctrl:1
	v_xor_b32_e32 v194, v181, v212
	v_add_f32_dpp v25, v25, v199 quad_perm:[2,3,0,1] row_mask:0xf bank_mask:0xf bound_ctrl:1
	v_xor_b32_e32 v199, v189, v187
	v_add_f32_dpp v194, v212, v194 quad_perm:[1,0,3,2] row_mask:0xf bank_mask:0xf bound_ctrl:1
	v_xor_b32_e32 v195, v181, v214
	v_add_f32_dpp v187, v187, v199 quad_perm:[2,3,0,1] row_mask:0xf bank_mask:0xf bound_ctrl:1
	v_xor_b32_e32 v199, v189, v193
	v_add_f32_dpp v195, v214, v195 quad_perm:[1,0,3,2] row_mask:0xf bank_mask:0xf bound_ctrl:1
	v_xor_b32_e32 v197, v181, v196
	v_add_f32_dpp v193, v193, v199 quad_perm:[2,3,0,1] row_mask:0xf bank_mask:0xf bound_ctrl:1
	v_xor_b32_e32 v199, v189, v194
	v_pk_add_f32 v[202:203], v[202:203], v[202:203] op_sel:[0,1] op_sel_hi:[1,0] neg_lo:[0,1] neg_hi:[0,1]
	v_add_f32_dpp v196, v196, v197 quad_perm:[1,0,3,2] row_mask:0xf bank_mask:0xf bound_ctrl:1
	v_xor_b32_e32 v197, v181, v24
	v_add_f32_dpp v194, v194, v199 quad_perm:[2,3,0,1] row_mask:0xf bank_mask:0xf bound_ctrl:1
	v_xor_b32_e32 v199, v189, v195
	v_add_f32_dpp v24, v24, v197 quad_perm:[1,0,3,2] row_mask:0xf bank_mask:0xf bound_ctrl:1
	v_xor_b32_e32 v197, v181, v202
	v_add_f32_dpp v195, v195, v199 quad_perm:[2,3,0,1] row_mask:0xf bank_mask:0xf bound_ctrl:1
	v_xor_b32_e32 v199, v189, v196
	v_add_f32_dpp v197, v202, v197 quad_perm:[1,0,3,2] row_mask:0xf bank_mask:0xf bound_ctrl:1
	v_xor_b32_e32 v198, v181, v22
	v_add_f32_dpp v196, v196, v199 quad_perm:[2,3,0,1] row_mask:0xf bank_mask:0xf bound_ctrl:1
	v_xor_b32_e32 v199, v189, v24
	v_add_f32_dpp v22, v22, v198 quad_perm:[1,0,3,2] row_mask:0xf bank_mask:0xf bound_ctrl:1
	v_xor_b32_e32 v198, v181, v16
	v_add_f32_dpp v24, v24, v199 quad_perm:[2,3,0,1] row_mask:0xf bank_mask:0xf bound_ctrl:1
	v_xor_b32_e32 v199, v189, v197
	v_pk_add_f32 v[206:207], v[206:207], v[206:207] op_sel:[0,1] op_sel_hi:[1,0] neg_lo:[0,1] neg_hi:[0,1]
	v_add_f32_dpp v16, v16, v198 quad_perm:[1,0,3,2] row_mask:0xf bank_mask:0xf bound_ctrl:1
	v_xor_b32_e32 v198, v181, v14
	v_add_f32_dpp v197, v197, v199 quad_perm:[2,3,0,1] row_mask:0xf bank_mask:0xf bound_ctrl:1
	v_xor_b32_e32 v199, v189, v22
	v_add_f32_dpp v14, v14, v198 quad_perm:[1,0,3,2] row_mask:0xf bank_mask:0xf bound_ctrl:1
	v_xor_b32_e32 v198, v181, v206
	v_add_f32_dpp v199, v22, v199 quad_perm:[2,3,0,1] row_mask:0xf bank_mask:0xf bound_ctrl:1
	v_xor_b32_e32 v22, v189, v16
	v_add_f32_dpp v198, v206, v198 quad_perm:[1,0,3,2] row_mask:0xf bank_mask:0xf bound_ctrl:1
	s_nop 0
	v_add_f32_dpp v200, v16, v22 quad_perm:[2,3,0,1] row_mask:0xf bank_mask:0xf bound_ctrl:1
	v_xor_b32_e32 v16, v189, v14
	v_max_f32_e64 v22, |v194|, |v195|
	s_nop 0
	v_add_f32_dpp v201, v14, v16 quad_perm:[2,3,0,1] row_mask:0xf bank_mask:0xf bound_ctrl:1
	v_xor_b32_e32 v14, v189, v198
	v_max_f32_e64 v16, |v23|, |v25|
	s_nop 0
	v_add_f32_dpp v198, v198, v14 quad_perm:[2,3,0,1] row_mask:0xf bank_mask:0xf bound_ctrl:1
	v_xor_b32_e32 v14, v189, v186
	s_nop 1
	v_add_f32_dpp v186, v186, v14 quad_perm:[2,3,0,1] row_mask:0xf bank_mask:0xf bound_ctrl:1
	v_max_f32_e64 v14, |v15|, |v17|
	v_max3_f32 v14, v216, v14, v16
	v_max_f32_e64 v16, |v187|, |v193|
	v_max3_f32 v14, v14, v16, v22
	v_max_f32_e64 v16, |v196|, |v24|
	v_max_f32_e64 v22, |v197|, |v199|
	v_max3_f32 v14, v14, v16, v22
	v_max_f32_e64 v16, |v200|, |v201|
	v_max_f32_e64 v22, |v198|, |v186|
	v_max3_f32 v216, v14, v16, v22
	v_cvt_pk_bf16_f32 v14, v15, v17
	v_cvt_pk_bf16_f32 v15, v23, v25
	v_cvt_pk_bf16_f32 v16, v187, v193
	v_cvt_pk_bf16_f32 v17, v194, v195
	v_cvt_pk_bf16_f32 v22, v196, v24
	v_cvt_pk_bf16_f32 v23, v197, v199
	v_cvt_pk_bf16_f32 v24, v200, v201
	v_cvt_pk_bf16_f32 v25, v198, v186
	v_and_b32_e32 v187, 0xffff0000, v29
	v_and_b32_e32 v186, 0xffff0000, v21
	v_lshlrev_b32_e32 v195, 16, v26
	v_lshlrev_b32_e32 v194, 16, v18
	v_and_b32_e32 v197, 0xffff0000, v26
	v_and_b32_e32 v196, 0xffff0000, v18
	v_lshlrev_b32_e32 v199, 16, v27
	v_lshlrev_b32_e32 v198, 16, v19
	v_and_b32_e32 v27, 0xffff0000, v27
	v_and_b32_e32 v26, 0xffff0000, v19
	v_lshlrev_b32_e32 v19, 16, v28
	v_lshlrev_b32_e32 v18, 16, v20
	v_and_b32_e32 v201, 0xffff0000, v28
	v_and_b32_e32 v200, 0xffff0000, v20
	v_lshlrev_b32_e32 v29, 16, v29
	v_lshlrev_b32_e32 v28, 16, v21
	v_pk_add_f32 v[20:21], v[194:195], v[196:197]
	v_pk_add_f32 v[202:203], v[198:199], v[26:27]
	v_pk_add_f32 v[204:205], v[18:19], v[200:201]
	v_pk_add_f32 v[206:207], v[28:29], v[186:187]
	v_pk_add_f32 v[194:195], v[194:195], v[196:197] neg_lo:[0,1] neg_hi:[0,1]
	v_pk_add_f32 v[26:27], v[198:199], v[26:27] neg_lo:[0,1] neg_hi:[0,1]
	v_pk_add_f32 v[18:19], v[18:19], v[200:201] neg_lo:[0,1] neg_hi:[0,1]
	v_pk_add_f32 v[28:29], v[28:29], v[186:187] neg_lo:[0,1] neg_hi:[0,1]
	v_pk_add_f32 v[208:209], v[20:21], v[202:203] neg_lo:[0,1] neg_hi:[0,1]
	v_pk_add_f32 v[20:21], v[20:21], v[202:203]
	v_pk_add_f32 v[202:203], v[204:205], v[206:207]
	v_pk_add_f32 v[186:187], v[194:195], v[26:27] neg_lo:[0,1] neg_hi:[0,1]
	v_pk_add_f32 v[196:197], v[18:19], v[28:29] neg_lo:[0,1] neg_hi:[0,1]
	v_pk_add_f32 v[26:27], v[194:195], v[26:27]
	v_pk_add_f32 v[18:19], v[18:19], v[28:29]
	v_pk_add_f32 v[210:211], v[204:205], v[206:207] neg_lo:[0,1] neg_hi:[0,1]
	v_pk_add_f32 v[204:205], v[20:21], v[202:203]
	v_pk_add_f32 v[28:29], v[26:27], v[18:19]
	v_pk_add_f32 v[18:19], v[26:27], v[18:19] neg_lo:[0,1] neg_hi:[0,1]
	v_pk_add_f32 v[20:21], v[20:21], v[202:203] neg_lo:[0,1] neg_hi:[0,1]
	v_pk_add_f32 v[202:203], v[208:209], v[210:211]
	v_pk_add_f32 v[206:207], v[208:209], v[210:211] neg_lo:[0,1] neg_hi:[0,1]
	v_pk_add_f32 v[26:27], v[186:187], v[196:197]
	v_pk_add_f32 v[186:187], v[186:187], v[196:197] neg_lo:[0,1] neg_hi:[0,1]
	v_pk_add_f32 v[194:195], v[204:205], v[204:205] op_sel:[0,1] op_sel_hi:[1,0]
	v_pk_add_f32 v[210:211], v[18:19], v[18:19] op_sel:[0,1] op_sel_hi:[1,0]
	v_pk_add_f32 v[18:19], v[18:19], v[18:19] op_sel:[0,1] op_sel_hi:[1,0] neg_lo:[0,1] neg_hi:[0,1]
	v_pk_add_f32 v[198:199], v[28:29], v[28:29] op_sel:[0,1] op_sel_hi:[1,0]
	v_pk_add_f32 v[208:209], v[20:21], v[20:21] op_sel:[0,1] op_sel_hi:[1,0]
	v_pk_add_f32 v[20:21], v[20:21], v[20:21] op_sel:[0,1] op_sel_hi:[1,0] neg_lo:[0,1] neg_hi:[0,1]
	v_pk_add_f32 v[214:215], v[186:187], v[186:187] op_sel:[0,1] op_sel_hi:[1,0]
	v_pk_add_f32 v[186:187], v[186:187], v[186:187] op_sel:[0,1] op_sel_hi:[1,0] neg_lo:[0,1] neg_hi:[0,1]
	v_xor_b32_e32 v19, v181, v194
	v_pk_add_f32 v[196:197], v[204:205], v[204:205] op_sel:[0,1] op_sel_hi:[1,0] neg_lo:[0,1] neg_hi:[0,1]
	v_pk_add_f32 v[200:201], v[202:203], v[202:203] op_sel:[0,1] op_sel_hi:[1,0]
	v_pk_add_f32 v[204:205], v[26:27], v[26:27] op_sel:[0,1] op_sel_hi:[1,0]
	v_pk_add_f32 v[26:27], v[26:27], v[26:27] op_sel:[0,1] op_sel_hi:[1,0] neg_lo:[0,1] neg_hi:[0,1]
	v_add_f32_dpp v19, v194, v19 quad_perm:[1,0,3,2] row_mask:0xf bank_mask:0xf bound_ctrl:1
	v_xor_b32_e32 v21, v181, v198
	v_xor_b32_e32 v199, v181, v186
	v_pk_add_f32 v[28:29], v[28:29], v[28:29] op_sel:[0,1] op_sel_hi:[1,0] neg_lo:[0,1] neg_hi:[0,1]
	v_add_f32_dpp v21, v198, v21 quad_perm:[1,0,3,2] row_mask:0xf bank_mask:0xf bound_ctrl:1
	v_xor_b32_e32 v27, v181, v200
	v_add_f32_dpp v186, v186, v199 quad_perm:[1,0,3,2] row_mask:0xf bank_mask:0xf bound_ctrl:1
	v_xor_b32_e32 v199, v189, v19
	v_add_f32_dpp v27, v200, v27 quad_perm:[1,0,3,2] row_mask:0xf bank_mask:0xf bound_ctrl:1
	v_xor_b32_e32 v29, v181, v204
	v_add_f32_dpp v19, v19, v199 quad_perm:[2,3,0,1] row_mask:0xf bank_mask:0xf bound_ctrl:1
	v_xor_b32_e32 v199, v189, v21
	v_add_f32_dpp v29, v204, v29 quad_perm:[1,0,3,2] row_mask:0xf bank_mask:0xf bound_ctrl:1
	v_xor_b32_e32 v187, v181, v208
	v_add_f32_dpp v21, v21, v199 quad_perm:[2,3,0,1] row_mask:0xf bank_mask:0xf bound_ctrl:1
	v_xor_b32_e32 v199, v189, v27
	v_pk_add_f32 v[212:213], v[206:207], v[206:207] op_sel:[0,1] op_sel_hi:[1,0]
	v_add_f32_dpp v187, v208, v187 quad_perm:[1,0,3,2] row_mask:0xf bank_mask:0xf bound_ctrl:1
	v_xor_b32_e32 v193, v181, v210
	v_add_f32_dpp v27, v27, v199 quad_perm:[2,3,0,1] row_mask:0xf bank_mask:0xf bound_ctrl:1
	v_xor_b32_e32 v199, v189, v29
	v_add_f32_dpp v193, v210, v193 quad_perm:[1,0,3,2] row_mask:0xf bank_mask:0xf bound_ctrl:1
	v_xor_b32_e32 v194, v181, v212
	v_add_f32_dpp v29, v29, v199 quad_perm:[2,3,0,1] row_mask:0xf bank_mask:0xf bound_ctrl:1
	v_xor_b32_e32 v199, v189, v187
	v_add_f32_dpp v194, v212, v194 quad_perm:[1,0,3,2] row_mask:0xf bank_mask:0xf bound_ctrl:1
	v_xor_b32_e32 v195, v181, v214
	v_add_f32_dpp v187, v187, v199 quad_perm:[2,3,0,1] row_mask:0xf bank_mask:0xf bound_ctrl:1
	v_xor_b32_e32 v199, v189, v193
	v_add_f32_dpp v195, v214, v195 quad_perm:[1,0,3,2] row_mask:0xf bank_mask:0xf bound_ctrl:1
	v_xor_b32_e32 v197, v181, v196
	v_add_f32_dpp v193, v193, v199 quad_perm:[2,3,0,1] row_mask:0xf bank_mask:0xf bound_ctrl:1
	v_xor_b32_e32 v199, v189, v194
	v_pk_add_f32 v[202:203], v[202:203], v[202:203] op_sel:[0,1] op_sel_hi:[1,0] neg_lo:[0,1] neg_hi:[0,1]
	v_add_f32_dpp v196, v196, v197 quad_perm:[1,0,3,2] row_mask:0xf bank_mask:0xf bound_ctrl:1
	v_xor_b32_e32 v197, v181, v28
	v_add_f32_dpp v194, v194, v199 quad_perm:[2,3,0,1] row_mask:0xf bank_mask:0xf bound_ctrl:1
	v_xor_b32_e32 v199, v189, v195
	v_add_f32_dpp v28, v28, v197 quad_perm:[1,0,3,2] row_mask:0xf bank_mask:0xf bound_ctrl:1
	v_xor_b32_e32 v197, v181, v202
	v_add_f32_dpp v195, v195, v199 quad_perm:[2,3,0,1] row_mask:0xf bank_mask:0xf bound_ctrl:1
	v_xor_b32_e32 v199, v189, v196
	v_add_f32_dpp v197, v202, v197 quad_perm:[1,0,3,2] row_mask:0xf bank_mask:0xf bound_ctrl:1
	v_xor_b32_e32 v198, v181, v26
	v_add_f32_dpp v196, v196, v199 quad_perm:[2,3,0,1] row_mask:0xf bank_mask:0xf bound_ctrl:1
	v_xor_b32_e32 v199, v189, v28
	v_add_f32_dpp v26, v26, v198 quad_perm:[1,0,3,2] row_mask:0xf bank_mask:0xf bound_ctrl:1
	v_xor_b32_e32 v198, v181, v20
	v_add_f32_dpp v28, v28, v199 quad_perm:[2,3,0,1] row_mask:0xf bank_mask:0xf bound_ctrl:1
	v_xor_b32_e32 v199, v189, v197
	v_pk_add_f32 v[206:207], v[206:207], v[206:207] op_sel:[0,1] op_sel_hi:[1,0] neg_lo:[0,1] neg_hi:[0,1]
	v_add_f32_dpp v20, v20, v198 quad_perm:[1,0,3,2] row_mask:0xf bank_mask:0xf bound_ctrl:1
	v_xor_b32_e32 v198, v181, v18
	v_add_f32_dpp v197, v197, v199 quad_perm:[2,3,0,1] row_mask:0xf bank_mask:0xf bound_ctrl:1
	v_xor_b32_e32 v199, v189, v26
	v_add_f32_dpp v18, v18, v198 quad_perm:[1,0,3,2] row_mask:0xf bank_mask:0xf bound_ctrl:1
	v_xor_b32_e32 v198, v181, v206
	v_add_f32_dpp v199, v26, v199 quad_perm:[2,3,0,1] row_mask:0xf bank_mask:0xf bound_ctrl:1
	v_xor_b32_e32 v26, v189, v20
	v_add_f32_dpp v198, v206, v198 quad_perm:[1,0,3,2] row_mask:0xf bank_mask:0xf bound_ctrl:1
	s_nop 0
	v_add_f32_dpp v200, v20, v26 quad_perm:[2,3,0,1] row_mask:0xf bank_mask:0xf bound_ctrl:1
	v_xor_b32_e32 v20, v189, v18
	v_max_f32_e64 v26, |v194|, |v195|
	s_nop 0
	v_add_f32_dpp v201, v18, v20 quad_perm:[2,3,0,1] row_mask:0xf bank_mask:0xf bound_ctrl:1
	v_xor_b32_e32 v18, v189, v198
	v_max_f32_e64 v20, |v27|, |v29|
	s_nop 0
	v_add_f32_dpp v198, v198, v18 quad_perm:[2,3,0,1] row_mask:0xf bank_mask:0xf bound_ctrl:1
	v_xor_b32_e32 v18, v189, v186
	s_nop 1
	v_add_f32_dpp v186, v186, v18 quad_perm:[2,3,0,1] row_mask:0xf bank_mask:0xf bound_ctrl:1
	v_max_f32_e64 v18, |v19|, |v21|
	v_max3_f32 v18, v216, v18, v20
	v_max_f32_e64 v20, |v187|, |v193|
	v_max3_f32 v18, v18, v20, v26
	v_max_f32_e64 v20, |v196|, |v28|
	v_max_f32_e64 v26, |v197|, |v199|
	v_max3_f32 v18, v18, v20, v26
	v_max_f32_e64 v20, |v200|, |v201|
	v_max_f32_e64 v26, |v198|, |v186|
	v_max3_f32 v216, v18, v20, v26
	v_cvt_pk_bf16_f32 v18, v19, v21
	v_cvt_pk_bf16_f32 v19, v27, v29
	v_cvt_pk_bf16_f32 v20, v187, v193
	v_cvt_pk_bf16_f32 v21, v194, v195
	v_cvt_pk_bf16_f32 v26, v196, v28
	v_cvt_pk_bf16_f32 v27, v197, v199
	v_cvt_pk_bf16_f32 v28, v200, v201
	v_cvt_pk_bf16_f32 v29, v198, v186
	v_and_b32_e32 v187, 0xffff0000, v37
	v_and_b32_e32 v186, 0xffff0000, v33
	v_lshlrev_b32_e32 v195, 16, v34
	v_lshlrev_b32_e32 v194, 16, v30
	v_and_b32_e32 v197, 0xffff0000, v34
	v_and_b32_e32 v196, 0xffff0000, v30
	v_lshlrev_b32_e32 v199, 16, v35
	v_lshlrev_b32_e32 v198, 16, v31
	v_and_b32_e32 v35, 0xffff0000, v35
	v_and_b32_e32 v34, 0xffff0000, v31
	v_lshlrev_b32_e32 v31, 16, v36
	v_lshlrev_b32_e32 v30, 16, v32
	v_and_b32_e32 v201, 0xffff0000, v36
	v_and_b32_e32 v200, 0xffff0000, v32
	v_lshlrev_b32_e32 v37, 16, v37
	v_lshlrev_b32_e32 v36, 16, v33
	v_pk_add_f32 v[32:33], v[194:195], v[196:197]
	v_pk_add_f32 v[202:203], v[198:199], v[34:35]
	v_pk_add_f32 v[204:205], v[30:31], v[200:201]
	v_pk_add_f32 v[206:207], v[36:37], v[186:187]
	v_pk_add_f32 v[194:195], v[194:195], v[196:197] neg_lo:[0,1] neg_hi:[0,1]
	v_pk_add_f32 v[34:35], v[198:199], v[34:35] neg_lo:[0,1] neg_hi:[0,1]
	v_pk_add_f32 v[30:31], v[30:31], v[200:201] neg_lo:[0,1] neg_hi:[0,1]
	v_pk_add_f32 v[36:37], v[36:37], v[186:187] neg_lo:[0,1] neg_hi:[0,1]
	v_pk_add_f32 v[208:209], v[32:33], v[202:203] neg_lo:[0,1] neg_hi:[0,1]
	v_pk_add_f32 v[32:33], v[32:33], v[202:203]
	v_pk_add_f32 v[202:203], v[204:205], v[206:207]
	v_pk_add_f32 v[186:187], v[194:195], v[34:35] neg_lo:[0,1] neg_hi:[0,1]
	v_pk_add_f32 v[196:197], v[30:31], v[36:37] neg_lo:[0,1] neg_hi:[0,1]
	v_pk_add_f32 v[34:35], v[194:195], v[34:35]
	v_pk_add_f32 v[30:31], v[30:31], v[36:37]
	v_pk_add_f32 v[210:211], v[204:205], v[206:207] neg_lo:[0,1] neg_hi:[0,1]
	v_pk_add_f32 v[204:205], v[32:33], v[202:203]
	v_pk_add_f32 v[36:37], v[34:35], v[30:31]
	v_pk_add_f32 v[30:31], v[34:35], v[30:31] neg_lo:[0,1] neg_hi:[0,1]
	v_pk_add_f32 v[32:33], v[32:33], v[202:203] neg_lo:[0,1] neg_hi:[0,1]
	v_pk_add_f32 v[202:203], v[208:209], v[210:211]
	v_pk_add_f32 v[206:207], v[208:209], v[210:211] neg_lo:[0,1] neg_hi:[0,1]
	v_pk_add_f32 v[34:35], v[186:187], v[196:197]
	v_pk_add_f32 v[186:187], v[186:187], v[196:197] neg_lo:[0,1] neg_hi:[0,1]
	v_pk_add_f32 v[194:195], v[204:205], v[204:205] op_sel:[0,1] op_sel_hi:[1,0]
	v_pk_add_f32 v[210:211], v[30:31], v[30:31] op_sel:[0,1] op_sel_hi:[1,0]
	v_pk_add_f32 v[30:31], v[30:31], v[30:31] op_sel:[0,1] op_sel_hi:[1,0] neg_lo:[0,1] neg_hi:[0,1]
	v_pk_add_f32 v[198:199], v[36:37], v[36:37] op_sel:[0,1] op_sel_hi:[1,0]
	v_pk_add_f32 v[208:209], v[32:33], v[32:33] op_sel:[0,1] op_sel_hi:[1,0]
	v_pk_add_f32 v[32:33], v[32:33], v[32:33] op_sel:[0,1] op_sel_hi:[1,0] neg_lo:[0,1] neg_hi:[0,1]
	v_pk_add_f32 v[214:215], v[186:187], v[186:187] op_sel:[0,1] op_sel_hi:[1,0]
	v_pk_add_f32 v[186:187], v[186:187], v[186:187] op_sel:[0,1] op_sel_hi:[1,0] neg_lo:[0,1] neg_hi:[0,1]
	v_xor_b32_e32 v31, v181, v194
	v_pk_add_f32 v[196:197], v[204:205], v[204:205] op_sel:[0,1] op_sel_hi:[1,0] neg_lo:[0,1] neg_hi:[0,1]
	v_pk_add_f32 v[200:201], v[202:203], v[202:203] op_sel:[0,1] op_sel_hi:[1,0]
	v_pk_add_f32 v[204:205], v[34:35], v[34:35] op_sel:[0,1] op_sel_hi:[1,0]
	v_pk_add_f32 v[34:35], v[34:35], v[34:35] op_sel:[0,1] op_sel_hi:[1,0] neg_lo:[0,1] neg_hi:[0,1]
	v_add_f32_dpp v31, v194, v31 quad_perm:[1,0,3,2] row_mask:0xf bank_mask:0xf bound_ctrl:1
	v_xor_b32_e32 v33, v181, v198
	v_xor_b32_e32 v199, v181, v186
	v_pk_add_f32 v[36:37], v[36:37], v[36:37] op_sel:[0,1] op_sel_hi:[1,0] neg_lo:[0,1] neg_hi:[0,1]
	v_add_f32_dpp v33, v198, v33 quad_perm:[1,0,3,2] row_mask:0xf bank_mask:0xf bound_ctrl:1
	v_xor_b32_e32 v35, v181, v200
	v_add_f32_dpp v186, v186, v199 quad_perm:[1,0,3,2] row_mask:0xf bank_mask:0xf bound_ctrl:1
	v_xor_b32_e32 v199, v189, v31
	v_add_f32_dpp v35, v200, v35 quad_perm:[1,0,3,2] row_mask:0xf bank_mask:0xf bound_ctrl:1
	v_xor_b32_e32 v37, v181, v204
	v_add_f32_dpp v31, v31, v199 quad_perm:[2,3,0,1] row_mask:0xf bank_mask:0xf bound_ctrl:1
	v_xor_b32_e32 v199, v189, v33
	v_add_f32_dpp v37, v204, v37 quad_perm:[1,0,3,2] row_mask:0xf bank_mask:0xf bound_ctrl:1
	v_xor_b32_e32 v187, v181, v208
	v_add_f32_dpp v33, v33, v199 quad_perm:[2,3,0,1] row_mask:0xf bank_mask:0xf bound_ctrl:1
	v_xor_b32_e32 v199, v189, v35
	v_pk_add_f32 v[212:213], v[206:207], v[206:207] op_sel:[0,1] op_sel_hi:[1,0]
	v_add_f32_dpp v187, v208, v187 quad_perm:[1,0,3,2] row_mask:0xf bank_mask:0xf bound_ctrl:1
	v_xor_b32_e32 v193, v181, v210
	v_add_f32_dpp v35, v35, v199 quad_perm:[2,3,0,1] row_mask:0xf bank_mask:0xf bound_ctrl:1
	v_xor_b32_e32 v199, v189, v37
	v_add_f32_dpp v193, v210, v193 quad_perm:[1,0,3,2] row_mask:0xf bank_mask:0xf bound_ctrl:1
	v_xor_b32_e32 v194, v181, v212
	v_add_f32_dpp v37, v37, v199 quad_perm:[2,3,0,1] row_mask:0xf bank_mask:0xf bound_ctrl:1
	v_xor_b32_e32 v199, v189, v187
	v_add_f32_dpp v194, v212, v194 quad_perm:[1,0,3,2] row_mask:0xf bank_mask:0xf bound_ctrl:1
	v_xor_b32_e32 v195, v181, v214
	v_add_f32_dpp v187, v187, v199 quad_perm:[2,3,0,1] row_mask:0xf bank_mask:0xf bound_ctrl:1
	v_xor_b32_e32 v199, v189, v193
	v_add_f32_dpp v195, v214, v195 quad_perm:[1,0,3,2] row_mask:0xf bank_mask:0xf bound_ctrl:1
	v_xor_b32_e32 v197, v181, v196
	v_add_f32_dpp v193, v193, v199 quad_perm:[2,3,0,1] row_mask:0xf bank_mask:0xf bound_ctrl:1
	v_xor_b32_e32 v199, v189, v194
	v_pk_add_f32 v[202:203], v[202:203], v[202:203] op_sel:[0,1] op_sel_hi:[1,0] neg_lo:[0,1] neg_hi:[0,1]
	v_add_f32_dpp v196, v196, v197 quad_perm:[1,0,3,2] row_mask:0xf bank_mask:0xf bound_ctrl:1
	v_xor_b32_e32 v197, v181, v36
	v_add_f32_dpp v194, v194, v199 quad_perm:[2,3,0,1] row_mask:0xf bank_mask:0xf bound_ctrl:1
	v_xor_b32_e32 v199, v189, v195
	v_add_f32_dpp v36, v36, v197 quad_perm:[1,0,3,2] row_mask:0xf bank_mask:0xf bound_ctrl:1
	v_xor_b32_e32 v197, v181, v202
	v_add_f32_dpp v195, v195, v199 quad_perm:[2,3,0,1] row_mask:0xf bank_mask:0xf bound_ctrl:1
	v_xor_b32_e32 v199, v189, v196
	v_add_f32_dpp v197, v202, v197 quad_perm:[1,0,3,2] row_mask:0xf bank_mask:0xf bound_ctrl:1
	v_xor_b32_e32 v198, v181, v34
	v_add_f32_dpp v196, v196, v199 quad_perm:[2,3,0,1] row_mask:0xf bank_mask:0xf bound_ctrl:1
	v_xor_b32_e32 v199, v189, v36
	v_add_f32_dpp v34, v34, v198 quad_perm:[1,0,3,2] row_mask:0xf bank_mask:0xf bound_ctrl:1
	v_xor_b32_e32 v198, v181, v32
	v_add_f32_dpp v36, v36, v199 quad_perm:[2,3,0,1] row_mask:0xf bank_mask:0xf bound_ctrl:1
	v_xor_b32_e32 v199, v189, v197
	v_pk_add_f32 v[206:207], v[206:207], v[206:207] op_sel:[0,1] op_sel_hi:[1,0] neg_lo:[0,1] neg_hi:[0,1]
	v_add_f32_dpp v32, v32, v198 quad_perm:[1,0,3,2] row_mask:0xf bank_mask:0xf bound_ctrl:1
	v_xor_b32_e32 v198, v181, v30
	v_add_f32_dpp v197, v197, v199 quad_perm:[2,3,0,1] row_mask:0xf bank_mask:0xf bound_ctrl:1
	v_xor_b32_e32 v199, v189, v34
	v_add_f32_dpp v30, v30, v198 quad_perm:[1,0,3,2] row_mask:0xf bank_mask:0xf bound_ctrl:1
	v_xor_b32_e32 v198, v181, v206
	v_add_f32_dpp v199, v34, v199 quad_perm:[2,3,0,1] row_mask:0xf bank_mask:0xf bound_ctrl:1
	v_xor_b32_e32 v34, v189, v32
	v_add_f32_dpp v198, v206, v198 quad_perm:[1,0,3,2] row_mask:0xf bank_mask:0xf bound_ctrl:1
	s_nop 0
	v_add_f32_dpp v200, v32, v34 quad_perm:[2,3,0,1] row_mask:0xf bank_mask:0xf bound_ctrl:1
	v_xor_b32_e32 v32, v189, v30
	v_max_f32_e64 v34, |v194|, |v195|
	s_nop 0
	v_add_f32_dpp v201, v30, v32 quad_perm:[2,3,0,1] row_mask:0xf bank_mask:0xf bound_ctrl:1
	v_xor_b32_e32 v30, v189, v198
	v_max_f32_e64 v32, |v35|, |v37|
	s_nop 0
	v_add_f32_dpp v198, v198, v30 quad_perm:[2,3,0,1] row_mask:0xf bank_mask:0xf bound_ctrl:1
	v_xor_b32_e32 v30, v189, v186
	s_nop 1
	v_add_f32_dpp v186, v186, v30 quad_perm:[2,3,0,1] row_mask:0xf bank_mask:0xf bound_ctrl:1
	v_max_f32_e64 v30, |v31|, |v33|
	v_max3_f32 v30, v216, v30, v32
	v_max_f32_e64 v32, |v187|, |v193|
	v_max3_f32 v30, v30, v32, v34
	v_max_f32_e64 v32, |v196|, |v36|
	v_max_f32_e64 v34, |v197|, |v199|
	v_max3_f32 v30, v30, v32, v34
	v_max_f32_e64 v32, |v200|, |v201|
	v_max_f32_e64 v34, |v198|, |v186|
	v_max3_f32 v216, v30, v32, v34
	v_cvt_pk_bf16_f32 v30, v31, v33
	v_cvt_pk_bf16_f32 v31, v35, v37
	v_cvt_pk_bf16_f32 v32, v187, v193
	v_cvt_pk_bf16_f32 v33, v194, v195
	v_cvt_pk_bf16_f32 v34, v196, v36
	v_cvt_pk_bf16_f32 v35, v197, v199
	v_cvt_pk_bf16_f32 v36, v200, v201
	v_cvt_pk_bf16_f32 v37, v198, v186
	v_and_b32_e32 v187, 0xffff0000, v49
	v_and_b32_e32 v186, 0xffff0000, v41
	v_lshlrev_b32_e32 v195, 16, v46
	v_lshlrev_b32_e32 v194, 16, v38
	v_and_b32_e32 v197, 0xffff0000, v46
	v_and_b32_e32 v196, 0xffff0000, v38
	v_lshlrev_b32_e32 v199, 16, v47
	v_lshlrev_b32_e32 v198, 16, v39
	v_and_b32_e32 v47, 0xffff0000, v47
	v_and_b32_e32 v46, 0xffff0000, v39
	v_lshlrev_b32_e32 v39, 16, v48
	v_lshlrev_b32_e32 v38, 16, v40
	v_and_b32_e32 v201, 0xffff0000, v48
	v_and_b32_e32 v200, 0xffff0000, v40
	v_lshlrev_b32_e32 v49, 16, v49
	v_lshlrev_b32_e32 v48, 16, v41
	v_pk_add_f32 v[40:41], v[194:195], v[196:197]
	v_pk_add_f32 v[202:203], v[198:199], v[46:47]
	v_pk_add_f32 v[204:205], v[38:39], v[200:201]
	v_pk_add_f32 v[206:207], v[48:49], v[186:187]
	v_pk_add_f32 v[194:195], v[194:195], v[196:197] neg_lo:[0,1] neg_hi:[0,1]
	v_pk_add_f32 v[46:47], v[198:199], v[46:47] neg_lo:[0,1] neg_hi:[0,1]
	v_pk_add_f32 v[38:39], v[38:39], v[200:201] neg_lo:[0,1] neg_hi:[0,1]
	v_pk_add_f32 v[48:49], v[48:49], v[186:187] neg_lo:[0,1] neg_hi:[0,1]
	v_pk_add_f32 v[208:209], v[40:41], v[202:203] neg_lo:[0,1] neg_hi:[0,1]
	v_pk_add_f32 v[40:41], v[40:41], v[202:203]
	v_pk_add_f32 v[202:203], v[204:205], v[206:207]
	v_pk_add_f32 v[186:187], v[194:195], v[46:47] neg_lo:[0,1] neg_hi:[0,1]
	v_pk_add_f32 v[196:197], v[38:39], v[48:49] neg_lo:[0,1] neg_hi:[0,1]
	v_pk_add_f32 v[46:47], v[194:195], v[46:47]
	v_pk_add_f32 v[38:39], v[38:39], v[48:49]
	v_pk_add_f32 v[210:211], v[204:205], v[206:207] neg_lo:[0,1] neg_hi:[0,1]
	v_pk_add_f32 v[204:205], v[40:41], v[202:203]
	v_pk_add_f32 v[48:49], v[46:47], v[38:39]
	v_pk_add_f32 v[38:39], v[46:47], v[38:39] neg_lo:[0,1] neg_hi:[0,1]
	v_pk_add_f32 v[40:41], v[40:41], v[202:203] neg_lo:[0,1] neg_hi:[0,1]
	v_pk_add_f32 v[202:203], v[208:209], v[210:211]
	v_pk_add_f32 v[206:207], v[208:209], v[210:211] neg_lo:[0,1] neg_hi:[0,1]
	v_pk_add_f32 v[46:47], v[186:187], v[196:197]
	v_pk_add_f32 v[186:187], v[186:187], v[196:197] neg_lo:[0,1] neg_hi:[0,1]
	v_pk_add_f32 v[194:195], v[204:205], v[204:205] op_sel:[0,1] op_sel_hi:[1,0]
	v_pk_add_f32 v[210:211], v[38:39], v[38:39] op_sel:[0,1] op_sel_hi:[1,0]
	v_pk_add_f32 v[38:39], v[38:39], v[38:39] op_sel:[0,1] op_sel_hi:[1,0] neg_lo:[0,1] neg_hi:[0,1]
	v_pk_add_f32 v[198:199], v[48:49], v[48:49] op_sel:[0,1] op_sel_hi:[1,0]
	v_pk_add_f32 v[208:209], v[40:41], v[40:41] op_sel:[0,1] op_sel_hi:[1,0]
	v_pk_add_f32 v[40:41], v[40:41], v[40:41] op_sel:[0,1] op_sel_hi:[1,0] neg_lo:[0,1] neg_hi:[0,1]
	v_pk_add_f32 v[214:215], v[186:187], v[186:187] op_sel:[0,1] op_sel_hi:[1,0]
	v_pk_add_f32 v[186:187], v[186:187], v[186:187] op_sel:[0,1] op_sel_hi:[1,0] neg_lo:[0,1] neg_hi:[0,1]
	v_xor_b32_e32 v39, v181, v194
	v_pk_add_f32 v[196:197], v[204:205], v[204:205] op_sel:[0,1] op_sel_hi:[1,0] neg_lo:[0,1] neg_hi:[0,1]
	v_pk_add_f32 v[200:201], v[202:203], v[202:203] op_sel:[0,1] op_sel_hi:[1,0]
	v_pk_add_f32 v[204:205], v[46:47], v[46:47] op_sel:[0,1] op_sel_hi:[1,0]
	v_pk_add_f32 v[46:47], v[46:47], v[46:47] op_sel:[0,1] op_sel_hi:[1,0] neg_lo:[0,1] neg_hi:[0,1]
	v_add_f32_dpp v39, v194, v39 quad_perm:[1,0,3,2] row_mask:0xf bank_mask:0xf bound_ctrl:1
	v_xor_b32_e32 v41, v181, v198
	v_xor_b32_e32 v199, v181, v186
	v_pk_add_f32 v[48:49], v[48:49], v[48:49] op_sel:[0,1] op_sel_hi:[1,0] neg_lo:[0,1] neg_hi:[0,1]
	v_add_f32_dpp v41, v198, v41 quad_perm:[1,0,3,2] row_mask:0xf bank_mask:0xf bound_ctrl:1
	v_xor_b32_e32 v47, v181, v200
	v_add_f32_dpp v186, v186, v199 quad_perm:[1,0,3,2] row_mask:0xf bank_mask:0xf bound_ctrl:1
	v_xor_b32_e32 v199, v189, v39
	v_add_f32_dpp v47, v200, v47 quad_perm:[1,0,3,2] row_mask:0xf bank_mask:0xf bound_ctrl:1
	v_xor_b32_e32 v49, v181, v204
	v_add_f32_dpp v39, v39, v199 quad_perm:[2,3,0,1] row_mask:0xf bank_mask:0xf bound_ctrl:1
	v_xor_b32_e32 v199, v189, v41
	v_add_f32_dpp v49, v204, v49 quad_perm:[1,0,3,2] row_mask:0xf bank_mask:0xf bound_ctrl:1
	v_xor_b32_e32 v187, v181, v208
	v_add_f32_dpp v41, v41, v199 quad_perm:[2,3,0,1] row_mask:0xf bank_mask:0xf bound_ctrl:1
	v_xor_b32_e32 v199, v189, v47
	v_pk_add_f32 v[212:213], v[206:207], v[206:207] op_sel:[0,1] op_sel_hi:[1,0]
	v_add_f32_dpp v187, v208, v187 quad_perm:[1,0,3,2] row_mask:0xf bank_mask:0xf bound_ctrl:1
	v_xor_b32_e32 v193, v181, v210
	v_add_f32_dpp v47, v47, v199 quad_perm:[2,3,0,1] row_mask:0xf bank_mask:0xf bound_ctrl:1
	v_xor_b32_e32 v199, v189, v49
	v_add_f32_dpp v193, v210, v193 quad_perm:[1,0,3,2] row_mask:0xf bank_mask:0xf bound_ctrl:1
	v_xor_b32_e32 v194, v181, v212
	v_add_f32_dpp v49, v49, v199 quad_perm:[2,3,0,1] row_mask:0xf bank_mask:0xf bound_ctrl:1
	v_xor_b32_e32 v199, v189, v187
	v_add_f32_dpp v194, v212, v194 quad_perm:[1,0,3,2] row_mask:0xf bank_mask:0xf bound_ctrl:1
	v_xor_b32_e32 v195, v181, v214
	v_add_f32_dpp v187, v187, v199 quad_perm:[2,3,0,1] row_mask:0xf bank_mask:0xf bound_ctrl:1
	v_xor_b32_e32 v199, v189, v193
	v_add_f32_dpp v195, v214, v195 quad_perm:[1,0,3,2] row_mask:0xf bank_mask:0xf bound_ctrl:1
	v_xor_b32_e32 v197, v181, v196
	v_add_f32_dpp v193, v193, v199 quad_perm:[2,3,0,1] row_mask:0xf bank_mask:0xf bound_ctrl:1
	v_xor_b32_e32 v199, v189, v194
	v_pk_add_f32 v[202:203], v[202:203], v[202:203] op_sel:[0,1] op_sel_hi:[1,0] neg_lo:[0,1] neg_hi:[0,1]
	v_add_f32_dpp v196, v196, v197 quad_perm:[1,0,3,2] row_mask:0xf bank_mask:0xf bound_ctrl:1
	v_xor_b32_e32 v197, v181, v48
	v_add_f32_dpp v194, v194, v199 quad_perm:[2,3,0,1] row_mask:0xf bank_mask:0xf bound_ctrl:1
	v_xor_b32_e32 v199, v189, v195
	v_add_f32_dpp v48, v48, v197 quad_perm:[1,0,3,2] row_mask:0xf bank_mask:0xf bound_ctrl:1
	v_xor_b32_e32 v197, v181, v202
	v_add_f32_dpp v195, v195, v199 quad_perm:[2,3,0,1] row_mask:0xf bank_mask:0xf bound_ctrl:1
	v_xor_b32_e32 v199, v189, v196
	v_add_f32_dpp v197, v202, v197 quad_perm:[1,0,3,2] row_mask:0xf bank_mask:0xf bound_ctrl:1
	v_xor_b32_e32 v198, v181, v46
	v_add_f32_dpp v196, v196, v199 quad_perm:[2,3,0,1] row_mask:0xf bank_mask:0xf bound_ctrl:1
	v_xor_b32_e32 v199, v189, v48
	v_add_f32_dpp v46, v46, v198 quad_perm:[1,0,3,2] row_mask:0xf bank_mask:0xf bound_ctrl:1
	v_xor_b32_e32 v198, v181, v40
	v_add_f32_dpp v48, v48, v199 quad_perm:[2,3,0,1] row_mask:0xf bank_mask:0xf bound_ctrl:1
	v_xor_b32_e32 v199, v189, v197
	v_pk_add_f32 v[206:207], v[206:207], v[206:207] op_sel:[0,1] op_sel_hi:[1,0] neg_lo:[0,1] neg_hi:[0,1]
	v_add_f32_dpp v40, v40, v198 quad_perm:[1,0,3,2] row_mask:0xf bank_mask:0xf bound_ctrl:1
	v_xor_b32_e32 v198, v181, v38
	v_add_f32_dpp v197, v197, v199 quad_perm:[2,3,0,1] row_mask:0xf bank_mask:0xf bound_ctrl:1
	v_xor_b32_e32 v199, v189, v46
	v_add_f32_dpp v38, v38, v198 quad_perm:[1,0,3,2] row_mask:0xf bank_mask:0xf bound_ctrl:1
	v_xor_b32_e32 v198, v181, v206
	v_add_f32_dpp v199, v46, v199 quad_perm:[2,3,0,1] row_mask:0xf bank_mask:0xf bound_ctrl:1
	v_xor_b32_e32 v46, v189, v40
	v_add_f32_dpp v198, v206, v198 quad_perm:[1,0,3,2] row_mask:0xf bank_mask:0xf bound_ctrl:1
	s_nop 0
	v_add_f32_dpp v200, v40, v46 quad_perm:[2,3,0,1] row_mask:0xf bank_mask:0xf bound_ctrl:1
	v_xor_b32_e32 v40, v189, v38
	v_max_f32_e64 v46, |v194|, |v195|
	s_nop 0
	v_add_f32_dpp v201, v38, v40 quad_perm:[2,3,0,1] row_mask:0xf bank_mask:0xf bound_ctrl:1
	v_xor_b32_e32 v38, v189, v198
	v_max_f32_e64 v40, |v47|, |v49|
	s_nop 0
	v_add_f32_dpp v198, v198, v38 quad_perm:[2,3,0,1] row_mask:0xf bank_mask:0xf bound_ctrl:1
	v_xor_b32_e32 v38, v189, v186
	s_nop 1
	v_add_f32_dpp v186, v186, v38 quad_perm:[2,3,0,1] row_mask:0xf bank_mask:0xf bound_ctrl:1
	v_max_f32_e64 v38, |v39|, |v41|
	v_max3_f32 v38, v216, v38, v40
	v_max_f32_e64 v40, |v187|, |v193|
	v_max3_f32 v38, v38, v40, v46
	v_max_f32_e64 v40, |v196|, |v48|
	v_max_f32_e64 v46, |v197|, |v199|
	v_max3_f32 v38, v38, v40, v46
	v_max_f32_e64 v40, |v200|, |v201|
	v_max_f32_e64 v46, |v198|, |v186|
	v_max3_f32 v216, v38, v40, v46
	v_cvt_pk_bf16_f32 v38, v39, v41
	v_cvt_pk_bf16_f32 v39, v47, v49
	v_cvt_pk_bf16_f32 v40, v187, v193
	v_cvt_pk_bf16_f32 v41, v194, v195
	v_cvt_pk_bf16_f32 v46, v196, v48
	v_cvt_pk_bf16_f32 v47, v197, v199
	v_cvt_pk_bf16_f32 v48, v200, v201
	v_cvt_pk_bf16_f32 v49, v198, v186
	v_and_b32_e32 v187, 0xffff0000, v57
	v_and_b32_e32 v186, 0xffff0000, v53
	v_lshlrev_b32_e32 v195, 16, v54
	v_lshlrev_b32_e32 v194, 16, v50
	v_and_b32_e32 v197, 0xffff0000, v54
	v_and_b32_e32 v196, 0xffff0000, v50
	v_lshlrev_b32_e32 v199, 16, v55
	v_lshlrev_b32_e32 v198, 16, v51
	v_and_b32_e32 v55, 0xffff0000, v55
	v_and_b32_e32 v54, 0xffff0000, v51
	v_lshlrev_b32_e32 v51, 16, v56
	v_lshlrev_b32_e32 v50, 16, v52
	v_and_b32_e32 v201, 0xffff0000, v56
	v_and_b32_e32 v200, 0xffff0000, v52
	v_lshlrev_b32_e32 v57, 16, v57
	v_lshlrev_b32_e32 v56, 16, v53
	v_pk_add_f32 v[52:53], v[194:195], v[196:197]
	v_pk_add_f32 v[202:203], v[198:199], v[54:55]
	v_pk_add_f32 v[204:205], v[50:51], v[200:201]
	v_pk_add_f32 v[206:207], v[56:57], v[186:187]
	v_pk_add_f32 v[194:195], v[194:195], v[196:197] neg_lo:[0,1] neg_hi:[0,1]
	v_pk_add_f32 v[54:55], v[198:199], v[54:55] neg_lo:[0,1] neg_hi:[0,1]
	v_pk_add_f32 v[50:51], v[50:51], v[200:201] neg_lo:[0,1] neg_hi:[0,1]
	v_pk_add_f32 v[56:57], v[56:57], v[186:187] neg_lo:[0,1] neg_hi:[0,1]
	v_pk_add_f32 v[208:209], v[52:53], v[202:203] neg_lo:[0,1] neg_hi:[0,1]
	v_pk_add_f32 v[52:53], v[52:53], v[202:203]
	v_pk_add_f32 v[202:203], v[204:205], v[206:207]
	v_pk_add_f32 v[186:187], v[194:195], v[54:55] neg_lo:[0,1] neg_hi:[0,1]
	v_pk_add_f32 v[196:197], v[50:51], v[56:57] neg_lo:[0,1] neg_hi:[0,1]
	v_pk_add_f32 v[54:55], v[194:195], v[54:55]
	v_pk_add_f32 v[50:51], v[50:51], v[56:57]
	v_pk_add_f32 v[210:211], v[204:205], v[206:207] neg_lo:[0,1] neg_hi:[0,1]
	v_pk_add_f32 v[204:205], v[52:53], v[202:203]
	v_pk_add_f32 v[56:57], v[54:55], v[50:51]
	v_pk_add_f32 v[50:51], v[54:55], v[50:51] neg_lo:[0,1] neg_hi:[0,1]
	v_pk_add_f32 v[52:53], v[52:53], v[202:203] neg_lo:[0,1] neg_hi:[0,1]
	v_pk_add_f32 v[202:203], v[208:209], v[210:211]
	v_pk_add_f32 v[206:207], v[208:209], v[210:211] neg_lo:[0,1] neg_hi:[0,1]
	v_pk_add_f32 v[54:55], v[186:187], v[196:197]
	v_pk_add_f32 v[186:187], v[186:187], v[196:197] neg_lo:[0,1] neg_hi:[0,1]
	v_pk_add_f32 v[194:195], v[204:205], v[204:205] op_sel:[0,1] op_sel_hi:[1,0]
	v_pk_add_f32 v[210:211], v[50:51], v[50:51] op_sel:[0,1] op_sel_hi:[1,0]
	v_pk_add_f32 v[50:51], v[50:51], v[50:51] op_sel:[0,1] op_sel_hi:[1,0] neg_lo:[0,1] neg_hi:[0,1]
	v_pk_add_f32 v[198:199], v[56:57], v[56:57] op_sel:[0,1] op_sel_hi:[1,0]
	v_pk_add_f32 v[208:209], v[52:53], v[52:53] op_sel:[0,1] op_sel_hi:[1,0]
	v_pk_add_f32 v[52:53], v[52:53], v[52:53] op_sel:[0,1] op_sel_hi:[1,0] neg_lo:[0,1] neg_hi:[0,1]
	v_pk_add_f32 v[214:215], v[186:187], v[186:187] op_sel:[0,1] op_sel_hi:[1,0]
	v_pk_add_f32 v[186:187], v[186:187], v[186:187] op_sel:[0,1] op_sel_hi:[1,0] neg_lo:[0,1] neg_hi:[0,1]
	v_xor_b32_e32 v51, v181, v194
	v_pk_add_f32 v[196:197], v[204:205], v[204:205] op_sel:[0,1] op_sel_hi:[1,0] neg_lo:[0,1] neg_hi:[0,1]
	v_pk_add_f32 v[200:201], v[202:203], v[202:203] op_sel:[0,1] op_sel_hi:[1,0]
	v_pk_add_f32 v[204:205], v[54:55], v[54:55] op_sel:[0,1] op_sel_hi:[1,0]
	v_pk_add_f32 v[54:55], v[54:55], v[54:55] op_sel:[0,1] op_sel_hi:[1,0] neg_lo:[0,1] neg_hi:[0,1]
	v_add_f32_dpp v51, v194, v51 quad_perm:[1,0,3,2] row_mask:0xf bank_mask:0xf bound_ctrl:1
	v_xor_b32_e32 v53, v181, v198
	v_xor_b32_e32 v199, v181, v186
	v_pk_add_f32 v[56:57], v[56:57], v[56:57] op_sel:[0,1] op_sel_hi:[1,0] neg_lo:[0,1] neg_hi:[0,1]
	v_add_f32_dpp v53, v198, v53 quad_perm:[1,0,3,2] row_mask:0xf bank_mask:0xf bound_ctrl:1
	v_xor_b32_e32 v55, v181, v200
	v_add_f32_dpp v186, v186, v199 quad_perm:[1,0,3,2] row_mask:0xf bank_mask:0xf bound_ctrl:1
	v_xor_b32_e32 v199, v189, v51
	v_add_f32_dpp v55, v200, v55 quad_perm:[1,0,3,2] row_mask:0xf bank_mask:0xf bound_ctrl:1
	v_xor_b32_e32 v57, v181, v204
	v_add_f32_dpp v51, v51, v199 quad_perm:[2,3,0,1] row_mask:0xf bank_mask:0xf bound_ctrl:1
	v_xor_b32_e32 v199, v189, v53
	v_add_f32_dpp v57, v204, v57 quad_perm:[1,0,3,2] row_mask:0xf bank_mask:0xf bound_ctrl:1
	v_xor_b32_e32 v187, v181, v208
	v_add_f32_dpp v53, v53, v199 quad_perm:[2,3,0,1] row_mask:0xf bank_mask:0xf bound_ctrl:1
	v_xor_b32_e32 v199, v189, v55
	v_pk_add_f32 v[212:213], v[206:207], v[206:207] op_sel:[0,1] op_sel_hi:[1,0]
	v_add_f32_dpp v187, v208, v187 quad_perm:[1,0,3,2] row_mask:0xf bank_mask:0xf bound_ctrl:1
	v_xor_b32_e32 v193, v181, v210
	v_add_f32_dpp v55, v55, v199 quad_perm:[2,3,0,1] row_mask:0xf bank_mask:0xf bound_ctrl:1
	v_xor_b32_e32 v199, v189, v57
	v_add_f32_dpp v193, v210, v193 quad_perm:[1,0,3,2] row_mask:0xf bank_mask:0xf bound_ctrl:1
	v_xor_b32_e32 v194, v181, v212
	v_add_f32_dpp v57, v57, v199 quad_perm:[2,3,0,1] row_mask:0xf bank_mask:0xf bound_ctrl:1
	v_xor_b32_e32 v199, v189, v187
	v_add_f32_dpp v194, v212, v194 quad_perm:[1,0,3,2] row_mask:0xf bank_mask:0xf bound_ctrl:1
	v_xor_b32_e32 v195, v181, v214
	v_add_f32_dpp v187, v187, v199 quad_perm:[2,3,0,1] row_mask:0xf bank_mask:0xf bound_ctrl:1
	v_xor_b32_e32 v199, v189, v193
	v_add_f32_dpp v195, v214, v195 quad_perm:[1,0,3,2] row_mask:0xf bank_mask:0xf bound_ctrl:1
	v_xor_b32_e32 v197, v181, v196
	v_add_f32_dpp v193, v193, v199 quad_perm:[2,3,0,1] row_mask:0xf bank_mask:0xf bound_ctrl:1
	v_xor_b32_e32 v199, v189, v194
	v_pk_add_f32 v[202:203], v[202:203], v[202:203] op_sel:[0,1] op_sel_hi:[1,0] neg_lo:[0,1] neg_hi:[0,1]
	v_add_f32_dpp v196, v196, v197 quad_perm:[1,0,3,2] row_mask:0xf bank_mask:0xf bound_ctrl:1
	v_xor_b32_e32 v197, v181, v56
	v_add_f32_dpp v194, v194, v199 quad_perm:[2,3,0,1] row_mask:0xf bank_mask:0xf bound_ctrl:1
	v_xor_b32_e32 v199, v189, v195
	v_add_f32_dpp v56, v56, v197 quad_perm:[1,0,3,2] row_mask:0xf bank_mask:0xf bound_ctrl:1
	v_xor_b32_e32 v197, v181, v202
	v_add_f32_dpp v195, v195, v199 quad_perm:[2,3,0,1] row_mask:0xf bank_mask:0xf bound_ctrl:1
	v_xor_b32_e32 v199, v189, v196
	v_add_f32_dpp v197, v202, v197 quad_perm:[1,0,3,2] row_mask:0xf bank_mask:0xf bound_ctrl:1
	v_xor_b32_e32 v198, v181, v54
	v_add_f32_dpp v196, v196, v199 quad_perm:[2,3,0,1] row_mask:0xf bank_mask:0xf bound_ctrl:1
	v_xor_b32_e32 v199, v189, v56
	v_add_f32_dpp v54, v54, v198 quad_perm:[1,0,3,2] row_mask:0xf bank_mask:0xf bound_ctrl:1
	v_xor_b32_e32 v198, v181, v52
	v_add_f32_dpp v56, v56, v199 quad_perm:[2,3,0,1] row_mask:0xf bank_mask:0xf bound_ctrl:1
	v_xor_b32_e32 v199, v189, v197
	v_pk_add_f32 v[206:207], v[206:207], v[206:207] op_sel:[0,1] op_sel_hi:[1,0] neg_lo:[0,1] neg_hi:[0,1]
	v_add_f32_dpp v52, v52, v198 quad_perm:[1,0,3,2] row_mask:0xf bank_mask:0xf bound_ctrl:1
	v_xor_b32_e32 v198, v181, v50
	v_add_f32_dpp v197, v197, v199 quad_perm:[2,3,0,1] row_mask:0xf bank_mask:0xf bound_ctrl:1
	v_xor_b32_e32 v199, v189, v54
	v_add_f32_dpp v50, v50, v198 quad_perm:[1,0,3,2] row_mask:0xf bank_mask:0xf bound_ctrl:1
	v_xor_b32_e32 v198, v181, v206
	v_add_f32_dpp v199, v54, v199 quad_perm:[2,3,0,1] row_mask:0xf bank_mask:0xf bound_ctrl:1
	v_xor_b32_e32 v54, v189, v52
	v_add_f32_dpp v198, v206, v198 quad_perm:[1,0,3,2] row_mask:0xf bank_mask:0xf bound_ctrl:1
	s_nop 0
	v_add_f32_dpp v200, v52, v54 quad_perm:[2,3,0,1] row_mask:0xf bank_mask:0xf bound_ctrl:1
	v_xor_b32_e32 v52, v189, v50
	v_max_f32_e64 v54, |v194|, |v195|
	s_nop 0
	v_add_f32_dpp v201, v50, v52 quad_perm:[2,3,0,1] row_mask:0xf bank_mask:0xf bound_ctrl:1
	v_xor_b32_e32 v50, v189, v198
	v_max_f32_e64 v52, |v55|, |v57|
	s_nop 0
	v_add_f32_dpp v198, v198, v50 quad_perm:[2,3,0,1] row_mask:0xf bank_mask:0xf bound_ctrl:1
	v_xor_b32_e32 v50, v189, v186
	s_nop 1
	v_add_f32_dpp v186, v186, v50 quad_perm:[2,3,0,1] row_mask:0xf bank_mask:0xf bound_ctrl:1
	v_max_f32_e64 v50, |v51|, |v53|
	v_max3_f32 v50, v216, v50, v52
	v_max_f32_e64 v52, |v187|, |v193|
	v_max3_f32 v50, v50, v52, v54
	v_max_f32_e64 v52, |v196|, |v56|
	v_max_f32_e64 v54, |v197|, |v199|
	v_max3_f32 v50, v50, v52, v54
	v_max_f32_e64 v52, |v200|, |v201|
	v_max_f32_e64 v54, |v198|, |v186|
	v_max3_f32 v216, v50, v52, v54
	v_cvt_pk_bf16_f32 v50, v51, v53
	v_cvt_pk_bf16_f32 v51, v55, v57
	v_cvt_pk_bf16_f32 v52, v187, v193
	v_cvt_pk_bf16_f32 v53, v194, v195
	v_cvt_pk_bf16_f32 v54, v196, v56
	v_cvt_pk_bf16_f32 v55, v197, v199
	v_cvt_pk_bf16_f32 v56, v200, v201
	v_cvt_pk_bf16_f32 v57, v198, v186
	v_and_b32_e32 v187, 0xffff0000, v65
	v_and_b32_e32 v186, 0xffff0000, v61
	v_lshlrev_b32_e32 v195, 16, v62
	v_lshlrev_b32_e32 v194, 16, v58
	v_and_b32_e32 v197, 0xffff0000, v62
	v_and_b32_e32 v196, 0xffff0000, v58
	v_lshlrev_b32_e32 v199, 16, v63
	v_lshlrev_b32_e32 v198, 16, v59
	v_and_b32_e32 v63, 0xffff0000, v63
	v_and_b32_e32 v62, 0xffff0000, v59
	v_lshlrev_b32_e32 v59, 16, v64
	v_lshlrev_b32_e32 v58, 16, v60
	v_and_b32_e32 v201, 0xffff0000, v64
	v_and_b32_e32 v200, 0xffff0000, v60
	v_lshlrev_b32_e32 v65, 16, v65
	v_lshlrev_b32_e32 v64, 16, v61
	v_pk_add_f32 v[60:61], v[194:195], v[196:197]
	v_pk_add_f32 v[202:203], v[198:199], v[62:63]
	v_pk_add_f32 v[204:205], v[58:59], v[200:201]
	v_pk_add_f32 v[206:207], v[64:65], v[186:187]
	v_pk_add_f32 v[194:195], v[194:195], v[196:197] neg_lo:[0,1] neg_hi:[0,1]
	v_pk_add_f32 v[62:63], v[198:199], v[62:63] neg_lo:[0,1] neg_hi:[0,1]
	v_pk_add_f32 v[58:59], v[58:59], v[200:201] neg_lo:[0,1] neg_hi:[0,1]
	v_pk_add_f32 v[64:65], v[64:65], v[186:187] neg_lo:[0,1] neg_hi:[0,1]
	v_pk_add_f32 v[208:209], v[60:61], v[202:203] neg_lo:[0,1] neg_hi:[0,1]
	v_pk_add_f32 v[60:61], v[60:61], v[202:203]
	v_pk_add_f32 v[202:203], v[204:205], v[206:207]
	v_pk_add_f32 v[186:187], v[194:195], v[62:63] neg_lo:[0,1] neg_hi:[0,1]
	v_pk_add_f32 v[196:197], v[58:59], v[64:65] neg_lo:[0,1] neg_hi:[0,1]
	v_pk_add_f32 v[62:63], v[194:195], v[62:63]
	v_pk_add_f32 v[58:59], v[58:59], v[64:65]
	v_pk_add_f32 v[210:211], v[204:205], v[206:207] neg_lo:[0,1] neg_hi:[0,1]
	v_pk_add_f32 v[204:205], v[60:61], v[202:203]
	v_pk_add_f32 v[64:65], v[62:63], v[58:59]
	v_pk_add_f32 v[58:59], v[62:63], v[58:59] neg_lo:[0,1] neg_hi:[0,1]
	v_pk_add_f32 v[60:61], v[60:61], v[202:203] neg_lo:[0,1] neg_hi:[0,1]
	v_pk_add_f32 v[202:203], v[208:209], v[210:211]
	v_pk_add_f32 v[206:207], v[208:209], v[210:211] neg_lo:[0,1] neg_hi:[0,1]
	v_pk_add_f32 v[62:63], v[186:187], v[196:197]
	v_pk_add_f32 v[186:187], v[186:187], v[196:197] neg_lo:[0,1] neg_hi:[0,1]
	v_pk_add_f32 v[194:195], v[204:205], v[204:205] op_sel:[0,1] op_sel_hi:[1,0]
	v_pk_add_f32 v[210:211], v[58:59], v[58:59] op_sel:[0,1] op_sel_hi:[1,0]
	v_pk_add_f32 v[58:59], v[58:59], v[58:59] op_sel:[0,1] op_sel_hi:[1,0] neg_lo:[0,1] neg_hi:[0,1]
	v_pk_add_f32 v[198:199], v[64:65], v[64:65] op_sel:[0,1] op_sel_hi:[1,0]
	v_pk_add_f32 v[208:209], v[60:61], v[60:61] op_sel:[0,1] op_sel_hi:[1,0]
	v_pk_add_f32 v[60:61], v[60:61], v[60:61] op_sel:[0,1] op_sel_hi:[1,0] neg_lo:[0,1] neg_hi:[0,1]
	v_pk_add_f32 v[214:215], v[186:187], v[186:187] op_sel:[0,1] op_sel_hi:[1,0]
	v_pk_add_f32 v[186:187], v[186:187], v[186:187] op_sel:[0,1] op_sel_hi:[1,0] neg_lo:[0,1] neg_hi:[0,1]
	v_xor_b32_e32 v59, v181, v194
	v_pk_add_f32 v[196:197], v[204:205], v[204:205] op_sel:[0,1] op_sel_hi:[1,0] neg_lo:[0,1] neg_hi:[0,1]
	v_pk_add_f32 v[200:201], v[202:203], v[202:203] op_sel:[0,1] op_sel_hi:[1,0]
	v_pk_add_f32 v[204:205], v[62:63], v[62:63] op_sel:[0,1] op_sel_hi:[1,0]
	v_pk_add_f32 v[62:63], v[62:63], v[62:63] op_sel:[0,1] op_sel_hi:[1,0] neg_lo:[0,1] neg_hi:[0,1]
	v_add_f32_dpp v59, v194, v59 quad_perm:[1,0,3,2] row_mask:0xf bank_mask:0xf bound_ctrl:1
	v_xor_b32_e32 v61, v181, v198
	v_xor_b32_e32 v199, v181, v186
	v_pk_add_f32 v[64:65], v[64:65], v[64:65] op_sel:[0,1] op_sel_hi:[1,0] neg_lo:[0,1] neg_hi:[0,1]
	v_add_f32_dpp v61, v198, v61 quad_perm:[1,0,3,2] row_mask:0xf bank_mask:0xf bound_ctrl:1
	v_xor_b32_e32 v63, v181, v200
	v_add_f32_dpp v186, v186, v199 quad_perm:[1,0,3,2] row_mask:0xf bank_mask:0xf bound_ctrl:1
	v_xor_b32_e32 v199, v189, v59
	v_add_f32_dpp v63, v200, v63 quad_perm:[1,0,3,2] row_mask:0xf bank_mask:0xf bound_ctrl:1
	v_xor_b32_e32 v65, v181, v204
	v_add_f32_dpp v59, v59, v199 quad_perm:[2,3,0,1] row_mask:0xf bank_mask:0xf bound_ctrl:1
	v_xor_b32_e32 v199, v189, v61
	v_add_f32_dpp v65, v204, v65 quad_perm:[1,0,3,2] row_mask:0xf bank_mask:0xf bound_ctrl:1
	v_xor_b32_e32 v187, v181, v208
	v_add_f32_dpp v61, v61, v199 quad_perm:[2,3,0,1] row_mask:0xf bank_mask:0xf bound_ctrl:1
	v_xor_b32_e32 v199, v189, v63
	v_pk_add_f32 v[212:213], v[206:207], v[206:207] op_sel:[0,1] op_sel_hi:[1,0]
	v_add_f32_dpp v187, v208, v187 quad_perm:[1,0,3,2] row_mask:0xf bank_mask:0xf bound_ctrl:1
	v_xor_b32_e32 v193, v181, v210
	v_add_f32_dpp v63, v63, v199 quad_perm:[2,3,0,1] row_mask:0xf bank_mask:0xf bound_ctrl:1
	v_xor_b32_e32 v199, v189, v65
	v_add_f32_dpp v193, v210, v193 quad_perm:[1,0,3,2] row_mask:0xf bank_mask:0xf bound_ctrl:1
	v_xor_b32_e32 v194, v181, v212
	v_add_f32_dpp v65, v65, v199 quad_perm:[2,3,0,1] row_mask:0xf bank_mask:0xf bound_ctrl:1
	v_xor_b32_e32 v199, v189, v187
	v_add_f32_dpp v194, v212, v194 quad_perm:[1,0,3,2] row_mask:0xf bank_mask:0xf bound_ctrl:1
	v_xor_b32_e32 v195, v181, v214
	v_add_f32_dpp v187, v187, v199 quad_perm:[2,3,0,1] row_mask:0xf bank_mask:0xf bound_ctrl:1
	v_xor_b32_e32 v199, v189, v193
	v_add_f32_dpp v195, v214, v195 quad_perm:[1,0,3,2] row_mask:0xf bank_mask:0xf bound_ctrl:1
	v_xor_b32_e32 v197, v181, v196
	v_add_f32_dpp v193, v193, v199 quad_perm:[2,3,0,1] row_mask:0xf bank_mask:0xf bound_ctrl:1
	v_xor_b32_e32 v199, v189, v194
	v_pk_add_f32 v[202:203], v[202:203], v[202:203] op_sel:[0,1] op_sel_hi:[1,0] neg_lo:[0,1] neg_hi:[0,1]
	v_add_f32_dpp v196, v196, v197 quad_perm:[1,0,3,2] row_mask:0xf bank_mask:0xf bound_ctrl:1
	v_xor_b32_e32 v197, v181, v64
	v_add_f32_dpp v194, v194, v199 quad_perm:[2,3,0,1] row_mask:0xf bank_mask:0xf bound_ctrl:1
	v_xor_b32_e32 v199, v189, v195
	v_add_f32_dpp v64, v64, v197 quad_perm:[1,0,3,2] row_mask:0xf bank_mask:0xf bound_ctrl:1
	v_xor_b32_e32 v197, v181, v202
	v_add_f32_dpp v195, v195, v199 quad_perm:[2,3,0,1] row_mask:0xf bank_mask:0xf bound_ctrl:1
	v_xor_b32_e32 v199, v189, v196
	v_add_f32_dpp v197, v202, v197 quad_perm:[1,0,3,2] row_mask:0xf bank_mask:0xf bound_ctrl:1
	v_xor_b32_e32 v198, v181, v62
	v_add_f32_dpp v196, v196, v199 quad_perm:[2,3,0,1] row_mask:0xf bank_mask:0xf bound_ctrl:1
	v_xor_b32_e32 v199, v189, v64
	v_add_f32_dpp v62, v62, v198 quad_perm:[1,0,3,2] row_mask:0xf bank_mask:0xf bound_ctrl:1
	v_xor_b32_e32 v198, v181, v60
	v_add_f32_dpp v64, v64, v199 quad_perm:[2,3,0,1] row_mask:0xf bank_mask:0xf bound_ctrl:1
	v_xor_b32_e32 v199, v189, v197
	v_pk_add_f32 v[206:207], v[206:207], v[206:207] op_sel:[0,1] op_sel_hi:[1,0] neg_lo:[0,1] neg_hi:[0,1]
	v_add_f32_dpp v60, v60, v198 quad_perm:[1,0,3,2] row_mask:0xf bank_mask:0xf bound_ctrl:1
	v_xor_b32_e32 v198, v181, v58
	v_add_f32_dpp v197, v197, v199 quad_perm:[2,3,0,1] row_mask:0xf bank_mask:0xf bound_ctrl:1
	v_xor_b32_e32 v199, v189, v62
	v_add_f32_dpp v58, v58, v198 quad_perm:[1,0,3,2] row_mask:0xf bank_mask:0xf bound_ctrl:1
	v_xor_b32_e32 v198, v181, v206
	v_add_f32_dpp v199, v62, v199 quad_perm:[2,3,0,1] row_mask:0xf bank_mask:0xf bound_ctrl:1
	v_xor_b32_e32 v62, v189, v60
	v_add_f32_dpp v198, v206, v198 quad_perm:[1,0,3,2] row_mask:0xf bank_mask:0xf bound_ctrl:1
	s_nop 0
	v_add_f32_dpp v200, v60, v62 quad_perm:[2,3,0,1] row_mask:0xf bank_mask:0xf bound_ctrl:1
	v_xor_b32_e32 v60, v189, v58
	v_max_f32_e64 v62, |v194|, |v195|
	s_nop 0
	v_add_f32_dpp v201, v58, v60 quad_perm:[2,3,0,1] row_mask:0xf bank_mask:0xf bound_ctrl:1
	v_xor_b32_e32 v58, v189, v198
	v_max_f32_e64 v60, |v63|, |v65|
	s_nop 0
	v_add_f32_dpp v198, v198, v58 quad_perm:[2,3,0,1] row_mask:0xf bank_mask:0xf bound_ctrl:1
	v_xor_b32_e32 v58, v189, v186
	s_nop 1
	v_add_f32_dpp v186, v186, v58 quad_perm:[2,3,0,1] row_mask:0xf bank_mask:0xf bound_ctrl:1
	v_max_f32_e64 v58, |v59|, |v61|
	v_max3_f32 v58, v216, v58, v60
	v_max_f32_e64 v60, |v187|, |v193|
	v_max3_f32 v58, v58, v60, v62
	v_max_f32_e64 v60, |v196|, |v64|
	v_max_f32_e64 v62, |v197|, |v199|
	v_max3_f32 v58, v58, v60, v62
	v_max_f32_e64 v60, |v200|, |v201|
	v_max_f32_e64 v62, |v198|, |v186|
	v_max3_f32 v216, v58, v60, v62
	v_cvt_pk_bf16_f32 v58, v59, v61
	v_cvt_pk_bf16_f32 v59, v63, v65
	v_cvt_pk_bf16_f32 v60, v187, v193
	v_cvt_pk_bf16_f32 v61, v194, v195
	v_cvt_pk_bf16_f32 v62, v196, v64
	v_cvt_pk_bf16_f32 v63, v197, v199
	v_cvt_pk_bf16_f32 v64, v200, v201
	v_cvt_pk_bf16_f32 v65, v198, v186
	v_and_b32_e32 v187, 0xffff0000, v157
	v_and_b32_e32 v186, 0xffff0000, v149
	v_lshlrev_b32_e32 v195, 16, v154
	v_lshlrev_b32_e32 v194, 16, v146
	v_and_b32_e32 v197, 0xffff0000, v154
	v_and_b32_e32 v196, 0xffff0000, v146
	v_lshlrev_b32_e32 v199, 16, v155
	v_lshlrev_b32_e32 v198, 16, v147
	v_and_b32_e32 v155, 0xffff0000, v155
	v_and_b32_e32 v154, 0xffff0000, v147
	v_lshlrev_b32_e32 v147, 16, v156
	v_lshlrev_b32_e32 v146, 16, v148
	v_and_b32_e32 v201, 0xffff0000, v156
	v_and_b32_e32 v200, 0xffff0000, v148
	v_lshlrev_b32_e32 v157, 16, v157
	v_lshlrev_b32_e32 v156, 16, v149
	v_pk_add_f32 v[148:149], v[194:195], v[196:197]
	v_pk_add_f32 v[202:203], v[198:199], v[154:155]
	v_pk_add_f32 v[204:205], v[146:147], v[200:201]
	v_pk_add_f32 v[206:207], v[156:157], v[186:187]
	v_pk_add_f32 v[194:195], v[194:195], v[196:197] neg_lo:[0,1] neg_hi:[0,1]
	v_pk_add_f32 v[154:155], v[198:199], v[154:155] neg_lo:[0,1] neg_hi:[0,1]
	v_pk_add_f32 v[146:147], v[146:147], v[200:201] neg_lo:[0,1] neg_hi:[0,1]
	v_pk_add_f32 v[156:157], v[156:157], v[186:187] neg_lo:[0,1] neg_hi:[0,1]
	v_pk_add_f32 v[208:209], v[148:149], v[202:203] neg_lo:[0,1] neg_hi:[0,1]
	v_pk_add_f32 v[148:149], v[148:149], v[202:203]
	v_pk_add_f32 v[202:203], v[204:205], v[206:207]
	v_pk_add_f32 v[186:187], v[194:195], v[154:155] neg_lo:[0,1] neg_hi:[0,1]
	v_pk_add_f32 v[196:197], v[146:147], v[156:157] neg_lo:[0,1] neg_hi:[0,1]
	v_pk_add_f32 v[154:155], v[194:195], v[154:155]
	v_pk_add_f32 v[146:147], v[146:147], v[156:157]
	v_pk_add_f32 v[210:211], v[204:205], v[206:207] neg_lo:[0,1] neg_hi:[0,1]
	v_pk_add_f32 v[204:205], v[148:149], v[202:203]
	v_pk_add_f32 v[156:157], v[154:155], v[146:147]
	v_pk_add_f32 v[146:147], v[154:155], v[146:147] neg_lo:[0,1] neg_hi:[0,1]
	v_pk_add_f32 v[148:149], v[148:149], v[202:203] neg_lo:[0,1] neg_hi:[0,1]
	v_pk_add_f32 v[202:203], v[208:209], v[210:211]
	v_pk_add_f32 v[206:207], v[208:209], v[210:211] neg_lo:[0,1] neg_hi:[0,1]
	v_pk_add_f32 v[154:155], v[186:187], v[196:197]
	v_pk_add_f32 v[186:187], v[186:187], v[196:197] neg_lo:[0,1] neg_hi:[0,1]
	v_pk_add_f32 v[194:195], v[204:205], v[204:205] op_sel:[0,1] op_sel_hi:[1,0]
	v_pk_add_f32 v[210:211], v[146:147], v[146:147] op_sel:[0,1] op_sel_hi:[1,0]
	v_pk_add_f32 v[146:147], v[146:147], v[146:147] op_sel:[0,1] op_sel_hi:[1,0] neg_lo:[0,1] neg_hi:[0,1]
	v_pk_add_f32 v[198:199], v[156:157], v[156:157] op_sel:[0,1] op_sel_hi:[1,0]
	v_pk_add_f32 v[208:209], v[148:149], v[148:149] op_sel:[0,1] op_sel_hi:[1,0]
	v_pk_add_f32 v[148:149], v[148:149], v[148:149] op_sel:[0,1] op_sel_hi:[1,0] neg_lo:[0,1] neg_hi:[0,1]
	v_pk_add_f32 v[214:215], v[186:187], v[186:187] op_sel:[0,1] op_sel_hi:[1,0]
	v_pk_add_f32 v[186:187], v[186:187], v[186:187] op_sel:[0,1] op_sel_hi:[1,0] neg_lo:[0,1] neg_hi:[0,1]
	v_xor_b32_e32 v147, v181, v194
	v_pk_add_f32 v[196:197], v[204:205], v[204:205] op_sel:[0,1] op_sel_hi:[1,0] neg_lo:[0,1] neg_hi:[0,1]
	v_pk_add_f32 v[200:201], v[202:203], v[202:203] op_sel:[0,1] op_sel_hi:[1,0]
	v_pk_add_f32 v[204:205], v[154:155], v[154:155] op_sel:[0,1] op_sel_hi:[1,0]
	v_pk_add_f32 v[154:155], v[154:155], v[154:155] op_sel:[0,1] op_sel_hi:[1,0] neg_lo:[0,1] neg_hi:[0,1]
	v_add_f32_dpp v147, v194, v147 quad_perm:[1,0,3,2] row_mask:0xf bank_mask:0xf bound_ctrl:1
	v_xor_b32_e32 v149, v181, v198
	v_xor_b32_e32 v199, v181, v186
	v_pk_add_f32 v[156:157], v[156:157], v[156:157] op_sel:[0,1] op_sel_hi:[1,0] neg_lo:[0,1] neg_hi:[0,1]
	v_add_f32_dpp v149, v198, v149 quad_perm:[1,0,3,2] row_mask:0xf bank_mask:0xf bound_ctrl:1
	v_xor_b32_e32 v155, v181, v200
	v_xor_b32_e32 v187, v181, v208
	v_add_f32_dpp v186, v186, v199 quad_perm:[1,0,3,2] row_mask:0xf bank_mask:0xf bound_ctrl:1
	v_xor_b32_e32 v199, v189, v147
	v_add_f32_dpp v155, v200, v155 quad_perm:[1,0,3,2] row_mask:0xf bank_mask:0xf bound_ctrl:1
	v_xor_b32_e32 v157, v181, v204
	v_add_f32_dpp v187, v208, v187 quad_perm:[1,0,3,2] row_mask:0xf bank_mask:0xf bound_ctrl:1
	v_add_f32_dpp v208, v147, v199 quad_perm:[2,3,0,1] row_mask:0xf bank_mask:0xf bound_ctrl:1
	v_xor_b32_e32 v147, v189, v149
	v_add_f32_dpp v157, v204, v157 quad_perm:[1,0,3,2] row_mask:0xf bank_mask:0xf bound_ctrl:1
	v_xor_b32_e32 v193, v181, v210
	v_add_f32_dpp v209, v149, v147 quad_perm:[2,3,0,1] row_mask:0xf bank_mask:0xf bound_ctrl:1
	v_xor_b32_e32 v147, v189, v155
	v_pk_add_f32 v[212:213], v[206:207], v[206:207] op_sel:[0,1] op_sel_hi:[1,0]
	v_add_f32_dpp v193, v210, v193 quad_perm:[1,0,3,2] row_mask:0xf bank_mask:0xf bound_ctrl:1
	v_add_f32_dpp v210, v155, v147 quad_perm:[2,3,0,1] row_mask:0xf bank_mask:0xf bound_ctrl:1
	v_xor_b32_e32 v147, v189, v157
	v_xor_b32_e32 v194, v181, v212
	v_xor_b32_e32 v195, v181, v214
	v_add_f32_dpp v211, v157, v147 quad_perm:[2,3,0,1] row_mask:0xf bank_mask:0xf bound_ctrl:1
	v_xor_b32_e32 v147, v189, v187
	v_add_f32_dpp v194, v212, v194 quad_perm:[1,0,3,2] row_mask:0xf bank_mask:0xf bound_ctrl:1
	v_add_f32_dpp v195, v214, v195 quad_perm:[1,0,3,2] row_mask:0xf bank_mask:0xf bound_ctrl:1
	v_add_f32_dpp v212, v187, v147 quad_perm:[2,3,0,1] row_mask:0xf bank_mask:0xf bound_ctrl:1
	v_xor_b32_e32 v147, v189, v193
	v_xor_b32_e32 v197, v181, v196
	v_pk_add_f32 v[202:203], v[202:203], v[202:203] op_sel:[0,1] op_sel_hi:[1,0] neg_lo:[0,1] neg_hi:[0,1]
	v_add_f32_dpp v213, v193, v147 quad_perm:[2,3,0,1] row_mask:0xf bank_mask:0xf bound_ctrl:1
	v_xor_b32_e32 v147, v189, v194
	v_add_f32_dpp v196, v196, v197 quad_perm:[1,0,3,2] row_mask:0xf bank_mask:0xf bound_ctrl:1
	v_xor_b32_e32 v197, v181, v156
	v_add_f32_dpp v214, v194, v147 quad_perm:[2,3,0,1] row_mask:0xf bank_mask:0xf bound_ctrl:1
	v_xor_b32_e32 v147, v189, v195
	v_add_f32_dpp v156, v156, v197 quad_perm:[1,0,3,2] row_mask:0xf bank_mask:0xf bound_ctrl:1
	v_xor_b32_e32 v197, v181, v202
	v_add_f32_dpp v215, v195, v147 quad_perm:[2,3,0,1] row_mask:0xf bank_mask:0xf bound_ctrl:1
	v_xor_b32_e32 v147, v189, v196
	v_add_f32_dpp v197, v202, v197 quad_perm:[1,0,3,2] row_mask:0xf bank_mask:0xf bound_ctrl:1
	v_xor_b32_e32 v198, v181, v154
	v_add_f32_dpp v217, v196, v147 quad_perm:[2,3,0,1] row_mask:0xf bank_mask:0xf bound_ctrl:1
	v_xor_b32_e32 v147, v189, v156
	v_add_f32_dpp v154, v154, v198 quad_perm:[1,0,3,2] row_mask:0xf bank_mask:0xf bound_ctrl:1
	v_xor_b32_e32 v198, v181, v148
	v_add_f32_dpp v218, v156, v147 quad_perm:[2,3,0,1] row_mask:0xf bank_mask:0xf bound_ctrl:1
	v_xor_b32_e32 v147, v189, v197
	v_pk_add_f32 v[206:207], v[206:207], v[206:207] op_sel:[0,1] op_sel_hi:[1,0] neg_lo:[0,1] neg_hi:[0,1]
	v_add_f32_dpp v148, v148, v198 quad_perm:[1,0,3,2] row_mask:0xf bank_mask:0xf bound_ctrl:1
	v_xor_b32_e32 v198, v181, v146
	v_add_f32_dpp v219, v197, v147 quad_perm:[2,3,0,1] row_mask:0xf bank_mask:0xf bound_ctrl:1
	v_xor_b32_e32 v147, v189, v154
	v_add_f32_dpp v146, v146, v198 quad_perm:[1,0,3,2] row_mask:0xf bank_mask:0xf bound_ctrl:1
	v_xor_b32_e32 v198, v181, v206
	v_add_f32_dpp v220, v154, v147 quad_perm:[2,3,0,1] row_mask:0xf bank_mask:0xf bound_ctrl:1
	v_xor_b32_e32 v147, v189, v148
	v_add_f32_dpp v198, v206, v198 quad_perm:[1,0,3,2] row_mask:0xf bank_mask:0xf bound_ctrl:1
	s_waitcnt vmcnt(0)
	v_lshlrev_b32_e32 v149, 16, v110
	v_add_f32_dpp v221, v148, v147 quad_perm:[2,3,0,1] row_mask:0xf bank_mask:0xf bound_ctrl:1
	v_xor_b32_e32 v147, v189, v146
	v_max_f32_e64 v148, |v214|, |v215|
	v_and_b32_e32 v155, 0xffff0000, v110
	v_add_f32_dpp v222, v146, v147 quad_perm:[2,3,0,1] row_mask:0xf bank_mask:0xf bound_ctrl:1
	v_xor_b32_e32 v146, v189, v198
	v_max_f32_e64 v147, |v210|, |v211|
	v_and_b32_e32 v154, 0xffff0000, v98
	v_add_f32_dpp v223, v198, v146 quad_perm:[2,3,0,1] row_mask:0xf bank_mask:0xf bound_ctrl:1
	v_xor_b32_e32 v146, v189, v186
	v_lshlrev_b32_e32 v157, 16, v111
	v_lshlrev_b32_e32 v156, 16, v99
	v_add_f32_dpp v224, v186, v146 quad_perm:[2,3,0,1] row_mask:0xf bank_mask:0xf bound_ctrl:1
	v_max_f32_e64 v146, |v208|, |v209|
	v_max3_f32 v146, v216, v146, v147
	v_max_f32_e64 v147, |v212|, |v213|
	v_max3_f32 v146, v146, v147, v148
	v_max_f32_e64 v147, |v217|, |v218|
	v_max_f32_e64 v148, |v219|, |v220|
	v_max3_f32 v146, v146, v147, v148
	v_max_f32_e64 v147, |v221|, |v222|
	v_max_f32_e64 v148, |v223|, |v224|
	v_max3_f32 v193, v146, v147, v148
	v_and_b32_e32 v147, 0xffff0000, v113
	v_and_b32_e32 v146, 0xffff0000, v101
	v_lshlrev_b32_e32 v148, 16, v98
	v_and_b32_e32 v111, 0xffff0000, v111
	v_and_b32_e32 v110, 0xffff0000, v99
	v_lshlrev_b32_e32 v99, 16, v112
	v_lshlrev_b32_e32 v98, 16, v100
	v_and_b32_e32 v187, 0xffff0000, v112
	v_and_b32_e32 v186, 0xffff0000, v100
	v_lshlrev_b32_e32 v113, 16, v113
	v_lshlrev_b32_e32 v112, 16, v101
	v_pk_add_f32 v[100:101], v[148:149], v[154:155]
	v_pk_add_f32 v[194:195], v[156:157], v[110:111]
	v_pk_add_f32 v[196:197], v[98:99], v[186:187]
	v_pk_add_f32 v[198:199], v[112:113], v[146:147]
	v_pk_add_f32 v[148:149], v[148:149], v[154:155] neg_lo:[0,1] neg_hi:[0,1]
	v_pk_add_f32 v[110:111], v[156:157], v[110:111] neg_lo:[0,1] neg_hi:[0,1]
	v_pk_add_f32 v[98:99], v[98:99], v[186:187] neg_lo:[0,1] neg_hi:[0,1]
	v_pk_add_f32 v[112:113], v[112:113], v[146:147] neg_lo:[0,1] neg_hi:[0,1]
	v_pk_add_f32 v[200:201], v[100:101], v[194:195] neg_lo:[0,1] neg_hi:[0,1]
	v_pk_add_f32 v[202:203], v[196:197], v[198:199] neg_lo:[0,1] neg_hi:[0,1]
	v_pk_add_f32 v[100:101], v[100:101], v[194:195]
	v_pk_add_f32 v[194:195], v[196:197], v[198:199]
	v_pk_add_f32 v[146:147], v[148:149], v[110:111] neg_lo:[0,1] neg_hi:[0,1]
	v_pk_add_f32 v[154:155], v[98:99], v[112:113] neg_lo:[0,1] neg_hi:[0,1]
	v_pk_add_f32 v[110:111], v[148:149], v[110:111]
	v_pk_add_f32 v[98:99], v[98:99], v[112:113]
	v_pk_add_f32 v[196:197], v[100:101], v[194:195]
	v_pk_add_f32 v[100:101], v[100:101], v[194:195] neg_lo:[0,1] neg_hi:[0,1]
	v_pk_add_f32 v[194:195], v[200:201], v[202:203]
	v_pk_add_f32 v[112:113], v[110:111], v[98:99]
	v_pk_add_f32 v[98:99], v[110:111], v[98:99] neg_lo:[0,1] neg_hi:[0,1]
	v_pk_add_f32 v[110:111], v[146:147], v[154:155]
	v_pk_add_f32 v[198:199], v[200:201], v[202:203] neg_lo:[0,1] neg_hi:[0,1]
	v_pk_add_f32 v[146:147], v[146:147], v[154:155] neg_lo:[0,1] neg_hi:[0,1]
	v_pk_add_f32 v[148:149], v[196:197], v[196:197] op_sel:[0,1] op_sel_hi:[1,0]
	v_pk_add_f32 v[154:155], v[196:197], v[196:197] op_sel:[0,1] op_sel_hi:[1,0] neg_lo:[0,1] neg_hi:[0,1]
	v_pk_add_f32 v[186:187], v[194:195], v[194:195] op_sel:[0,1] op_sel_hi:[1,0]
	v_pk_add_f32 v[196:197], v[110:111], v[110:111] op_sel:[0,1] op_sel_hi:[1,0]
	v_pk_add_f32 v[110:111], v[110:111], v[110:111] op_sel:[0,1] op_sel_hi:[1,0] neg_lo:[0,1] neg_hi:[0,1]
	v_pk_add_f32 v[202:203], v[98:99], v[98:99] op_sel:[0,1] op_sel_hi:[1,0]
	v_pk_add_f32 v[98:99], v[98:99], v[98:99] op_sel:[0,1] op_sel_hi:[1,0] neg_lo:[0,1] neg_hi:[0,1]
	v_pk_add_f32 v[156:157], v[112:113], v[112:113] op_sel:[0,1] op_sel_hi:[1,0]
	v_pk_add_f32 v[200:201], v[100:101], v[100:101] op_sel:[0,1] op_sel_hi:[1,0]
	v_pk_add_f32 v[100:101], v[100:101], v[100:101] op_sel:[0,1] op_sel_hi:[1,0] neg_lo:[0,1] neg_hi:[0,1]
	v_pk_add_f32 v[206:207], v[146:147], v[146:147] op_sel:[0,1] op_sel_hi:[1,0]
	v_pk_add_f32 v[146:147], v[146:147], v[146:147] op_sel:[0,1] op_sel_hi:[1,0] neg_lo:[0,1] neg_hi:[0,1]
	v_xor_b32_e32 v99, v181, v148
	v_xor_b32_e32 v111, v181, v186
	v_xor_b32_e32 v101, v181, v156
	v_add_f32_dpp v99, v148, v99 quad_perm:[1,0,3,2] row_mask:0xf bank_mask:0xf bound_ctrl:1
	v_add_f32_dpp v111, v186, v111 quad_perm:[1,0,3,2] row_mask:0xf bank_mask:0xf bound_ctrl:1
	v_xor_b32_e32 v186, v181, v146
	v_pk_add_f32 v[112:113], v[112:113], v[112:113] op_sel:[0,1] op_sel_hi:[1,0] neg_lo:[0,1] neg_hi:[0,1]
	v_add_f32_dpp v101, v156, v101 quad_perm:[1,0,3,2] row_mask:0xf bank_mask:0xf bound_ctrl:1
	v_xor_b32_e32 v147, v181, v200
	v_add_f32_dpp v146, v146, v186 quad_perm:[1,0,3,2] row_mask:0xf bank_mask:0xf bound_ctrl:1
	v_xor_b32_e32 v186, v189, v99
	v_xor_b32_e32 v113, v181, v196
	v_add_f32_dpp v147, v200, v147 quad_perm:[1,0,3,2] row_mask:0xf bank_mask:0xf bound_ctrl:1
	v_add_f32_dpp v200, v99, v186 quad_perm:[2,3,0,1] row_mask:0xf bank_mask:0xf bound_ctrl:1
	v_xor_b32_e32 v99, v189, v101
	v_add_f32_dpp v113, v196, v113 quad_perm:[1,0,3,2] row_mask:0xf bank_mask:0xf bound_ctrl:1
	v_xor_b32_e32 v148, v181, v202
	v_add_f32_dpp v201, v101, v99 quad_perm:[2,3,0,1] row_mask:0xf bank_mask:0xf bound_ctrl:1
	v_xor_b32_e32 v99, v189, v111
	v_pk_add_f32 v[204:205], v[198:199], v[198:199] op_sel:[0,1] op_sel_hi:[1,0]
	v_add_f32_dpp v148, v202, v148 quad_perm:[1,0,3,2] row_mask:0xf bank_mask:0xf bound_ctrl:1
	v_add_f32_dpp v202, v111, v99 quad_perm:[2,3,0,1] row_mask:0xf bank_mask:0xf bound_ctrl:1
	v_xor_b32_e32 v99, v189, v113
	v_xor_b32_e32 v149, v181, v204
	v_xor_b32_e32 v155, v181, v206
	v_add_f32_dpp v203, v113, v99 quad_perm:[2,3,0,1] row_mask:0xf bank_mask:0xf bound_ctrl:1
	v_xor_b32_e32 v99, v189, v147
	v_add_f32_dpp v149, v204, v149 quad_perm:[1,0,3,2] row_mask:0xf bank_mask:0xf bound_ctrl:1
	v_add_f32_dpp v155, v206, v155 quad_perm:[1,0,3,2] row_mask:0xf bank_mask:0xf bound_ctrl:1
	v_add_f32_dpp v204, v147, v99 quad_perm:[2,3,0,1] row_mask:0xf bank_mask:0xf bound_ctrl:1
	v_xor_b32_e32 v99, v189, v148
	v_xor_b32_e32 v156, v181, v154
	v_pk_add_f32 v[194:195], v[194:195], v[194:195] op_sel:[0,1] op_sel_hi:[1,0] neg_lo:[0,1] neg_hi:[0,1]
	v_add_f32_dpp v205, v148, v99 quad_perm:[2,3,0,1] row_mask:0xf bank_mask:0xf bound_ctrl:1
	v_xor_b32_e32 v99, v189, v149
	v_add_f32_dpp v154, v154, v156 quad_perm:[1,0,3,2] row_mask:0xf bank_mask:0xf bound_ctrl:1
	v_xor_b32_e32 v156, v181, v112
	v_add_f32_dpp v206, v149, v99 quad_perm:[2,3,0,1] row_mask:0xf bank_mask:0xf bound_ctrl:1
	v_xor_b32_e32 v99, v189, v155
	v_add_f32_dpp v112, v112, v156 quad_perm:[1,0,3,2] row_mask:0xf bank_mask:0xf bound_ctrl:1
	v_xor_b32_e32 v156, v181, v194
	v_add_f32_dpp v207, v155, v99 quad_perm:[2,3,0,1] row_mask:0xf bank_mask:0xf bound_ctrl:1
	v_xor_b32_e32 v99, v189, v154
	v_add_f32_dpp v156, v194, v156 quad_perm:[1,0,3,2] row_mask:0xf bank_mask:0xf bound_ctrl:1
	v_xor_b32_e32 v157, v181, v110
	v_add_f32_dpp v216, v154, v99 quad_perm:[2,3,0,1] row_mask:0xf bank_mask:0xf bound_ctrl:1
	v_xor_b32_e32 v99, v189, v112
	v_add_f32_dpp v110, v110, v157 quad_perm:[1,0,3,2] row_mask:0xf bank_mask:0xf bound_ctrl:1
	v_xor_b32_e32 v157, v181, v100
	v_add_f32_dpp v225, v112, v99 quad_perm:[2,3,0,1] row_mask:0xf bank_mask:0xf bound_ctrl:1
	v_xor_b32_e32 v99, v189, v156
	v_pk_add_f32 v[198:199], v[198:199], v[198:199] op_sel:[0,1] op_sel_hi:[1,0] neg_lo:[0,1] neg_hi:[0,1]
	v_add_f32_dpp v100, v100, v157 quad_perm:[1,0,3,2] row_mask:0xf bank_mask:0xf bound_ctrl:1
	v_xor_b32_e32 v157, v181, v98
	v_add_f32_dpp v226, v156, v99 quad_perm:[2,3,0,1] row_mask:0xf bank_mask:0xf bound_ctrl:1
	v_xor_b32_e32 v99, v189, v110
	v_add_f32_dpp v98, v98, v157 quad_perm:[1,0,3,2] row_mask:0xf bank_mask:0xf bound_ctrl:1
	v_xor_b32_e32 v157, v181, v198
	v_add_f32_dpp v227, v110, v99 quad_perm:[2,3,0,1] row_mask:0xf bank_mask:0xf bound_ctrl:1
	v_xor_b32_e32 v99, v189, v100
	v_add_f32_dpp v157, v198, v157 quad_perm:[1,0,3,2] row_mask:0xf bank_mask:0xf bound_ctrl:1
	v_lshlrev_b32_e32 v101, 16, v70
	v_add_f32_dpp v228, v100, v99 quad_perm:[2,3,0,1] row_mask:0xf bank_mask:0xf bound_ctrl:1
	v_xor_b32_e32 v99, v189, v98
	v_max_f32_e64 v100, |v206|, |v207|
	v_and_b32_e32 v111, 0xffff0000, v70
	v_add_f32_dpp v229, v98, v99 quad_perm:[2,3,0,1] row_mask:0xf bank_mask:0xf bound_ctrl:1
	v_xor_b32_e32 v98, v189, v157
	v_max_f32_e64 v99, |v202|, |v203|
	v_and_b32_e32 v110, 0xffff0000, v66
	v_add_f32_dpp v230, v157, v98 quad_perm:[2,3,0,1] row_mask:0xf bank_mask:0xf bound_ctrl:1
	v_xor_b32_e32 v98, v189, v146
	v_lshlrev_b32_e32 v112, 16, v67
	v_lshlrev_b32_e32 v113, 16, v71
	v_add_f32_dpp v231, v146, v98 quad_perm:[2,3,0,1] row_mask:0xf bank_mask:0xf bound_ctrl:1
	v_max_f32_e64 v98, |v200|, |v201|
	v_max3_f32 v98, v193, v98, v99
	v_max_f32_e64 v99, |v204|, |v205|
	v_max3_f32 v98, v98, v99, v100
	v_max_f32_e64 v99, |v216|, |v225|
	v_max_f32_e64 v100, |v226|, |v227|
	v_max3_f32 v98, v98, v99, v100
	v_max_f32_e64 v99, |v228|, |v229|
	v_max_f32_e64 v100, |v230|, |v231|
	v_max3_f32 v193, v98, v99, v100
	v_and_b32_e32 v99, 0xffff0000, v73
	v_and_b32_e32 v98, 0xffff0000, v69
	v_lshlrev_b32_e32 v100, 16, v66
	v_and_b32_e32 v71, 0xffff0000, v71
	v_and_b32_e32 v70, 0xffff0000, v67
	v_lshlrev_b32_e32 v67, 16, v72
	v_lshlrev_b32_e32 v66, 16, v68
	v_and_b32_e32 v147, 0xffff0000, v72
	v_and_b32_e32 v146, 0xffff0000, v68
	v_lshlrev_b32_e32 v68, 16, v69
	v_lshlrev_b32_e32 v69, 16, v73
	v_pk_add_f32 v[72:73], v[100:101], v[110:111]
	v_pk_add_f32 v[148:149], v[112:113], v[70:71]
	v_pk_add_f32 v[154:155], v[66:67], v[146:147]
	v_pk_add_f32 v[156:157], v[68:69], v[98:99]
	v_pk_add_f32 v[100:101], v[100:101], v[110:111] neg_lo:[0,1] neg_hi:[0,1]
	v_pk_add_f32 v[70:71], v[112:113], v[70:71] neg_lo:[0,1] neg_hi:[0,1]
	v_pk_add_f32 v[66:67], v[66:67], v[146:147] neg_lo:[0,1] neg_hi:[0,1]
	v_pk_add_f32 v[68:69], v[68:69], v[98:99] neg_lo:[0,1] neg_hi:[0,1]
	v_pk_add_f32 v[186:187], v[72:73], v[148:149] neg_lo:[0,1] neg_hi:[0,1]
	v_pk_add_f32 v[194:195], v[154:155], v[156:157] neg_lo:[0,1] neg_hi:[0,1]
	v_pk_add_f32 v[72:73], v[72:73], v[148:149]
	v_pk_add_f32 v[148:149], v[154:155], v[156:157]
	v_pk_add_f32 v[98:99], v[100:101], v[70:71] neg_lo:[0,1] neg_hi:[0,1]
	v_pk_add_f32 v[110:111], v[66:67], v[68:69] neg_lo:[0,1] neg_hi:[0,1]
	v_pk_add_f32 v[70:71], v[100:101], v[70:71]
	v_pk_add_f32 v[66:67], v[66:67], v[68:69]
	v_pk_add_f32 v[154:155], v[72:73], v[148:149]
	v_pk_add_f32 v[72:73], v[72:73], v[148:149] neg_lo:[0,1] neg_hi:[0,1]
	v_pk_add_f32 v[148:149], v[186:187], v[194:195]
	v_pk_add_f32 v[68:69], v[70:71], v[66:67]
	v_pk_add_f32 v[66:67], v[70:71], v[66:67] neg_lo:[0,1] neg_hi:[0,1]
	v_pk_add_f32 v[70:71], v[98:99], v[110:111]
	v_pk_add_f32 v[156:157], v[186:187], v[194:195] neg_lo:[0,1] neg_hi:[0,1]
	v_pk_add_f32 v[98:99], v[98:99], v[110:111] neg_lo:[0,1] neg_hi:[0,1]
	v_pk_add_f32 v[100:101], v[154:155], v[154:155] op_sel:[0,1] op_sel_hi:[1,0]
	v_pk_add_f32 v[110:111], v[154:155], v[154:155] op_sel:[0,1] op_sel_hi:[1,0] neg_lo:[0,1] neg_hi:[0,1]
	v_pk_add_f32 v[146:147], v[148:149], v[148:149] op_sel:[0,1] op_sel_hi:[1,0]
	v_pk_add_f32 v[154:155], v[70:71], v[70:71] op_sel:[0,1] op_sel_hi:[1,0]
	v_pk_add_f32 v[70:71], v[70:71], v[70:71] op_sel:[0,1] op_sel_hi:[1,0] neg_lo:[0,1] neg_hi:[0,1]
	v_pk_add_f32 v[194:195], v[66:67], v[66:67] op_sel:[0,1] op_sel_hi:[1,0]
	v_pk_add_f32 v[66:67], v[66:67], v[66:67] op_sel:[0,1] op_sel_hi:[1,0] neg_lo:[0,1] neg_hi:[0,1]
	v_pk_add_f32 v[112:113], v[68:69], v[68:69] op_sel:[0,1] op_sel_hi:[1,0]
	v_pk_add_f32 v[68:69], v[68:69], v[68:69] op_sel:[0,1] op_sel_hi:[1,0] neg_lo:[0,1] neg_hi:[0,1]
	v_pk_add_f32 v[198:199], v[98:99], v[98:99] op_sel:[0,1] op_sel_hi:[1,0]
	v_pk_add_f32 v[98:99], v[98:99], v[98:99] op_sel:[0,1] op_sel_hi:[1,0] neg_lo:[0,1] neg_hi:[0,1]
	v_xor_b32_e32 v67, v181, v100
	v_xor_b32_e32 v71, v181, v146
	v_xor_b32_e32 v69, v181, v112
	v_add_f32_dpp v67, v100, v67 quad_perm:[1,0,3,2] row_mask:0xf bank_mask:0xf bound_ctrl:1
	v_add_f32_dpp v71, v146, v71 quad_perm:[1,0,3,2] row_mask:0xf bank_mask:0xf bound_ctrl:1
	v_xor_b32_e32 v146, v181, v98
	v_pk_add_f32 v[186:187], v[72:73], v[72:73] op_sel:[0,1] op_sel_hi:[1,0]
	v_pk_add_f32 v[72:73], v[72:73], v[72:73] op_sel:[0,1] op_sel_hi:[1,0] neg_lo:[0,1] neg_hi:[0,1]
	v_add_f32_dpp v69, v112, v69 quad_perm:[1,0,3,2] row_mask:0xf bank_mask:0xf bound_ctrl:1
	v_add_f32_dpp v98, v98, v146 quad_perm:[1,0,3,2] row_mask:0xf bank_mask:0xf bound_ctrl:1
	v_xor_b32_e32 v146, v189, v67
	v_xor_b32_e32 v73, v181, v154
	v_xor_b32_e32 v99, v181, v186
	v_add_f32_dpp v67, v67, v146 quad_perm:[2,3,0,1] row_mask:0xf bank_mask:0xf bound_ctrl:1
	v_xor_b32_e32 v146, v189, v69
	v_add_f32_dpp v73, v154, v73 quad_perm:[1,0,3,2] row_mask:0xf bank_mask:0xf bound_ctrl:1
	v_pk_add_f32 v[196:197], v[156:157], v[156:157] op_sel:[0,1] op_sel_hi:[1,0]
	v_add_f32_dpp v69, v69, v146 quad_perm:[2,3,0,1] row_mask:0xf bank_mask:0xf bound_ctrl:1
	v_xor_b32_e32 v146, v189, v71
	v_add_f32_dpp v99, v186, v99 quad_perm:[1,0,3,2] row_mask:0xf bank_mask:0xf bound_ctrl:1
	v_xor_b32_e32 v100, v181, v194
	v_add_f32_dpp v71, v71, v146 quad_perm:[2,3,0,1] row_mask:0xf bank_mask:0xf bound_ctrl:1
	v_xor_b32_e32 v146, v189, v73
	v_add_f32_dpp v100, v194, v100 quad_perm:[1,0,3,2] row_mask:0xf bank_mask:0xf bound_ctrl:1
	v_xor_b32_e32 v101, v181, v196
	v_add_f32_dpp v73, v73, v146 quad_perm:[2,3,0,1] row_mask:0xf bank_mask:0xf bound_ctrl:1
	v_xor_b32_e32 v146, v189, v99
	v_add_f32_dpp v101, v196, v101 quad_perm:[1,0,3,2] row_mask:0xf bank_mask:0xf bound_ctrl:1
	v_xor_b32_e32 v111, v181, v198
	v_add_f32_dpp v186, v99, v146 quad_perm:[2,3,0,1] row_mask:0xf bank_mask:0xf bound_ctrl:1
	v_xor_b32_e32 v99, v189, v100
	v_add_f32_dpp v111, v198, v111 quad_perm:[1,0,3,2] row_mask:0xf bank_mask:0xf bound_ctrl:1
	v_xor_b32_e32 v112, v181, v110
	v_add_f32_dpp v187, v100, v99 quad_perm:[2,3,0,1] row_mask:0xf bank_mask:0xf bound_ctrl:1
	v_xor_b32_e32 v99, v189, v101
	v_pk_add_f32 v[148:149], v[148:149], v[148:149] op_sel:[0,1] op_sel_hi:[1,0] neg_lo:[0,1] neg_hi:[0,1]
	v_add_f32_dpp v110, v110, v112 quad_perm:[1,0,3,2] row_mask:0xf bank_mask:0xf bound_ctrl:1
	v_xor_b32_e32 v112, v181, v68
	v_add_f32_dpp v198, v101, v99 quad_perm:[2,3,0,1] row_mask:0xf bank_mask:0xf bound_ctrl:1
	v_xor_b32_e32 v99, v189, v111
	v_add_f32_dpp v68, v68, v112 quad_perm:[1,0,3,2] row_mask:0xf bank_mask:0xf bound_ctrl:1
	v_xor_b32_e32 v112, v181, v148
	v_add_f32_dpp v199, v111, v99 quad_perm:[2,3,0,1] row_mask:0xf bank_mask:0xf bound_ctrl:1
	v_xor_b32_e32 v99, v189, v110
	v_add_f32_dpp v112, v148, v112 quad_perm:[1,0,3,2] row_mask:0xf bank_mask:0xf bound_ctrl:1
	v_xor_b32_e32 v113, v181, v70
	v_add_f32_dpp v232, v110, v99 quad_perm:[2,3,0,1] row_mask:0xf bank_mask:0xf bound_ctrl:1
	v_xor_b32_e32 v99, v189, v68
	v_add_f32_dpp v70, v70, v113 quad_perm:[1,0,3,2] row_mask:0xf bank_mask:0xf bound_ctrl:1
	v_xor_b32_e32 v113, v181, v72
	v_add_f32_dpp v233, v68, v99 quad_perm:[2,3,0,1] row_mask:0xf bank_mask:0xf bound_ctrl:1
	v_xor_b32_e32 v68, v189, v112
	v_pk_add_f32 v[156:157], v[156:157], v[156:157] op_sel:[0,1] op_sel_hi:[1,0] neg_lo:[0,1] neg_hi:[0,1]
	v_add_f32_dpp v72, v72, v113 quad_perm:[1,0,3,2] row_mask:0xf bank_mask:0xf bound_ctrl:1
	v_xor_b32_e32 v113, v181, v66
	v_add_f32_dpp v235, v112, v68 quad_perm:[2,3,0,1] row_mask:0xf bank_mask:0xf bound_ctrl:1
	v_xor_b32_e32 v68, v189, v70
	v_add_f32_dpp v66, v66, v113 quad_perm:[1,0,3,2] row_mask:0xf bank_mask:0xf bound_ctrl:1
	v_xor_b32_e32 v113, v181, v156
	v_add_f32_dpp v236, v70, v68 quad_perm:[2,3,0,1] row_mask:0xf bank_mask:0xf bound_ctrl:1
	v_xor_b32_e32 v68, v189, v72
	v_add_f32_dpp v113, v156, v113 quad_perm:[1,0,3,2] row_mask:0xf bank_mask:0xf bound_ctrl:1
	v_max_f32_e64 v70, |v198|, |v199|
	v_add_f32_dpp v72, v72, v68 quad_perm:[2,3,0,1] row_mask:0xf bank_mask:0xf bound_ctrl:1
	v_xor_b32_e32 v68, v189, v66
	v_cvt_pk_bf16_f32 v146, v208, v209
	v_cvt_pk_bf16_f32 v147, v210, v211
	v_cvt_pk_bf16_f32 v148, v212, v213
	v_cvt_pk_bf16_f32 v149, v214, v215
	v_cvt_pk_bf16_f32 v154, v217, v218
	s_nop 1
	v_add_f32_dpp v237, v66, v68 quad_perm:[2,3,0,1] row_mask:0xf bank_mask:0xf bound_ctrl:1
	v_xor_b32_e32 v66, v189, v113
	v_max_f32_e64 v68, |v71|, |v73|
	v_cvt_pk_bf16_f32 v155, v219, v220
	v_cvt_pk_bf16_f32 v156, v221, v222
	v_cvt_pk_bf16_f32 v157, v223, v224
	s_nop 0
	v_add_f32_dpp v238, v113, v66 quad_perm:[2,3,0,1] row_mask:0xf bank_mask:0xf bound_ctrl:1
	v_xor_b32_e32 v66, v189, v98
	s_nop 1
	v_add_f32_dpp v239, v98, v66 quad_perm:[2,3,0,1] row_mask:0xf bank_mask:0xf bound_ctrl:1
	v_max_f32_e64 v66, |v67|, |v69|
	v_max3_f32 v66, v193, v66, v68
	v_max_f32_e64 v68, |v186|, |v187|
	v_max3_f32 v66, v66, v68, v70
	v_max_f32_e64 v68, |v232|, |v233|
	v_max_f32_e64 v70, |v235|, |v236|
	v_max3_f32 v66, v66, v68, v70
	v_max_f32_e64 v68, |v72|, |v237|
	v_max_f32_e64 v70, |v238|, |v239|
	v_max3_f32 v66, v66, v68, v70
	v_and_b32_e32 v68, 64, v190
	v_add_u32_e32 v70, 64, v68
	v_xor_b32_e32 v68, 1, v190
	v_cmp_lt_i32_e32 vcc, v68, v70
	v_cvt_pk_bf16_f32 v98, v200, v201
	v_cvt_pk_bf16_f32 v99, v202, v203
	v_cvt_pk_bf16_f32 v100, v204, v205
	v_cvt_pk_bf16_f32 v101, v206, v207
	v_cvt_pk_bf16_f32 v110, v216, v225
	s_nop 1
	v_cndmask_b32_e32 v68, v190, v68, vcc
	v_lshlrev_b32_e32 v193, 2, v68
	ds_bpermute_b32 v68, v193, v66
	v_cvt_pk_bf16_f32 v111, v226, v227
	v_cvt_pk_bf16_f32 v112, v228, v229
	v_cvt_pk_bf16_f32 v113, v230, v231
	s_waitcnt lgkmcnt(0)
	v_max_f32_e32 v68, v68, v68
	v_max_f32_e32 v66, v66, v68
	v_xor_b32_e32 v68, 2, v190
	v_cmp_lt_i32_e32 vcc, v68, v70
	s_nop 1
	v_cndmask_b32_e32 v68, v190, v68, vcc
	v_lshlrev_b32_e32 v194, 2, v68
	ds_bpermute_b32 v68, v194, v66
	s_waitcnt lgkmcnt(0)
	v_max_f32_e32 v68, v68, v68
	v_max_f32_e32 v66, v66, v68
	v_xor_b32_e32 v68, 4, v190
	v_cmp_lt_i32_e32 vcc, v68, v70
	s_nop 1
	v_cndmask_b32_e32 v68, v190, v68, vcc
	v_lshlrev_b32_e32 v195, 2, v68
	ds_bpermute_b32 v68, v195, v66
	s_waitcnt lgkmcnt(0)
	v_max_f32_e32 v68, v68, v68
	v_max_f32_e32 v66, v66, v68
	v_xor_b32_e32 v68, 8, v190
	v_cmp_lt_i32_e32 vcc, v68, v70
	s_nop 1
	v_cndmask_b32_e32 v68, v190, v68, vcc
	v_lshlrev_b32_e32 v196, 2, v68
	ds_bpermute_b32 v68, v196, v66
	s_waitcnt lgkmcnt(0)
	v_max_f32_e32 v68, v68, v68
	v_max_f32_e32 v200, v66, v68
	v_xor_b32_e32 v66, 16, v190
	v_cmp_lt_i32_e32 vcc, v66, v70
	s_nop 1
	v_cndmask_b32_e32 v66, v190, v66, vcc
	v_lshlrev_b32_e32 v197, 2, v66
	ds_bpermute_b32 v201, v197, v200
	v_cvt_pk_bf16_f32 v66, v67, v69
	v_cvt_pk_bf16_f32 v67, v71, v73
	v_cvt_pk_bf16_f32 v68, v186, v187
	v_cvt_pk_bf16_f32 v69, v198, v199
	s_waitcnt lgkmcnt(0)
	v_max_f32_e32 v71, v201, v201
	v_max_f32_e32 v186, v200, v71
	v_xor_b32_e32 v71, 32, v190
	v_cmp_lt_i32_e32 vcc, v71, v70
	s_nop 1
	v_cndmask_b32_e32 v70, v190, v71, vcc
	v_lshlrev_b32_e32 v198, 2, v70
	ds_bpermute_b32 v187, v198, v186
	v_cvt_pk_bf16_f32 v70, v232, v233
	v_cvt_pk_bf16_f32 v71, v235, v236
	v_cvt_pk_bf16_f32 v72, v72, v237
	v_cvt_pk_bf16_f32 v73, v238, v239
	s_waitcnt lgkmcnt(0)
	v_max_f32_e32 v187, v187, v187
	v_max_f32_e32 v186, v186, v187
	s_and_saveexec_b64 s[34:35], s[2:3]
	s_cbranch_execz .LBB0_1862
	s_lshl_b64 s[46:47], s[30:31], 2
	s_sub_u32 s46, s37, s46
	s_subb_u32 s47, s38, s47
	v_mul_f32_e32 v187, 0x3a810204, v186
	global_store_dword v179, v187, s[46:47]

.LBB0_1869:
	v_lshlrev_b32_e32 v187, 16, v78
	v_lshlrev_b32_e32 v186, 16, v74
	v_and_b32_e32 v201, 0xffff0000, v78
	v_and_b32_e32 v200, 0xffff0000, v74
	v_lshlrev_b32_e32 v202, 16, v75
	v_lshlrev_b32_e32 v203, 16, v79
	v_and_b32_e32 v79, 0xffff0000, v79
	v_and_b32_e32 v78, 0xffff0000, v75
	v_lshlrev_b32_e32 v75, 16, v80
	v_lshlrev_b32_e32 v74, 16, v76
	v_and_b32_e32 v205, 0xffff0000, v80
	v_and_b32_e32 v204, 0xffff0000, v76
	v_lshlrev_b32_e32 v206, 16, v77
	v_lshlrev_b32_e32 v207, 16, v81
	v_and_b32_e32 v81, 0xffff0000, v81
	v_and_b32_e32 v80, 0xffff0000, v77
	v_pk_add_f32 v[76:77], v[186:187], v[200:201]
	v_pk_add_f32 v[208:209], v[202:203], v[78:79]
	v_pk_add_f32 v[210:211], v[74:75], v[204:205]
	v_pk_add_f32 v[212:213], v[206:207], v[80:81]
	v_pk_add_f32 v[186:187], v[186:187], v[200:201] neg_lo:[0,1] neg_hi:[0,1]
	v_pk_add_f32 v[78:79], v[202:203], v[78:79] neg_lo:[0,1] neg_hi:[0,1]
	v_pk_add_f32 v[74:75], v[74:75], v[204:205] neg_lo:[0,1] neg_hi:[0,1]
	v_pk_add_f32 v[80:81], v[206:207], v[80:81] neg_lo:[0,1] neg_hi:[0,1]
	v_pk_add_f32 v[214:215], v[76:77], v[208:209] neg_lo:[0,1] neg_hi:[0,1]
	v_pk_add_f32 v[76:77], v[76:77], v[208:209]
	v_pk_add_f32 v[208:209], v[210:211], v[212:213]
	v_pk_add_f32 v[200:201], v[186:187], v[78:79] neg_lo:[0,1] neg_hi:[0,1]
	v_pk_add_f32 v[202:203], v[74:75], v[80:81] neg_lo:[0,1] neg_hi:[0,1]
	v_pk_add_f32 v[78:79], v[186:187], v[78:79]
	v_pk_add_f32 v[74:75], v[74:75], v[80:81]
	v_pk_add_f32 v[216:217], v[210:211], v[212:213] neg_lo:[0,1] neg_hi:[0,1]
	v_pk_add_f32 v[210:211], v[76:77], v[208:209]
	v_pk_add_f32 v[80:81], v[78:79], v[74:75]
	v_pk_add_f32 v[74:75], v[78:79], v[74:75] neg_lo:[0,1] neg_hi:[0,1]
	v_pk_add_f32 v[76:77], v[76:77], v[208:209] neg_lo:[0,1] neg_hi:[0,1]
	v_pk_add_f32 v[208:209], v[214:215], v[216:217]
	v_pk_add_f32 v[212:213], v[214:215], v[216:217] neg_lo:[0,1] neg_hi:[0,1]
	v_pk_add_f32 v[78:79], v[200:201], v[202:203]
	v_pk_add_f32 v[186:187], v[200:201], v[202:203] neg_lo:[0,1] neg_hi:[0,1]
	v_pk_add_f32 v[200:201], v[210:211], v[210:211] op_sel:[1,0] op_sel_hi:[0,1]
	v_pk_add_f32 v[216:217], v[74:75], v[74:75] op_sel:[1,0] op_sel_hi:[0,1]
	v_pk_add_f32 v[74:75], v[74:75], v[74:75] op_sel:[0,1] op_sel_hi:[1,0] neg_lo:[0,1] neg_hi:[0,1]
	v_pk_add_f32 v[204:205], v[80:81], v[80:81] op_sel:[1,0] op_sel_hi:[0,1]
	v_pk_add_f32 v[214:215], v[76:77], v[76:77] op_sel:[1,0] op_sel_hi:[0,1]
	v_pk_add_f32 v[76:77], v[76:77], v[76:77] op_sel:[0,1] op_sel_hi:[1,0] neg_lo:[0,1] neg_hi:[0,1]
	v_pk_add_f32 v[220:221], v[186:187], v[186:187] op_sel:[1,0] op_sel_hi:[0,1]
	v_pk_add_f32 v[186:187], v[186:187], v[186:187] op_sel:[0,1] op_sel_hi:[1,0] neg_lo:[0,1] neg_hi:[0,1]
	v_xor_b32_e32 v75, v181, v200
	v_pk_add_f32 v[202:203], v[210:211], v[210:211] op_sel:[0,1] op_sel_hi:[1,0] neg_lo:[0,1] neg_hi:[0,1]
	v_pk_add_f32 v[206:207], v[208:209], v[208:209] op_sel:[1,0] op_sel_hi:[0,1]
	v_pk_add_f32 v[210:211], v[78:79], v[78:79] op_sel:[1,0] op_sel_hi:[0,1]
	v_pk_add_f32 v[78:79], v[78:79], v[78:79] op_sel:[0,1] op_sel_hi:[1,0] neg_lo:[0,1] neg_hi:[0,1]
	v_add_f32_dpp v75, v200, v75 quad_perm:[1,0,3,2] row_mask:0xf bank_mask:0xf bound_ctrl:1
	v_xor_b32_e32 v77, v181, v204
	v_xor_b32_e32 v205, v181, v186
	v_pk_add_f32 v[80:81], v[80:81], v[80:81] op_sel:[0,1] op_sel_hi:[1,0] neg_lo:[0,1] neg_hi:[0,1]
	v_add_f32_dpp v77, v204, v77 quad_perm:[1,0,3,2] row_mask:0xf bank_mask:0xf bound_ctrl:1
	v_xor_b32_e32 v79, v181, v206
	v_add_f32_dpp v186, v186, v205 quad_perm:[1,0,3,2] row_mask:0xf bank_mask:0xf bound_ctrl:1
	v_xor_b32_e32 v205, v189, v75
	v_add_f32_dpp v79, v206, v79 quad_perm:[1,0,3,2] row_mask:0xf bank_mask:0xf bound_ctrl:1
	v_xor_b32_e32 v81, v181, v210
	v_add_f32_dpp v75, v75, v205 quad_perm:[2,3,0,1] row_mask:0xf bank_mask:0xf bound_ctrl:1
	v_xor_b32_e32 v205, v189, v77
	v_add_f32_dpp v81, v210, v81 quad_perm:[1,0,3,2] row_mask:0xf bank_mask:0xf bound_ctrl:1
	v_xor_b32_e32 v187, v181, v214
	v_add_f32_dpp v77, v77, v205 quad_perm:[2,3,0,1] row_mask:0xf bank_mask:0xf bound_ctrl:1
	v_xor_b32_e32 v205, v189, v79
	v_pk_add_f32 v[218:219], v[212:213], v[212:213] op_sel:[1,0] op_sel_hi:[0,1]
	v_add_f32_dpp v187, v214, v187 quad_perm:[1,0,3,2] row_mask:0xf bank_mask:0xf bound_ctrl:1
	v_xor_b32_e32 v199, v181, v216
	v_add_f32_dpp v79, v79, v205 quad_perm:[2,3,0,1] row_mask:0xf bank_mask:0xf bound_ctrl:1
	v_xor_b32_e32 v205, v189, v81
	v_add_f32_dpp v199, v216, v199 quad_perm:[1,0,3,2] row_mask:0xf bank_mask:0xf bound_ctrl:1
	v_xor_b32_e32 v200, v181, v218
	v_add_f32_dpp v81, v81, v205 quad_perm:[2,3,0,1] row_mask:0xf bank_mask:0xf bound_ctrl:1
	v_xor_b32_e32 v205, v189, v187
	v_add_f32_dpp v200, v218, v200 quad_perm:[1,0,3,2] row_mask:0xf bank_mask:0xf bound_ctrl:1
	v_xor_b32_e32 v201, v181, v220
	v_add_f32_dpp v187, v187, v205 quad_perm:[2,3,0,1] row_mask:0xf bank_mask:0xf bound_ctrl:1
	v_xor_b32_e32 v205, v189, v199
	v_add_f32_dpp v201, v220, v201 quad_perm:[1,0,3,2] row_mask:0xf bank_mask:0xf bound_ctrl:1
	v_xor_b32_e32 v203, v181, v202
	v_add_f32_dpp v199, v199, v205 quad_perm:[2,3,0,1] row_mask:0xf bank_mask:0xf bound_ctrl:1
	v_xor_b32_e32 v205, v189, v200
	v_pk_add_f32 v[208:209], v[208:209], v[208:209] op_sel:[0,1] op_sel_hi:[1,0] neg_lo:[0,1] neg_hi:[0,1]
	v_add_f32_dpp v202, v202, v203 quad_perm:[1,0,3,2] row_mask:0xf bank_mask:0xf bound_ctrl:1
	v_xor_b32_e32 v203, v181, v80
	v_add_f32_dpp v200, v200, v205 quad_perm:[2,3,0,1] row_mask:0xf bank_mask:0xf bound_ctrl:1
	v_xor_b32_e32 v205, v189, v201
	v_add_f32_dpp v80, v80, v203 quad_perm:[1,0,3,2] row_mask:0xf bank_mask:0xf bound_ctrl:1
	v_xor_b32_e32 v203, v181, v208
	v_add_f32_dpp v201, v201, v205 quad_perm:[2,3,0,1] row_mask:0xf bank_mask:0xf bound_ctrl:1
	v_xor_b32_e32 v205, v189, v202
	v_add_f32_dpp v203, v208, v203 quad_perm:[1,0,3,2] row_mask:0xf bank_mask:0xf bound_ctrl:1
	v_xor_b32_e32 v204, v181, v78
	v_add_f32_dpp v202, v202, v205 quad_perm:[2,3,0,1] row_mask:0xf bank_mask:0xf bound_ctrl:1
	v_xor_b32_e32 v205, v189, v80
	v_add_f32_dpp v78, v78, v204 quad_perm:[1,0,3,2] row_mask:0xf bank_mask:0xf bound_ctrl:1
	v_xor_b32_e32 v204, v181, v76
	v_add_f32_dpp v80, v80, v205 quad_perm:[2,3,0,1] row_mask:0xf bank_mask:0xf bound_ctrl:1
	v_xor_b32_e32 v205, v189, v203
	v_pk_add_f32 v[212:213], v[212:213], v[212:213] op_sel:[0,1] op_sel_hi:[1,0] neg_lo:[0,1] neg_hi:[0,1]
	v_add_f32_dpp v76, v76, v204 quad_perm:[1,0,3,2] row_mask:0xf bank_mask:0xf bound_ctrl:1
	v_xor_b32_e32 v204, v181, v74
	v_add_f32_dpp v203, v203, v205 quad_perm:[2,3,0,1] row_mask:0xf bank_mask:0xf bound_ctrl:1
	v_xor_b32_e32 v205, v189, v78
	v_add_f32_dpp v74, v74, v204 quad_perm:[1,0,3,2] row_mask:0xf bank_mask:0xf bound_ctrl:1
	v_xor_b32_e32 v204, v181, v212
	v_add_f32_dpp v205, v78, v205 quad_perm:[2,3,0,1] row_mask:0xf bank_mask:0xf bound_ctrl:1
	v_xor_b32_e32 v78, v189, v76
	v_add_f32_dpp v204, v212, v204 quad_perm:[1,0,3,2] row_mask:0xf bank_mask:0xf bound_ctrl:1
	s_ashr_i32 s27, s26, 31
	v_add_f32_dpp v206, v76, v78 quad_perm:[2,3,0,1] row_mask:0xf bank_mask:0xf bound_ctrl:1
	v_xor_b32_e32 v76, v189, v74
	v_max_f32_e64 v78, |v200|, |v201|
	s_nop 0
	v_add_f32_dpp v207, v74, v76 quad_perm:[2,3,0,1] row_mask:0xf bank_mask:0xf bound_ctrl:1
	v_xor_b32_e32 v74, v189, v204
	v_max_f32_e64 v76, |v79|, |v81|
	s_nop 0
	v_add_f32_dpp v204, v204, v74 quad_perm:[2,3,0,1] row_mask:0xf bank_mask:0xf bound_ctrl:1
	v_xor_b32_e32 v74, v189, v186
	s_nop 1
	v_add_f32_dpp v186, v186, v74 quad_perm:[2,3,0,1] row_mask:0xf bank_mask:0xf bound_ctrl:1
	v_max_f32_e64 v74, |v75|, |v77|
	v_max3_f32 v74, v74, 0, v76
	v_max_f32_e64 v76, |v187|, |v199|
	v_max3_f32 v74, v74, v76, v78
	v_max_f32_e64 v76, |v202|, |v80|
	v_max_f32_e64 v78, |v203|, |v205|
	v_max3_f32 v74, v74, v76, v78
	v_max_f32_e64 v76, |v206|, |v207|
	v_max_f32_e64 v78, |v204|, |v186|
	v_max3_f32 v222, v74, v76, v78
	v_cvt_pk_bf16_f32 v74, v75, v77
	v_cvt_pk_bf16_f32 v75, v79, v81
	v_cvt_pk_bf16_f32 v76, v187, v199
	v_cvt_pk_bf16_f32 v77, v200, v201
	v_cvt_pk_bf16_f32 v78, v202, v80
	v_cvt_pk_bf16_f32 v79, v203, v205
	v_cvt_pk_bf16_f32 v80, v206, v207
	v_cvt_pk_bf16_f32 v81, v204, v186
	v_and_b32_e32 v187, 0xffff0000, v89
	v_and_b32_e32 v186, 0xffff0000, v85
	v_lshlrev_b32_e32 v201, 16, v86
	v_lshlrev_b32_e32 v200, 16, v82
	v_and_b32_e32 v203, 0xffff0000, v86
	v_and_b32_e32 v202, 0xffff0000, v82
	v_lshlrev_b32_e32 v204, 16, v83
	v_lshlrev_b32_e32 v205, 16, v87
	v_and_b32_e32 v87, 0xffff0000, v87
	v_and_b32_e32 v86, 0xffff0000, v83
	v_lshlrev_b32_e32 v83, 16, v88
	v_lshlrev_b32_e32 v82, 16, v84
	v_and_b32_e32 v207, 0xffff0000, v88
	v_and_b32_e32 v206, 0xffff0000, v84
	v_lshlrev_b32_e32 v84, 16, v85
	v_lshlrev_b32_e32 v85, 16, v89
	v_pk_add_f32 v[88:89], v[200:201], v[202:203]
	v_pk_add_f32 v[208:209], v[204:205], v[86:87]
	v_pk_add_f32 v[210:211], v[82:83], v[206:207]
	v_pk_add_f32 v[212:213], v[84:85], v[186:187]
	v_pk_add_f32 v[200:201], v[200:201], v[202:203] neg_lo:[0,1] neg_hi:[0,1]
	v_pk_add_f32 v[86:87], v[204:205], v[86:87] neg_lo:[0,1] neg_hi:[0,1]
	v_pk_add_f32 v[82:83], v[82:83], v[206:207] neg_lo:[0,1] neg_hi:[0,1]
	v_pk_add_f32 v[84:85], v[84:85], v[186:187] neg_lo:[0,1] neg_hi:[0,1]
	v_pk_add_f32 v[214:215], v[88:89], v[208:209] neg_lo:[0,1] neg_hi:[0,1]
	v_pk_add_f32 v[88:89], v[88:89], v[208:209]
	v_pk_add_f32 v[208:209], v[210:211], v[212:213]
	v_pk_add_f32 v[186:187], v[200:201], v[86:87] neg_lo:[0,1] neg_hi:[0,1]
	v_pk_add_f32 v[202:203], v[82:83], v[84:85] neg_lo:[0,1] neg_hi:[0,1]
	v_pk_add_f32 v[86:87], v[200:201], v[86:87]
	v_pk_add_f32 v[82:83], v[82:83], v[84:85]
	v_pk_add_f32 v[216:217], v[210:211], v[212:213] neg_lo:[0,1] neg_hi:[0,1]
	v_pk_add_f32 v[210:211], v[88:89], v[208:209]
	v_pk_add_f32 v[84:85], v[86:87], v[82:83]
	v_pk_add_f32 v[82:83], v[86:87], v[82:83] neg_lo:[0,1] neg_hi:[0,1]
	v_pk_add_f32 v[88:89], v[88:89], v[208:209] neg_lo:[0,1] neg_hi:[0,1]
	v_pk_add_f32 v[208:209], v[214:215], v[216:217]
	v_pk_add_f32 v[212:213], v[214:215], v[216:217] neg_lo:[0,1] neg_hi:[0,1]
	v_pk_add_f32 v[86:87], v[186:187], v[202:203]
	v_pk_add_f32 v[186:187], v[186:187], v[202:203] neg_lo:[0,1] neg_hi:[0,1]
	v_pk_add_f32 v[200:201], v[210:211], v[210:211] op_sel:[1,0] op_sel_hi:[0,1]
	v_pk_add_f32 v[216:217], v[82:83], v[82:83] op_sel:[1,0] op_sel_hi:[0,1]
	v_pk_add_f32 v[82:83], v[82:83], v[82:83] op_sel:[0,1] op_sel_hi:[1,0] neg_lo:[0,1] neg_hi:[0,1]
	v_pk_add_f32 v[204:205], v[84:85], v[84:85] op_sel:[1,0] op_sel_hi:[0,1]
	v_pk_add_f32 v[84:85], v[84:85], v[84:85] op_sel:[0,1] op_sel_hi:[1,0] neg_lo:[0,1] neg_hi:[0,1]
	v_pk_add_f32 v[220:221], v[186:187], v[186:187] op_sel:[1,0] op_sel_hi:[0,1]
	v_pk_add_f32 v[186:187], v[186:187], v[186:187] op_sel:[0,1] op_sel_hi:[1,0] neg_lo:[0,1] neg_hi:[0,1]
	v_xor_b32_e32 v83, v181, v200
	v_pk_add_f32 v[202:203], v[210:211], v[210:211] op_sel:[0,1] op_sel_hi:[1,0] neg_lo:[0,1] neg_hi:[0,1]
	v_pk_add_f32 v[206:207], v[208:209], v[208:209] op_sel:[1,0] op_sel_hi:[0,1]
	v_pk_add_f32 v[210:211], v[86:87], v[86:87] op_sel:[1,0] op_sel_hi:[0,1]
	v_pk_add_f32 v[86:87], v[86:87], v[86:87] op_sel:[0,1] op_sel_hi:[1,0] neg_lo:[0,1] neg_hi:[0,1]
	v_add_f32_dpp v83, v200, v83 quad_perm:[1,0,3,2] row_mask:0xf bank_mask:0xf bound_ctrl:1
	v_xor_b32_e32 v85, v181, v204
	v_xor_b32_e32 v205, v181, v186
	v_pk_add_f32 v[214:215], v[88:89], v[88:89] op_sel:[1,0] op_sel_hi:[0,1]
	v_pk_add_f32 v[88:89], v[88:89], v[88:89] op_sel:[0,1] op_sel_hi:[1,0] neg_lo:[0,1] neg_hi:[0,1]
	v_add_f32_dpp v85, v204, v85 quad_perm:[1,0,3,2] row_mask:0xf bank_mask:0xf bound_ctrl:1
	v_xor_b32_e32 v87, v181, v206
	v_add_f32_dpp v186, v186, v205 quad_perm:[1,0,3,2] row_mask:0xf bank_mask:0xf bound_ctrl:1
	v_xor_b32_e32 v205, v189, v83
	v_add_f32_dpp v87, v206, v87 quad_perm:[1,0,3,2] row_mask:0xf bank_mask:0xf bound_ctrl:1
	v_xor_b32_e32 v89, v181, v210
	v_add_f32_dpp v83, v83, v205 quad_perm:[2,3,0,1] row_mask:0xf bank_mask:0xf bound_ctrl:1
	v_xor_b32_e32 v205, v189, v85
	v_add_f32_dpp v89, v210, v89 quad_perm:[1,0,3,2] row_mask:0xf bank_mask:0xf bound_ctrl:1
	v_xor_b32_e32 v187, v181, v214
	v_add_f32_dpp v85, v85, v205 quad_perm:[2,3,0,1] row_mask:0xf bank_mask:0xf bound_ctrl:1
	v_xor_b32_e32 v205, v189, v87
	v_pk_add_f32 v[218:219], v[212:213], v[212:213] op_sel:[1,0] op_sel_hi:[0,1]
	v_add_f32_dpp v187, v214, v187 quad_perm:[1,0,3,2] row_mask:0xf bank_mask:0xf bound_ctrl:1
	v_xor_b32_e32 v199, v181, v216
	v_add_f32_dpp v87, v87, v205 quad_perm:[2,3,0,1] row_mask:0xf bank_mask:0xf bound_ctrl:1
	v_xor_b32_e32 v205, v189, v89
	v_add_f32_dpp v199, v216, v199 quad_perm:[1,0,3,2] row_mask:0xf bank_mask:0xf bound_ctrl:1
	v_xor_b32_e32 v200, v181, v218
	v_add_f32_dpp v89, v89, v205 quad_perm:[2,3,0,1] row_mask:0xf bank_mask:0xf bound_ctrl:1
	v_xor_b32_e32 v205, v189, v187
	v_add_f32_dpp v200, v218, v200 quad_perm:[1,0,3,2] row_mask:0xf bank_mask:0xf bound_ctrl:1
	v_xor_b32_e32 v201, v181, v220
	v_add_f32_dpp v187, v187, v205 quad_perm:[2,3,0,1] row_mask:0xf bank_mask:0xf bound_ctrl:1
	v_xor_b32_e32 v205, v189, v199
	v_add_f32_dpp v201, v220, v201 quad_perm:[1,0,3,2] row_mask:0xf bank_mask:0xf bound_ctrl:1
	v_xor_b32_e32 v203, v181, v202
	v_add_f32_dpp v199, v199, v205 quad_perm:[2,3,0,1] row_mask:0xf bank_mask:0xf bound_ctrl:1
	v_xor_b32_e32 v205, v189, v200
	v_pk_add_f32 v[208:209], v[208:209], v[208:209] op_sel:[0,1] op_sel_hi:[1,0] neg_lo:[0,1] neg_hi:[0,1]
	v_add_f32_dpp v202, v202, v203 quad_perm:[1,0,3,2] row_mask:0xf bank_mask:0xf bound_ctrl:1
	v_xor_b32_e32 v203, v181, v84
	v_add_f32_dpp v200, v200, v205 quad_perm:[2,3,0,1] row_mask:0xf bank_mask:0xf bound_ctrl:1
	v_xor_b32_e32 v205, v189, v201
	v_add_f32_dpp v84, v84, v203 quad_perm:[1,0,3,2] row_mask:0xf bank_mask:0xf bound_ctrl:1
	v_xor_b32_e32 v203, v181, v208
	v_add_f32_dpp v201, v201, v205 quad_perm:[2,3,0,1] row_mask:0xf bank_mask:0xf bound_ctrl:1
	v_xor_b32_e32 v205, v189, v202
	v_add_f32_dpp v203, v208, v203 quad_perm:[1,0,3,2] row_mask:0xf bank_mask:0xf bound_ctrl:1
	v_xor_b32_e32 v204, v181, v86
	v_add_f32_dpp v202, v202, v205 quad_perm:[2,3,0,1] row_mask:0xf bank_mask:0xf bound_ctrl:1
	v_xor_b32_e32 v205, v189, v84
	v_add_f32_dpp v86, v86, v204 quad_perm:[1,0,3,2] row_mask:0xf bank_mask:0xf bound_ctrl:1
	v_xor_b32_e32 v204, v181, v88
	v_add_f32_dpp v205, v84, v205 quad_perm:[2,3,0,1] row_mask:0xf bank_mask:0xf bound_ctrl:1
	v_xor_b32_e32 v84, v189, v203
	v_pk_add_f32 v[212:213], v[212:213], v[212:213] op_sel:[0,1] op_sel_hi:[1,0] neg_lo:[0,1] neg_hi:[0,1]
	v_add_f32_dpp v88, v88, v204 quad_perm:[1,0,3,2] row_mask:0xf bank_mask:0xf bound_ctrl:1
	v_xor_b32_e32 v204, v181, v82
	v_add_f32_dpp v203, v203, v84 quad_perm:[2,3,0,1] row_mask:0xf bank_mask:0xf bound_ctrl:1
	v_xor_b32_e32 v84, v189, v86
	v_add_f32_dpp v82, v82, v204 quad_perm:[1,0,3,2] row_mask:0xf bank_mask:0xf bound_ctrl:1
	v_xor_b32_e32 v204, v181, v212
	v_add_f32_dpp v206, v86, v84 quad_perm:[2,3,0,1] row_mask:0xf bank_mask:0xf bound_ctrl:1
	v_xor_b32_e32 v84, v189, v88
	v_add_f32_dpp v204, v212, v204 quad_perm:[1,0,3,2] row_mask:0xf bank_mask:0xf bound_ctrl:1
	v_max_f32_e64 v86, |v200|, |v201|
	v_add_f32_dpp v88, v88, v84 quad_perm:[2,3,0,1] row_mask:0xf bank_mask:0xf bound_ctrl:1
	v_xor_b32_e32 v84, v189, v82
	s_nop 1
	v_add_f32_dpp v207, v82, v84 quad_perm:[2,3,0,1] row_mask:0xf bank_mask:0xf bound_ctrl:1
	v_xor_b32_e32 v82, v189, v204
	v_max_f32_e64 v84, |v87|, |v89|
	s_nop 0
	v_add_f32_dpp v204, v204, v82 quad_perm:[2,3,0,1] row_mask:0xf bank_mask:0xf bound_ctrl:1
	v_xor_b32_e32 v82, v189, v186
	s_nop 1
	v_add_f32_dpp v186, v186, v82 quad_perm:[2,3,0,1] row_mask:0xf bank_mask:0xf bound_ctrl:1
	v_max_f32_e64 v82, |v83|, |v85|
	v_max3_f32 v82, v222, v82, v84
	v_max_f32_e64 v84, |v187|, |v199|
	v_max3_f32 v82, v82, v84, v86
	v_max_f32_e64 v84, |v202|, |v205|
	v_max_f32_e64 v86, |v203|, |v206|
	v_max3_f32 v82, v82, v84, v86
	v_max_f32_e64 v84, |v88|, |v207|
	v_max_f32_e64 v86, |v204|, |v186|
	v_max3_f32 v222, v82, v84, v86
	v_cvt_pk_bf16_f32 v82, v83, v85
	v_cvt_pk_bf16_f32 v83, v87, v89
	v_cvt_pk_bf16_f32 v84, v187, v199
	v_cvt_pk_bf16_f32 v85, v200, v201
	v_cvt_pk_bf16_f32 v86, v202, v205
	v_cvt_pk_bf16_f32 v87, v203, v206
	v_cvt_pk_bf16_f32 v88, v88, v207
	v_cvt_pk_bf16_f32 v89, v204, v186
	v_and_b32_e32 v187, 0xffff0000, v97
	v_and_b32_e32 v186, 0xffff0000, v93
	v_lshlrev_b32_e32 v201, 16, v94
	v_lshlrev_b32_e32 v200, 16, v90
	v_and_b32_e32 v203, 0xffff0000, v94
	v_and_b32_e32 v202, 0xffff0000, v90
	v_lshlrev_b32_e32 v204, 16, v91
	v_lshlrev_b32_e32 v205, 16, v95
	v_and_b32_e32 v95, 0xffff0000, v95
	v_and_b32_e32 v94, 0xffff0000, v91
	v_lshlrev_b32_e32 v91, 16, v96
	v_lshlrev_b32_e32 v90, 16, v92
	v_and_b32_e32 v207, 0xffff0000, v96
	v_and_b32_e32 v206, 0xffff0000, v92
	v_lshlrev_b32_e32 v92, 16, v93
	v_lshlrev_b32_e32 v93, 16, v97
	v_pk_add_f32 v[96:97], v[200:201], v[202:203]
	v_pk_add_f32 v[208:209], v[204:205], v[94:95]
	v_pk_add_f32 v[210:211], v[90:91], v[206:207]
	v_pk_add_f32 v[212:213], v[92:93], v[186:187]
	v_pk_add_f32 v[200:201], v[200:201], v[202:203] neg_lo:[0,1] neg_hi:[0,1]
	v_pk_add_f32 v[94:95], v[204:205], v[94:95] neg_lo:[0,1] neg_hi:[0,1]
	v_pk_add_f32 v[90:91], v[90:91], v[206:207] neg_lo:[0,1] neg_hi:[0,1]
	v_pk_add_f32 v[92:93], v[92:93], v[186:187] neg_lo:[0,1] neg_hi:[0,1]
	v_pk_add_f32 v[214:215], v[96:97], v[208:209] neg_lo:[0,1] neg_hi:[0,1]
	v_pk_add_f32 v[96:97], v[96:97], v[208:209]
	v_pk_add_f32 v[208:209], v[210:211], v[212:213]
	v_pk_add_f32 v[186:187], v[200:201], v[94:95] neg_lo:[0,1] neg_hi:[0,1]
	v_pk_add_f32 v[202:203], v[90:91], v[92:93] neg_lo:[0,1] neg_hi:[0,1]
	v_pk_add_f32 v[94:95], v[200:201], v[94:95]
	v_pk_add_f32 v[90:91], v[90:91], v[92:93]
	v_pk_add_f32 v[216:217], v[210:211], v[212:213] neg_lo:[0,1] neg_hi:[0,1]
	v_pk_add_f32 v[210:211], v[96:97], v[208:209]
	v_pk_add_f32 v[92:93], v[94:95], v[90:91]
	v_pk_add_f32 v[90:91], v[94:95], v[90:91] neg_lo:[0,1] neg_hi:[0,1]
	v_pk_add_f32 v[96:97], v[96:97], v[208:209] neg_lo:[0,1] neg_hi:[0,1]
	v_pk_add_f32 v[208:209], v[214:215], v[216:217]
	v_pk_add_f32 v[212:213], v[214:215], v[216:217] neg_lo:[0,1] neg_hi:[0,1]
	v_pk_add_f32 v[94:95], v[186:187], v[202:203]
	v_pk_add_f32 v[186:187], v[186:187], v[202:203] neg_lo:[0,1] neg_hi:[0,1]
	v_pk_add_f32 v[200:201], v[210:211], v[210:211] op_sel:[1,0] op_sel_hi:[0,1]
	v_pk_add_f32 v[216:217], v[90:91], v[90:91] op_sel:[1,0] op_sel_hi:[0,1]
	v_pk_add_f32 v[90:91], v[90:91], v[90:91] op_sel:[0,1] op_sel_hi:[1,0] neg_lo:[0,1] neg_hi:[0,1]
	v_pk_add_f32 v[204:205], v[92:93], v[92:93] op_sel:[1,0] op_sel_hi:[0,1]
	v_pk_add_f32 v[92:93], v[92:93], v[92:93] op_sel:[0,1] op_sel_hi:[1,0] neg_lo:[0,1] neg_hi:[0,1]
	v_pk_add_f32 v[220:221], v[186:187], v[186:187] op_sel:[1,0] op_sel_hi:[0,1]
	v_pk_add_f32 v[186:187], v[186:187], v[186:187] op_sel:[0,1] op_sel_hi:[1,0] neg_lo:[0,1] neg_hi:[0,1]
	v_xor_b32_e32 v91, v181, v200
	v_pk_add_f32 v[202:203], v[210:211], v[210:211] op_sel:[0,1] op_sel_hi:[1,0] neg_lo:[0,1] neg_hi:[0,1]
	v_pk_add_f32 v[206:207], v[208:209], v[208:209] op_sel:[1,0] op_sel_hi:[0,1]
	v_pk_add_f32 v[210:211], v[94:95], v[94:95] op_sel:[1,0] op_sel_hi:[0,1]
	v_pk_add_f32 v[94:95], v[94:95], v[94:95] op_sel:[0,1] op_sel_hi:[1,0] neg_lo:[0,1] neg_hi:[0,1]
	v_add_f32_dpp v91, v200, v91 quad_perm:[1,0,3,2] row_mask:0xf bank_mask:0xf bound_ctrl:1
	v_xor_b32_e32 v93, v181, v204
	v_xor_b32_e32 v205, v181, v186
	v_pk_add_f32 v[214:215], v[96:97], v[96:97] op_sel:[1,0] op_sel_hi:[0,1]
	v_pk_add_f32 v[96:97], v[96:97], v[96:97] op_sel:[0,1] op_sel_hi:[1,0] neg_lo:[0,1] neg_hi:[0,1]
	v_add_f32_dpp v93, v204, v93 quad_perm:[1,0,3,2] row_mask:0xf bank_mask:0xf bound_ctrl:1
	v_xor_b32_e32 v95, v181, v206
	v_add_f32_dpp v186, v186, v205 quad_perm:[1,0,3,2] row_mask:0xf bank_mask:0xf bound_ctrl:1
	v_xor_b32_e32 v205, v189, v91
	v_add_f32_dpp v95, v206, v95 quad_perm:[1,0,3,2] row_mask:0xf bank_mask:0xf bound_ctrl:1
	v_xor_b32_e32 v97, v181, v210
	v_add_f32_dpp v91, v91, v205 quad_perm:[2,3,0,1] row_mask:0xf bank_mask:0xf bound_ctrl:1
	v_xor_b32_e32 v205, v189, v93
	v_add_f32_dpp v97, v210, v97 quad_perm:[1,0,3,2] row_mask:0xf bank_mask:0xf bound_ctrl:1
	v_xor_b32_e32 v187, v181, v214
	v_add_f32_dpp v93, v93, v205 quad_perm:[2,3,0,1] row_mask:0xf bank_mask:0xf bound_ctrl:1
	v_xor_b32_e32 v205, v189, v95
	v_pk_add_f32 v[218:219], v[212:213], v[212:213] op_sel:[1,0] op_sel_hi:[0,1]
	v_add_f32_dpp v187, v214, v187 quad_perm:[1,0,3,2] row_mask:0xf bank_mask:0xf bound_ctrl:1
	v_xor_b32_e32 v199, v181, v216
	v_add_f32_dpp v95, v95, v205 quad_perm:[2,3,0,1] row_mask:0xf bank_mask:0xf bound_ctrl:1
	v_xor_b32_e32 v205, v189, v97
	v_add_f32_dpp v199, v216, v199 quad_perm:[1,0,3,2] row_mask:0xf bank_mask:0xf bound_ctrl:1
	v_xor_b32_e32 v200, v181, v218
	v_add_f32_dpp v97, v97, v205 quad_perm:[2,3,0,1] row_mask:0xf bank_mask:0xf bound_ctrl:1
	v_xor_b32_e32 v205, v189, v187
	v_add_f32_dpp v200, v218, v200 quad_perm:[1,0,3,2] row_mask:0xf bank_mask:0xf bound_ctrl:1
	v_xor_b32_e32 v201, v181, v220
	v_add_f32_dpp v187, v187, v205 quad_perm:[2,3,0,1] row_mask:0xf bank_mask:0xf bound_ctrl:1
	v_xor_b32_e32 v205, v189, v199
	v_add_f32_dpp v201, v220, v201 quad_perm:[1,0,3,2] row_mask:0xf bank_mask:0xf bound_ctrl:1
	v_xor_b32_e32 v203, v181, v202
	v_add_f32_dpp v199, v199, v205 quad_perm:[2,3,0,1] row_mask:0xf bank_mask:0xf bound_ctrl:1
	v_xor_b32_e32 v205, v189, v200
	v_pk_add_f32 v[208:209], v[208:209], v[208:209] op_sel:[0,1] op_sel_hi:[1,0] neg_lo:[0,1] neg_hi:[0,1]
	v_add_f32_dpp v202, v202, v203 quad_perm:[1,0,3,2] row_mask:0xf bank_mask:0xf bound_ctrl:1
	v_xor_b32_e32 v203, v181, v92
	v_add_f32_dpp v200, v200, v205 quad_perm:[2,3,0,1] row_mask:0xf bank_mask:0xf bound_ctrl:1
	v_xor_b32_e32 v205, v189, v201
	v_add_f32_dpp v92, v92, v203 quad_perm:[1,0,3,2] row_mask:0xf bank_mask:0xf bound_ctrl:1
	v_xor_b32_e32 v203, v181, v208
	v_add_f32_dpp v201, v201, v205 quad_perm:[2,3,0,1] row_mask:0xf bank_mask:0xf bound_ctrl:1
	v_xor_b32_e32 v205, v189, v202
	v_add_f32_dpp v203, v208, v203 quad_perm:[1,0,3,2] row_mask:0xf bank_mask:0xf bound_ctrl:1
	v_xor_b32_e32 v204, v181, v94
	v_add_f32_dpp v202, v202, v205 quad_perm:[2,3,0,1] row_mask:0xf bank_mask:0xf bound_ctrl:1
	v_xor_b32_e32 v205, v189, v92
	v_add_f32_dpp v94, v94, v204 quad_perm:[1,0,3,2] row_mask:0xf bank_mask:0xf bound_ctrl:1
	v_xor_b32_e32 v204, v181, v96
	v_add_f32_dpp v205, v92, v205 quad_perm:[2,3,0,1] row_mask:0xf bank_mask:0xf bound_ctrl:1
	v_xor_b32_e32 v92, v189, v203
	v_pk_add_f32 v[212:213], v[212:213], v[212:213] op_sel:[0,1] op_sel_hi:[1,0] neg_lo:[0,1] neg_hi:[0,1]
	v_add_f32_dpp v96, v96, v204 quad_perm:[1,0,3,2] row_mask:0xf bank_mask:0xf bound_ctrl:1
	v_xor_b32_e32 v204, v181, v90
	v_add_f32_dpp v203, v203, v92 quad_perm:[2,3,0,1] row_mask:0xf bank_mask:0xf bound_ctrl:1
	v_xor_b32_e32 v92, v189, v94
	v_add_f32_dpp v90, v90, v204 quad_perm:[1,0,3,2] row_mask:0xf bank_mask:0xf bound_ctrl:1
	v_xor_b32_e32 v204, v181, v212
	v_add_f32_dpp v206, v94, v92 quad_perm:[2,3,0,1] row_mask:0xf bank_mask:0xf bound_ctrl:1
	v_xor_b32_e32 v92, v189, v96
	v_add_f32_dpp v204, v212, v204 quad_perm:[1,0,3,2] row_mask:0xf bank_mask:0xf bound_ctrl:1
	v_max_f32_e64 v94, |v200|, |v201|
	v_add_f32_dpp v96, v96, v92 quad_perm:[2,3,0,1] row_mask:0xf bank_mask:0xf bound_ctrl:1
	v_xor_b32_e32 v92, v189, v90
	s_nop 1
	v_add_f32_dpp v207, v90, v92 quad_perm:[2,3,0,1] row_mask:0xf bank_mask:0xf bound_ctrl:1
	v_xor_b32_e32 v90, v189, v204
	v_max_f32_e64 v92, |v95|, |v97|
	s_nop 0
	v_add_f32_dpp v204, v204, v90 quad_perm:[2,3,0,1] row_mask:0xf bank_mask:0xf bound_ctrl:1
	v_xor_b32_e32 v90, v189, v186
	s_nop 1
	v_add_f32_dpp v186, v186, v90 quad_perm:[2,3,0,1] row_mask:0xf bank_mask:0xf bound_ctrl:1
	v_max_f32_e64 v90, |v91|, |v93|
	v_max3_f32 v90, v222, v90, v92
	v_max_f32_e64 v92, |v187|, |v199|
	v_max3_f32 v90, v90, v92, v94
	v_max_f32_e64 v92, |v202|, |v205|
	v_max_f32_e64 v94, |v203|, |v206|
	v_max3_f32 v90, v90, v92, v94
	v_max_f32_e64 v92, |v96|, |v207|
	v_max_f32_e64 v94, |v204|, |v186|
	v_max3_f32 v222, v90, v92, v94
	v_cvt_pk_bf16_f32 v90, v91, v93
	v_cvt_pk_bf16_f32 v91, v95, v97
	v_cvt_pk_bf16_f32 v92, v187, v199
	v_cvt_pk_bf16_f32 v93, v200, v201
	v_cvt_pk_bf16_f32 v94, v202, v205
	v_cvt_pk_bf16_f32 v95, v203, v206
	v_cvt_pk_bf16_f32 v96, v96, v207
	v_cvt_pk_bf16_f32 v97, v204, v186
	v_and_b32_e32 v187, 0xffff0000, v109
	v_and_b32_e32 v186, 0xffff0000, v105
	v_lshlrev_b32_e32 v201, 16, v106
	v_lshlrev_b32_e32 v200, 16, v102
	v_and_b32_e32 v203, 0xffff0000, v106
	v_and_b32_e32 v202, 0xffff0000, v102
	v_lshlrev_b32_e32 v204, 16, v103
	v_lshlrev_b32_e32 v205, 16, v107
	v_and_b32_e32 v107, 0xffff0000, v107
	v_and_b32_e32 v106, 0xffff0000, v103
	v_lshlrev_b32_e32 v103, 16, v108
	v_lshlrev_b32_e32 v102, 16, v104
	v_and_b32_e32 v207, 0xffff0000, v108
	v_and_b32_e32 v206, 0xffff0000, v104
	v_lshlrev_b32_e32 v104, 16, v105
	v_lshlrev_b32_e32 v105, 16, v109
	v_pk_add_f32 v[108:109], v[200:201], v[202:203]
	v_pk_add_f32 v[208:209], v[204:205], v[106:107]
	v_pk_add_f32 v[210:211], v[102:103], v[206:207]
	v_pk_add_f32 v[212:213], v[104:105], v[186:187]
	v_pk_add_f32 v[200:201], v[200:201], v[202:203] neg_lo:[0,1] neg_hi:[0,1]
	v_pk_add_f32 v[106:107], v[204:205], v[106:107] neg_lo:[0,1] neg_hi:[0,1]
	v_pk_add_f32 v[102:103], v[102:103], v[206:207] neg_lo:[0,1] neg_hi:[0,1]
	v_pk_add_f32 v[104:105], v[104:105], v[186:187] neg_lo:[0,1] neg_hi:[0,1]
	v_pk_add_f32 v[214:215], v[108:109], v[208:209] neg_lo:[0,1] neg_hi:[0,1]
	v_pk_add_f32 v[108:109], v[108:109], v[208:209]
	v_pk_add_f32 v[208:209], v[210:211], v[212:213]
	v_pk_add_f32 v[186:187], v[200:201], v[106:107] neg_lo:[0,1] neg_hi:[0,1]
	v_pk_add_f32 v[202:203], v[102:103], v[104:105] neg_lo:[0,1] neg_hi:[0,1]
	v_pk_add_f32 v[106:107], v[200:201], v[106:107]
	v_pk_add_f32 v[102:103], v[102:103], v[104:105]
	v_pk_add_f32 v[216:217], v[210:211], v[212:213] neg_lo:[0,1] neg_hi:[0,1]
	v_pk_add_f32 v[210:211], v[108:109], v[208:209]
	v_pk_add_f32 v[104:105], v[106:107], v[102:103]
	v_pk_add_f32 v[102:103], v[106:107], v[102:103] neg_lo:[0,1] neg_hi:[0,1]
	v_pk_add_f32 v[108:109], v[108:109], v[208:209] neg_lo:[0,1] neg_hi:[0,1]
	v_pk_add_f32 v[208:209], v[214:215], v[216:217]
	v_pk_add_f32 v[212:213], v[214:215], v[216:217] neg_lo:[0,1] neg_hi:[0,1]
	v_pk_add_f32 v[106:107], v[186:187], v[202:203]
	v_pk_add_f32 v[186:187], v[186:187], v[202:203] neg_lo:[0,1] neg_hi:[0,1]
	v_pk_add_f32 v[200:201], v[210:211], v[210:211] op_sel:[1,0] op_sel_hi:[0,1]
	v_pk_add_f32 v[216:217], v[102:103], v[102:103] op_sel:[1,0] op_sel_hi:[0,1]
	v_pk_add_f32 v[102:103], v[102:103], v[102:103] op_sel:[0,1] op_sel_hi:[1,0] neg_lo:[0,1] neg_hi:[0,1]
	v_pk_add_f32 v[204:205], v[104:105], v[104:105] op_sel:[1,0] op_sel_hi:[0,1]
	v_pk_add_f32 v[104:105], v[104:105], v[104:105] op_sel:[0,1] op_sel_hi:[1,0] neg_lo:[0,1] neg_hi:[0,1]
	v_pk_add_f32 v[220:221], v[186:187], v[186:187] op_sel:[1,0] op_sel_hi:[0,1]
	v_pk_add_f32 v[186:187], v[186:187], v[186:187] op_sel:[0,1] op_sel_hi:[1,0] neg_lo:[0,1] neg_hi:[0,1]
	v_xor_b32_e32 v103, v181, v200
	v_pk_add_f32 v[202:203], v[210:211], v[210:211] op_sel:[0,1] op_sel_hi:[1,0] neg_lo:[0,1] neg_hi:[0,1]
	v_pk_add_f32 v[206:207], v[208:209], v[208:209] op_sel:[1,0] op_sel_hi:[0,1]
	v_pk_add_f32 v[210:211], v[106:107], v[106:107] op_sel:[1,0] op_sel_hi:[0,1]
	v_pk_add_f32 v[106:107], v[106:107], v[106:107] op_sel:[0,1] op_sel_hi:[1,0] neg_lo:[0,1] neg_hi:[0,1]
	v_add_f32_dpp v103, v200, v103 quad_perm:[1,0,3,2] row_mask:0xf bank_mask:0xf bound_ctrl:1
	v_xor_b32_e32 v105, v181, v204
	v_xor_b32_e32 v205, v181, v186
	v_pk_add_f32 v[214:215], v[108:109], v[108:109] op_sel:[1,0] op_sel_hi:[0,1]
	v_pk_add_f32 v[108:109], v[108:109], v[108:109] op_sel:[0,1] op_sel_hi:[1,0] neg_lo:[0,1] neg_hi:[0,1]
	v_add_f32_dpp v105, v204, v105 quad_perm:[1,0,3,2] row_mask:0xf bank_mask:0xf bound_ctrl:1
	v_xor_b32_e32 v107, v181, v206
	v_add_f32_dpp v186, v186, v205 quad_perm:[1,0,3,2] row_mask:0xf bank_mask:0xf bound_ctrl:1
	v_xor_b32_e32 v205, v189, v103
	v_add_f32_dpp v107, v206, v107 quad_perm:[1,0,3,2] row_mask:0xf bank_mask:0xf bound_ctrl:1
	v_xor_b32_e32 v109, v181, v210
	v_add_f32_dpp v103, v103, v205 quad_perm:[2,3,0,1] row_mask:0xf bank_mask:0xf bound_ctrl:1
	v_xor_b32_e32 v205, v189, v105
	v_add_f32_dpp v109, v210, v109 quad_perm:[1,0,3,2] row_mask:0xf bank_mask:0xf bound_ctrl:1
	v_xor_b32_e32 v187, v181, v214
	v_add_f32_dpp v105, v105, v205 quad_perm:[2,3,0,1] row_mask:0xf bank_mask:0xf bound_ctrl:1
	v_xor_b32_e32 v205, v189, v107
	v_pk_add_f32 v[218:219], v[212:213], v[212:213] op_sel:[1,0] op_sel_hi:[0,1]
	v_add_f32_dpp v187, v214, v187 quad_perm:[1,0,3,2] row_mask:0xf bank_mask:0xf bound_ctrl:1
	v_xor_b32_e32 v199, v181, v216
	v_add_f32_dpp v107, v107, v205 quad_perm:[2,3,0,1] row_mask:0xf bank_mask:0xf bound_ctrl:1
	v_xor_b32_e32 v205, v189, v109
	v_add_f32_dpp v199, v216, v199 quad_perm:[1,0,3,2] row_mask:0xf bank_mask:0xf bound_ctrl:1
	v_xor_b32_e32 v200, v181, v218
	v_add_f32_dpp v109, v109, v205 quad_perm:[2,3,0,1] row_mask:0xf bank_mask:0xf bound_ctrl:1
	v_xor_b32_e32 v205, v189, v187
	v_add_f32_dpp v200, v218, v200 quad_perm:[1,0,3,2] row_mask:0xf bank_mask:0xf bound_ctrl:1
	v_xor_b32_e32 v201, v181, v220
	v_add_f32_dpp v187, v187, v205 quad_perm:[2,3,0,1] row_mask:0xf bank_mask:0xf bound_ctrl:1
	v_xor_b32_e32 v205, v189, v199
	v_add_f32_dpp v201, v220, v201 quad_perm:[1,0,3,2] row_mask:0xf bank_mask:0xf bound_ctrl:1
	v_xor_b32_e32 v203, v181, v202
	v_add_f32_dpp v199, v199, v205 quad_perm:[2,3,0,1] row_mask:0xf bank_mask:0xf bound_ctrl:1
	v_xor_b32_e32 v205, v189, v200
	v_pk_add_f32 v[208:209], v[208:209], v[208:209] op_sel:[0,1] op_sel_hi:[1,0] neg_lo:[0,1] neg_hi:[0,1]
	v_add_f32_dpp v202, v202, v203 quad_perm:[1,0,3,2] row_mask:0xf bank_mask:0xf bound_ctrl:1
	v_xor_b32_e32 v203, v181, v104
	v_add_f32_dpp v200, v200, v205 quad_perm:[2,3,0,1] row_mask:0xf bank_mask:0xf bound_ctrl:1
	v_xor_b32_e32 v205, v189, v201
	v_add_f32_dpp v104, v104, v203 quad_perm:[1,0,3,2] row_mask:0xf bank_mask:0xf bound_ctrl:1
	v_xor_b32_e32 v203, v181, v208
	v_add_f32_dpp v201, v201, v205 quad_perm:[2,3,0,1] row_mask:0xf bank_mask:0xf bound_ctrl:1
	v_xor_b32_e32 v205, v189, v202
	v_add_f32_dpp v203, v208, v203 quad_perm:[1,0,3,2] row_mask:0xf bank_mask:0xf bound_ctrl:1
	v_xor_b32_e32 v204, v181, v106
	v_add_f32_dpp v202, v202, v205 quad_perm:[2,3,0,1] row_mask:0xf bank_mask:0xf bound_ctrl:1
	v_xor_b32_e32 v205, v189, v104
	v_add_f32_dpp v106, v106, v204 quad_perm:[1,0,3,2] row_mask:0xf bank_mask:0xf bound_ctrl:1
	v_xor_b32_e32 v204, v181, v108
	v_add_f32_dpp v205, v104, v205 quad_perm:[2,3,0,1] row_mask:0xf bank_mask:0xf bound_ctrl:1
	v_xor_b32_e32 v104, v189, v203
	v_pk_add_f32 v[212:213], v[212:213], v[212:213] op_sel:[0,1] op_sel_hi:[1,0] neg_lo:[0,1] neg_hi:[0,1]
	v_add_f32_dpp v108, v108, v204 quad_perm:[1,0,3,2] row_mask:0xf bank_mask:0xf bound_ctrl:1
	v_xor_b32_e32 v204, v181, v102
	v_add_f32_dpp v203, v203, v104 quad_perm:[2,3,0,1] row_mask:0xf bank_mask:0xf bound_ctrl:1
	v_xor_b32_e32 v104, v189, v106
	v_add_f32_dpp v102, v102, v204 quad_perm:[1,0,3,2] row_mask:0xf bank_mask:0xf bound_ctrl:1
	v_xor_b32_e32 v204, v181, v212
	v_add_f32_dpp v206, v106, v104 quad_perm:[2,3,0,1] row_mask:0xf bank_mask:0xf bound_ctrl:1
	v_xor_b32_e32 v104, v189, v108
	v_add_f32_dpp v204, v212, v204 quad_perm:[1,0,3,2] row_mask:0xf bank_mask:0xf bound_ctrl:1
	v_max_f32_e64 v106, |v200|, |v201|
	v_add_f32_dpp v108, v108, v104 quad_perm:[2,3,0,1] row_mask:0xf bank_mask:0xf bound_ctrl:1
	v_xor_b32_e32 v104, v189, v102
	s_nop 1
	v_add_f32_dpp v207, v102, v104 quad_perm:[2,3,0,1] row_mask:0xf bank_mask:0xf bound_ctrl:1
	v_xor_b32_e32 v102, v189, v204
	v_max_f32_e64 v104, |v107|, |v109|
	s_nop 0
	v_add_f32_dpp v204, v204, v102 quad_perm:[2,3,0,1] row_mask:0xf bank_mask:0xf bound_ctrl:1
	v_xor_b32_e32 v102, v189, v186
	s_nop 1
	v_add_f32_dpp v186, v186, v102 quad_perm:[2,3,0,1] row_mask:0xf bank_mask:0xf bound_ctrl:1
	v_max_f32_e64 v102, |v103|, |v105|
	v_max3_f32 v102, v222, v102, v104
	v_max_f32_e64 v104, |v187|, |v199|
	v_max3_f32 v102, v102, v104, v106
	v_max_f32_e64 v104, |v202|, |v205|
	v_max_f32_e64 v106, |v203|, |v206|
	v_max3_f32 v102, v102, v104, v106
	v_max_f32_e64 v104, |v108|, |v207|
	v_max_f32_e64 v106, |v204|, |v186|
	v_max3_f32 v222, v102, v104, v106
	v_cvt_pk_bf16_f32 v102, v103, v105
	v_cvt_pk_bf16_f32 v103, v107, v109
	v_cvt_pk_bf16_f32 v104, v187, v199
	v_cvt_pk_bf16_f32 v105, v200, v201
	v_cvt_pk_bf16_f32 v106, v202, v205
	v_cvt_pk_bf16_f32 v107, v203, v206
	v_cvt_pk_bf16_f32 v108, v108, v207
	v_cvt_pk_bf16_f32 v109, v204, v186
	v_and_b32_e32 v187, 0xffff0000, v121
	v_and_b32_e32 v186, 0xffff0000, v117
	v_lshlrev_b32_e32 v201, 16, v118
	v_lshlrev_b32_e32 v200, 16, v114
	v_and_b32_e32 v203, 0xffff0000, v118
	v_and_b32_e32 v202, 0xffff0000, v114
	v_lshlrev_b32_e32 v204, 16, v115
	v_lshlrev_b32_e32 v205, 16, v119
	v_and_b32_e32 v119, 0xffff0000, v119
	v_and_b32_e32 v118, 0xffff0000, v115
	v_lshlrev_b32_e32 v115, 16, v120
	v_lshlrev_b32_e32 v114, 16, v116
	v_and_b32_e32 v207, 0xffff0000, v120
	v_and_b32_e32 v206, 0xffff0000, v116
	v_lshlrev_b32_e32 v116, 16, v117
	v_lshlrev_b32_e32 v117, 16, v121
	v_pk_add_f32 v[120:121], v[200:201], v[202:203]
	v_pk_add_f32 v[208:209], v[204:205], v[118:119]
	v_pk_add_f32 v[210:211], v[114:115], v[206:207]
	v_pk_add_f32 v[212:213], v[116:117], v[186:187]
	v_pk_add_f32 v[200:201], v[200:201], v[202:203] neg_lo:[0,1] neg_hi:[0,1]
	v_pk_add_f32 v[118:119], v[204:205], v[118:119] neg_lo:[0,1] neg_hi:[0,1]
	v_pk_add_f32 v[114:115], v[114:115], v[206:207] neg_lo:[0,1] neg_hi:[0,1]
	v_pk_add_f32 v[116:117], v[116:117], v[186:187] neg_lo:[0,1] neg_hi:[0,1]
	v_pk_add_f32 v[214:215], v[120:121], v[208:209] neg_lo:[0,1] neg_hi:[0,1]
	v_pk_add_f32 v[120:121], v[120:121], v[208:209]
	v_pk_add_f32 v[208:209], v[210:211], v[212:213]
	v_pk_add_f32 v[186:187], v[200:201], v[118:119] neg_lo:[0,1] neg_hi:[0,1]
	v_pk_add_f32 v[202:203], v[114:115], v[116:117] neg_lo:[0,1] neg_hi:[0,1]
	v_pk_add_f32 v[118:119], v[200:201], v[118:119]
	v_pk_add_f32 v[114:115], v[114:115], v[116:117]
	v_pk_add_f32 v[216:217], v[210:211], v[212:213] neg_lo:[0,1] neg_hi:[0,1]
	v_pk_add_f32 v[210:211], v[120:121], v[208:209]
	v_pk_add_f32 v[116:117], v[118:119], v[114:115]
	v_pk_add_f32 v[114:115], v[118:119], v[114:115] neg_lo:[0,1] neg_hi:[0,1]
	v_pk_add_f32 v[120:121], v[120:121], v[208:209] neg_lo:[0,1] neg_hi:[0,1]
	v_pk_add_f32 v[208:209], v[214:215], v[216:217]
	v_pk_add_f32 v[212:213], v[214:215], v[216:217] neg_lo:[0,1] neg_hi:[0,1]
	v_pk_add_f32 v[118:119], v[186:187], v[202:203]
	v_pk_add_f32 v[186:187], v[186:187], v[202:203] neg_lo:[0,1] neg_hi:[0,1]
	v_pk_add_f32 v[200:201], v[210:211], v[210:211] op_sel:[1,0] op_sel_hi:[0,1]
	v_pk_add_f32 v[216:217], v[114:115], v[114:115] op_sel:[1,0] op_sel_hi:[0,1]
	v_pk_add_f32 v[114:115], v[114:115], v[114:115] op_sel:[0,1] op_sel_hi:[1,0] neg_lo:[0,1] neg_hi:[0,1]
	v_pk_add_f32 v[204:205], v[116:117], v[116:117] op_sel:[1,0] op_sel_hi:[0,1]
	v_pk_add_f32 v[116:117], v[116:117], v[116:117] op_sel:[0,1] op_sel_hi:[1,0] neg_lo:[0,1] neg_hi:[0,1]
	v_pk_add_f32 v[220:221], v[186:187], v[186:187] op_sel:[1,0] op_sel_hi:[0,1]
	v_pk_add_f32 v[186:187], v[186:187], v[186:187] op_sel:[0,1] op_sel_hi:[1,0] neg_lo:[0,1] neg_hi:[0,1]
	v_xor_b32_e32 v115, v181, v200
	v_pk_add_f32 v[202:203], v[210:211], v[210:211] op_sel:[0,1] op_sel_hi:[1,0] neg_lo:[0,1] neg_hi:[0,1]
	v_pk_add_f32 v[206:207], v[208:209], v[208:209] op_sel:[1,0] op_sel_hi:[0,1]
	v_pk_add_f32 v[210:211], v[118:119], v[118:119] op_sel:[1,0] op_sel_hi:[0,1]
	v_pk_add_f32 v[118:119], v[118:119], v[118:119] op_sel:[0,1] op_sel_hi:[1,0] neg_lo:[0,1] neg_hi:[0,1]
	v_add_f32_dpp v115, v200, v115 quad_perm:[1,0,3,2] row_mask:0xf bank_mask:0xf bound_ctrl:1
	v_xor_b32_e32 v117, v181, v204
	v_xor_b32_e32 v205, v181, v186
	v_pk_add_f32 v[214:215], v[120:121], v[120:121] op_sel:[1,0] op_sel_hi:[0,1]
	v_pk_add_f32 v[120:121], v[120:121], v[120:121] op_sel:[0,1] op_sel_hi:[1,0] neg_lo:[0,1] neg_hi:[0,1]
	v_add_f32_dpp v117, v204, v117 quad_perm:[1,0,3,2] row_mask:0xf bank_mask:0xf bound_ctrl:1
	v_xor_b32_e32 v119, v181, v206
	v_add_f32_dpp v186, v186, v205 quad_perm:[1,0,3,2] row_mask:0xf bank_mask:0xf bound_ctrl:1
	v_xor_b32_e32 v205, v189, v115
	v_add_f32_dpp v119, v206, v119 quad_perm:[1,0,3,2] row_mask:0xf bank_mask:0xf bound_ctrl:1
	v_xor_b32_e32 v121, v181, v210
	v_add_f32_dpp v115, v115, v205 quad_perm:[2,3,0,1] row_mask:0xf bank_mask:0xf bound_ctrl:1
	v_xor_b32_e32 v205, v189, v117
	v_add_f32_dpp v121, v210, v121 quad_perm:[1,0,3,2] row_mask:0xf bank_mask:0xf bound_ctrl:1
	v_xor_b32_e32 v187, v181, v214
	v_add_f32_dpp v117, v117, v205 quad_perm:[2,3,0,1] row_mask:0xf bank_mask:0xf bound_ctrl:1
	v_xor_b32_e32 v205, v189, v119
	v_pk_add_f32 v[218:219], v[212:213], v[212:213] op_sel:[1,0] op_sel_hi:[0,1]
	v_add_f32_dpp v187, v214, v187 quad_perm:[1,0,3,2] row_mask:0xf bank_mask:0xf bound_ctrl:1
	v_xor_b32_e32 v199, v181, v216
	v_add_f32_dpp v119, v119, v205 quad_perm:[2,3,0,1] row_mask:0xf bank_mask:0xf bound_ctrl:1
	v_xor_b32_e32 v205, v189, v121
	v_add_f32_dpp v199, v216, v199 quad_perm:[1,0,3,2] row_mask:0xf bank_mask:0xf bound_ctrl:1
	v_xor_b32_e32 v200, v181, v218
	v_add_f32_dpp v121, v121, v205 quad_perm:[2,3,0,1] row_mask:0xf bank_mask:0xf bound_ctrl:1
	v_xor_b32_e32 v205, v189, v187
	v_add_f32_dpp v200, v218, v200 quad_perm:[1,0,3,2] row_mask:0xf bank_mask:0xf bound_ctrl:1
	v_xor_b32_e32 v201, v181, v220
	v_add_f32_dpp v187, v187, v205 quad_perm:[2,3,0,1] row_mask:0xf bank_mask:0xf bound_ctrl:1
	v_xor_b32_e32 v205, v189, v199
	v_add_f32_dpp v201, v220, v201 quad_perm:[1,0,3,2] row_mask:0xf bank_mask:0xf bound_ctrl:1
	v_xor_b32_e32 v203, v181, v202
	v_add_f32_dpp v199, v199, v205 quad_perm:[2,3,0,1] row_mask:0xf bank_mask:0xf bound_ctrl:1
	v_xor_b32_e32 v205, v189, v200
	v_pk_add_f32 v[208:209], v[208:209], v[208:209] op_sel:[0,1] op_sel_hi:[1,0] neg_lo:[0,1] neg_hi:[0,1]
	v_add_f32_dpp v202, v202, v203 quad_perm:[1,0,3,2] row_mask:0xf bank_mask:0xf bound_ctrl:1
	v_xor_b32_e32 v203, v181, v116
	v_add_f32_dpp v200, v200, v205 quad_perm:[2,3,0,1] row_mask:0xf bank_mask:0xf bound_ctrl:1
	v_xor_b32_e32 v205, v189, v201
	v_add_f32_dpp v116, v116, v203 quad_perm:[1,0,3,2] row_mask:0xf bank_mask:0xf bound_ctrl:1
	v_xor_b32_e32 v203, v181, v208
	v_add_f32_dpp v201, v201, v205 quad_perm:[2,3,0,1] row_mask:0xf bank_mask:0xf bound_ctrl:1
	v_xor_b32_e32 v205, v189, v202
	v_add_f32_dpp v203, v208, v203 quad_perm:[1,0,3,2] row_mask:0xf bank_mask:0xf bound_ctrl:1
	v_xor_b32_e32 v204, v181, v118
	v_add_f32_dpp v202, v202, v205 quad_perm:[2,3,0,1] row_mask:0xf bank_mask:0xf bound_ctrl:1
	v_xor_b32_e32 v205, v189, v116
	v_add_f32_dpp v118, v118, v204 quad_perm:[1,0,3,2] row_mask:0xf bank_mask:0xf bound_ctrl:1
	v_xor_b32_e32 v204, v181, v120
	v_add_f32_dpp v205, v116, v205 quad_perm:[2,3,0,1] row_mask:0xf bank_mask:0xf bound_ctrl:1
	v_xor_b32_e32 v116, v189, v203
	v_pk_add_f32 v[212:213], v[212:213], v[212:213] op_sel:[0,1] op_sel_hi:[1,0] neg_lo:[0,1] neg_hi:[0,1]
	v_add_f32_dpp v120, v120, v204 quad_perm:[1,0,3,2] row_mask:0xf bank_mask:0xf bound_ctrl:1
	v_xor_b32_e32 v204, v181, v114
	v_add_f32_dpp v203, v203, v116 quad_perm:[2,3,0,1] row_mask:0xf bank_mask:0xf bound_ctrl:1
	v_xor_b32_e32 v116, v189, v118
	v_add_f32_dpp v114, v114, v204 quad_perm:[1,0,3,2] row_mask:0xf bank_mask:0xf bound_ctrl:1
	v_xor_b32_e32 v204, v181, v212
	v_add_f32_dpp v206, v118, v116 quad_perm:[2,3,0,1] row_mask:0xf bank_mask:0xf bound_ctrl:1
	v_xor_b32_e32 v116, v189, v120
	v_add_f32_dpp v204, v212, v204 quad_perm:[1,0,3,2] row_mask:0xf bank_mask:0xf bound_ctrl:1
	v_max_f32_e64 v118, |v200|, |v201|
	v_add_f32_dpp v120, v120, v116 quad_perm:[2,3,0,1] row_mask:0xf bank_mask:0xf bound_ctrl:1
	v_xor_b32_e32 v116, v189, v114
	s_nop 1
	v_add_f32_dpp v207, v114, v116 quad_perm:[2,3,0,1] row_mask:0xf bank_mask:0xf bound_ctrl:1
	v_xor_b32_e32 v114, v189, v204
	v_max_f32_e64 v116, |v119|, |v121|
	s_nop 0
	v_add_f32_dpp v204, v204, v114 quad_perm:[2,3,0,1] row_mask:0xf bank_mask:0xf bound_ctrl:1
	v_xor_b32_e32 v114, v189, v186
	s_nop 1
	v_add_f32_dpp v186, v186, v114 quad_perm:[2,3,0,1] row_mask:0xf bank_mask:0xf bound_ctrl:1
	v_max_f32_e64 v114, |v115|, |v117|
	v_max3_f32 v114, v222, v114, v116
	v_max_f32_e64 v116, |v187|, |v199|
	v_max3_f32 v114, v114, v116, v118
	v_max_f32_e64 v116, |v202|, |v205|
	v_max_f32_e64 v118, |v203|, |v206|
	v_max3_f32 v114, v114, v116, v118
	v_max_f32_e64 v116, |v120|, |v207|
	v_max_f32_e64 v118, |v204|, |v186|
	v_max3_f32 v222, v114, v116, v118
	v_cvt_pk_bf16_f32 v114, v115, v117
	v_cvt_pk_bf16_f32 v115, v119, v121
	v_cvt_pk_bf16_f32 v116, v187, v199
	v_cvt_pk_bf16_f32 v117, v200, v201
	v_cvt_pk_bf16_f32 v118, v202, v205
	v_cvt_pk_bf16_f32 v119, v203, v206
	v_cvt_pk_bf16_f32 v120, v120, v207
	v_cvt_pk_bf16_f32 v121, v204, v186
	v_and_b32_e32 v187, 0xffff0000, v129
	v_and_b32_e32 v186, 0xffff0000, v125
	v_lshlrev_b32_e32 v201, 16, v126
	v_lshlrev_b32_e32 v200, 16, v122
	v_and_b32_e32 v203, 0xffff0000, v126
	v_and_b32_e32 v202, 0xffff0000, v122
	v_lshlrev_b32_e32 v204, 16, v123
	v_lshlrev_b32_e32 v205, 16, v127
	v_and_b32_e32 v127, 0xffff0000, v127
	v_and_b32_e32 v126, 0xffff0000, v123
	v_lshlrev_b32_e32 v123, 16, v128
	v_lshlrev_b32_e32 v122, 16, v124
	v_and_b32_e32 v207, 0xffff0000, v128
	v_and_b32_e32 v206, 0xffff0000, v124
	v_lshlrev_b32_e32 v124, 16, v125
	v_lshlrev_b32_e32 v125, 16, v129
	v_pk_add_f32 v[128:129], v[200:201], v[202:203]
	v_pk_add_f32 v[208:209], v[204:205], v[126:127]
	v_pk_add_f32 v[210:211], v[122:123], v[206:207]
	v_pk_add_f32 v[212:213], v[124:125], v[186:187]
	v_pk_add_f32 v[200:201], v[200:201], v[202:203] neg_lo:[0,1] neg_hi:[0,1]
	v_pk_add_f32 v[126:127], v[204:205], v[126:127] neg_lo:[0,1] neg_hi:[0,1]
	v_pk_add_f32 v[122:123], v[122:123], v[206:207] neg_lo:[0,1] neg_hi:[0,1]
	v_pk_add_f32 v[124:125], v[124:125], v[186:187] neg_lo:[0,1] neg_hi:[0,1]
	v_pk_add_f32 v[214:215], v[128:129], v[208:209] neg_lo:[0,1] neg_hi:[0,1]
	v_pk_add_f32 v[128:129], v[128:129], v[208:209]
	v_pk_add_f32 v[208:209], v[210:211], v[212:213]
	v_pk_add_f32 v[186:187], v[200:201], v[126:127] neg_lo:[0,1] neg_hi:[0,1]
	v_pk_add_f32 v[202:203], v[122:123], v[124:125] neg_lo:[0,1] neg_hi:[0,1]
	v_pk_add_f32 v[126:127], v[200:201], v[126:127]
	v_pk_add_f32 v[122:123], v[122:123], v[124:125]
	v_pk_add_f32 v[216:217], v[210:211], v[212:213] neg_lo:[0,1] neg_hi:[0,1]
	v_pk_add_f32 v[210:211], v[128:129], v[208:209]
	v_pk_add_f32 v[124:125], v[126:127], v[122:123]
	v_pk_add_f32 v[122:123], v[126:127], v[122:123] neg_lo:[0,1] neg_hi:[0,1]
	v_pk_add_f32 v[128:129], v[128:129], v[208:209] neg_lo:[0,1] neg_hi:[0,1]
	v_pk_add_f32 v[208:209], v[214:215], v[216:217]
	v_pk_add_f32 v[212:213], v[214:215], v[216:217] neg_lo:[0,1] neg_hi:[0,1]
	v_pk_add_f32 v[126:127], v[186:187], v[202:203]
	v_pk_add_f32 v[186:187], v[186:187], v[202:203] neg_lo:[0,1] neg_hi:[0,1]
	v_pk_add_f32 v[200:201], v[210:211], v[210:211] op_sel:[1,0] op_sel_hi:[0,1]
	v_pk_add_f32 v[216:217], v[122:123], v[122:123] op_sel:[1,0] op_sel_hi:[0,1]
	v_pk_add_f32 v[122:123], v[122:123], v[122:123] op_sel:[0,1] op_sel_hi:[1,0] neg_lo:[0,1] neg_hi:[0,1]
	v_pk_add_f32 v[204:205], v[124:125], v[124:125] op_sel:[1,0] op_sel_hi:[0,1]
	v_pk_add_f32 v[124:125], v[124:125], v[124:125] op_sel:[0,1] op_sel_hi:[1,0] neg_lo:[0,1] neg_hi:[0,1]
	v_pk_add_f32 v[220:221], v[186:187], v[186:187] op_sel:[1,0] op_sel_hi:[0,1]
	v_pk_add_f32 v[186:187], v[186:187], v[186:187] op_sel:[0,1] op_sel_hi:[1,0] neg_lo:[0,1] neg_hi:[0,1]
	v_xor_b32_e32 v123, v181, v200
	v_pk_add_f32 v[202:203], v[210:211], v[210:211] op_sel:[0,1] op_sel_hi:[1,0] neg_lo:[0,1] neg_hi:[0,1]
	v_pk_add_f32 v[206:207], v[208:209], v[208:209] op_sel:[1,0] op_sel_hi:[0,1]
	v_pk_add_f32 v[210:211], v[126:127], v[126:127] op_sel:[1,0] op_sel_hi:[0,1]
	v_pk_add_f32 v[126:127], v[126:127], v[126:127] op_sel:[0,1] op_sel_hi:[1,0] neg_lo:[0,1] neg_hi:[0,1]
	v_add_f32_dpp v123, v200, v123 quad_perm:[1,0,3,2] row_mask:0xf bank_mask:0xf bound_ctrl:1
	v_xor_b32_e32 v125, v181, v204
	v_xor_b32_e32 v205, v181, v186
	v_pk_add_f32 v[214:215], v[128:129], v[128:129] op_sel:[1,0] op_sel_hi:[0,1]
	v_pk_add_f32 v[128:129], v[128:129], v[128:129] op_sel:[0,1] op_sel_hi:[1,0] neg_lo:[0,1] neg_hi:[0,1]
	v_add_f32_dpp v125, v204, v125 quad_perm:[1,0,3,2] row_mask:0xf bank_mask:0xf bound_ctrl:1
	v_xor_b32_e32 v127, v181, v206
	v_add_f32_dpp v186, v186, v205 quad_perm:[1,0,3,2] row_mask:0xf bank_mask:0xf bound_ctrl:1
	v_xor_b32_e32 v205, v189, v123
	v_add_f32_dpp v127, v206, v127 quad_perm:[1,0,3,2] row_mask:0xf bank_mask:0xf bound_ctrl:1
	v_xor_b32_e32 v129, v181, v210
	v_add_f32_dpp v123, v123, v205 quad_perm:[2,3,0,1] row_mask:0xf bank_mask:0xf bound_ctrl:1
	v_xor_b32_e32 v205, v189, v125
	v_add_f32_dpp v129, v210, v129 quad_perm:[1,0,3,2] row_mask:0xf bank_mask:0xf bound_ctrl:1
	v_xor_b32_e32 v187, v181, v214
	v_add_f32_dpp v125, v125, v205 quad_perm:[2,3,0,1] row_mask:0xf bank_mask:0xf bound_ctrl:1
	v_xor_b32_e32 v205, v189, v127
	v_pk_add_f32 v[218:219], v[212:213], v[212:213] op_sel:[1,0] op_sel_hi:[0,1]
	v_add_f32_dpp v187, v214, v187 quad_perm:[1,0,3,2] row_mask:0xf bank_mask:0xf bound_ctrl:1
	v_xor_b32_e32 v199, v181, v216
	v_add_f32_dpp v127, v127, v205 quad_perm:[2,3,0,1] row_mask:0xf bank_mask:0xf bound_ctrl:1
	v_xor_b32_e32 v205, v189, v129
	v_add_f32_dpp v199, v216, v199 quad_perm:[1,0,3,2] row_mask:0xf bank_mask:0xf bound_ctrl:1
	v_xor_b32_e32 v200, v181, v218
	v_add_f32_dpp v129, v129, v205 quad_perm:[2,3,0,1] row_mask:0xf bank_mask:0xf bound_ctrl:1
	v_xor_b32_e32 v205, v189, v187
	v_add_f32_dpp v200, v218, v200 quad_perm:[1,0,3,2] row_mask:0xf bank_mask:0xf bound_ctrl:1
	v_xor_b32_e32 v201, v181, v220
	v_add_f32_dpp v187, v187, v205 quad_perm:[2,3,0,1] row_mask:0xf bank_mask:0xf bound_ctrl:1
	v_xor_b32_e32 v205, v189, v199
	v_add_f32_dpp v201, v220, v201 quad_perm:[1,0,3,2] row_mask:0xf bank_mask:0xf bound_ctrl:1
	v_xor_b32_e32 v203, v181, v202
	v_add_f32_dpp v199, v199, v205 quad_perm:[2,3,0,1] row_mask:0xf bank_mask:0xf bound_ctrl:1
	v_xor_b32_e32 v205, v189, v200
	v_pk_add_f32 v[208:209], v[208:209], v[208:209] op_sel:[0,1] op_sel_hi:[1,0] neg_lo:[0,1] neg_hi:[0,1]
	v_add_f32_dpp v202, v202, v203 quad_perm:[1,0,3,2] row_mask:0xf bank_mask:0xf bound_ctrl:1
	v_xor_b32_e32 v203, v181, v124
	v_add_f32_dpp v200, v200, v205 quad_perm:[2,3,0,1] row_mask:0xf bank_mask:0xf bound_ctrl:1
	v_xor_b32_e32 v205, v189, v201
	v_add_f32_dpp v124, v124, v203 quad_perm:[1,0,3,2] row_mask:0xf bank_mask:0xf bound_ctrl:1
	v_xor_b32_e32 v203, v181, v208
	v_add_f32_dpp v201, v201, v205 quad_perm:[2,3,0,1] row_mask:0xf bank_mask:0xf bound_ctrl:1
	v_xor_b32_e32 v205, v189, v202
	v_add_f32_dpp v203, v208, v203 quad_perm:[1,0,3,2] row_mask:0xf bank_mask:0xf bound_ctrl:1
	v_xor_b32_e32 v204, v181, v126
	v_add_f32_dpp v202, v202, v205 quad_perm:[2,3,0,1] row_mask:0xf bank_mask:0xf bound_ctrl:1
	v_xor_b32_e32 v205, v189, v124
	v_add_f32_dpp v126, v126, v204 quad_perm:[1,0,3,2] row_mask:0xf bank_mask:0xf bound_ctrl:1
	v_xor_b32_e32 v204, v181, v128
	v_add_f32_dpp v205, v124, v205 quad_perm:[2,3,0,1] row_mask:0xf bank_mask:0xf bound_ctrl:1
	v_xor_b32_e32 v124, v189, v203
	v_pk_add_f32 v[212:213], v[212:213], v[212:213] op_sel:[0,1] op_sel_hi:[1,0] neg_lo:[0,1] neg_hi:[0,1]
	v_add_f32_dpp v128, v128, v204 quad_perm:[1,0,3,2] row_mask:0xf bank_mask:0xf bound_ctrl:1
	v_xor_b32_e32 v204, v181, v122
	v_add_f32_dpp v203, v203, v124 quad_perm:[2,3,0,1] row_mask:0xf bank_mask:0xf bound_ctrl:1
	v_xor_b32_e32 v124, v189, v126
	v_add_f32_dpp v122, v122, v204 quad_perm:[1,0,3,2] row_mask:0xf bank_mask:0xf bound_ctrl:1
	v_xor_b32_e32 v204, v181, v212
	v_add_f32_dpp v206, v126, v124 quad_perm:[2,3,0,1] row_mask:0xf bank_mask:0xf bound_ctrl:1
	v_xor_b32_e32 v124, v189, v128
	v_add_f32_dpp v204, v212, v204 quad_perm:[1,0,3,2] row_mask:0xf bank_mask:0xf bound_ctrl:1
	v_max_f32_e64 v126, |v200|, |v201|
	v_add_f32_dpp v128, v128, v124 quad_perm:[2,3,0,1] row_mask:0xf bank_mask:0xf bound_ctrl:1
	v_xor_b32_e32 v124, v189, v122
	s_nop 1
	v_add_f32_dpp v207, v122, v124 quad_perm:[2,3,0,1] row_mask:0xf bank_mask:0xf bound_ctrl:1
	v_xor_b32_e32 v122, v189, v204
	v_max_f32_e64 v124, |v127|, |v129|
	s_nop 0
	v_add_f32_dpp v204, v204, v122 quad_perm:[2,3,0,1] row_mask:0xf bank_mask:0xf bound_ctrl:1
	v_xor_b32_e32 v122, v189, v186
	s_nop 1
	v_add_f32_dpp v186, v186, v122 quad_perm:[2,3,0,1] row_mask:0xf bank_mask:0xf bound_ctrl:1
	v_max_f32_e64 v122, |v123|, |v125|
	v_max3_f32 v122, v222, v122, v124
	v_max_f32_e64 v124, |v187|, |v199|
	v_max3_f32 v122, v122, v124, v126
	v_max_f32_e64 v124, |v202|, |v205|
	v_max_f32_e64 v126, |v203|, |v206|
	v_max3_f32 v122, v122, v124, v126
	v_max_f32_e64 v124, |v128|, |v207|
	v_max_f32_e64 v126, |v204|, |v186|
	v_max3_f32 v222, v122, v124, v126
	v_cvt_pk_bf16_f32 v122, v123, v125
	v_cvt_pk_bf16_f32 v123, v127, v129
	v_cvt_pk_bf16_f32 v124, v187, v199
	v_cvt_pk_bf16_f32 v125, v200, v201
	v_cvt_pk_bf16_f32 v126, v202, v205
	v_cvt_pk_bf16_f32 v127, v203, v206
	v_cvt_pk_bf16_f32 v128, v128, v207
	v_cvt_pk_bf16_f32 v129, v204, v186
	v_and_b32_e32 v187, 0xffff0000, v137
	v_and_b32_e32 v186, 0xffff0000, v133
	v_lshlrev_b32_e32 v201, 16, v134
	v_lshlrev_b32_e32 v200, 16, v130
	v_and_b32_e32 v203, 0xffff0000, v134
	v_and_b32_e32 v202, 0xffff0000, v130
	v_lshlrev_b32_e32 v204, 16, v131
	v_lshlrev_b32_e32 v205, 16, v135
	v_and_b32_e32 v135, 0xffff0000, v135
	v_and_b32_e32 v134, 0xffff0000, v131
	v_lshlrev_b32_e32 v131, 16, v136
	v_lshlrev_b32_e32 v130, 16, v132
	v_and_b32_e32 v207, 0xffff0000, v136
	v_and_b32_e32 v206, 0xffff0000, v132
	v_lshlrev_b32_e32 v132, 16, v133
	v_lshlrev_b32_e32 v133, 16, v137
	v_pk_add_f32 v[136:137], v[200:201], v[202:203]
	v_pk_add_f32 v[208:209], v[204:205], v[134:135]
	v_pk_add_f32 v[210:211], v[130:131], v[206:207]
	v_pk_add_f32 v[212:213], v[132:133], v[186:187]
	v_pk_add_f32 v[200:201], v[200:201], v[202:203] neg_lo:[0,1] neg_hi:[0,1]
	v_pk_add_f32 v[134:135], v[204:205], v[134:135] neg_lo:[0,1] neg_hi:[0,1]
	v_pk_add_f32 v[130:131], v[130:131], v[206:207] neg_lo:[0,1] neg_hi:[0,1]
	v_pk_add_f32 v[132:133], v[132:133], v[186:187] neg_lo:[0,1] neg_hi:[0,1]
	v_pk_add_f32 v[214:215], v[136:137], v[208:209] neg_lo:[0,1] neg_hi:[0,1]
	v_pk_add_f32 v[136:137], v[136:137], v[208:209]
	v_pk_add_f32 v[208:209], v[210:211], v[212:213]
	v_pk_add_f32 v[186:187], v[200:201], v[134:135] neg_lo:[0,1] neg_hi:[0,1]
	v_pk_add_f32 v[202:203], v[130:131], v[132:133] neg_lo:[0,1] neg_hi:[0,1]
	v_pk_add_f32 v[134:135], v[200:201], v[134:135]
	v_pk_add_f32 v[130:131], v[130:131], v[132:133]
	v_pk_add_f32 v[216:217], v[210:211], v[212:213] neg_lo:[0,1] neg_hi:[0,1]
	v_pk_add_f32 v[210:211], v[136:137], v[208:209]
	v_pk_add_f32 v[132:133], v[134:135], v[130:131]
	v_pk_add_f32 v[130:131], v[134:135], v[130:131] neg_lo:[0,1] neg_hi:[0,1]
	v_pk_add_f32 v[136:137], v[136:137], v[208:209] neg_lo:[0,1] neg_hi:[0,1]
	v_pk_add_f32 v[208:209], v[214:215], v[216:217]
	v_pk_add_f32 v[212:213], v[214:215], v[216:217] neg_lo:[0,1] neg_hi:[0,1]
	v_pk_add_f32 v[134:135], v[186:187], v[202:203]
	v_pk_add_f32 v[186:187], v[186:187], v[202:203] neg_lo:[0,1] neg_hi:[0,1]
	v_pk_add_f32 v[200:201], v[210:211], v[210:211] op_sel:[1,0] op_sel_hi:[0,1]
	v_pk_add_f32 v[216:217], v[130:131], v[130:131] op_sel:[1,0] op_sel_hi:[0,1]
	v_pk_add_f32 v[130:131], v[130:131], v[130:131] op_sel:[0,1] op_sel_hi:[1,0] neg_lo:[0,1] neg_hi:[0,1]
	v_pk_add_f32 v[204:205], v[132:133], v[132:133] op_sel:[1,0] op_sel_hi:[0,1]
	v_pk_add_f32 v[132:133], v[132:133], v[132:133] op_sel:[0,1] op_sel_hi:[1,0] neg_lo:[0,1] neg_hi:[0,1]
	v_pk_add_f32 v[220:221], v[186:187], v[186:187] op_sel:[1,0] op_sel_hi:[0,1]
	v_pk_add_f32 v[186:187], v[186:187], v[186:187] op_sel:[0,1] op_sel_hi:[1,0] neg_lo:[0,1] neg_hi:[0,1]
	v_xor_b32_e32 v131, v181, v200
	v_pk_add_f32 v[202:203], v[210:211], v[210:211] op_sel:[0,1] op_sel_hi:[1,0] neg_lo:[0,1] neg_hi:[0,1]
	v_pk_add_f32 v[206:207], v[208:209], v[208:209] op_sel:[1,0] op_sel_hi:[0,1]
	v_pk_add_f32 v[210:211], v[134:135], v[134:135] op_sel:[1,0] op_sel_hi:[0,1]
	v_pk_add_f32 v[134:135], v[134:135], v[134:135] op_sel:[0,1] op_sel_hi:[1,0] neg_lo:[0,1] neg_hi:[0,1]
	v_add_f32_dpp v131, v200, v131 quad_perm:[1,0,3,2] row_mask:0xf bank_mask:0xf bound_ctrl:1
	v_xor_b32_e32 v133, v181, v204
	v_xor_b32_e32 v205, v181, v186
	v_pk_add_f32 v[214:215], v[136:137], v[136:137] op_sel:[1,0] op_sel_hi:[0,1]
	v_pk_add_f32 v[136:137], v[136:137], v[136:137] op_sel:[0,1] op_sel_hi:[1,0] neg_lo:[0,1] neg_hi:[0,1]
	v_add_f32_dpp v133, v204, v133 quad_perm:[1,0,3,2] row_mask:0xf bank_mask:0xf bound_ctrl:1
	v_xor_b32_e32 v135, v181, v206
	v_add_f32_dpp v186, v186, v205 quad_perm:[1,0,3,2] row_mask:0xf bank_mask:0xf bound_ctrl:1
	v_xor_b32_e32 v205, v189, v131
	v_add_f32_dpp v135, v206, v135 quad_perm:[1,0,3,2] row_mask:0xf bank_mask:0xf bound_ctrl:1
	v_xor_b32_e32 v137, v181, v210
	v_add_f32_dpp v131, v131, v205 quad_perm:[2,3,0,1] row_mask:0xf bank_mask:0xf bound_ctrl:1
	v_xor_b32_e32 v205, v189, v133
	v_add_f32_dpp v137, v210, v137 quad_perm:[1,0,3,2] row_mask:0xf bank_mask:0xf bound_ctrl:1
	v_xor_b32_e32 v187, v181, v214
	v_add_f32_dpp v133, v133, v205 quad_perm:[2,3,0,1] row_mask:0xf bank_mask:0xf bound_ctrl:1
	v_xor_b32_e32 v205, v189, v135
	v_pk_add_f32 v[218:219], v[212:213], v[212:213] op_sel:[1,0] op_sel_hi:[0,1]
	v_add_f32_dpp v187, v214, v187 quad_perm:[1,0,3,2] row_mask:0xf bank_mask:0xf bound_ctrl:1
	v_xor_b32_e32 v199, v181, v216
	v_add_f32_dpp v135, v135, v205 quad_perm:[2,3,0,1] row_mask:0xf bank_mask:0xf bound_ctrl:1
	v_xor_b32_e32 v205, v189, v137
	v_add_f32_dpp v199, v216, v199 quad_perm:[1,0,3,2] row_mask:0xf bank_mask:0xf bound_ctrl:1
	v_xor_b32_e32 v200, v181, v218
	v_add_f32_dpp v137, v137, v205 quad_perm:[2,3,0,1] row_mask:0xf bank_mask:0xf bound_ctrl:1
	v_xor_b32_e32 v205, v189, v187
	v_add_f32_dpp v200, v218, v200 quad_perm:[1,0,3,2] row_mask:0xf bank_mask:0xf bound_ctrl:1
	v_xor_b32_e32 v201, v181, v220
	v_add_f32_dpp v187, v187, v205 quad_perm:[2,3,0,1] row_mask:0xf bank_mask:0xf bound_ctrl:1
	v_xor_b32_e32 v205, v189, v199
	v_add_f32_dpp v201, v220, v201 quad_perm:[1,0,3,2] row_mask:0xf bank_mask:0xf bound_ctrl:1
	v_xor_b32_e32 v203, v181, v202
	v_add_f32_dpp v199, v199, v205 quad_perm:[2,3,0,1] row_mask:0xf bank_mask:0xf bound_ctrl:1
	v_xor_b32_e32 v205, v189, v200
	v_pk_add_f32 v[208:209], v[208:209], v[208:209] op_sel:[0,1] op_sel_hi:[1,0] neg_lo:[0,1] neg_hi:[0,1]
	v_add_f32_dpp v202, v202, v203 quad_perm:[1,0,3,2] row_mask:0xf bank_mask:0xf bound_ctrl:1
	v_xor_b32_e32 v203, v181, v132
	v_add_f32_dpp v200, v200, v205 quad_perm:[2,3,0,1] row_mask:0xf bank_mask:0xf bound_ctrl:1
	v_xor_b32_e32 v205, v189, v201
	v_add_f32_dpp v132, v132, v203 quad_perm:[1,0,3,2] row_mask:0xf bank_mask:0xf bound_ctrl:1
	v_xor_b32_e32 v203, v181, v208
	v_add_f32_dpp v201, v201, v205 quad_perm:[2,3,0,1] row_mask:0xf bank_mask:0xf bound_ctrl:1
	v_xor_b32_e32 v205, v189, v202
	v_add_f32_dpp v203, v208, v203 quad_perm:[1,0,3,2] row_mask:0xf bank_mask:0xf bound_ctrl:1
	v_xor_b32_e32 v204, v181, v134
	v_add_f32_dpp v202, v202, v205 quad_perm:[2,3,0,1] row_mask:0xf bank_mask:0xf bound_ctrl:1
	v_xor_b32_e32 v205, v189, v132
	v_add_f32_dpp v134, v134, v204 quad_perm:[1,0,3,2] row_mask:0xf bank_mask:0xf bound_ctrl:1
	v_xor_b32_e32 v204, v181, v136
	v_add_f32_dpp v205, v132, v205 quad_perm:[2,3,0,1] row_mask:0xf bank_mask:0xf bound_ctrl:1
	v_xor_b32_e32 v132, v189, v203
	v_pk_add_f32 v[212:213], v[212:213], v[212:213] op_sel:[0,1] op_sel_hi:[1,0] neg_lo:[0,1] neg_hi:[0,1]
	v_add_f32_dpp v136, v136, v204 quad_perm:[1,0,3,2] row_mask:0xf bank_mask:0xf bound_ctrl:1
	v_xor_b32_e32 v204, v181, v130
	v_add_f32_dpp v203, v203, v132 quad_perm:[2,3,0,1] row_mask:0xf bank_mask:0xf bound_ctrl:1
	v_xor_b32_e32 v132, v189, v134
	v_add_f32_dpp v130, v130, v204 quad_perm:[1,0,3,2] row_mask:0xf bank_mask:0xf bound_ctrl:1
	v_xor_b32_e32 v204, v181, v212
	v_add_f32_dpp v206, v134, v132 quad_perm:[2,3,0,1] row_mask:0xf bank_mask:0xf bound_ctrl:1
	v_xor_b32_e32 v132, v189, v136
	v_add_f32_dpp v204, v212, v204 quad_perm:[1,0,3,2] row_mask:0xf bank_mask:0xf bound_ctrl:1
	v_max_f32_e64 v134, |v200|, |v201|
	v_add_f32_dpp v136, v136, v132 quad_perm:[2,3,0,1] row_mask:0xf bank_mask:0xf bound_ctrl:1
	v_xor_b32_e32 v132, v189, v130
	s_nop 1
	v_add_f32_dpp v207, v130, v132 quad_perm:[2,3,0,1] row_mask:0xf bank_mask:0xf bound_ctrl:1
	v_xor_b32_e32 v130, v189, v204
	v_max_f32_e64 v132, |v135|, |v137|
	s_nop 0
	v_add_f32_dpp v204, v204, v130 quad_perm:[2,3,0,1] row_mask:0xf bank_mask:0xf bound_ctrl:1
	v_xor_b32_e32 v130, v189, v186
	s_nop 1
	v_add_f32_dpp v186, v186, v130 quad_perm:[2,3,0,1] row_mask:0xf bank_mask:0xf bound_ctrl:1
	v_max_f32_e64 v130, |v131|, |v133|
	v_max3_f32 v130, v222, v130, v132
	v_max_f32_e64 v132, |v187|, |v199|
	v_max3_f32 v130, v130, v132, v134
	v_max_f32_e64 v132, |v202|, |v205|
	v_max_f32_e64 v134, |v203|, |v206|
	v_max3_f32 v130, v130, v132, v134
	v_max_f32_e64 v132, |v136|, |v207|
	v_max_f32_e64 v134, |v204|, |v186|
	v_max3_f32 v222, v130, v132, v134
	v_cvt_pk_bf16_f32 v130, v131, v133
	v_cvt_pk_bf16_f32 v131, v135, v137
	v_cvt_pk_bf16_f32 v132, v187, v199
	v_cvt_pk_bf16_f32 v133, v200, v201
	v_cvt_pk_bf16_f32 v134, v202, v205
	v_cvt_pk_bf16_f32 v135, v203, v206
	v_cvt_pk_bf16_f32 v136, v136, v207
	v_cvt_pk_bf16_f32 v137, v204, v186
	v_and_b32_e32 v187, 0xffff0000, v145
	v_and_b32_e32 v186, 0xffff0000, v141
	v_lshlrev_b32_e32 v201, 16, v142
	v_lshlrev_b32_e32 v200, 16, v138
	v_and_b32_e32 v203, 0xffff0000, v142
	v_and_b32_e32 v202, 0xffff0000, v138
	v_lshlrev_b32_e32 v204, 16, v139
	v_lshlrev_b32_e32 v205, 16, v143
	v_and_b32_e32 v143, 0xffff0000, v143
	v_and_b32_e32 v142, 0xffff0000, v139
	v_lshlrev_b32_e32 v139, 16, v144
	v_lshlrev_b32_e32 v138, 16, v140
	v_and_b32_e32 v207, 0xffff0000, v144
	v_and_b32_e32 v206, 0xffff0000, v140
	v_lshlrev_b32_e32 v140, 16, v141
	v_lshlrev_b32_e32 v141, 16, v145
	v_pk_add_f32 v[144:145], v[200:201], v[202:203]
	v_pk_add_f32 v[208:209], v[204:205], v[142:143]
	v_pk_add_f32 v[210:211], v[138:139], v[206:207]
	v_pk_add_f32 v[212:213], v[140:141], v[186:187]
	v_pk_add_f32 v[200:201], v[200:201], v[202:203] neg_lo:[0,1] neg_hi:[0,1]
	v_pk_add_f32 v[142:143], v[204:205], v[142:143] neg_lo:[0,1] neg_hi:[0,1]
	v_pk_add_f32 v[138:139], v[138:139], v[206:207] neg_lo:[0,1] neg_hi:[0,1]
	v_pk_add_f32 v[140:141], v[140:141], v[186:187] neg_lo:[0,1] neg_hi:[0,1]
	v_pk_add_f32 v[214:215], v[144:145], v[208:209] neg_lo:[0,1] neg_hi:[0,1]
	v_pk_add_f32 v[144:145], v[144:145], v[208:209]
	v_pk_add_f32 v[208:209], v[210:211], v[212:213]
	v_pk_add_f32 v[186:187], v[200:201], v[142:143] neg_lo:[0,1] neg_hi:[0,1]
	v_pk_add_f32 v[202:203], v[138:139], v[140:141] neg_lo:[0,1] neg_hi:[0,1]
	v_pk_add_f32 v[142:143], v[200:201], v[142:143]
	v_pk_add_f32 v[138:139], v[138:139], v[140:141]
	v_pk_add_f32 v[216:217], v[210:211], v[212:213] neg_lo:[0,1] neg_hi:[0,1]
	v_pk_add_f32 v[210:211], v[144:145], v[208:209]
	v_pk_add_f32 v[140:141], v[142:143], v[138:139]
	v_pk_add_f32 v[138:139], v[142:143], v[138:139] neg_lo:[0,1] neg_hi:[0,1]
	v_pk_add_f32 v[144:145], v[144:145], v[208:209] neg_lo:[0,1] neg_hi:[0,1]
	v_pk_add_f32 v[208:209], v[214:215], v[216:217]
	v_pk_add_f32 v[212:213], v[214:215], v[216:217] neg_lo:[0,1] neg_hi:[0,1]
	v_pk_add_f32 v[142:143], v[186:187], v[202:203]
	v_pk_add_f32 v[186:187], v[186:187], v[202:203] neg_lo:[0,1] neg_hi:[0,1]
	v_pk_add_f32 v[200:201], v[210:211], v[210:211] op_sel:[1,0] op_sel_hi:[0,1]
	v_pk_add_f32 v[216:217], v[138:139], v[138:139] op_sel:[1,0] op_sel_hi:[0,1]
	v_pk_add_f32 v[138:139], v[138:139], v[138:139] op_sel:[0,1] op_sel_hi:[1,0] neg_lo:[0,1] neg_hi:[0,1]
	v_pk_add_f32 v[204:205], v[140:141], v[140:141] op_sel:[1,0] op_sel_hi:[0,1]
	v_pk_add_f32 v[140:141], v[140:141], v[140:141] op_sel:[0,1] op_sel_hi:[1,0] neg_lo:[0,1] neg_hi:[0,1]
	v_pk_add_f32 v[220:221], v[186:187], v[186:187] op_sel:[1,0] op_sel_hi:[0,1]
	v_pk_add_f32 v[186:187], v[186:187], v[186:187] op_sel:[0,1] op_sel_hi:[1,0] neg_lo:[0,1] neg_hi:[0,1]
	v_xor_b32_e32 v139, v181, v200
	v_pk_add_f32 v[202:203], v[210:211], v[210:211] op_sel:[0,1] op_sel_hi:[1,0] neg_lo:[0,1] neg_hi:[0,1]
	v_pk_add_f32 v[206:207], v[208:209], v[208:209] op_sel:[1,0] op_sel_hi:[0,1]
	v_pk_add_f32 v[210:211], v[142:143], v[142:143] op_sel:[1,0] op_sel_hi:[0,1]
	v_pk_add_f32 v[142:143], v[142:143], v[142:143] op_sel:[0,1] op_sel_hi:[1,0] neg_lo:[0,1] neg_hi:[0,1]
	v_add_f32_dpp v139, v200, v139 quad_perm:[1,0,3,2] row_mask:0xf bank_mask:0xf bound_ctrl:1
	v_xor_b32_e32 v141, v181, v204
	v_xor_b32_e32 v205, v181, v186
	v_pk_add_f32 v[214:215], v[144:145], v[144:145] op_sel:[1,0] op_sel_hi:[0,1]
	v_pk_add_f32 v[144:145], v[144:145], v[144:145] op_sel:[0,1] op_sel_hi:[1,0] neg_lo:[0,1] neg_hi:[0,1]
	v_add_f32_dpp v141, v204, v141 quad_perm:[1,0,3,2] row_mask:0xf bank_mask:0xf bound_ctrl:1
	v_xor_b32_e32 v143, v181, v206
	v_add_f32_dpp v186, v186, v205 quad_perm:[1,0,3,2] row_mask:0xf bank_mask:0xf bound_ctrl:1
	v_xor_b32_e32 v205, v189, v139
	v_add_f32_dpp v143, v206, v143 quad_perm:[1,0,3,2] row_mask:0xf bank_mask:0xf bound_ctrl:1
	v_xor_b32_e32 v145, v181, v210
	v_add_f32_dpp v139, v139, v205 quad_perm:[2,3,0,1] row_mask:0xf bank_mask:0xf bound_ctrl:1
	v_xor_b32_e32 v205, v189, v141
	v_add_f32_dpp v145, v210, v145 quad_perm:[1,0,3,2] row_mask:0xf bank_mask:0xf bound_ctrl:1
	v_xor_b32_e32 v187, v181, v214
	v_add_f32_dpp v141, v141, v205 quad_perm:[2,3,0,1] row_mask:0xf bank_mask:0xf bound_ctrl:1
	v_xor_b32_e32 v205, v189, v143
	v_pk_add_f32 v[218:219], v[212:213], v[212:213] op_sel:[1,0] op_sel_hi:[0,1]
	v_add_f32_dpp v187, v214, v187 quad_perm:[1,0,3,2] row_mask:0xf bank_mask:0xf bound_ctrl:1
	v_xor_b32_e32 v199, v181, v216
	v_add_f32_dpp v143, v143, v205 quad_perm:[2,3,0,1] row_mask:0xf bank_mask:0xf bound_ctrl:1
	v_xor_b32_e32 v205, v189, v145
	v_add_f32_dpp v199, v216, v199 quad_perm:[1,0,3,2] row_mask:0xf bank_mask:0xf bound_ctrl:1
	v_xor_b32_e32 v200, v181, v218
	v_add_f32_dpp v145, v145, v205 quad_perm:[2,3,0,1] row_mask:0xf bank_mask:0xf bound_ctrl:1
	v_xor_b32_e32 v205, v189, v187
	v_add_f32_dpp v200, v218, v200 quad_perm:[1,0,3,2] row_mask:0xf bank_mask:0xf bound_ctrl:1
	v_xor_b32_e32 v201, v181, v220
	v_add_f32_dpp v187, v187, v205 quad_perm:[2,3,0,1] row_mask:0xf bank_mask:0xf bound_ctrl:1
	v_xor_b32_e32 v205, v189, v199
	v_add_f32_dpp v201, v220, v201 quad_perm:[1,0,3,2] row_mask:0xf bank_mask:0xf bound_ctrl:1
	v_xor_b32_e32 v203, v181, v202
	v_add_f32_dpp v199, v199, v205 quad_perm:[2,3,0,1] row_mask:0xf bank_mask:0xf bound_ctrl:1
	v_xor_b32_e32 v205, v189, v200
	v_pk_add_f32 v[208:209], v[208:209], v[208:209] op_sel:[0,1] op_sel_hi:[1,0] neg_lo:[0,1] neg_hi:[0,1]
	v_add_f32_dpp v202, v202, v203 quad_perm:[1,0,3,2] row_mask:0xf bank_mask:0xf bound_ctrl:1
	v_xor_b32_e32 v203, v181, v140
	v_add_f32_dpp v200, v200, v205 quad_perm:[2,3,0,1] row_mask:0xf bank_mask:0xf bound_ctrl:1
	v_xor_b32_e32 v205, v189, v201
	v_add_f32_dpp v140, v140, v203 quad_perm:[1,0,3,2] row_mask:0xf bank_mask:0xf bound_ctrl:1
	v_xor_b32_e32 v203, v181, v208
	v_add_f32_dpp v201, v201, v205 quad_perm:[2,3,0,1] row_mask:0xf bank_mask:0xf bound_ctrl:1
	v_xor_b32_e32 v205, v189, v202
	v_add_f32_dpp v203, v208, v203 quad_perm:[1,0,3,2] row_mask:0xf bank_mask:0xf bound_ctrl:1
	v_xor_b32_e32 v204, v181, v142
	v_add_f32_dpp v202, v202, v205 quad_perm:[2,3,0,1] row_mask:0xf bank_mask:0xf bound_ctrl:1
	v_xor_b32_e32 v205, v189, v140
	v_add_f32_dpp v142, v142, v204 quad_perm:[1,0,3,2] row_mask:0xf bank_mask:0xf bound_ctrl:1
	v_xor_b32_e32 v204, v181, v144
	v_add_f32_dpp v205, v140, v205 quad_perm:[2,3,0,1] row_mask:0xf bank_mask:0xf bound_ctrl:1
	v_xor_b32_e32 v140, v189, v203
	v_pk_add_f32 v[212:213], v[212:213], v[212:213] op_sel:[0,1] op_sel_hi:[1,0] neg_lo:[0,1] neg_hi:[0,1]
	v_add_f32_dpp v144, v144, v204 quad_perm:[1,0,3,2] row_mask:0xf bank_mask:0xf bound_ctrl:1
	v_xor_b32_e32 v204, v181, v138
	v_add_f32_dpp v203, v203, v140 quad_perm:[2,3,0,1] row_mask:0xf bank_mask:0xf bound_ctrl:1
	v_xor_b32_e32 v140, v189, v142
	v_add_f32_dpp v138, v138, v204 quad_perm:[1,0,3,2] row_mask:0xf bank_mask:0xf bound_ctrl:1
	v_xor_b32_e32 v204, v181, v212
	v_add_f32_dpp v206, v142, v140 quad_perm:[2,3,0,1] row_mask:0xf bank_mask:0xf bound_ctrl:1
	v_xor_b32_e32 v140, v189, v144
	v_add_f32_dpp v204, v212, v204 quad_perm:[1,0,3,2] row_mask:0xf bank_mask:0xf bound_ctrl:1
	v_max_f32_e64 v142, |v200|, |v201|
	v_add_f32_dpp v144, v144, v140 quad_perm:[2,3,0,1] row_mask:0xf bank_mask:0xf bound_ctrl:1
	v_xor_b32_e32 v140, v189, v138
	s_nop 1
	v_add_f32_dpp v207, v138, v140 quad_perm:[2,3,0,1] row_mask:0xf bank_mask:0xf bound_ctrl:1
	v_xor_b32_e32 v138, v189, v204
	v_max_f32_e64 v140, |v143|, |v145|
	s_nop 0
	v_add_f32_dpp v204, v204, v138 quad_perm:[2,3,0,1] row_mask:0xf bank_mask:0xf bound_ctrl:1
	v_xor_b32_e32 v138, v189, v186
	s_nop 1
	v_add_f32_dpp v186, v186, v138 quad_perm:[2,3,0,1] row_mask:0xf bank_mask:0xf bound_ctrl:1
	v_max_f32_e64 v138, |v139|, |v141|
	v_max3_f32 v138, v222, v138, v140
	v_max_f32_e64 v140, |v187|, |v199|
	v_max3_f32 v138, v138, v140, v142
	v_max_f32_e64 v140, |v202|, |v205|
	v_max_f32_e64 v142, |v203|, |v206|
	v_max3_f32 v138, v138, v140, v142
	v_max_f32_e64 v140, |v144|, |v207|
	v_max_f32_e64 v142, |v204|, |v186|
	v_max3_f32 v222, v138, v140, v142
	v_cvt_pk_bf16_f32 v138, v139, v141
	v_cvt_pk_bf16_f32 v139, v143, v145
	v_cvt_pk_bf16_f32 v140, v187, v199
	v_cvt_pk_bf16_f32 v141, v200, v201
	v_cvt_pk_bf16_f32 v142, v202, v205
	v_cvt_pk_bf16_f32 v143, v203, v206
	v_cvt_pk_bf16_f32 v144, v144, v207
	v_cvt_pk_bf16_f32 v145, v204, v186
	v_and_b32_e32 v187, 0xffff0000, v177
	v_and_b32_e32 v186, 0xffff0000, v173
	v_lshlrev_b32_e32 v201, 16, v174
	v_lshlrev_b32_e32 v200, 16, v170
	v_and_b32_e32 v203, 0xffff0000, v174
	v_and_b32_e32 v202, 0xffff0000, v170
	v_lshlrev_b32_e32 v204, 16, v171
	v_lshlrev_b32_e32 v205, 16, v175
	v_and_b32_e32 v175, 0xffff0000, v175
	v_and_b32_e32 v174, 0xffff0000, v171
	v_lshlrev_b32_e32 v171, 16, v176
	v_lshlrev_b32_e32 v170, 16, v172
	v_and_b32_e32 v207, 0xffff0000, v176
	v_and_b32_e32 v206, 0xffff0000, v172
	v_lshlrev_b32_e32 v172, 16, v173
	v_lshlrev_b32_e32 v173, 16, v177
	v_pk_add_f32 v[176:177], v[200:201], v[202:203]
	v_pk_add_f32 v[208:209], v[204:205], v[174:175]
	v_pk_add_f32 v[210:211], v[170:171], v[206:207]
	v_pk_add_f32 v[212:213], v[172:173], v[186:187]
	v_pk_add_f32 v[200:201], v[200:201], v[202:203] neg_lo:[0,1] neg_hi:[0,1]
	v_pk_add_f32 v[174:175], v[204:205], v[174:175] neg_lo:[0,1] neg_hi:[0,1]
	v_pk_add_f32 v[170:171], v[170:171], v[206:207] neg_lo:[0,1] neg_hi:[0,1]
	v_pk_add_f32 v[172:173], v[172:173], v[186:187] neg_lo:[0,1] neg_hi:[0,1]
	v_pk_add_f32 v[214:215], v[176:177], v[208:209] neg_lo:[0,1] neg_hi:[0,1]
	v_pk_add_f32 v[176:177], v[176:177], v[208:209]
	v_pk_add_f32 v[208:209], v[210:211], v[212:213]
	v_pk_add_f32 v[186:187], v[200:201], v[174:175] neg_lo:[0,1] neg_hi:[0,1]
	v_pk_add_f32 v[202:203], v[170:171], v[172:173] neg_lo:[0,1] neg_hi:[0,1]
	v_pk_add_f32 v[174:175], v[200:201], v[174:175]
	v_pk_add_f32 v[170:171], v[170:171], v[172:173]
	v_pk_add_f32 v[216:217], v[210:211], v[212:213] neg_lo:[0,1] neg_hi:[0,1]
	v_pk_add_f32 v[210:211], v[176:177], v[208:209]
	v_pk_add_f32 v[172:173], v[174:175], v[170:171]
	v_pk_add_f32 v[170:171], v[174:175], v[170:171] neg_lo:[0,1] neg_hi:[0,1]
	v_pk_add_f32 v[176:177], v[176:177], v[208:209] neg_lo:[0,1] neg_hi:[0,1]
	v_pk_add_f32 v[208:209], v[214:215], v[216:217]
	v_pk_add_f32 v[212:213], v[214:215], v[216:217] neg_lo:[0,1] neg_hi:[0,1]
	v_pk_add_f32 v[174:175], v[186:187], v[202:203]
	v_pk_add_f32 v[186:187], v[186:187], v[202:203] neg_lo:[0,1] neg_hi:[0,1]
	v_pk_add_f32 v[200:201], v[210:211], v[210:211] op_sel:[1,0] op_sel_hi:[0,1]
	v_pk_add_f32 v[216:217], v[170:171], v[170:171] op_sel:[1,0] op_sel_hi:[0,1]
	v_pk_add_f32 v[170:171], v[170:171], v[170:171] op_sel:[0,1] op_sel_hi:[1,0] neg_lo:[0,1] neg_hi:[0,1]
	v_pk_add_f32 v[204:205], v[172:173], v[172:173] op_sel:[1,0] op_sel_hi:[0,1]
	v_pk_add_f32 v[172:173], v[172:173], v[172:173] op_sel:[0,1] op_sel_hi:[1,0] neg_lo:[0,1] neg_hi:[0,1]
	v_pk_add_f32 v[220:221], v[186:187], v[186:187] op_sel:[1,0] op_sel_hi:[0,1]
	v_pk_add_f32 v[186:187], v[186:187], v[186:187] op_sel:[0,1] op_sel_hi:[1,0] neg_lo:[0,1] neg_hi:[0,1]
	v_xor_b32_e32 v171, v181, v200
	v_pk_add_f32 v[202:203], v[210:211], v[210:211] op_sel:[0,1] op_sel_hi:[1,0] neg_lo:[0,1] neg_hi:[0,1]
	v_pk_add_f32 v[206:207], v[208:209], v[208:209] op_sel:[1,0] op_sel_hi:[0,1]
	v_pk_add_f32 v[210:211], v[174:175], v[174:175] op_sel:[1,0] op_sel_hi:[0,1]
	v_pk_add_f32 v[174:175], v[174:175], v[174:175] op_sel:[0,1] op_sel_hi:[1,0] neg_lo:[0,1] neg_hi:[0,1]
	v_pk_add_f32 v[214:215], v[176:177], v[176:177] op_sel:[1,0] op_sel_hi:[0,1]
	v_add_f32_dpp v171, v200, v171 quad_perm:[1,0,3,2] row_mask:0xf bank_mask:0xf bound_ctrl:1
	v_xor_b32_e32 v173, v181, v204
	v_xor_b32_e32 v205, v181, v186
	v_pk_add_f32 v[176:177], v[176:177], v[176:177] op_sel:[0,1] op_sel_hi:[1,0] neg_lo:[0,1] neg_hi:[0,1]
	v_add_f32_dpp v173, v204, v173 quad_perm:[1,0,3,2] row_mask:0xf bank_mask:0xf bound_ctrl:1
	v_xor_b32_e32 v175, v181, v206
	v_xor_b32_e32 v187, v181, v214
	v_add_f32_dpp v186, v186, v205 quad_perm:[1,0,3,2] row_mask:0xf bank_mask:0xf bound_ctrl:1
	v_xor_b32_e32 v205, v189, v171
	v_add_f32_dpp v175, v206, v175 quad_perm:[1,0,3,2] row_mask:0xf bank_mask:0xf bound_ctrl:1
	v_xor_b32_e32 v177, v181, v210
	v_add_f32_dpp v187, v214, v187 quad_perm:[1,0,3,2] row_mask:0xf bank_mask:0xf bound_ctrl:1
	v_add_f32_dpp v214, v171, v205 quad_perm:[2,3,0,1] row_mask:0xf bank_mask:0xf bound_ctrl:1
	v_xor_b32_e32 v171, v189, v173
	v_add_f32_dpp v177, v210, v177 quad_perm:[1,0,3,2] row_mask:0xf bank_mask:0xf bound_ctrl:1
	v_xor_b32_e32 v199, v181, v216
	v_add_f32_dpp v215, v173, v171 quad_perm:[2,3,0,1] row_mask:0xf bank_mask:0xf bound_ctrl:1
	v_xor_b32_e32 v171, v189, v175
	v_pk_add_f32 v[218:219], v[212:213], v[212:213] op_sel:[1,0] op_sel_hi:[0,1]
	v_add_f32_dpp v199, v216, v199 quad_perm:[1,0,3,2] row_mask:0xf bank_mask:0xf bound_ctrl:1
	v_add_f32_dpp v216, v175, v171 quad_perm:[2,3,0,1] row_mask:0xf bank_mask:0xf bound_ctrl:1
	v_xor_b32_e32 v171, v189, v177
	v_xor_b32_e32 v200, v181, v218
	v_xor_b32_e32 v201, v181, v220
	v_add_f32_dpp v217, v177, v171 quad_perm:[2,3,0,1] row_mask:0xf bank_mask:0xf bound_ctrl:1
	v_xor_b32_e32 v171, v189, v187
	v_add_f32_dpp v200, v218, v200 quad_perm:[1,0,3,2] row_mask:0xf bank_mask:0xf bound_ctrl:1
	v_add_f32_dpp v201, v220, v201 quad_perm:[1,0,3,2] row_mask:0xf bank_mask:0xf bound_ctrl:1
	v_add_f32_dpp v218, v187, v171 quad_perm:[2,3,0,1] row_mask:0xf bank_mask:0xf bound_ctrl:1
	v_xor_b32_e32 v171, v189, v199
	v_xor_b32_e32 v203, v181, v202
	v_pk_add_f32 v[208:209], v[208:209], v[208:209] op_sel:[0,1] op_sel_hi:[1,0] neg_lo:[0,1] neg_hi:[0,1]
	v_add_f32_dpp v199, v199, v171 quad_perm:[2,3,0,1] row_mask:0xf bank_mask:0xf bound_ctrl:1
	v_xor_b32_e32 v171, v189, v200
	v_add_f32_dpp v202, v202, v203 quad_perm:[1,0,3,2] row_mask:0xf bank_mask:0xf bound_ctrl:1
	v_xor_b32_e32 v203, v181, v172
	v_add_f32_dpp v219, v200, v171 quad_perm:[2,3,0,1] row_mask:0xf bank_mask:0xf bound_ctrl:1
	v_xor_b32_e32 v171, v189, v201
	v_add_f32_dpp v172, v172, v203 quad_perm:[1,0,3,2] row_mask:0xf bank_mask:0xf bound_ctrl:1
	v_xor_b32_e32 v203, v181, v208
	v_add_f32_dpp v220, v201, v171 quad_perm:[2,3,0,1] row_mask:0xf bank_mask:0xf bound_ctrl:1
	v_xor_b32_e32 v171, v189, v202
	v_add_f32_dpp v203, v208, v203 quad_perm:[1,0,3,2] row_mask:0xf bank_mask:0xf bound_ctrl:1
	v_xor_b32_e32 v204, v181, v174
	v_add_f32_dpp v221, v202, v171 quad_perm:[2,3,0,1] row_mask:0xf bank_mask:0xf bound_ctrl:1
	v_xor_b32_e32 v171, v189, v172
	v_add_f32_dpp v174, v174, v204 quad_perm:[1,0,3,2] row_mask:0xf bank_mask:0xf bound_ctrl:1
	v_xor_b32_e32 v204, v181, v176
	v_add_f32_dpp v223, v172, v171 quad_perm:[2,3,0,1] row_mask:0xf bank_mask:0xf bound_ctrl:1
	v_xor_b32_e32 v171, v189, v203
	v_pk_add_f32 v[212:213], v[212:213], v[212:213] op_sel:[0,1] op_sel_hi:[1,0] neg_lo:[0,1] neg_hi:[0,1]
	v_add_f32_dpp v176, v176, v204 quad_perm:[1,0,3,2] row_mask:0xf bank_mask:0xf bound_ctrl:1
	v_xor_b32_e32 v204, v181, v170
	v_add_f32_dpp v224, v203, v171 quad_perm:[2,3,0,1] row_mask:0xf bank_mask:0xf bound_ctrl:1
	v_xor_b32_e32 v171, v189, v174
	v_add_f32_dpp v170, v170, v204 quad_perm:[1,0,3,2] row_mask:0xf bank_mask:0xf bound_ctrl:1
	v_xor_b32_e32 v204, v181, v212
	v_add_f32_dpp v225, v174, v171 quad_perm:[2,3,0,1] row_mask:0xf bank_mask:0xf bound_ctrl:1
	v_xor_b32_e32 v171, v189, v176
	v_add_f32_dpp v204, v212, v204 quad_perm:[1,0,3,2] row_mask:0xf bank_mask:0xf bound_ctrl:1
	v_max_f32_e64 v172, |v219|, |v220|
	v_add_f32_dpp v226, v176, v171 quad_perm:[2,3,0,1] row_mask:0xf bank_mask:0xf bound_ctrl:1
	v_xor_b32_e32 v171, v189, v170
	v_lshlrev_b32_e32 v173, 16, v166
	v_and_b32_e32 v175, 0xffff0000, v166
	v_add_f32_dpp v227, v170, v171 quad_perm:[2,3,0,1] row_mask:0xf bank_mask:0xf bound_ctrl:1
	v_xor_b32_e32 v170, v189, v204
	v_max_f32_e64 v171, |v216|, |v217|
	v_and_b32_e32 v174, 0xffff0000, v162
	v_add_f32_dpp v228, v204, v170 quad_perm:[2,3,0,1] row_mask:0xf bank_mask:0xf bound_ctrl:1
	v_xor_b32_e32 v170, v189, v186
	v_lshlrev_b32_e32 v176, 16, v163
	v_lshlrev_b32_e32 v177, 16, v167
	v_add_f32_dpp v229, v186, v170 quad_perm:[2,3,0,1] row_mask:0xf bank_mask:0xf bound_ctrl:1
	v_max_f32_e64 v170, |v214|, |v215|
	v_max3_f32 v170, v222, v170, v171
	v_max_f32_e64 v171, |v218|, |v199|
	v_max3_f32 v170, v170, v171, v172
	v_max_f32_e64 v171, |v221|, |v223|
	v_max_f32_e64 v172, |v224|, |v225|
	v_max3_f32 v170, v170, v171, v172
	v_max_f32_e64 v171, |v226|, |v227|
	v_max_f32_e64 v172, |v228|, |v229|
	v_max3_f32 v222, v170, v171, v172
	v_and_b32_e32 v171, 0xffff0000, v169
	v_and_b32_e32 v170, 0xffff0000, v165
	v_lshlrev_b32_e32 v172, 16, v162
	v_and_b32_e32 v167, 0xffff0000, v167
	v_and_b32_e32 v166, 0xffff0000, v163
	v_lshlrev_b32_e32 v163, 16, v168
	v_lshlrev_b32_e32 v162, 16, v164
	v_and_b32_e32 v187, 0xffff0000, v168
	v_and_b32_e32 v186, 0xffff0000, v164
	v_lshlrev_b32_e32 v164, 16, v165
	v_lshlrev_b32_e32 v165, 16, v169
	v_pk_add_f32 v[168:169], v[172:173], v[174:175]
	v_pk_add_f32 v[200:201], v[176:177], v[166:167]
	v_pk_add_f32 v[202:203], v[162:163], v[186:187]
	v_pk_add_f32 v[204:205], v[164:165], v[170:171]
	v_pk_add_f32 v[172:173], v[172:173], v[174:175] neg_lo:[0,1] neg_hi:[0,1]
	v_pk_add_f32 v[166:167], v[176:177], v[166:167] neg_lo:[0,1] neg_hi:[0,1]
	v_pk_add_f32 v[162:163], v[162:163], v[186:187] neg_lo:[0,1] neg_hi:[0,1]
	v_pk_add_f32 v[164:165], v[164:165], v[170:171] neg_lo:[0,1] neg_hi:[0,1]
	v_pk_add_f32 v[206:207], v[168:169], v[200:201] neg_lo:[0,1] neg_hi:[0,1]
	v_pk_add_f32 v[208:209], v[202:203], v[204:205] neg_lo:[0,1] neg_hi:[0,1]
	v_pk_add_f32 v[168:169], v[168:169], v[200:201]
	v_pk_add_f32 v[200:201], v[202:203], v[204:205]
	v_pk_add_f32 v[170:171], v[172:173], v[166:167] neg_lo:[0,1] neg_hi:[0,1]
	v_pk_add_f32 v[174:175], v[162:163], v[164:165] neg_lo:[0,1] neg_hi:[0,1]
	v_pk_add_f32 v[166:167], v[172:173], v[166:167]
	v_pk_add_f32 v[162:163], v[162:163], v[164:165]
	v_pk_add_f32 v[202:203], v[168:169], v[200:201]
	v_pk_add_f32 v[168:169], v[168:169], v[200:201] neg_lo:[0,1] neg_hi:[0,1]
	v_pk_add_f32 v[200:201], v[206:207], v[208:209]
	v_pk_add_f32 v[164:165], v[166:167], v[162:163]
	v_pk_add_f32 v[162:163], v[166:167], v[162:163] neg_lo:[0,1] neg_hi:[0,1]
	v_pk_add_f32 v[166:167], v[170:171], v[174:175]
	v_pk_add_f32 v[204:205], v[206:207], v[208:209] neg_lo:[0,1] neg_hi:[0,1]
	v_pk_add_f32 v[170:171], v[170:171], v[174:175] neg_lo:[0,1] neg_hi:[0,1]
	v_pk_add_f32 v[172:173], v[202:203], v[202:203] op_sel:[1,0] op_sel_hi:[0,1]
	v_pk_add_f32 v[174:175], v[202:203], v[202:203] op_sel:[0,1] op_sel_hi:[1,0] neg_lo:[0,1] neg_hi:[0,1]
	v_pk_add_f32 v[186:187], v[200:201], v[200:201] op_sel:[1,0] op_sel_hi:[0,1]
	v_pk_add_f32 v[202:203], v[166:167], v[166:167] op_sel:[1,0] op_sel_hi:[0,1]
	v_pk_add_f32 v[166:167], v[166:167], v[166:167] op_sel:[0,1] op_sel_hi:[1,0] neg_lo:[0,1] neg_hi:[0,1]
	v_pk_add_f32 v[208:209], v[162:163], v[162:163] op_sel:[1,0] op_sel_hi:[0,1]
	v_pk_add_f32 v[162:163], v[162:163], v[162:163] op_sel:[0,1] op_sel_hi:[1,0] neg_lo:[0,1] neg_hi:[0,1]
	v_pk_add_f32 v[176:177], v[164:165], v[164:165] op_sel:[1,0] op_sel_hi:[0,1]
	v_pk_add_f32 v[164:165], v[164:165], v[164:165] op_sel:[0,1] op_sel_hi:[1,0] neg_lo:[0,1] neg_hi:[0,1]
	v_pk_add_f32 v[212:213], v[170:171], v[170:171] op_sel:[1,0] op_sel_hi:[0,1]
	v_pk_add_f32 v[170:171], v[170:171], v[170:171] op_sel:[0,1] op_sel_hi:[1,0] neg_lo:[0,1] neg_hi:[0,1]
	v_xor_b32_e32 v163, v181, v172
	v_xor_b32_e32 v167, v181, v186
	v_pk_add_f32 v[206:207], v[168:169], v[168:169] op_sel:[1,0] op_sel_hi:[0,1]
	v_add_f32_dpp v163, v172, v163 quad_perm:[1,0,3,2] row_mask:0xf bank_mask:0xf bound_ctrl:1
	v_xor_b32_e32 v165, v181, v176
	v_add_f32_dpp v167, v186, v167 quad_perm:[1,0,3,2] row_mask:0xf bank_mask:0xf bound_ctrl:1
	v_xor_b32_e32 v186, v181, v170
	v_pk_add_f32 v[168:169], v[168:169], v[168:169] op_sel:[0,1] op_sel_hi:[1,0] neg_lo:[0,1] neg_hi:[0,1]
	v_add_f32_dpp v165, v176, v165 quad_perm:[1,0,3,2] row_mask:0xf bank_mask:0xf bound_ctrl:1
	v_xor_b32_e32 v171, v181, v206
	v_add_f32_dpp v170, v170, v186 quad_perm:[1,0,3,2] row_mask:0xf bank_mask:0xf bound_ctrl:1
	v_xor_b32_e32 v186, v189, v163
	v_xor_b32_e32 v169, v181, v202
	v_add_f32_dpp v171, v206, v171 quad_perm:[1,0,3,2] row_mask:0xf bank_mask:0xf bound_ctrl:1
	v_add_f32_dpp v206, v163, v186 quad_perm:[2,3,0,1] row_mask:0xf bank_mask:0xf bound_ctrl:1
	v_xor_b32_e32 v163, v189, v165
	v_add_f32_dpp v169, v202, v169 quad_perm:[1,0,3,2] row_mask:0xf bank_mask:0xf bound_ctrl:1
	v_xor_b32_e32 v172, v181, v208
	v_add_f32_dpp v207, v165, v163 quad_perm:[2,3,0,1] row_mask:0xf bank_mask:0xf bound_ctrl:1
	v_xor_b32_e32 v163, v189, v167
	v_pk_add_f32 v[210:211], v[204:205], v[204:205] op_sel:[1,0] op_sel_hi:[0,1]
	v_add_f32_dpp v172, v208, v172 quad_perm:[1,0,3,2] row_mask:0xf bank_mask:0xf bound_ctrl:1
	v_add_f32_dpp v208, v167, v163 quad_perm:[2,3,0,1] row_mask:0xf bank_mask:0xf bound_ctrl:1
	v_xor_b32_e32 v163, v189, v169
	v_xor_b32_e32 v173, v181, v210
	v_xor_b32_e32 v175, v181, v212
	v_add_f32_dpp v209, v169, v163 quad_perm:[2,3,0,1] row_mask:0xf bank_mask:0xf bound_ctrl:1
	v_xor_b32_e32 v163, v189, v171
	v_add_f32_dpp v173, v210, v173 quad_perm:[1,0,3,2] row_mask:0xf bank_mask:0xf bound_ctrl:1
	v_add_f32_dpp v175, v212, v175 quad_perm:[1,0,3,2] row_mask:0xf bank_mask:0xf bound_ctrl:1
	v_add_f32_dpp v210, v171, v163 quad_perm:[2,3,0,1] row_mask:0xf bank_mask:0xf bound_ctrl:1
	v_xor_b32_e32 v163, v189, v172
	v_xor_b32_e32 v176, v181, v174
	v_pk_add_f32 v[200:201], v[200:201], v[200:201] op_sel:[0,1] op_sel_hi:[1,0] neg_lo:[0,1] neg_hi:[0,1]
	v_add_f32_dpp v211, v172, v163 quad_perm:[2,3,0,1] row_mask:0xf bank_mask:0xf bound_ctrl:1
	v_xor_b32_e32 v163, v189, v173
	v_add_f32_dpp v174, v174, v176 quad_perm:[1,0,3,2] row_mask:0xf bank_mask:0xf bound_ctrl:1
	v_xor_b32_e32 v176, v181, v164
	v_add_f32_dpp v212, v173, v163 quad_perm:[2,3,0,1] row_mask:0xf bank_mask:0xf bound_ctrl:1
	v_xor_b32_e32 v163, v189, v175
	v_add_f32_dpp v164, v164, v176 quad_perm:[1,0,3,2] row_mask:0xf bank_mask:0xf bound_ctrl:1
	v_xor_b32_e32 v176, v181, v200
	v_add_f32_dpp v213, v175, v163 quad_perm:[2,3,0,1] row_mask:0xf bank_mask:0xf bound_ctrl:1
	v_xor_b32_e32 v163, v189, v174
	v_add_f32_dpp v176, v200, v176 quad_perm:[1,0,3,2] row_mask:0xf bank_mask:0xf bound_ctrl:1
	v_xor_b32_e32 v177, v181, v166
	v_add_f32_dpp v230, v174, v163 quad_perm:[2,3,0,1] row_mask:0xf bank_mask:0xf bound_ctrl:1
	v_xor_b32_e32 v163, v189, v164
	v_add_f32_dpp v166, v166, v177 quad_perm:[1,0,3,2] row_mask:0xf bank_mask:0xf bound_ctrl:1
	v_xor_b32_e32 v177, v181, v168
	v_add_f32_dpp v231, v164, v163 quad_perm:[2,3,0,1] row_mask:0xf bank_mask:0xf bound_ctrl:1
	v_xor_b32_e32 v163, v189, v176
	v_pk_add_f32 v[204:205], v[204:205], v[204:205] op_sel:[0,1] op_sel_hi:[1,0] neg_lo:[0,1] neg_hi:[0,1]
	v_add_f32_dpp v168, v168, v177 quad_perm:[1,0,3,2] row_mask:0xf bank_mask:0xf bound_ctrl:1
	v_xor_b32_e32 v177, v181, v162
	v_add_f32_dpp v232, v176, v163 quad_perm:[2,3,0,1] row_mask:0xf bank_mask:0xf bound_ctrl:1
	v_xor_b32_e32 v163, v189, v166
	v_add_f32_dpp v162, v162, v177 quad_perm:[1,0,3,2] row_mask:0xf bank_mask:0xf bound_ctrl:1
	v_xor_b32_e32 v177, v181, v204
	v_add_f32_dpp v233, v166, v163 quad_perm:[2,3,0,1] row_mask:0xf bank_mask:0xf bound_ctrl:1
	v_xor_b32_e32 v163, v189, v168
	v_add_f32_dpp v177, v204, v177 quad_perm:[1,0,3,2] row_mask:0xf bank_mask:0xf bound_ctrl:1
	v_max_f32_e64 v164, |v212|, |v213|
	v_add_f32_dpp v235, v168, v163 quad_perm:[2,3,0,1] row_mask:0xf bank_mask:0xf bound_ctrl:1
	v_xor_b32_e32 v163, v189, v162
	v_lshlrev_b32_e32 v165, 16, v158
	v_and_b32_e32 v167, 0xffff0000, v158
	v_add_f32_dpp v236, v162, v163 quad_perm:[2,3,0,1] row_mask:0xf bank_mask:0xf bound_ctrl:1
	v_xor_b32_e32 v162, v189, v177
	v_max_f32_e64 v163, |v208|, |v209|
	v_and_b32_e32 v166, 0xffff0000, v150
	v_add_f32_dpp v237, v177, v162 quad_perm:[2,3,0,1] row_mask:0xf bank_mask:0xf bound_ctrl:1
	v_xor_b32_e32 v162, v189, v170
	v_lshlrev_b32_e32 v168, 16, v151
	v_lshlrev_b32_e32 v169, 16, v159
	v_add_f32_dpp v238, v170, v162 quad_perm:[2,3,0,1] row_mask:0xf bank_mask:0xf bound_ctrl:1
	v_max_f32_e64 v162, |v206|, |v207|
	v_max3_f32 v162, v222, v162, v163
	v_max_f32_e64 v163, |v210|, |v211|
	v_max3_f32 v162, v162, v163, v164
	v_max_f32_e64 v163, |v230|, |v231|
	v_max_f32_e64 v164, |v232|, |v233|
	v_max3_f32 v162, v162, v163, v164
	v_max_f32_e64 v163, |v235|, |v236|
	v_max_f32_e64 v164, |v237|, |v238|
	v_max3_f32 v222, v162, v163, v164
	v_and_b32_e32 v163, 0xffff0000, v161
	v_and_b32_e32 v162, 0xffff0000, v153
	v_lshlrev_b32_e32 v164, 16, v150
	v_and_b32_e32 v159, 0xffff0000, v159
	v_and_b32_e32 v158, 0xffff0000, v151
	v_lshlrev_b32_e32 v151, 16, v160
	v_lshlrev_b32_e32 v150, 16, v152
	v_and_b32_e32 v171, 0xffff0000, v160
	v_and_b32_e32 v170, 0xffff0000, v152
	v_lshlrev_b32_e32 v152, 16, v153
	v_lshlrev_b32_e32 v153, 16, v161
	v_pk_add_f32 v[160:161], v[164:165], v[166:167]
	v_pk_add_f32 v[172:173], v[168:169], v[158:159]
	v_pk_add_f32 v[174:175], v[150:151], v[170:171]
	v_pk_add_f32 v[176:177], v[152:153], v[162:163]
	v_pk_add_f32 v[164:165], v[164:165], v[166:167] neg_lo:[0,1] neg_hi:[0,1]
	v_pk_add_f32 v[158:159], v[168:169], v[158:159] neg_lo:[0,1] neg_hi:[0,1]
	v_pk_add_f32 v[150:151], v[150:151], v[170:171] neg_lo:[0,1] neg_hi:[0,1]
	v_pk_add_f32 v[152:153], v[152:153], v[162:163] neg_lo:[0,1] neg_hi:[0,1]
	v_pk_add_f32 v[186:187], v[160:161], v[172:173] neg_lo:[0,1] neg_hi:[0,1]
	v_pk_add_f32 v[200:201], v[174:175], v[176:177] neg_lo:[0,1] neg_hi:[0,1]
	v_pk_add_f32 v[160:161], v[160:161], v[172:173]
	v_pk_add_f32 v[172:173], v[174:175], v[176:177]
	v_pk_add_f32 v[162:163], v[164:165], v[158:159] neg_lo:[0,1] neg_hi:[0,1]
	v_pk_add_f32 v[166:167], v[150:151], v[152:153] neg_lo:[0,1] neg_hi:[0,1]
	v_pk_add_f32 v[158:159], v[164:165], v[158:159]
	v_pk_add_f32 v[150:151], v[150:151], v[152:153]
	v_pk_add_f32 v[174:175], v[160:161], v[172:173]
	v_pk_add_f32 v[160:161], v[160:161], v[172:173] neg_lo:[0,1] neg_hi:[0,1]
	v_pk_add_f32 v[172:173], v[186:187], v[200:201]
	v_pk_add_f32 v[152:153], v[158:159], v[150:151]
	v_pk_add_f32 v[150:151], v[158:159], v[150:151] neg_lo:[0,1] neg_hi:[0,1]
	v_pk_add_f32 v[158:159], v[162:163], v[166:167]
	v_pk_add_f32 v[176:177], v[186:187], v[200:201] neg_lo:[0,1] neg_hi:[0,1]
	v_pk_add_f32 v[162:163], v[162:163], v[166:167] neg_lo:[0,1] neg_hi:[0,1]
	v_pk_add_f32 v[164:165], v[174:175], v[174:175] op_sel:[1,0] op_sel_hi:[0,1]
	v_pk_add_f32 v[166:167], v[174:175], v[174:175] op_sel:[0,1] op_sel_hi:[1,0] neg_lo:[0,1] neg_hi:[0,1]
	v_pk_add_f32 v[170:171], v[172:173], v[172:173] op_sel:[1,0] op_sel_hi:[0,1]
	v_pk_add_f32 v[174:175], v[158:159], v[158:159] op_sel:[1,0] op_sel_hi:[0,1]
	v_pk_add_f32 v[158:159], v[158:159], v[158:159] op_sel:[0,1] op_sel_hi:[1,0] neg_lo:[0,1] neg_hi:[0,1]
	v_pk_add_f32 v[200:201], v[150:151], v[150:151] op_sel:[1,0] op_sel_hi:[0,1]
	v_pk_add_f32 v[150:151], v[150:151], v[150:151] op_sel:[0,1] op_sel_hi:[1,0] neg_lo:[0,1] neg_hi:[0,1]
	v_pk_add_f32 v[168:169], v[152:153], v[152:153] op_sel:[1,0] op_sel_hi:[0,1]
	v_pk_add_f32 v[152:153], v[152:153], v[152:153] op_sel:[0,1] op_sel_hi:[1,0] neg_lo:[0,1] neg_hi:[0,1]
	v_pk_add_f32 v[204:205], v[162:163], v[162:163] op_sel:[1,0] op_sel_hi:[0,1]
	v_pk_add_f32 v[162:163], v[162:163], v[162:163] op_sel:[0,1] op_sel_hi:[1,0] neg_lo:[0,1] neg_hi:[0,1]
	v_xor_b32_e32 v151, v181, v164
	v_xor_b32_e32 v159, v181, v170
	v_xor_b32_e32 v153, v181, v168
	v_add_f32_dpp v151, v164, v151 quad_perm:[1,0,3,2] row_mask:0xf bank_mask:0xf bound_ctrl:1
	v_add_f32_dpp v159, v170, v159 quad_perm:[1,0,3,2] row_mask:0xf bank_mask:0xf bound_ctrl:1
	v_xor_b32_e32 v170, v181, v162
	v_pk_add_f32 v[186:187], v[160:161], v[160:161] op_sel:[1,0] op_sel_hi:[0,1]
	v_pk_add_f32 v[160:161], v[160:161], v[160:161] op_sel:[0,1] op_sel_hi:[1,0] neg_lo:[0,1] neg_hi:[0,1]
	v_add_f32_dpp v153, v168, v153 quad_perm:[1,0,3,2] row_mask:0xf bank_mask:0xf bound_ctrl:1
	v_add_f32_dpp v162, v162, v170 quad_perm:[1,0,3,2] row_mask:0xf bank_mask:0xf bound_ctrl:1
	v_xor_b32_e32 v170, v189, v151
	v_xor_b32_e32 v161, v181, v174
	v_xor_b32_e32 v163, v181, v186
	v_add_f32_dpp v151, v151, v170 quad_perm:[2,3,0,1] row_mask:0xf bank_mask:0xf bound_ctrl:1
	v_xor_b32_e32 v170, v189, v153
	v_add_f32_dpp v161, v174, v161 quad_perm:[1,0,3,2] row_mask:0xf bank_mask:0xf bound_ctrl:1
	v_pk_add_f32 v[202:203], v[176:177], v[176:177] op_sel:[1,0] op_sel_hi:[0,1]
	v_add_f32_dpp v153, v153, v170 quad_perm:[2,3,0,1] row_mask:0xf bank_mask:0xf bound_ctrl:1
	v_xor_b32_e32 v170, v189, v159
	v_add_f32_dpp v163, v186, v163 quad_perm:[1,0,3,2] row_mask:0xf bank_mask:0xf bound_ctrl:1
	v_xor_b32_e32 v164, v181, v200
	v_add_f32_dpp v159, v159, v170 quad_perm:[2,3,0,1] row_mask:0xf bank_mask:0xf bound_ctrl:1
	v_xor_b32_e32 v170, v189, v161
	v_add_f32_dpp v164, v200, v164 quad_perm:[1,0,3,2] row_mask:0xf bank_mask:0xf bound_ctrl:1
	v_xor_b32_e32 v165, v181, v202
	v_add_f32_dpp v161, v161, v170 quad_perm:[2,3,0,1] row_mask:0xf bank_mask:0xf bound_ctrl:1
	v_xor_b32_e32 v170, v189, v163
	v_add_f32_dpp v165, v202, v165 quad_perm:[1,0,3,2] row_mask:0xf bank_mask:0xf bound_ctrl:1
	v_xor_b32_e32 v167, v181, v204
	v_add_f32_dpp v186, v163, v170 quad_perm:[2,3,0,1] row_mask:0xf bank_mask:0xf bound_ctrl:1
	v_xor_b32_e32 v163, v189, v164
	v_add_f32_dpp v167, v204, v167 quad_perm:[1,0,3,2] row_mask:0xf bank_mask:0xf bound_ctrl:1
	v_xor_b32_e32 v168, v181, v166
	v_add_f32_dpp v187, v164, v163 quad_perm:[2,3,0,1] row_mask:0xf bank_mask:0xf bound_ctrl:1
	v_xor_b32_e32 v163, v189, v165
	v_pk_add_f32 v[172:173], v[172:173], v[172:173] op_sel:[0,1] op_sel_hi:[1,0] neg_lo:[0,1] neg_hi:[0,1]
	v_add_f32_dpp v166, v166, v168 quad_perm:[1,0,3,2] row_mask:0xf bank_mask:0xf bound_ctrl:1
	v_xor_b32_e32 v168, v181, v152
	v_add_f32_dpp v200, v165, v163 quad_perm:[2,3,0,1] row_mask:0xf bank_mask:0xf bound_ctrl:1
	v_xor_b32_e32 v163, v189, v167
	v_add_f32_dpp v152, v152, v168 quad_perm:[1,0,3,2] row_mask:0xf bank_mask:0xf bound_ctrl:1
	v_xor_b32_e32 v168, v181, v172
	v_add_f32_dpp v201, v167, v163 quad_perm:[2,3,0,1] row_mask:0xf bank_mask:0xf bound_ctrl:1
	v_xor_b32_e32 v163, v189, v166
	v_add_f32_dpp v168, v172, v168 quad_perm:[1,0,3,2] row_mask:0xf bank_mask:0xf bound_ctrl:1
	v_xor_b32_e32 v169, v181, v158
	v_add_f32_dpp v202, v166, v163 quad_perm:[2,3,0,1] row_mask:0xf bank_mask:0xf bound_ctrl:1
	v_xor_b32_e32 v163, v189, v152
	v_add_f32_dpp v158, v158, v169 quad_perm:[1,0,3,2] row_mask:0xf bank_mask:0xf bound_ctrl:1
	v_xor_b32_e32 v169, v181, v160
	v_add_f32_dpp v203, v152, v163 quad_perm:[2,3,0,1] row_mask:0xf bank_mask:0xf bound_ctrl:1
	v_xor_b32_e32 v152, v189, v168
	v_pk_add_f32 v[176:177], v[176:177], v[176:177] op_sel:[0,1] op_sel_hi:[1,0] neg_lo:[0,1] neg_hi:[0,1]
	v_add_f32_dpp v160, v160, v169 quad_perm:[1,0,3,2] row_mask:0xf bank_mask:0xf bound_ctrl:1
	v_xor_b32_e32 v169, v181, v150
	v_add_f32_dpp v204, v168, v152 quad_perm:[2,3,0,1] row_mask:0xf bank_mask:0xf bound_ctrl:1
	v_xor_b32_e32 v152, v189, v158
	v_add_f32_dpp v150, v150, v169 quad_perm:[1,0,3,2] row_mask:0xf bank_mask:0xf bound_ctrl:1
	v_xor_b32_e32 v169, v181, v176
	v_add_f32_dpp v205, v158, v152 quad_perm:[2,3,0,1] row_mask:0xf bank_mask:0xf bound_ctrl:1
	v_xor_b32_e32 v152, v189, v160
	v_add_f32_dpp v169, v176, v169 quad_perm:[1,0,3,2] row_mask:0xf bank_mask:0xf bound_ctrl:1
	v_max_f32_e64 v158, |v200|, |v201|
	v_add_f32_dpp v160, v160, v152 quad_perm:[2,3,0,1] row_mask:0xf bank_mask:0xf bound_ctrl:1
	v_xor_b32_e32 v152, v189, v150
	v_cvt_pk_bf16_f32 v170, v214, v215
	v_cvt_pk_bf16_f32 v171, v216, v217
	v_cvt_pk_bf16_f32 v172, v218, v199
	v_cvt_pk_bf16_f32 v173, v219, v220
	v_cvt_pk_bf16_f32 v174, v221, v223
	s_nop 1
	v_add_f32_dpp v239, v150, v152 quad_perm:[2,3,0,1] row_mask:0xf bank_mask:0xf bound_ctrl:1
	v_xor_b32_e32 v150, v189, v169
	v_max_f32_e64 v152, |v159|, |v161|
	v_cvt_pk_bf16_f32 v175, v224, v225
	v_cvt_pk_bf16_f32 v176, v226, v227
	v_cvt_pk_bf16_f32 v177, v228, v229
	s_nop 0
	v_add_f32_dpp v240, v169, v150 quad_perm:[2,3,0,1] row_mask:0xf bank_mask:0xf bound_ctrl:1
	v_xor_b32_e32 v150, v189, v162
	s_nop 1
	v_add_f32_dpp v241, v162, v150 quad_perm:[2,3,0,1] row_mask:0xf bank_mask:0xf bound_ctrl:1
	v_max_f32_e64 v150, |v151|, |v153|
	v_max3_f32 v150, v222, v150, v152
	v_max_f32_e64 v152, |v186|, |v187|
	v_max3_f32 v150, v150, v152, v158
	v_max_f32_e64 v152, |v202|, |v203|
	v_max_f32_e64 v158, |v204|, |v205|
	v_max3_f32 v150, v150, v152, v158
	v_max_f32_e64 v152, |v160|, |v239|
	v_max_f32_e64 v158, |v240|, |v241|
	v_max3_f32 v150, v150, v152, v158
	ds_bpermute_b32 v152, v193, v150
	v_cvt_pk_bf16_f32 v162, v206, v207
	v_cvt_pk_bf16_f32 v163, v208, v209
	v_cvt_pk_bf16_f32 v164, v210, v211
	v_cvt_pk_bf16_f32 v165, v212, v213
	s_waitcnt lgkmcnt(0)
	v_max_f32_e32 v152, v152, v152
	v_max_f32_e32 v150, v150, v152
	ds_bpermute_b32 v152, v194, v150
	v_cvt_pk_bf16_f32 v166, v230, v231
	v_cvt_pk_bf16_f32 v167, v232, v233
	v_cvt_pk_bf16_f32 v168, v235, v236
	v_cvt_pk_bf16_f32 v169, v237, v238
	s_waitcnt lgkmcnt(0)
	v_max_f32_e32 v152, v152, v152
	v_max_f32_e32 v150, v150, v152
	ds_bpermute_b32 v152, v195, v150
	s_waitcnt lgkmcnt(0)
	v_max_f32_e32 v152, v152, v152
	v_max_f32_e32 v150, v150, v152
	ds_bpermute_b32 v152, v196, v150
	s_waitcnt lgkmcnt(0)
	v_max_f32_e32 v152, v152, v152
	v_max_f32_e32 v158, v150, v152
	ds_bpermute_b32 v193, v197, v158
	v_cvt_pk_bf16_f32 v150, v151, v153
	v_cvt_pk_bf16_f32 v151, v159, v161
	v_cvt_pk_bf16_f32 v152, v186, v187
	v_cvt_pk_bf16_f32 v153, v200, v201
	s_waitcnt lgkmcnt(0)
	v_max_f32_e32 v159, v193, v193
	v_max_f32_e32 v186, v158, v159
	ds_bpermute_b32 v187, v198, v186
	v_cvt_pk_bf16_f32 v158, v202, v203
	v_cvt_pk_bf16_f32 v159, v204, v205
	v_cvt_pk_bf16_f32 v160, v160, v239
	v_cvt_pk_bf16_f32 v161, v240, v241
	s_waitcnt lgkmcnt(0)
	v_max_f32_e32 v187, v187, v187
	v_max_f32_e32 v186, v186, v187
	s_and_saveexec_b64 s[28:29], s[2:3]
	s_cbranch_execz .LBB0_1871
	s_lshl_b64 s[30:31], s[26:27], 2
	s_sub_u32 s30, s37, s30
	s_subb_u32 s31, s38, s31
	v_mul_f32_e32 v187, 0x3a810204, v186
	global_store_dword v179, v187, s[30:31]
